# GEMM MFMA issue order serpentine in n: every consecutive MFMA pair shares one operand fragment (energy per MFMA in a clock-limited loop)
# baseline (speedup 1.0000x reference)
; #define PG8_STAGE(bufoff, gbase, voff) do { _Pragma("unroll") for (int _i = 0; _i < 2; ++_i) \
;         __builtin_amdgcn_global_load_lds((const unsigned*)((const char*)(gbase) + (voff)[_i]), (PG8_LAS unsigned*)(lds + (bufoff) + ldsw + _i * 8192), 16, 0, 0); } while (0)
; #define PG8_LDA(dst, b, h) do { _Pragma("unroll") for (int m = 0; m < 4; ++m) _Pragma("unroll") for (int k = 0; k < 2; ++k) dst[m][k] = *(const PG8_LAS bf16x8*)(lds + PG8_SA(b, h) + aoff + m * 2048 + k * 1024); } while (0)
; #define PG8_LDB(dst, b, h) do { _Pragma("unroll") for (int n = 0; n < 2; ++n) _Pragma("unroll") for (int k = 0; k < 2; ++k) dst[n][k] = *(const PG8_LAS bf16x8*)(lds + PG8_SB(b, h) + boff + n * 2048 + k * 1024); } while (0)
; #define PG8_MMA(ai, bj, At, Bt) do { __builtin_amdgcn_s_setprio(1); _Pragma("unroll") for (int m = 0; m < 4; ++m) _Pragma("unroll") for (int n = 0; n < 2; ++n) _Pragma("unroll") for (int k = 0; k < 2; ++k) \
;         acc[ai][bj][m][n] = __builtin_amdgcn_mfma_f32_16x16x32_bf16(Bt[n][k], At[m][k], acc[ai][bj][m][n], 0, 0, 0); __builtin_amdgcn_s_setprio(0); } while (0)
; #define PG8_BAR __builtin_amdgcn_s_barrier()
; template <class Epi, class Sched, bool ALIGN_EPI = false, bool SP2 = false>
; __device__ __forceinline__ void gemm_phase(PG8_LAS unsigned char* lds, const Gemm g, const Sched& S, const Epi& E) {
;     ...
;         const bool has_next = S.next(ui + 1, nxt);
;         const char* nA = has_next ? (const char*)g.A + (size_t)nxt.pm * tstep : cA; const char* nB = has_next ? (const char*)g.Bt + (size_t)nxt.pn * tstep : cB;
;         for (int t = 0; t < nt; t += 2) {
;             const bool last = (t == nt - 2);
;             const char* a1 = cA + (size_t)(t + 1) * kstep;
;             const char* a2 = last ? nA : cA + (size_t)(t + 2) * kstep; const char* b2 = last ? nB : cB + (size_t)(t + 2) * kstep;
;             const char* a3 = a2 + kstep; const char* b3 = b2 + kstep;
;             if (last && has_next) S.a_ready(nxt);
;             if constexpr (SP2) {
;             PG8_LDB(B0, 0, 0); PG8_LDB(B1, 0, 1); PG8_SCHED; PG8_LDA(At, 0, 0); PG8_STAGE(PG8_SA(1, 1), a1 + hstep, voffA);
;             PG8_WAIT_V(8); PG8_WAIT_L(0); PG8_BAR; PG8_MMA(0, 0, At, B0); PG8_MMA(0, 1, At, B1); PG8_BAR; PG8_SCHED;
;             PG8_LDA(At, 0, 1); PG8_STAGE(PG8_SB(0, 0), b2, voffB); PG8_STAGE(PG8_SB(0, 1), b2 + hstep, voffB); PG8_STAGE(PG8_SA(0, 0), a2, voffA);
.LBB0_223:
	s_ashr_i32 s15, s14, 31
	s_lshl_b64 s[16:17], s[14:15], 19
	s_add_u32 s16, s36, s16
	s_addc_u32 s17, s37, s17
	s_and_b64 s[18:19], s[4:5], exec
	s_cselect_b32 s15, s17, s21
	s_cselect_b32 s68, s16, s20
	s_ashr_i32 s13, s12, 31
	s_lshl_b64 s[18:19], s[12:13], 19
	s_add_u32 s18, s53, s18
	s_addc_u32 s19, s54, s19
	s_and_b64 s[46:47], s[4:5], exec
	s_cselect_b32 s13, s19, s43
	s_cselect_b32 s69, s18, s42
	s_add_u32 s20, s20, 0x40080
	s_addc_u32 s21, s21, 0
	s_add_u32 s70, s42, 0x100
	s_addc_u32 s71, s43, 0
	s_mov_b32 s72, -2
	ds_read_b128 v[154:157], v150
	ds_read_b128 v[158:161], v150 offset:1024
	ds_read_b128 v[162:165], v150 offset:2048
	ds_read_b128 v[166:169], v150 offset:3072
	ds_read_b128 v[170:173], v151
	ds_read_b128 v[174:177], v151 offset:1024
	ds_read_b128 v[178:181], v151 offset:2048
	ds_read_b128 v[182:185], v151 offset:3072
	s_add_u32 s42, s20, 0xfffc0080
	s_addc_u32 s43, s21, -1
	s_cmp_eq_u32 s72, 12
	s_cselect_b32 s47, s15, s43
	s_cselect_b32 s46, s68, s42
	s_cselect_b32 s43, s13, s71
	s_cselect_b32 s42, s69, s70
	s_add_i32 m0, s35, 0xc000
	ds_read_b128 v[186:189], v152
	ds_read_b128 v[190:193], v152 offset:1024
	ds_read_b128 v[198:201], v152 offset:2048
	ds_read_b128 v[202:205], v152 offset:3072
	ds_read_b128 v[206:209], v152 offset:4096
	ds_read_b128 v[210:213], v152 offset:5120
	ds_read_b128 v[214:217], v152 offset:6144
	ds_read_b128 v[218:221], v152 offset:7168
	global_load_lds_dwordx4 v136, s[20:21]
	s_add_i32 m0, s35, 0xe000
	s_nop 0
	global_load_lds_dwordx4 v138, s[20:21]
	s_waitcnt vmcnt(8)
	s_waitcnt lgkmcnt(0)
	s_barrier
	v_mfma_f32_16x16x32_bf16 v[124:127], v[154:157], v[186:189], 0
	v_mfma_f32_16x16x32_bf16 v[116:119], v[162:165], v[186:189], 0
	v_mfma_f32_16x16x32_bf16 v[100:103], v[162:165], v[198:201], 0
	v_mfma_f32_16x16x32_bf16 v[108:111], v[154:157], v[198:201], 0
	v_mfma_f32_16x16x32_bf16 v[92:95], v[154:157], v[206:209], 0
	v_mfma_f32_16x16x32_bf16 v[84:87], v[162:165], v[206:209], 0
	v_mfma_f32_16x16x32_bf16 v[68:71], v[162:165], v[214:217], 0
	v_mfma_f32_16x16x32_bf16 v[76:79], v[154:157], v[214:217], 0
	v_mfma_f32_16x16x32_bf16 v[124:127], v[158:161], v[190:193], v[124:127]
	v_mfma_f32_16x16x32_bf16 v[116:119], v[166:169], v[190:193], v[116:119]
	v_mfma_f32_16x16x32_bf16 v[100:103], v[166:169], v[202:205], v[100:103]
	v_mfma_f32_16x16x32_bf16 v[108:111], v[158:161], v[202:205], v[108:111]
	v_mfma_f32_16x16x32_bf16 v[92:95], v[158:161], v[210:213], v[92:95]
	v_mfma_f32_16x16x32_bf16 v[84:87], v[166:169], v[210:213], v[84:87]
	v_mfma_f32_16x16x32_bf16 v[68:71], v[166:169], v[218:221], v[68:71]
	v_mfma_f32_16x16x32_bf16 v[76:79], v[158:161], v[218:221], v[76:79]
	v_mfma_f32_16x16x32_bf16 v[120:123], v[170:173], v[186:189], 0
	v_mfma_f32_16x16x32_bf16 v[112:115], v[178:181], v[186:189], 0
	v_mfma_f32_16x16x32_bf16 v[96:99], v[178:181], v[198:201], 0
	v_mfma_f32_16x16x32_bf16 v[104:107], v[170:173], v[198:201], 0
	v_mfma_f32_16x16x32_bf16 v[88:91], v[170:173], v[206:209], 0
	v_mfma_f32_16x16x32_bf16 v[80:83], v[178:181], v[206:209], 0
	v_mfma_f32_16x16x32_bf16 v[64:67], v[178:181], v[214:217], 0
	v_mfma_f32_16x16x32_bf16 v[72:75], v[170:173], v[214:217], 0
	v_mfma_f32_16x16x32_bf16 v[120:123], v[174:177], v[190:193], v[120:123]
	v_mfma_f32_16x16x32_bf16 v[112:115], v[182:185], v[190:193], v[112:115]
	v_mfma_f32_16x16x32_bf16 v[96:99], v[182:185], v[202:205], v[96:99]
	v_mfma_f32_16x16x32_bf16 v[104:107], v[174:177], v[202:205], v[104:107]
	v_mfma_f32_16x16x32_bf16 v[88:91], v[174:177], v[210:213], v[88:91]
	v_mfma_f32_16x16x32_bf16 v[80:83], v[182:185], v[210:213], v[80:83]
	v_mfma_f32_16x16x32_bf16 v[64:67], v[182:185], v[218:221], v[64:67]
	v_mfma_f32_16x16x32_bf16 v[72:75], v[174:177], v[218:221], v[72:75]
	s_barrier
	s_add_i32 s73, s63, s55
	s_add_u32 s98, s42, s8
	s_addc_u32 s99, s43, s9
	s_add_u32 s100, s46, s8
	s_addc_u32 s101, s47, s9
	s_mov_b32 m0, s73
	ds_read_b128 v[186:189], v152 offset:16384
	ds_read_b128 v[190:193], v152 offset:17408
	ds_read_b128 v[198:201], v152 offset:18432
	ds_read_b128 v[202:205], v152 offset:19456
	ds_read_b128 v[206:209], v152 offset:20480
	ds_read_b128 v[210:213], v152 offset:21504
	ds_read_b128 v[214:217], v152 offset:22528
	ds_read_b128 v[218:221], v152 offset:23552
	global_load_lds_dwordx4 v132, s[42:43]
	s_add_i32 m0, s73, 0x2000
	s_add_u32 s74, s42, 0x40000
	s_addc_u32 s75, s43, 0
	s_add_i32 s73, s64, s55
	global_load_lds_dwordx4 v128, s[42:43]
	s_mov_b32 m0, s73
	s_nop 0
	global_load_lds_dwordx4 v132, s[74:75]
	s_add_i32 m0, s73, 0x2000
	s_nop 0
	global_load_lds_dwordx4 v128, s[74:75]
	s_mov_b32 m0, s35
	s_nop 0
	global_load_lds_dwordx4 v134, s[46:47]
	s_mov_b32 m0, s57
	s_nop 0
	global_load_lds_dwordx4 v130, s[46:47]
	s_waitcnt vmcnt(8)
	s_waitcnt lgkmcnt(0)
	s_barrier
; #define PG8_STAGE(bufoff, gbase, voff) do { _Pragma("unroll") for (int _i = 0; _i < 2; ++_i) \
;         __builtin_amdgcn_global_load_lds((const unsigned*)((const char*)(gbase) + (voff)[_i]), (PG8_LAS unsigned*)(lds + (bufoff) + ldsw + _i * 8192), 16, 0, 0); } while (0)
; #define PG8_LDA(dst, b, h) do { _Pragma("unroll") for (int m = 0; m < 4; ++m) _Pragma("unroll") for (int k = 0; k < 2; ++k) dst[m][k] = *(const PG8_LAS bf16x8*)(lds + PG8_SA(b, h) + aoff + m * 2048 + k * 1024); } while (0)
; #define PG8_LDB(dst, b, h) do { _Pragma("unroll") for (int n = 0; n < 2; ++n) _Pragma("unroll") for (int k = 0; k < 2; ++k) dst[n][k] = *(const PG8_LAS bf16x8*)(lds + PG8_SB(b, h) + boff + n * 2048 + k * 1024); } while (0)
; #define PG8_MMA(ai, bj, At, Bt) do { __builtin_amdgcn_s_setprio(1); _Pragma("unroll") for (int m = 0; m < 4; ++m) _Pragma("unroll") for (int n = 0; n < 2; ++n) _Pragma("unroll") for (int k = 0; k < 2; ++k) \
;         acc[ai][bj][m][n] = __builtin_amdgcn_mfma_f32_16x16x32_bf16(Bt[n][k], At[m][k], acc[ai][bj][m][n], 0, 0, 0); __builtin_amdgcn_s_setprio(0); } while (0)
; #define PG8_WAIT_V(n) asm volatile("s_waitcnt vmcnt(" #n ")" ::: "memory")
; #define PG8_WAIT_L(n) asm volatile("s_waitcnt lgkmcnt(" #n ")" ::: "memory")
; #define PG8_BAR __builtin_amdgcn_s_barrier()
; #define PG8_SCHED __builtin_amdgcn_sched_barrier(0)
; template <class Epi, class Sched, bool ALIGN_EPI = false, bool SP2 = false>
; __device__ __forceinline__ void gemm_phase(PG8_LAS unsigned char* lds, const Gemm g, const Sched& S, const Epi& E) {
;     ...
;             PG8_LDB(B0, 0, 0); PG8_LDB(B1, 0, 1); PG8_SCHED; PG8_LDA(At, 0, 0); PG8_STAGE(PG8_SA(1, 1), a1 + hstep, voffA);
;             PG8_WAIT_V(8); PG8_WAIT_L(0); PG8_BAR; PG8_MMA(0, 0, At, B0); PG8_MMA(0, 1, At, B1); PG8_BAR; PG8_SCHED;
;             PG8_LDA(At, 0, 1); PG8_STAGE(PG8_SB(0, 0), b2, voffB); PG8_STAGE(PG8_SB(0, 1), b2 + hstep, voffB); PG8_STAGE(PG8_SA(0, 0), a2, voffA);
;             PG8_WAIT_V(8); PG8_WAIT_L(0); PG8_BAR; PG8_MMA(1, 0, At, B0); PG8_MMA(1, 1, At, B1); PG8_BAR; PG8_SCHED;
;             PG8_LDB(B0, 1, 0); PG8_LDB(B1, 1, 1); PG8_SCHED; PG8_LDA(At, 1, 0); PG8_STAGE(PG8_SA(0, 1), a2 + hstep, voffA);
;             PG8_WAIT_V(8); PG8_WAIT_L(0); PG8_BAR; PG8_MMA(0, 0, At, B0); PG8_MMA(0, 1, At, B1); PG8_BAR; PG8_SCHED;
	v_mfma_f32_16x16x32_bf16 v[60:63], v[154:157], v[186:189], 0
	v_mfma_f32_16x16x32_bf16 v[52:55], v[162:165], v[186:189], 0
	v_mfma_f32_16x16x32_bf16 v[36:39], v[162:165], v[198:201], 0
	v_mfma_f32_16x16x32_bf16 v[44:47], v[154:157], v[198:201], 0
	v_mfma_f32_16x16x32_bf16 v[28:31], v[154:157], v[206:209], 0
	v_mfma_f32_16x16x32_bf16 v[20:23], v[162:165], v[206:209], 0
	v_mfma_f32_16x16x32_bf16 v[4:7], v[162:165], v[214:217], 0
	v_mfma_f32_16x16x32_bf16 v[12:15], v[154:157], v[214:217], 0
	v_mfma_f32_16x16x32_bf16 v[60:63], v[158:161], v[190:193], v[60:63]
	v_mfma_f32_16x16x32_bf16 v[52:55], v[166:169], v[190:193], v[52:55]
	v_mfma_f32_16x16x32_bf16 v[36:39], v[166:169], v[202:205], v[36:39]
	v_mfma_f32_16x16x32_bf16 v[44:47], v[158:161], v[202:205], v[44:47]
	v_mfma_f32_16x16x32_bf16 v[28:31], v[158:161], v[210:213], v[28:31]
	v_mfma_f32_16x16x32_bf16 v[20:23], v[166:169], v[210:213], v[20:23]
	v_mfma_f32_16x16x32_bf16 v[4:7], v[166:169], v[218:221], v[4:7]
	v_mfma_f32_16x16x32_bf16 v[12:15], v[158:161], v[218:221], v[12:15]
	v_mfma_f32_16x16x32_bf16 v[56:59], v[170:173], v[186:189], 0
	v_mfma_f32_16x16x32_bf16 v[48:51], v[178:181], v[186:189], 0
	v_mfma_f32_16x16x32_bf16 v[32:35], v[178:181], v[198:201], 0
	v_mfma_f32_16x16x32_bf16 v[40:43], v[170:173], v[198:201], 0
	v_mfma_f32_16x16x32_bf16 v[24:27], v[170:173], v[206:209], 0
	v_mfma_f32_16x16x32_bf16 v[16:19], v[178:181], v[206:209], 0
	v_mfma_f32_16x16x32_bf16 v[0:3], v[178:181], v[214:217], 0
	v_mfma_f32_16x16x32_bf16 v[8:11], v[170:173], v[214:217], 0
	v_mfma_f32_16x16x32_bf16 v[56:59], v[174:177], v[190:193], v[56:59]
	v_mfma_f32_16x16x32_bf16 v[48:51], v[182:185], v[190:193], v[48:51]
	v_mfma_f32_16x16x32_bf16 v[32:35], v[182:185], v[202:205], v[32:35]
	v_mfma_f32_16x16x32_bf16 v[40:43], v[174:177], v[202:205], v[40:43]
	v_mfma_f32_16x16x32_bf16 v[24:27], v[174:177], v[210:213], v[24:27]
	v_mfma_f32_16x16x32_bf16 v[16:19], v[182:185], v[210:213], v[16:19]
	v_mfma_f32_16x16x32_bf16 v[0:3], v[182:185], v[218:221], v[0:3]
	v_mfma_f32_16x16x32_bf16 v[8:11], v[174:177], v[218:221], v[8:11]
	s_barrier
	s_add_i32 s73, 0, 0x18000
	v_add_u32_e32 v153, s73, v147
	s_add_i32 s74, 0, 0x1c000
	ds_read_b128 v[154:157], v153
	ds_read_b128 v[158:161], v153 offset:1024
	ds_read_b128 v[162:165], v153 offset:2048
	ds_read_b128 v[166:169], v153 offset:3072
	v_add_u32_e32 v153, s74, v147
	ds_read_b128 v[170:173], v153
	ds_read_b128 v[174:177], v153 offset:1024
	ds_read_b128 v[178:181], v153 offset:2048
	ds_read_b128 v[182:185], v153 offset:3072
	s_add_u32 s46, s46, 0x40000
	s_addc_u32 s47, s47, 0
	s_mov_b32 m0, s58
	ds_read_b128 v[186:189], v152 offset:32768
	ds_read_b128 v[190:193], v152 offset:33792
	ds_read_b128 v[198:201], v152 offset:34816
	ds_read_b128 v[202:205], v152 offset:35840
	ds_read_b128 v[206:209], v152 offset:36864
	ds_read_b128 v[210:213], v152 offset:37888
	ds_read_b128 v[214:217], v152 offset:38912
	ds_read_b128 v[218:221], v152 offset:39936
	global_load_lds_dwordx4 v134, s[46:47]
	s_mov_b32 m0, s59
	s_nop 0
	global_load_lds_dwordx4 v130, s[46:47]
	s_waitcnt vmcnt(8)
	s_waitcnt lgkmcnt(0)
	s_barrier
	v_mfma_f32_16x16x32_bf16 v[124:127], v[154:157], v[186:189], v[124:127]
	v_mfma_f32_16x16x32_bf16 v[116:119], v[162:165], v[186:189], v[116:119]
	v_mfma_f32_16x16x32_bf16 v[100:103], v[162:165], v[198:201], v[100:103]
	v_mfma_f32_16x16x32_bf16 v[108:111], v[154:157], v[198:201], v[108:111]
	v_mfma_f32_16x16x32_bf16 v[92:95], v[154:157], v[206:209], v[92:95]
	v_mfma_f32_16x16x32_bf16 v[84:87], v[162:165], v[206:209], v[84:87]
	v_mfma_f32_16x16x32_bf16 v[68:71], v[162:165], v[214:217], v[68:71]
	v_mfma_f32_16x16x32_bf16 v[76:79], v[154:157], v[214:217], v[76:79]
	v_mfma_f32_16x16x32_bf16 v[124:127], v[158:161], v[190:193], v[124:127]
	v_mfma_f32_16x16x32_bf16 v[116:119], v[166:169], v[190:193], v[116:119]
	v_mfma_f32_16x16x32_bf16 v[100:103], v[166:169], v[202:205], v[100:103]
	v_mfma_f32_16x16x32_bf16 v[108:111], v[158:161], v[202:205], v[108:111]
	v_mfma_f32_16x16x32_bf16 v[92:95], v[158:161], v[210:213], v[92:95]
	v_mfma_f32_16x16x32_bf16 v[84:87], v[166:169], v[210:213], v[84:87]
	v_mfma_f32_16x16x32_bf16 v[68:71], v[166:169], v[218:221], v[68:71]
	v_mfma_f32_16x16x32_bf16 v[76:79], v[158:161], v[218:221], v[76:79]
	v_mfma_f32_16x16x32_bf16 v[120:123], v[170:173], v[186:189], v[120:123]
	v_mfma_f32_16x16x32_bf16 v[112:115], v[178:181], v[186:189], v[112:115]
	v_mfma_f32_16x16x32_bf16 v[96:99], v[178:181], v[198:201], v[96:99]
	v_mfma_f32_16x16x32_bf16 v[104:107], v[170:173], v[198:201], v[104:107]
	v_mfma_f32_16x16x32_bf16 v[88:91], v[170:173], v[206:209], v[88:91]
	v_mfma_f32_16x16x32_bf16 v[80:83], v[178:181], v[206:209], v[80:83]
	v_mfma_f32_16x16x32_bf16 v[64:67], v[178:181], v[214:217], v[64:67]
	v_mfma_f32_16x16x32_bf16 v[72:75], v[170:173], v[214:217], v[72:75]
	v_mfma_f32_16x16x32_bf16 v[120:123], v[174:177], v[190:193], v[120:123]
	v_mfma_f32_16x16x32_bf16 v[112:115], v[182:185], v[190:193], v[112:115]
	v_mfma_f32_16x16x32_bf16 v[96:99], v[182:185], v[202:205], v[96:99]
	v_mfma_f32_16x16x32_bf16 v[104:107], v[174:177], v[202:205], v[104:107]
	v_mfma_f32_16x16x32_bf16 v[88:91], v[174:177], v[210:213], v[88:91]
	v_mfma_f32_16x16x32_bf16 v[80:83], v[182:185], v[210:213], v[80:83]
	v_mfma_f32_16x16x32_bf16 v[64:67], v[182:185], v[218:221], v[64:67]
	v_mfma_f32_16x16x32_bf16 v[72:75], v[174:177], v[218:221], v[72:75]
	s_barrier
; #define PG8_STAGE(bufoff, gbase, voff) do { _Pragma("unroll") for (int _i = 0; _i < 2; ++_i) \
;         __builtin_amdgcn_global_load_lds((const unsigned*)((const char*)(gbase) + (voff)[_i]), (PG8_LAS unsigned*)(lds + (bufoff) + ldsw + _i * 8192), 16, 0, 0); } while (0)
; #define PG8_LDA(dst, b, h) do { _Pragma("unroll") for (int m = 0; m < 4; ++m) _Pragma("unroll") for (int k = 0; k < 2; ++k) dst[m][k] = *(const PG8_LAS bf16x8*)(lds + PG8_SA(b, h) + aoff + m * 2048 + k * 1024); } while (0)
; #define PG8_LDB(dst, b, h) do { _Pragma("unroll") for (int n = 0; n < 2; ++n) _Pragma("unroll") for (int k = 0; k < 2; ++k) dst[n][k] = *(const PG8_LAS bf16x8*)(lds + PG8_SB(b, h) + boff + n * 2048 + k * 1024); } while (0)
; #define PG8_MMA(ai, bj, At, Bt) do { __builtin_amdgcn_s_setprio(1); _Pragma("unroll") for (int m = 0; m < 4; ++m) _Pragma("unroll") for (int n = 0; n < 2; ++n) _Pragma("unroll") for (int k = 0; k < 2; ++k) \
;         acc[ai][bj][m][n] = __builtin_amdgcn_mfma_f32_16x16x32_bf16(Bt[n][k], At[m][k], acc[ai][bj][m][n], 0, 0, 0); __builtin_amdgcn_s_setprio(0); } while (0)
; #define PG8_WAIT_V(n) asm volatile("s_waitcnt vmcnt(" #n ")" ::: "memory")
; template <class Epi, class Sched, bool ALIGN_EPI = false, bool SP2 = false>
; __device__ __forceinline__ void gemm_phase(PG8_LAS unsigned char* lds, const Gemm g, const Sched& S, const Epi& E) {
;     ...
;             PG8_LDB(B0, 0, 0); PG8_LDB(B1, 0, 1); PG8_SCHED; PG8_LDA(At, 0, 0); PG8_STAGE(PG8_SA(1, 1), a1 + hstep, voffA);
;             PG8_WAIT_V(8); PG8_WAIT_L(0); PG8_BAR; PG8_MMA(0, 0, At, B0); PG8_MMA(0, 1, At, B1); PG8_BAR; PG8_SCHED;
;             PG8_LDA(At, 0, 1); PG8_STAGE(PG8_SB(0, 0), b2, voffB); PG8_STAGE(PG8_SB(0, 1), b2 + hstep, voffB); PG8_STAGE(PG8_SA(0, 0), a2, voffA);
;             PG8_WAIT_V(8); PG8_WAIT_L(0); PG8_BAR; PG8_MMA(1, 0, At, B0); PG8_MMA(1, 1, At, B1); PG8_BAR; PG8_SCHED;
;             PG8_LDB(B0, 1, 0); PG8_LDB(B1, 1, 1); PG8_SCHED; PG8_LDA(At, 1, 0); PG8_STAGE(PG8_SA(0, 1), a2 + hstep, voffA);
;             PG8_WAIT_V(8); PG8_WAIT_L(0); PG8_BAR; PG8_MMA(0, 0, At, B0); PG8_MMA(0, 1, At, B1); PG8_BAR; PG8_SCHED;
;             PG8_LDA(At, 1, 1); PG8_STAGE(PG8_SB(1, 0), b3, voffB); PG8_STAGE(PG8_SB(1, 1), b3 + hstep, voffB); PG8_STAGE(PG8_SA(1, 0), a3, voffA);
;             PG8_WAIT_V(8); PG8_WAIT_L(0); PG8_BAR; PG8_MMA(1, 0, At, B0); PG8_MMA(1, 1, At, B1); PG8_BAR; PG8_SCHED;
	s_add_i32 s46, s73, s55
	s_mov_b32 m0, s46
	ds_read_b128 v[186:189], v152 offset:49152
	ds_read_b128 v[190:193], v152 offset:50176
	ds_read_b128 v[198:201], v152 offset:51200
	ds_read_b128 v[202:205], v152 offset:52224
	ds_read_b128 v[206:209], v152 offset:53248
	ds_read_b128 v[210:213], v152 offset:54272
	ds_read_b128 v[214:217], v152 offset:55296
	ds_read_b128 v[218:221], v152 offset:56320
	global_load_lds_dwordx4 v132, s[98:99]
	s_add_i32 m0, s46, 0x2000
	s_add_u32 s42, s42, 0x40080
	s_addc_u32 s43, s43, 0
	s_add_i32 s46, s74, s55
	global_load_lds_dwordx4 v128, s[98:99]
	s_mov_b32 m0, s46
	s_nop 0
	global_load_lds_dwordx4 v132, s[42:43]
	s_add_i32 m0, s46, 0x2000
	s_nop 0
	global_load_lds_dwordx4 v128, s[42:43]
	s_mov_b32 m0, s61
	s_nop 0
	global_load_lds_dwordx4 v134, s[100:101]
	s_mov_b32 m0, s62
	s_nop 0
	global_load_lds_dwordx4 v130, s[100:101]
	s_waitcnt vmcnt(8)
	s_waitcnt lgkmcnt(0)
	s_barrier
	v_mfma_f32_16x16x32_bf16 v[60:63], v[154:157], v[186:189], v[60:63]
	v_mfma_f32_16x16x32_bf16 v[52:55], v[162:165], v[186:189], v[52:55]
	v_mfma_f32_16x16x32_bf16 v[36:39], v[162:165], v[198:201], v[36:39]
	v_mfma_f32_16x16x32_bf16 v[44:47], v[154:157], v[198:201], v[44:47]
	v_mfma_f32_16x16x32_bf16 v[28:31], v[154:157], v[206:209], v[28:31]
	v_mfma_f32_16x16x32_bf16 v[20:23], v[162:165], v[206:209], v[20:23]
	v_mfma_f32_16x16x32_bf16 v[4:7], v[162:165], v[214:217], v[4:7]
	v_mfma_f32_16x16x32_bf16 v[12:15], v[154:157], v[214:217], v[12:15]
	v_mfma_f32_16x16x32_bf16 v[60:63], v[158:161], v[190:193], v[60:63]
	v_mfma_f32_16x16x32_bf16 v[52:55], v[166:169], v[190:193], v[52:55]
	v_mfma_f32_16x16x32_bf16 v[36:39], v[166:169], v[202:205], v[36:39]
	v_mfma_f32_16x16x32_bf16 v[44:47], v[158:161], v[202:205], v[44:47]
	v_mfma_f32_16x16x32_bf16 v[28:31], v[158:161], v[210:213], v[28:31]
	v_mfma_f32_16x16x32_bf16 v[20:23], v[166:169], v[210:213], v[20:23]
	v_mfma_f32_16x16x32_bf16 v[4:7], v[166:169], v[218:221], v[4:7]
	v_mfma_f32_16x16x32_bf16 v[12:15], v[158:161], v[218:221], v[12:15]
	v_mfma_f32_16x16x32_bf16 v[56:59], v[170:173], v[186:189], v[56:59]
	v_mfma_f32_16x16x32_bf16 v[48:51], v[178:181], v[186:189], v[48:51]
	v_mfma_f32_16x16x32_bf16 v[32:35], v[178:181], v[198:201], v[32:35]
	v_mfma_f32_16x16x32_bf16 v[40:43], v[170:173], v[198:201], v[40:43]
	v_mfma_f32_16x16x32_bf16 v[24:27], v[170:173], v[206:209], v[24:27]
	v_mfma_f32_16x16x32_bf16 v[16:19], v[178:181], v[206:209], v[16:19]
	v_mfma_f32_16x16x32_bf16 v[0:3], v[178:181], v[214:217], v[0:3]
	v_mfma_f32_16x16x32_bf16 v[8:11], v[170:173], v[214:217], v[8:11]
	v_mfma_f32_16x16x32_bf16 v[56:59], v[174:177], v[190:193], v[56:59]
	v_mfma_f32_16x16x32_bf16 v[48:51], v[182:185], v[190:193], v[48:51]
	v_mfma_f32_16x16x32_bf16 v[32:35], v[182:185], v[202:205], v[32:35]
	v_mfma_f32_16x16x32_bf16 v[40:43], v[174:177], v[202:205], v[40:43]
	v_mfma_f32_16x16x32_bf16 v[24:27], v[174:177], v[210:213], v[24:27]
	v_mfma_f32_16x16x32_bf16 v[16:19], v[182:185], v[210:213], v[16:19]
	v_mfma_f32_16x16x32_bf16 v[0:3], v[182:185], v[218:221], v[0:3]
	v_mfma_f32_16x16x32_bf16 v[8:11], v[174:177], v[218:221], v[8:11]
	s_barrier
	s_add_i32 s72, s72, 2
	s_add_u32 s20, s20, 0x100
	s_addc_u32 s21, s21, 0
	s_add_u32 s70, s70, 0x100
	s_addc_u32 s71, s71, 0
	s_cmp_gt_u32 s72, 13
.LBB0_224:
	ds_read_b128 v[154:157], v150
	ds_read_b128 v[158:161], v150 offset:1024
	ds_read_b128 v[162:165], v150 offset:2048
	ds_read_b128 v[166:169], v150 offset:3072
	ds_read_b128 v[170:173], v151
	ds_read_b128 v[174:177], v151 offset:1024
	ds_read_b128 v[178:181], v151 offset:2048
	ds_read_b128 v[182:185], v151 offset:3072
	s_add_u32 s42, s20, 0xfffc0080
	s_addc_u32 s43, s21, -1
	s_cmp_eq_u32 s72, 12
	s_cselect_b32 s47, s15, s43
	s_cselect_b32 s46, s68, s42
	s_cselect_b32 s43, s13, s71
	s_cselect_b32 s42, s69, s70
	s_add_i32 m0, s35, 0xc000
	ds_read_b128 v[186:189], v152
	ds_read_b128 v[190:193], v152 offset:1024
	ds_read_b128 v[198:201], v152 offset:2048
	ds_read_b128 v[202:205], v152 offset:3072
	ds_read_b128 v[206:209], v152 offset:4096
	ds_read_b128 v[210:213], v152 offset:5120
	ds_read_b128 v[214:217], v152 offset:6144
	ds_read_b128 v[218:221], v152 offset:7168
	global_load_lds_dwordx4 v136, s[20:21]
	s_add_i32 m0, s35, 0xe000
	s_nop 0
	global_load_lds_dwordx4 v138, s[20:21]
	s_waitcnt vmcnt(8)
	s_waitcnt lgkmcnt(0)
	s_barrier
	v_mfma_f32_16x16x32_bf16 v[124:127], v[154:157], v[186:189], v[124:127]
	v_mfma_f32_16x16x32_bf16 v[116:119], v[162:165], v[186:189], v[116:119]
	v_mfma_f32_16x16x32_bf16 v[100:103], v[162:165], v[198:201], v[100:103]
	v_mfma_f32_16x16x32_bf16 v[108:111], v[154:157], v[198:201], v[108:111]
	v_mfma_f32_16x16x32_bf16 v[92:95], v[154:157], v[206:209], v[92:95]
	v_mfma_f32_16x16x32_bf16 v[84:87], v[162:165], v[206:209], v[84:87]
	v_mfma_f32_16x16x32_bf16 v[68:71], v[162:165], v[214:217], v[68:71]
	v_mfma_f32_16x16x32_bf16 v[76:79], v[154:157], v[214:217], v[76:79]
	v_mfma_f32_16x16x32_bf16 v[124:127], v[158:161], v[190:193], v[124:127]
	v_mfma_f32_16x16x32_bf16 v[116:119], v[166:169], v[190:193], v[116:119]
	v_mfma_f32_16x16x32_bf16 v[100:103], v[166:169], v[202:205], v[100:103]
	v_mfma_f32_16x16x32_bf16 v[108:111], v[158:161], v[202:205], v[108:111]
	v_mfma_f32_16x16x32_bf16 v[92:95], v[158:161], v[210:213], v[92:95]
	v_mfma_f32_16x16x32_bf16 v[84:87], v[166:169], v[210:213], v[84:87]
	v_mfma_f32_16x16x32_bf16 v[68:71], v[166:169], v[218:221], v[68:71]
	v_mfma_f32_16x16x32_bf16 v[76:79], v[158:161], v[218:221], v[76:79]
	v_mfma_f32_16x16x32_bf16 v[120:123], v[170:173], v[186:189], v[120:123]
	v_mfma_f32_16x16x32_bf16 v[112:115], v[178:181], v[186:189], v[112:115]
	v_mfma_f32_16x16x32_bf16 v[96:99], v[178:181], v[198:201], v[96:99]
	v_mfma_f32_16x16x32_bf16 v[104:107], v[170:173], v[198:201], v[104:107]
	v_mfma_f32_16x16x32_bf16 v[88:91], v[170:173], v[206:209], v[88:91]
	v_mfma_f32_16x16x32_bf16 v[80:83], v[178:181], v[206:209], v[80:83]
	v_mfma_f32_16x16x32_bf16 v[64:67], v[178:181], v[214:217], v[64:67]
	v_mfma_f32_16x16x32_bf16 v[72:75], v[170:173], v[214:217], v[72:75]
	v_mfma_f32_16x16x32_bf16 v[120:123], v[174:177], v[190:193], v[120:123]
	v_mfma_f32_16x16x32_bf16 v[112:115], v[182:185], v[190:193], v[112:115]
	v_mfma_f32_16x16x32_bf16 v[96:99], v[182:185], v[202:205], v[96:99]
	v_mfma_f32_16x16x32_bf16 v[104:107], v[174:177], v[202:205], v[104:107]
	v_mfma_f32_16x16x32_bf16 v[88:91], v[174:177], v[210:213], v[88:91]
	v_mfma_f32_16x16x32_bf16 v[80:83], v[182:185], v[210:213], v[80:83]
	v_mfma_f32_16x16x32_bf16 v[64:67], v[182:185], v[218:221], v[64:67]
	v_mfma_f32_16x16x32_bf16 v[72:75], v[174:177], v[218:221], v[72:75]
	s_barrier
; #define PG8_STAGE(bufoff, gbase, voff) do { _Pragma("unroll") for (int _i = 0; _i < 2; ++_i) \
;         __builtin_amdgcn_global_load_lds((const unsigned*)((const char*)(gbase) + (voff)[_i]), (PG8_LAS unsigned*)(lds + (bufoff) + ldsw + _i * 8192), 16, 0, 0); } while (0)
; #define PG8_LDA(dst, b, h) do { _Pragma("unroll") for (int m = 0; m < 4; ++m) _Pragma("unroll") for (int k = 0; k < 2; ++k) dst[m][k] = *(const PG8_LAS bf16x8*)(lds + PG8_SA(b, h) + aoff + m * 2048 + k * 1024); } while (0)
; #define PG8_LDB(dst, b, h) do { _Pragma("unroll") for (int n = 0; n < 2; ++n) _Pragma("unroll") for (int k = 0; k < 2; ++k) dst[n][k] = *(const PG8_LAS bf16x8*)(lds + PG8_SB(b, h) + boff + n * 2048 + k * 1024); } while (0)
; #define PG8_MMA(ai, bj, At, Bt) do { __builtin_amdgcn_s_setprio(1); _Pragma("unroll") for (int m = 0; m < 4; ++m) _Pragma("unroll") for (int n = 0; n < 2; ++n) _Pragma("unroll") for (int k = 0; k < 2; ++k) \
;         acc[ai][bj][m][n] = __builtin_amdgcn_mfma_f32_16x16x32_bf16(Bt[n][k], At[m][k], acc[ai][bj][m][n], 0, 0, 0); __builtin_amdgcn_s_setprio(0); } while (0)
; #define PG8_WAIT_V(n) asm volatile("s_waitcnt vmcnt(" #n ")" ::: "memory")
; template <class Epi, class Sched, bool ALIGN_EPI = false, bool SP2 = false>
; __device__ __forceinline__ void gemm_phase(PG8_LAS unsigned char* lds, const Gemm g, const Sched& S, const Epi& E) {
;     ...
;             PG8_LDB(B0, 0, 0); PG8_LDB(B1, 0, 1); PG8_SCHED; PG8_LDA(At, 0, 0); PG8_STAGE(PG8_SA(1, 1), a1 + hstep, voffA);
;             PG8_WAIT_V(8); PG8_WAIT_L(0); PG8_BAR; PG8_MMA(0, 0, At, B0); PG8_MMA(0, 1, At, B1); PG8_BAR; PG8_SCHED;
;             PG8_LDA(At, 0, 1); PG8_STAGE(PG8_SB(0, 0), b2, voffB); PG8_STAGE(PG8_SB(0, 1), b2 + hstep, voffB); PG8_STAGE(PG8_SA(0, 0), a2, voffA);
;             PG8_WAIT_V(8); PG8_WAIT_L(0); PG8_BAR; PG8_MMA(1, 0, At, B0); PG8_MMA(1, 1, At, B1); PG8_BAR; PG8_SCHED;
;             PG8_LDB(B0, 1, 0); PG8_LDB(B1, 1, 1); PG8_SCHED; PG8_LDA(At, 1, 0); PG8_STAGE(PG8_SA(0, 1), a2 + hstep, voffA);
;             PG8_WAIT_V(8); PG8_WAIT_L(0); PG8_BAR; PG8_MMA(0, 0, At, B0); PG8_MMA(0, 1, At, B1); PG8_BAR; PG8_SCHED;
;             PG8_LDA(At, 1, 1); PG8_STAGE(PG8_SB(1, 0), b3, voffB); PG8_STAGE(PG8_SB(1, 1), b3 + hstep, voffB); PG8_STAGE(PG8_SA(1, 0), a3, voffA);
;             PG8_WAIT_V(8); PG8_WAIT_L(0); PG8_BAR; PG8_MMA(1, 0, At, B0); PG8_MMA(1, 1, At, B1); PG8_BAR; PG8_SCHED;
	s_add_i32 s73, s63, s55
	s_add_u32 s98, s42, s8
	s_addc_u32 s99, s43, s9
	s_add_u32 s100, s46, s8
	s_addc_u32 s101, s47, s9
	s_mov_b32 m0, s73
	ds_read_b128 v[186:189], v152 offset:16384
	ds_read_b128 v[190:193], v152 offset:17408
	ds_read_b128 v[198:201], v152 offset:18432
	ds_read_b128 v[202:205], v152 offset:19456
	ds_read_b128 v[206:209], v152 offset:20480
	ds_read_b128 v[210:213], v152 offset:21504
	ds_read_b128 v[214:217], v152 offset:22528
	ds_read_b128 v[218:221], v152 offset:23552
	global_load_lds_dwordx4 v132, s[42:43]
	s_add_i32 m0, s73, 0x2000
	s_add_u32 s74, s42, 0x40000
	s_addc_u32 s75, s43, 0
	s_add_i32 s73, s64, s55
	global_load_lds_dwordx4 v128, s[42:43]
	s_mov_b32 m0, s73
	s_nop 0
	global_load_lds_dwordx4 v132, s[74:75]
	s_add_i32 m0, s73, 0x2000
	s_nop 0
	global_load_lds_dwordx4 v128, s[74:75]
	s_mov_b32 m0, s35
	s_nop 0
	global_load_lds_dwordx4 v134, s[46:47]
	s_mov_b32 m0, s57
	s_nop 0
	global_load_lds_dwordx4 v130, s[46:47]
	s_waitcnt vmcnt(8)
	s_waitcnt lgkmcnt(0)
	s_barrier
	v_mfma_f32_16x16x32_bf16 v[60:63], v[154:157], v[186:189], v[60:63]
	v_mfma_f32_16x16x32_bf16 v[52:55], v[162:165], v[186:189], v[52:55]
	v_mfma_f32_16x16x32_bf16 v[36:39], v[162:165], v[198:201], v[36:39]
	v_mfma_f32_16x16x32_bf16 v[44:47], v[154:157], v[198:201], v[44:47]
	v_mfma_f32_16x16x32_bf16 v[28:31], v[154:157], v[206:209], v[28:31]
	v_mfma_f32_16x16x32_bf16 v[20:23], v[162:165], v[206:209], v[20:23]
	v_mfma_f32_16x16x32_bf16 v[4:7], v[162:165], v[214:217], v[4:7]
	v_mfma_f32_16x16x32_bf16 v[12:15], v[154:157], v[214:217], v[12:15]
	v_mfma_f32_16x16x32_bf16 v[60:63], v[158:161], v[190:193], v[60:63]
	v_mfma_f32_16x16x32_bf16 v[52:55], v[166:169], v[190:193], v[52:55]
	v_mfma_f32_16x16x32_bf16 v[36:39], v[166:169], v[202:205], v[36:39]
	v_mfma_f32_16x16x32_bf16 v[44:47], v[158:161], v[202:205], v[44:47]
	v_mfma_f32_16x16x32_bf16 v[28:31], v[158:161], v[210:213], v[28:31]
	v_mfma_f32_16x16x32_bf16 v[20:23], v[166:169], v[210:213], v[20:23]
	v_mfma_f32_16x16x32_bf16 v[4:7], v[166:169], v[218:221], v[4:7]
	v_mfma_f32_16x16x32_bf16 v[12:15], v[158:161], v[218:221], v[12:15]
	v_mfma_f32_16x16x32_bf16 v[56:59], v[170:173], v[186:189], v[56:59]
	v_mfma_f32_16x16x32_bf16 v[48:51], v[178:181], v[186:189], v[48:51]
	v_mfma_f32_16x16x32_bf16 v[32:35], v[178:181], v[198:201], v[32:35]
	v_mfma_f32_16x16x32_bf16 v[40:43], v[170:173], v[198:201], v[40:43]
	v_mfma_f32_16x16x32_bf16 v[24:27], v[170:173], v[206:209], v[24:27]
	v_mfma_f32_16x16x32_bf16 v[16:19], v[178:181], v[206:209], v[16:19]
	v_mfma_f32_16x16x32_bf16 v[0:3], v[178:181], v[214:217], v[0:3]
	v_mfma_f32_16x16x32_bf16 v[8:11], v[170:173], v[214:217], v[8:11]
	v_mfma_f32_16x16x32_bf16 v[56:59], v[174:177], v[190:193], v[56:59]
	v_mfma_f32_16x16x32_bf16 v[48:51], v[182:185], v[190:193], v[48:51]
	v_mfma_f32_16x16x32_bf16 v[32:35], v[182:185], v[202:205], v[32:35]
	v_mfma_f32_16x16x32_bf16 v[40:43], v[174:177], v[202:205], v[40:43]
	v_mfma_f32_16x16x32_bf16 v[24:27], v[174:177], v[210:213], v[24:27]
	v_mfma_f32_16x16x32_bf16 v[16:19], v[182:185], v[210:213], v[16:19]
	v_mfma_f32_16x16x32_bf16 v[0:3], v[182:185], v[218:221], v[0:3]
	v_mfma_f32_16x16x32_bf16 v[8:11], v[174:177], v[218:221], v[8:11]
	s_barrier
	s_add_i32 s73, 0, 0x18000
	v_add_u32_e32 v153, s73, v147
	s_add_i32 s74, 0, 0x1c000
	ds_read_b128 v[154:157], v153
	ds_read_b128 v[158:161], v153 offset:1024
	ds_read_b128 v[162:165], v153 offset:2048
	ds_read_b128 v[166:169], v153 offset:3072
	v_add_u32_e32 v153, s74, v147
	ds_read_b128 v[170:173], v153
	ds_read_b128 v[174:177], v153 offset:1024
	ds_read_b128 v[178:181], v153 offset:2048
	ds_read_b128 v[182:185], v153 offset:3072
	s_add_u32 s46, s46, 0x40000
	s_addc_u32 s47, s47, 0
	s_mov_b32 m0, s58
	ds_read_b128 v[186:189], v152 offset:32768
	ds_read_b128 v[190:193], v152 offset:33792
	ds_read_b128 v[198:201], v152 offset:34816
	ds_read_b128 v[202:205], v152 offset:35840
	ds_read_b128 v[206:209], v152 offset:36864
	ds_read_b128 v[210:213], v152 offset:37888
	ds_read_b128 v[214:217], v152 offset:38912
	ds_read_b128 v[218:221], v152 offset:39936
	global_load_lds_dwordx4 v134, s[46:47]
	s_mov_b32 m0, s59
	s_nop 0
	global_load_lds_dwordx4 v130, s[46:47]
	s_waitcnt vmcnt(8)
	s_waitcnt lgkmcnt(0)
	s_barrier
; #define PG8_STAGE(bufoff, gbase, voff) do { _Pragma("unroll") for (int _i = 0; _i < 2; ++_i) \
;         __builtin_amdgcn_global_load_lds((const unsigned*)((const char*)(gbase) + (voff)[_i]), (PG8_LAS unsigned*)(lds + (bufoff) + ldsw + _i * 8192), 16, 0, 0); } while (0)
; #define PG8_LDA(dst, b, h) do { _Pragma("unroll") for (int m = 0; m < 4; ++m) _Pragma("unroll") for (int k = 0; k < 2; ++k) dst[m][k] = *(const PG8_LAS bf16x8*)(lds + PG8_SA(b, h) + aoff + m * 2048 + k * 1024); } while (0)
; #define PG8_LDB(dst, b, h) do { _Pragma("unroll") for (int n = 0; n < 2; ++n) _Pragma("unroll") for (int k = 0; k < 2; ++k) dst[n][k] = *(const PG8_LAS bf16x8*)(lds + PG8_SB(b, h) + boff + n * 2048 + k * 1024); } while (0)
; #define PG8_MMA(ai, bj, At, Bt) do { __builtin_amdgcn_s_setprio(1); _Pragma("unroll") for (int m = 0; m < 4; ++m) _Pragma("unroll") for (int n = 0; n < 2; ++n) _Pragma("unroll") for (int k = 0; k < 2; ++k) \
;         acc[ai][bj][m][n] = __builtin_amdgcn_mfma_f32_16x16x32_bf16(Bt[n][k], At[m][k], acc[ai][bj][m][n], 0, 0, 0); __builtin_amdgcn_s_setprio(0); } while (0)
; #define PG8_WAIT_V(n) asm volatile("s_waitcnt vmcnt(" #n ")" ::: "memory")
; #define PG8_WAIT_L(n) asm volatile("s_waitcnt lgkmcnt(" #n ")" ::: "memory")
; #define PG8_BAR __builtin_amdgcn_s_barrier()
; #define PG8_SCHED __builtin_amdgcn_sched_barrier(0)
; template <class Epi, class Sched, bool ALIGN_EPI = false, bool SP2 = false>
; __device__ __forceinline__ void gemm_phase(PG8_LAS unsigned char* lds, const Gemm g, const Sched& S, const Epi& E) {
;     ...
;             PG8_LDA(At, 0, 1); PG8_STAGE(PG8_SB(0, 0), b2, voffB); PG8_STAGE(PG8_SB(0, 1), b2 + hstep, voffB); PG8_STAGE(PG8_SA(0, 0), a2, voffA);
;             PG8_WAIT_V(8); PG8_WAIT_L(0); PG8_BAR; PG8_MMA(1, 0, At, B0); PG8_MMA(1, 1, At, B1); PG8_BAR; PG8_SCHED;
;             PG8_LDB(B0, 1, 0); PG8_LDB(B1, 1, 1); PG8_SCHED; PG8_LDA(At, 1, 0); PG8_STAGE(PG8_SA(0, 1), a2 + hstep, voffA);
;             PG8_WAIT_V(8); PG8_WAIT_L(0); PG8_BAR; PG8_MMA(0, 0, At, B0); PG8_MMA(0, 1, At, B1); PG8_BAR; PG8_SCHED;
;             PG8_LDA(At, 1, 1); PG8_STAGE(PG8_SB(1, 0), b3, voffB); PG8_STAGE(PG8_SB(1, 1), b3 + hstep, voffB); PG8_STAGE(PG8_SA(1, 0), a3, voffA);
;             PG8_WAIT_V(8); PG8_WAIT_L(0); PG8_BAR; PG8_MMA(1, 0, At, B0); PG8_MMA(1, 1, At, B1); PG8_BAR; PG8_SCHED;
;     ...
;         if constexpr (ALIGN_EPI) { if (wr == 0) PG8_BAR; }
	v_mfma_f32_16x16x32_bf16 v[124:127], v[154:157], v[186:189], v[124:127]
	v_mfma_f32_16x16x32_bf16 v[116:119], v[162:165], v[186:189], v[116:119]
	v_mfma_f32_16x16x32_bf16 v[100:103], v[162:165], v[198:201], v[100:103]
	v_mfma_f32_16x16x32_bf16 v[108:111], v[154:157], v[198:201], v[108:111]
	v_mfma_f32_16x16x32_bf16 v[92:95], v[154:157], v[206:209], v[92:95]
	v_mfma_f32_16x16x32_bf16 v[84:87], v[162:165], v[206:209], v[84:87]
	v_mfma_f32_16x16x32_bf16 v[68:71], v[162:165], v[214:217], v[68:71]
	v_mfma_f32_16x16x32_bf16 v[76:79], v[154:157], v[214:217], v[76:79]
	v_mfma_f32_16x16x32_bf16 v[124:127], v[158:161], v[190:193], v[124:127]
	v_mfma_f32_16x16x32_bf16 v[116:119], v[166:169], v[190:193], v[116:119]
	v_mfma_f32_16x16x32_bf16 v[100:103], v[166:169], v[202:205], v[100:103]
	v_mfma_f32_16x16x32_bf16 v[108:111], v[158:161], v[202:205], v[108:111]
	v_mfma_f32_16x16x32_bf16 v[92:95], v[158:161], v[210:213], v[92:95]
	v_mfma_f32_16x16x32_bf16 v[84:87], v[166:169], v[210:213], v[84:87]
	v_mfma_f32_16x16x32_bf16 v[68:71], v[166:169], v[218:221], v[68:71]
	v_mfma_f32_16x16x32_bf16 v[76:79], v[158:161], v[218:221], v[76:79]
	v_mfma_f32_16x16x32_bf16 v[120:123], v[170:173], v[186:189], v[120:123]
	v_mfma_f32_16x16x32_bf16 v[112:115], v[178:181], v[186:189], v[112:115]
	v_mfma_f32_16x16x32_bf16 v[96:99], v[178:181], v[198:201], v[96:99]
	v_mfma_f32_16x16x32_bf16 v[104:107], v[170:173], v[198:201], v[104:107]
	v_mfma_f32_16x16x32_bf16 v[88:91], v[170:173], v[206:209], v[88:91]
	v_mfma_f32_16x16x32_bf16 v[80:83], v[178:181], v[206:209], v[80:83]
	v_mfma_f32_16x16x32_bf16 v[64:67], v[178:181], v[214:217], v[64:67]
	v_mfma_f32_16x16x32_bf16 v[72:75], v[170:173], v[214:217], v[72:75]
	v_mfma_f32_16x16x32_bf16 v[120:123], v[174:177], v[190:193], v[120:123]
	v_mfma_f32_16x16x32_bf16 v[112:115], v[182:185], v[190:193], v[112:115]
	v_mfma_f32_16x16x32_bf16 v[96:99], v[182:185], v[202:205], v[96:99]
	v_mfma_f32_16x16x32_bf16 v[104:107], v[174:177], v[202:205], v[104:107]
	v_mfma_f32_16x16x32_bf16 v[88:91], v[174:177], v[210:213], v[88:91]
	v_mfma_f32_16x16x32_bf16 v[80:83], v[182:185], v[210:213], v[80:83]
	v_mfma_f32_16x16x32_bf16 v[64:67], v[182:185], v[218:221], v[64:67]
	v_mfma_f32_16x16x32_bf16 v[72:75], v[174:177], v[218:221], v[72:75]
	s_barrier
	s_add_i32 s46, s73, s55
	s_mov_b32 m0, s46
	ds_read_b128 v[186:189], v152 offset:49152
	ds_read_b128 v[190:193], v152 offset:50176
	ds_read_b128 v[198:201], v152 offset:51200
	ds_read_b128 v[202:205], v152 offset:52224
	ds_read_b128 v[206:209], v152 offset:53248
	ds_read_b128 v[210:213], v152 offset:54272
	ds_read_b128 v[214:217], v152 offset:55296
	ds_read_b128 v[218:221], v152 offset:56320
	global_load_lds_dwordx4 v132, s[98:99]
	s_add_i32 m0, s46, 0x2000
	s_add_u32 s42, s42, 0x40080
	s_addc_u32 s43, s43, 0
	s_add_i32 s46, s74, s55
	global_load_lds_dwordx4 v128, s[98:99]
	s_mov_b32 m0, s46
	s_nop 0
	global_load_lds_dwordx4 v132, s[42:43]
	s_add_i32 m0, s46, 0x2000
	s_nop 0
	global_load_lds_dwordx4 v128, s[42:43]
	s_mov_b32 m0, s61
	s_nop 0
	global_load_lds_dwordx4 v134, s[100:101]
	s_mov_b32 m0, s62
	s_nop 0
	global_load_lds_dwordx4 v130, s[100:101]
	s_waitcnt vmcnt(8)
	s_waitcnt lgkmcnt(0)
	s_barrier
	v_mfma_f32_16x16x32_bf16 v[60:63], v[154:157], v[186:189], v[60:63]
	v_mfma_f32_16x16x32_bf16 v[52:55], v[162:165], v[186:189], v[52:55]
	v_mfma_f32_16x16x32_bf16 v[36:39], v[162:165], v[198:201], v[36:39]
	v_mfma_f32_16x16x32_bf16 v[44:47], v[154:157], v[198:201], v[44:47]
	v_mfma_f32_16x16x32_bf16 v[28:31], v[154:157], v[206:209], v[28:31]
	v_mfma_f32_16x16x32_bf16 v[20:23], v[162:165], v[206:209], v[20:23]
	v_mfma_f32_16x16x32_bf16 v[4:7], v[162:165], v[214:217], v[4:7]
	v_mfma_f32_16x16x32_bf16 v[12:15], v[154:157], v[214:217], v[12:15]
	v_mfma_f32_16x16x32_bf16 v[60:63], v[158:161], v[190:193], v[60:63]
	v_mfma_f32_16x16x32_bf16 v[52:55], v[166:169], v[190:193], v[52:55]
	v_mfma_f32_16x16x32_bf16 v[36:39], v[166:169], v[202:205], v[36:39]
	v_mfma_f32_16x16x32_bf16 v[44:47], v[158:161], v[202:205], v[44:47]
	v_mfma_f32_16x16x32_bf16 v[28:31], v[158:161], v[210:213], v[28:31]
	v_mfma_f32_16x16x32_bf16 v[20:23], v[166:169], v[210:213], v[20:23]
	v_mfma_f32_16x16x32_bf16 v[4:7], v[166:169], v[218:221], v[4:7]
	v_mfma_f32_16x16x32_bf16 v[12:15], v[158:161], v[218:221], v[12:15]
	v_mfma_f32_16x16x32_bf16 v[56:59], v[170:173], v[186:189], v[56:59]
	v_mfma_f32_16x16x32_bf16 v[48:51], v[178:181], v[186:189], v[48:51]
	v_mfma_f32_16x16x32_bf16 v[32:35], v[178:181], v[198:201], v[32:35]
	v_mfma_f32_16x16x32_bf16 v[40:43], v[170:173], v[198:201], v[40:43]
	v_mfma_f32_16x16x32_bf16 v[24:27], v[170:173], v[206:209], v[24:27]
	v_mfma_f32_16x16x32_bf16 v[16:19], v[178:181], v[206:209], v[16:19]
	v_mfma_f32_16x16x32_bf16 v[0:3], v[178:181], v[214:217], v[0:3]
	v_mfma_f32_16x16x32_bf16 v[8:11], v[170:173], v[214:217], v[8:11]
	v_mfma_f32_16x16x32_bf16 v[56:59], v[174:177], v[190:193], v[56:59]
	v_mfma_f32_16x16x32_bf16 v[48:51], v[182:185], v[190:193], v[48:51]
	v_mfma_f32_16x16x32_bf16 v[32:35], v[182:185], v[202:205], v[32:35]
	v_mfma_f32_16x16x32_bf16 v[40:43], v[174:177], v[202:205], v[40:43]
	v_mfma_f32_16x16x32_bf16 v[24:27], v[174:177], v[210:213], v[24:27]
	v_mfma_f32_16x16x32_bf16 v[16:19], v[182:185], v[210:213], v[16:19]
	v_mfma_f32_16x16x32_bf16 v[0:3], v[182:185], v[218:221], v[0:3]
	v_mfma_f32_16x16x32_bf16 v[8:11], v[174:177], v[218:221], v[8:11]
	s_barrier
	s_add_i32 s72, s72, 2
	s_add_u32 s20, s20, 0x100
	s_addc_u32 s21, s21, 0
	s_add_u32 s70, s70, 0x100
	s_addc_u32 s71, s71, 0
	s_cmp_gt_u32 s72, 13
	s_cbranch_scc0 .LBB0_224
	s_and_b64 vcc, exec, s[10:11]
	s_cbranch_vccz .LBB0_227
	s_barrier

; #define PG8_STAGE(bufoff, gbase, voff) do { _Pragma("unroll") for (int _i = 0; _i < 2; ++_i) \
;         __builtin_amdgcn_global_load_lds((const unsigned*)((const char*)(gbase) + (voff)[_i]), (PG8_LAS unsigned*)(lds + (bufoff) + ldsw + _i * 8192), 16, 0, 0); } while (0)
; #define PG8_LDA(dst, b, h) do { _Pragma("unroll") for (int m = 0; m < 4; ++m) _Pragma("unroll") for (int k = 0; k < 2; ++k) dst[m][k] = *(const PG8_LAS bf16x8*)(lds + PG8_SA(b, h) + aoff + m * 2048 + k * 1024); } while (0)
; #define PG8_LDB(dst, b, h) do { _Pragma("unroll") for (int n = 0; n < 2; ++n) _Pragma("unroll") for (int k = 0; k < 2; ++k) dst[n][k] = *(const PG8_LAS bf16x8*)(lds + PG8_SB(b, h) + boff + n * 2048 + k * 1024); } while (0)
; template <class Epi, class Sched, bool ALIGN_EPI = false, bool SP2 = false>
; __device__ __forceinline__ void gemm_phase(PG8_LAS unsigned char* lds, const Gemm g, const Sched& S, const Epi& E) {
;     ...
;         for (int t = 0; t < nt; t += 2) {
;             const bool last = (t == nt - 2);
;             const char* a1 = cA + (size_t)(t + 1) * kstep;
;             const char* a2 = last ? nA : cA + (size_t)(t + 2) * kstep; const char* b2 = last ? nB : cB + (size_t)(t + 2) * kstep;
;             const char* a3 = a2 + kstep; const char* b3 = b2 + kstep;
;             if (last && has_next) S.a_ready(nxt);
;             if constexpr (SP2) {
;             PG8_LDB(B0, 0, 0); PG8_LDB(B1, 0, 1); PG8_SCHED; PG8_LDA(At, 0, 0); PG8_STAGE(PG8_SA(1, 1), a1 + hstep, voffA);
;             PG8_WAIT_V(8); PG8_WAIT_L(0); PG8_BAR; PG8_MMA(0, 0, At, B0); PG8_MMA(0, 1, At, B1); PG8_BAR; PG8_SCHED;
;             PG8_LDA(At, 0, 1); PG8_STAGE(PG8_SB(0, 0), b2, voffB); PG8_STAGE(PG8_SB(0, 1), b2 + hstep, voffB); PG8_STAGE(PG8_SA(0, 0), a2, voffA);
;             PG8_WAIT_V(8); PG8_WAIT_L(0); PG8_BAR; PG8_MMA(1, 0, At, B0); PG8_MMA(1, 1, At, B1); PG8_BAR; PG8_SCHED;
;             PG8_LDB(B0, 1, 0); PG8_LDB(B1, 1, 1); PG8_SCHED; PG8_LDA(At, 1, 0); PG8_STAGE(PG8_SA(0, 1), a2 + hstep, voffA);
;             PG8_WAIT_V(8); PG8_WAIT_L(0); PG8_BAR; PG8_MMA(0, 0, At, B0); PG8_MMA(0, 1, At, B1); PG8_BAR; PG8_SCHED;
;             PG8_LDA(At, 1, 1); PG8_STAGE(PG8_SB(1, 0), b3, voffB); PG8_STAGE(PG8_SB(1, 1), b3 + hstep, voffB); PG8_STAGE(PG8_SA(1, 0), a3, voffA);
;             PG8_WAIT_V(8); PG8_WAIT_L(0); PG8_BAR; PG8_MMA(1, 0, At, B0); PG8_MMA(1, 1, At, B1); PG8_BAR; PG8_SCHED;
.LBB0_308:
	s_add_u32 s20, s20, 0xb0080
	s_addc_u32 s21, s21, 0
	s_add_u32 s73, s34, 0x100
	s_addc_u32 s74, s35, 0
	s_mov_b32 s75, -2
	s_waitcnt lgkmcnt(0)
	s_waitcnt lgkmcnt(0)
	ds_read_b128 v[96:99], v223
	ds_read_b128 v[108:111], v223 offset:1024
	ds_read_b128 v[120:123], v223 offset:2048
	ds_read_b128 v[128:131], v223 offset:3072
	ds_read_b128 v[144:147], v224
	ds_read_b128 v[148:151], v224 offset:1024
	ds_read_b128 v[152:155], v224 offset:2048
	ds_read_b128 v[156:159], v224 offset:3072
	s_add_u32 s34, s20, 0xfff50080
	s_addc_u32 s35, s21, -1
	s_cmp_eq_u32 s75, 40
	s_cselect_b32 s51, s1, s35
	s_cselect_b32 s50, s0, s34
	s_cselect_b32 s35, s49, s74
	s_cselect_b32 s34, s48, s73
	s_add_i32 m0, s54, 0xc000
	ds_read_b128 v[160:163], v225
	ds_read_b128 v[164:167], v225 offset:1024
	ds_read_b128 v[168:171], v225 offset:2048
	ds_read_b128 v[172:175], v225 offset:3072
	ds_read_b128 v[176:179], v225 offset:4096
	ds_read_b128 v[180:183], v225 offset:5120
	ds_read_b128 v[202:205], v225 offset:6144
	ds_read_b128 v[206:209], v225 offset:7168
	global_load_lds_dwordx4 v192, s[20:21]
	s_add_i32 m0, s54, 0xe000
	s_nop 0
	global_load_lds_dwordx4 v194, s[20:21]
	s_waitcnt vmcnt(8)
	s_waitcnt lgkmcnt(0)
	s_barrier
	v_mfma_f32_16x16x32_bf16 v[140:143], v[96:99], v[160:163], 0
	v_mfma_f32_16x16x32_bf16 v[136:139], v[120:123], v[160:163], 0
	v_mfma_f32_16x16x32_bf16 v[112:115], v[120:123], v[168:171], 0
	v_mfma_f32_16x16x32_bf16 v[116:119], v[96:99], v[168:171], 0
	v_mfma_f32_16x16x32_bf16 v[92:95], v[96:99], v[176:179], 0
	v_mfma_f32_16x16x32_bf16 v[88:91], v[120:123], v[176:179], 0
	v_mfma_f32_16x16x32_bf16 v[72:75], v[120:123], v[202:205], 0
	v_mfma_f32_16x16x32_bf16 v[76:79], v[96:99], v[202:205], 0
	v_mfma_f32_16x16x32_bf16 v[140:143], v[108:111], v[164:167], v[140:143]
	v_mfma_f32_16x16x32_bf16 v[136:139], v[128:131], v[164:167], v[136:139]
	v_mfma_f32_16x16x32_bf16 v[112:115], v[128:131], v[172:175], v[112:115]
	v_mfma_f32_16x16x32_bf16 v[116:119], v[108:111], v[172:175], v[116:119]
	v_mfma_f32_16x16x32_bf16 v[92:95], v[108:111], v[180:183], v[92:95]
	v_mfma_f32_16x16x32_bf16 v[88:91], v[128:131], v[180:183], v[88:91]
	v_mfma_f32_16x16x32_bf16 v[72:75], v[128:131], v[206:209], v[72:75]
	v_mfma_f32_16x16x32_bf16 v[76:79], v[108:111], v[206:209], v[76:79]
	v_mfma_f32_16x16x32_bf16 v[132:135], v[144:147], v[160:163], 0
	v_mfma_f32_16x16x32_bf16 v[124:127], v[152:155], v[160:163], 0
	v_mfma_f32_16x16x32_bf16 v[100:103], v[152:155], v[168:171], 0
	v_mfma_f32_16x16x32_bf16 v[104:107], v[144:147], v[168:171], 0
	v_mfma_f32_16x16x32_bf16 v[84:87], v[144:147], v[176:179], 0
	v_mfma_f32_16x16x32_bf16 v[80:83], v[152:155], v[176:179], 0
	v_mfma_f32_16x16x32_bf16 v[64:67], v[152:155], v[202:205], 0
	v_mfma_f32_16x16x32_bf16 v[68:71], v[144:147], v[202:205], 0
	v_mfma_f32_16x16x32_bf16 v[132:135], v[148:151], v[164:167], v[132:135]
	v_mfma_f32_16x16x32_bf16 v[124:127], v[156:159], v[164:167], v[124:127]
	v_mfma_f32_16x16x32_bf16 v[100:103], v[156:159], v[172:175], v[100:103]
	v_mfma_f32_16x16x32_bf16 v[104:107], v[148:151], v[172:175], v[104:107]
	v_mfma_f32_16x16x32_bf16 v[84:87], v[148:151], v[180:183], v[84:87]
	v_mfma_f32_16x16x32_bf16 v[80:83], v[156:159], v[180:183], v[80:83]
	v_mfma_f32_16x16x32_bf16 v[64:67], v[156:159], v[206:209], v[64:67]
	v_mfma_f32_16x16x32_bf16 v[68:71], v[148:151], v[206:209], v[68:71]
	s_barrier
	s_add_i32 s76, s67, s53
	s_add_u32 s98, s34, s12
	s_addc_u32 s99, s35, s13
	s_add_u32 s100, s50, s12
	s_addc_u32 s101, s51, s13
	s_mov_b32 m0, s76
	ds_read_b128 v[160:163], v225 offset:16384
	ds_read_b128 v[164:167], v225 offset:17408
	ds_read_b128 v[168:171], v225 offset:18432
	ds_read_b128 v[172:175], v225 offset:19456
	ds_read_b128 v[176:179], v225 offset:20480
	ds_read_b128 v[180:183], v225 offset:21504
	ds_read_b128 v[202:205], v225 offset:22528
	ds_read_b128 v[206:209], v225 offset:23552
	global_load_lds_dwordx4 v186, s[34:35]
	s_add_i32 m0, s76, 0x2000
	s_add_u32 s76, s34, 0xb0000
	s_addc_u32 s77, s35, 0
	s_add_i32 s78, s68, s53
	global_load_lds_dwordx4 v190, s[34:35]
	s_mov_b32 m0, s78
	s_nop 0
	global_load_lds_dwordx4 v186, s[76:77]
	s_add_i32 m0, s78, 0x2000
	s_nop 0
	global_load_lds_dwordx4 v190, s[76:77]
	s_mov_b32 m0, s54
	s_nop 0
	global_load_lds_dwordx4 v184, s[50:51]
	s_mov_b32 m0, s55
	s_nop 0
	global_load_lds_dwordx4 v188, s[50:51]
	s_waitcnt vmcnt(8)
	s_waitcnt lgkmcnt(0)
	s_barrier
	v_mfma_f32_16x16x32_bf16 v[60:63], v[96:99], v[160:163], 0
	v_mfma_f32_16x16x32_bf16 v[56:59], v[120:123], v[160:163], 0
	v_mfma_f32_16x16x32_bf16 v[40:43], v[120:123], v[168:171], 0
	v_mfma_f32_16x16x32_bf16 v[44:47], v[96:99], v[168:171], 0
	v_mfma_f32_16x16x32_bf16 v[28:31], v[96:99], v[176:179], 0
	v_mfma_f32_16x16x32_bf16 v[24:27], v[120:123], v[176:179], 0
	v_mfma_f32_16x16x32_bf16 v[8:11], v[120:123], v[202:205], 0
	v_mfma_f32_16x16x32_bf16 v[12:15], v[96:99], v[202:205], 0
	v_mfma_f32_16x16x32_bf16 v[60:63], v[108:111], v[164:167], v[60:63]
	v_mfma_f32_16x16x32_bf16 v[56:59], v[128:131], v[164:167], v[56:59]
	v_mfma_f32_16x16x32_bf16 v[40:43], v[128:131], v[172:175], v[40:43]
	v_mfma_f32_16x16x32_bf16 v[44:47], v[108:111], v[172:175], v[44:47]
	v_mfma_f32_16x16x32_bf16 v[28:31], v[108:111], v[180:183], v[28:31]
	v_mfma_f32_16x16x32_bf16 v[24:27], v[128:131], v[180:183], v[24:27]
	v_mfma_f32_16x16x32_bf16 v[8:11], v[128:131], v[206:209], v[8:11]
	v_mfma_f32_16x16x32_bf16 v[12:15], v[108:111], v[206:209], v[12:15]
	v_mfma_f32_16x16x32_bf16 v[52:55], v[144:147], v[160:163], 0
	v_mfma_f32_16x16x32_bf16 v[48:51], v[152:155], v[160:163], 0
	v_mfma_f32_16x16x32_bf16 v[32:35], v[152:155], v[168:171], 0
	v_mfma_f32_16x16x32_bf16 v[36:39], v[144:147], v[168:171], 0
	v_mfma_f32_16x16x32_bf16 v[20:23], v[144:147], v[176:179], 0
	v_mfma_f32_16x16x32_bf16 v[16:19], v[152:155], v[176:179], 0
	v_mfma_f32_16x16x32_bf16 v[0:3], v[152:155], v[202:205], 0
	v_mfma_f32_16x16x32_bf16 v[4:7], v[144:147], v[202:205], 0
	v_mfma_f32_16x16x32_bf16 v[52:55], v[148:151], v[164:167], v[52:55]
	v_mfma_f32_16x16x32_bf16 v[48:51], v[156:159], v[164:167], v[48:51]
	v_mfma_f32_16x16x32_bf16 v[32:35], v[156:159], v[172:175], v[32:35]
	v_mfma_f32_16x16x32_bf16 v[36:39], v[148:151], v[172:175], v[36:39]
	v_mfma_f32_16x16x32_bf16 v[20:23], v[148:151], v[180:183], v[20:23]
	v_mfma_f32_16x16x32_bf16 v[16:19], v[156:159], v[180:183], v[16:19]
	v_mfma_f32_16x16x32_bf16 v[0:3], v[156:159], v[206:209], v[0:3]
	v_mfma_f32_16x16x32_bf16 v[4:7], v[148:151], v[206:209], v[4:7]
	s_barrier
; #define PG8_STAGE(bufoff, gbase, voff) do { _Pragma("unroll") for (int _i = 0; _i < 2; ++_i) \
;         __builtin_amdgcn_global_load_lds((const unsigned*)((const char*)(gbase) + (voff)[_i]), (PG8_LAS unsigned*)(lds + (bufoff) + ldsw + _i * 8192), 16, 0, 0); } while (0)
; #define PG8_LDA(dst, b, h) do { _Pragma("unroll") for (int m = 0; m < 4; ++m) _Pragma("unroll") for (int k = 0; k < 2; ++k) dst[m][k] = *(const PG8_LAS bf16x8*)(lds + PG8_SA(b, h) + aoff + m * 2048 + k * 1024); } while (0)
; #define PG8_LDB(dst, b, h) do { _Pragma("unroll") for (int n = 0; n < 2; ++n) _Pragma("unroll") for (int k = 0; k < 2; ++k) dst[n][k] = *(const PG8_LAS bf16x8*)(lds + PG8_SB(b, h) + boff + n * 2048 + k * 1024); } while (0)
; #define PG8_MMA(ai, bj, At, Bt) do { __builtin_amdgcn_s_setprio(1); _Pragma("unroll") for (int m = 0; m < 4; ++m) _Pragma("unroll") for (int n = 0; n < 2; ++n) _Pragma("unroll") for (int k = 0; k < 2; ++k) \
;         acc[ai][bj][m][n] = __builtin_amdgcn_mfma_f32_16x16x32_bf16(Bt[n][k], At[m][k], acc[ai][bj][m][n], 0, 0, 0); __builtin_amdgcn_s_setprio(0); } while (0)
; #define PG8_WAIT_V(n) asm volatile("s_waitcnt vmcnt(" #n ")" ::: "memory")
; #define PG8_WAIT_L(n) asm volatile("s_waitcnt lgkmcnt(" #n ")" ::: "memory")
; #define PG8_BAR __builtin_amdgcn_s_barrier()
; #define PG8_SCHED __builtin_amdgcn_sched_barrier(0)
; template <class Epi, class Sched, bool ALIGN_EPI = false, bool SP2 = false>
; __device__ __forceinline__ void gemm_phase(PG8_LAS unsigned char* lds, const Gemm g, const Sched& S, const Epi& E) {
;     ...
;             PG8_LDB(B0, 1, 0); PG8_LDB(B1, 1, 1); PG8_SCHED; PG8_LDA(At, 1, 0); PG8_STAGE(PG8_SA(0, 1), a2 + hstep, voffA);
;             PG8_WAIT_V(8); PG8_WAIT_L(0); PG8_BAR; PG8_MMA(0, 0, At, B0); PG8_MMA(0, 1, At, B1); PG8_BAR; PG8_SCHED;
;             PG8_LDA(At, 1, 1); PG8_STAGE(PG8_SB(1, 0), b3, voffB); PG8_STAGE(PG8_SB(1, 1), b3 + hstep, voffB); PG8_STAGE(PG8_SA(1, 0), a3, voffA);
;             PG8_WAIT_V(8); PG8_WAIT_L(0); PG8_BAR; PG8_MMA(1, 0, At, B0); PG8_MMA(1, 1, At, B1); PG8_BAR; PG8_SCHED;
	s_add_i32 s76, 0, 0x18000
	s_add_i32 s77, 0, 0x1c000
	v_add_u32_e32 v128, s76, v221
	v_add_u32_e32 v156, s77, v221
	ds_read_b128 v[96:99], v128
	ds_read_b128 v[108:111], v128 offset:1024
	ds_read_b128 v[120:123], v128 offset:2048
	ds_read_b128 v[128:131], v128 offset:3072
	ds_read_b128 v[144:147], v156
	ds_read_b128 v[148:151], v156 offset:1024
	ds_read_b128 v[152:155], v156 offset:2048
	ds_read_b128 v[156:159], v156 offset:3072
	s_add_u32 s50, s50, 0xb0000
	s_addc_u32 s51, s51, 0
	s_mov_b32 m0, s56
	ds_read_b128 v[160:163], v225 offset:32768
	ds_read_b128 v[164:167], v225 offset:33792
	ds_read_b128 v[168:171], v225 offset:34816
	ds_read_b128 v[172:175], v225 offset:35840
	ds_read_b128 v[176:179], v225 offset:36864
	ds_read_b128 v[180:183], v225 offset:37888
	ds_read_b128 v[202:205], v225 offset:38912
	ds_read_b128 v[206:209], v225 offset:39936
	global_load_lds_dwordx4 v184, s[50:51]
	s_mov_b32 m0, s57
	s_nop 0
	global_load_lds_dwordx4 v188, s[50:51]
	s_waitcnt vmcnt(8)
	s_waitcnt lgkmcnt(0)
	s_barrier
	v_mfma_f32_16x16x32_bf16 v[140:143], v[96:99], v[160:163], v[140:143]
	v_mfma_f32_16x16x32_bf16 v[136:139], v[120:123], v[160:163], v[136:139]
	v_mfma_f32_16x16x32_bf16 v[112:115], v[120:123], v[168:171], v[112:115]
	v_mfma_f32_16x16x32_bf16 v[116:119], v[96:99], v[168:171], v[116:119]
	v_mfma_f32_16x16x32_bf16 v[92:95], v[96:99], v[176:179], v[92:95]
	v_mfma_f32_16x16x32_bf16 v[88:91], v[120:123], v[176:179], v[88:91]
	v_mfma_f32_16x16x32_bf16 v[72:75], v[120:123], v[202:205], v[72:75]
	v_mfma_f32_16x16x32_bf16 v[76:79], v[96:99], v[202:205], v[76:79]
	v_mfma_f32_16x16x32_bf16 v[140:143], v[108:111], v[164:167], v[140:143]
	v_mfma_f32_16x16x32_bf16 v[136:139], v[128:131], v[164:167], v[136:139]
	v_mfma_f32_16x16x32_bf16 v[112:115], v[128:131], v[172:175], v[112:115]
	v_mfma_f32_16x16x32_bf16 v[116:119], v[108:111], v[172:175], v[116:119]
	v_mfma_f32_16x16x32_bf16 v[92:95], v[108:111], v[180:183], v[92:95]
	v_mfma_f32_16x16x32_bf16 v[88:91], v[128:131], v[180:183], v[88:91]
	v_mfma_f32_16x16x32_bf16 v[72:75], v[128:131], v[206:209], v[72:75]
	v_mfma_f32_16x16x32_bf16 v[76:79], v[108:111], v[206:209], v[76:79]
	v_mfma_f32_16x16x32_bf16 v[132:135], v[144:147], v[160:163], v[132:135]
	v_mfma_f32_16x16x32_bf16 v[124:127], v[152:155], v[160:163], v[124:127]
	v_mfma_f32_16x16x32_bf16 v[100:103], v[152:155], v[168:171], v[100:103]
	v_mfma_f32_16x16x32_bf16 v[104:107], v[144:147], v[168:171], v[104:107]
	v_mfma_f32_16x16x32_bf16 v[84:87], v[144:147], v[176:179], v[84:87]
	v_mfma_f32_16x16x32_bf16 v[80:83], v[152:155], v[176:179], v[80:83]
	v_mfma_f32_16x16x32_bf16 v[64:67], v[152:155], v[202:205], v[64:67]
	v_mfma_f32_16x16x32_bf16 v[68:71], v[144:147], v[202:205], v[68:71]
	v_mfma_f32_16x16x32_bf16 v[132:135], v[148:151], v[164:167], v[132:135]
	v_mfma_f32_16x16x32_bf16 v[124:127], v[156:159], v[164:167], v[124:127]
	v_mfma_f32_16x16x32_bf16 v[100:103], v[156:159], v[172:175], v[100:103]
	v_mfma_f32_16x16x32_bf16 v[104:107], v[148:151], v[172:175], v[104:107]
	v_mfma_f32_16x16x32_bf16 v[84:87], v[148:151], v[180:183], v[84:87]
	v_mfma_f32_16x16x32_bf16 v[80:83], v[156:159], v[180:183], v[80:83]
	v_mfma_f32_16x16x32_bf16 v[64:67], v[156:159], v[206:209], v[64:67]
	v_mfma_f32_16x16x32_bf16 v[68:71], v[148:151], v[206:209], v[68:71]
	s_barrier
	s_add_i32 s50, s76, s53
	s_mov_b32 m0, s50
	ds_read_b128 v[160:163], v225 offset:49152
	ds_read_b128 v[164:167], v225 offset:50176
	ds_read_b128 v[168:171], v225 offset:51200
	ds_read_b128 v[172:175], v225 offset:52224
	ds_read_b128 v[176:179], v225 offset:53248
	ds_read_b128 v[180:183], v225 offset:54272
	ds_read_b128 v[202:205], v225 offset:55296
	ds_read_b128 v[206:209], v225 offset:56320
	global_load_lds_dwordx4 v186, s[98:99]
	s_add_i32 m0, s50, 0x2000
	s_add_u32 s34, s34, 0xb0080
	s_addc_u32 s35, s35, 0
	s_add_i32 s50, s77, s53
	global_load_lds_dwordx4 v190, s[98:99]
	s_mov_b32 m0, s50
	s_nop 0
	global_load_lds_dwordx4 v186, s[34:35]
	s_add_i32 m0, s50, 0x2000
	s_nop 0
	global_load_lds_dwordx4 v190, s[34:35]
	s_mov_b32 m0, s62
	s_nop 0
	global_load_lds_dwordx4 v184, s[100:101]
	s_mov_b32 m0, s63
	s_nop 0
	global_load_lds_dwordx4 v188, s[100:101]
	s_waitcnt vmcnt(8)
	s_waitcnt lgkmcnt(0)
	s_barrier
	v_mfma_f32_16x16x32_bf16 v[60:63], v[96:99], v[160:163], v[60:63]
	v_mfma_f32_16x16x32_bf16 v[56:59], v[120:123], v[160:163], v[56:59]
	v_mfma_f32_16x16x32_bf16 v[40:43], v[120:123], v[168:171], v[40:43]
	v_mfma_f32_16x16x32_bf16 v[44:47], v[96:99], v[168:171], v[44:47]
	v_mfma_f32_16x16x32_bf16 v[28:31], v[96:99], v[176:179], v[28:31]
	v_mfma_f32_16x16x32_bf16 v[24:27], v[120:123], v[176:179], v[24:27]
	v_mfma_f32_16x16x32_bf16 v[8:11], v[120:123], v[202:205], v[8:11]
	v_mfma_f32_16x16x32_bf16 v[12:15], v[96:99], v[202:205], v[12:15]
	v_mfma_f32_16x16x32_bf16 v[60:63], v[108:111], v[164:167], v[60:63]
	v_mfma_f32_16x16x32_bf16 v[56:59], v[128:131], v[164:167], v[56:59]
	v_mfma_f32_16x16x32_bf16 v[40:43], v[128:131], v[172:175], v[40:43]
	v_mfma_f32_16x16x32_bf16 v[44:47], v[108:111], v[172:175], v[44:47]
	v_mfma_f32_16x16x32_bf16 v[28:31], v[108:111], v[180:183], v[28:31]
	v_mfma_f32_16x16x32_bf16 v[24:27], v[128:131], v[180:183], v[24:27]
	v_mfma_f32_16x16x32_bf16 v[8:11], v[128:131], v[206:209], v[8:11]
	v_mfma_f32_16x16x32_bf16 v[12:15], v[108:111], v[206:209], v[12:15]
	v_mfma_f32_16x16x32_bf16 v[52:55], v[144:147], v[160:163], v[52:55]
	v_mfma_f32_16x16x32_bf16 v[48:51], v[152:155], v[160:163], v[48:51]
	v_mfma_f32_16x16x32_bf16 v[32:35], v[152:155], v[168:171], v[32:35]
	v_mfma_f32_16x16x32_bf16 v[36:39], v[144:147], v[168:171], v[36:39]
	v_mfma_f32_16x16x32_bf16 v[20:23], v[144:147], v[176:179], v[20:23]
	v_mfma_f32_16x16x32_bf16 v[16:19], v[152:155], v[176:179], v[16:19]
	v_mfma_f32_16x16x32_bf16 v[0:3], v[152:155], v[202:205], v[0:3]
	v_mfma_f32_16x16x32_bf16 v[4:7], v[144:147], v[202:205], v[4:7]
	v_mfma_f32_16x16x32_bf16 v[52:55], v[148:151], v[164:167], v[52:55]
	v_mfma_f32_16x16x32_bf16 v[48:51], v[156:159], v[164:167], v[48:51]
	v_mfma_f32_16x16x32_bf16 v[32:35], v[156:159], v[172:175], v[32:35]
	v_mfma_f32_16x16x32_bf16 v[36:39], v[148:151], v[172:175], v[36:39]
	v_mfma_f32_16x16x32_bf16 v[20:23], v[148:151], v[180:183], v[20:23]
	v_mfma_f32_16x16x32_bf16 v[16:19], v[156:159], v[180:183], v[16:19]
	v_mfma_f32_16x16x32_bf16 v[0:3], v[156:159], v[206:209], v[0:3]
	v_mfma_f32_16x16x32_bf16 v[4:7], v[148:151], v[206:209], v[4:7]
	s_barrier
	s_add_i32 s75, s75, 2
	s_add_u32 s20, s20, 0x100
	s_addc_u32 s21, s21, 0
	s_add_u32 s73, s73, 0x100
	s_addc_u32 s74, s74, 0
	s_cmp_gt_u32 s75, 41
; #define PG8_STAGE(bufoff, gbase, voff) do { _Pragma("unroll") for (int _i = 0; _i < 2; ++_i) \
;         __builtin_amdgcn_global_load_lds((const unsigned*)((const char*)(gbase) + (voff)[_i]), (PG8_LAS unsigned*)(lds + (bufoff) + ldsw + _i * 8192), 16, 0, 0); } while (0)
; #define PG8_LDA(dst, b, h) do { _Pragma("unroll") for (int m = 0; m < 4; ++m) _Pragma("unroll") for (int k = 0; k < 2; ++k) dst[m][k] = *(const PG8_LAS bf16x8*)(lds + PG8_SA(b, h) + aoff + m * 2048 + k * 1024); } while (0)
; #define PG8_LDB(dst, b, h) do { _Pragma("unroll") for (int n = 0; n < 2; ++n) _Pragma("unroll") for (int k = 0; k < 2; ++k) dst[n][k] = *(const PG8_LAS bf16x8*)(lds + PG8_SB(b, h) + boff + n * 2048 + k * 1024); } while (0)
; #define PG8_MMA(ai, bj, At, Bt) do { __builtin_amdgcn_s_setprio(1); _Pragma("unroll") for (int m = 0; m < 4; ++m) _Pragma("unroll") for (int n = 0; n < 2; ++n) _Pragma("unroll") for (int k = 0; k < 2; ++k) \
;         acc[ai][bj][m][n] = __builtin_amdgcn_mfma_f32_16x16x32_bf16(Bt[n][k], At[m][k], acc[ai][bj][m][n], 0, 0, 0); __builtin_amdgcn_s_setprio(0); } while (0)
; #define PG8_WAIT_V(n) asm volatile("s_waitcnt vmcnt(" #n ")" ::: "memory")
; #define PG8_WAIT_L(n) asm volatile("s_waitcnt lgkmcnt(" #n ")" ::: "memory")
; #define PG8_BAR __builtin_amdgcn_s_barrier()
; #define PG8_SCHED __builtin_amdgcn_sched_barrier(0)
; template <class Epi, class Sched, bool ALIGN_EPI = false, bool SP2 = false>
; __device__ __forceinline__ void gemm_phase(PG8_LAS unsigned char* lds, const Gemm g, const Sched& S, const Epi& E) {
;     ...
;             PG8_LDB(B0, 0, 0); PG8_LDB(B1, 0, 1); PG8_SCHED; PG8_LDA(At, 0, 0); PG8_STAGE(PG8_SA(1, 1), a1 + hstep, voffA);
;             PG8_WAIT_V(8); PG8_WAIT_L(0); PG8_BAR; PG8_MMA(0, 0, At, B0); PG8_MMA(0, 1, At, B1); PG8_BAR; PG8_SCHED;
;             PG8_LDA(At, 0, 1); PG8_STAGE(PG8_SB(0, 0), b2, voffB); PG8_STAGE(PG8_SB(0, 1), b2 + hstep, voffB); PG8_STAGE(PG8_SA(0, 0), a2, voffA);
;             PG8_WAIT_V(8); PG8_WAIT_L(0); PG8_BAR; PG8_MMA(1, 0, At, B0); PG8_MMA(1, 1, At, B1); PG8_BAR; PG8_SCHED;
;             PG8_LDB(B0, 1, 0); PG8_LDB(B1, 1, 1); PG8_SCHED; PG8_LDA(At, 1, 0); PG8_STAGE(PG8_SA(0, 1), a2 + hstep, voffA);
;             PG8_WAIT_V(8); PG8_WAIT_L(0); PG8_BAR; PG8_MMA(0, 0, At, B0); PG8_MMA(0, 1, At, B1); PG8_BAR; PG8_SCHED;
.LBB0_309:
	ds_read_b128 v[96:99], v223
	ds_read_b128 v[108:111], v223 offset:1024
	ds_read_b128 v[120:123], v223 offset:2048
	ds_read_b128 v[128:131], v223 offset:3072
	ds_read_b128 v[144:147], v224
	ds_read_b128 v[148:151], v224 offset:1024
	ds_read_b128 v[152:155], v224 offset:2048
	ds_read_b128 v[156:159], v224 offset:3072
	s_add_u32 s34, s20, 0xfff50080
	s_addc_u32 s35, s21, -1
	s_cmp_eq_u32 s75, 40
	s_cselect_b32 s51, s1, s35
	s_cselect_b32 s50, s0, s34
	s_cselect_b32 s35, s49, s74
	s_cselect_b32 s34, s48, s73
	s_add_i32 m0, s54, 0xc000
	ds_read_b128 v[160:163], v225
	ds_read_b128 v[164:167], v225 offset:1024
	ds_read_b128 v[168:171], v225 offset:2048
	ds_read_b128 v[172:175], v225 offset:3072
	ds_read_b128 v[176:179], v225 offset:4096
	ds_read_b128 v[180:183], v225 offset:5120
	ds_read_b128 v[202:205], v225 offset:6144
	ds_read_b128 v[206:209], v225 offset:7168
	global_load_lds_dwordx4 v192, s[20:21]
	s_add_i32 m0, s54, 0xe000
	s_nop 0
	global_load_lds_dwordx4 v194, s[20:21]
	s_waitcnt vmcnt(8)
	s_waitcnt lgkmcnt(0)
	s_barrier
	v_mfma_f32_16x16x32_bf16 v[140:143], v[96:99], v[160:163], v[140:143]
	v_mfma_f32_16x16x32_bf16 v[136:139], v[120:123], v[160:163], v[136:139]
	v_mfma_f32_16x16x32_bf16 v[112:115], v[120:123], v[168:171], v[112:115]
	v_mfma_f32_16x16x32_bf16 v[116:119], v[96:99], v[168:171], v[116:119]
	v_mfma_f32_16x16x32_bf16 v[92:95], v[96:99], v[176:179], v[92:95]
	v_mfma_f32_16x16x32_bf16 v[88:91], v[120:123], v[176:179], v[88:91]
	v_mfma_f32_16x16x32_bf16 v[72:75], v[120:123], v[202:205], v[72:75]
	v_mfma_f32_16x16x32_bf16 v[76:79], v[96:99], v[202:205], v[76:79]
	v_mfma_f32_16x16x32_bf16 v[140:143], v[108:111], v[164:167], v[140:143]
	v_mfma_f32_16x16x32_bf16 v[136:139], v[128:131], v[164:167], v[136:139]
	v_mfma_f32_16x16x32_bf16 v[112:115], v[128:131], v[172:175], v[112:115]
	v_mfma_f32_16x16x32_bf16 v[116:119], v[108:111], v[172:175], v[116:119]
	v_mfma_f32_16x16x32_bf16 v[92:95], v[108:111], v[180:183], v[92:95]
	v_mfma_f32_16x16x32_bf16 v[88:91], v[128:131], v[180:183], v[88:91]
	v_mfma_f32_16x16x32_bf16 v[72:75], v[128:131], v[206:209], v[72:75]
	v_mfma_f32_16x16x32_bf16 v[76:79], v[108:111], v[206:209], v[76:79]
	v_mfma_f32_16x16x32_bf16 v[132:135], v[144:147], v[160:163], v[132:135]
	v_mfma_f32_16x16x32_bf16 v[124:127], v[152:155], v[160:163], v[124:127]
	v_mfma_f32_16x16x32_bf16 v[100:103], v[152:155], v[168:171], v[100:103]
	v_mfma_f32_16x16x32_bf16 v[104:107], v[144:147], v[168:171], v[104:107]
	v_mfma_f32_16x16x32_bf16 v[84:87], v[144:147], v[176:179], v[84:87]
	v_mfma_f32_16x16x32_bf16 v[80:83], v[152:155], v[176:179], v[80:83]
	v_mfma_f32_16x16x32_bf16 v[64:67], v[152:155], v[202:205], v[64:67]
	v_mfma_f32_16x16x32_bf16 v[68:71], v[144:147], v[202:205], v[68:71]
	v_mfma_f32_16x16x32_bf16 v[132:135], v[148:151], v[164:167], v[132:135]
	v_mfma_f32_16x16x32_bf16 v[124:127], v[156:159], v[164:167], v[124:127]
	v_mfma_f32_16x16x32_bf16 v[100:103], v[156:159], v[172:175], v[100:103]
	v_mfma_f32_16x16x32_bf16 v[104:107], v[148:151], v[172:175], v[104:107]
	v_mfma_f32_16x16x32_bf16 v[84:87], v[148:151], v[180:183], v[84:87]
	v_mfma_f32_16x16x32_bf16 v[80:83], v[156:159], v[180:183], v[80:83]
	v_mfma_f32_16x16x32_bf16 v[64:67], v[156:159], v[206:209], v[64:67]
	v_mfma_f32_16x16x32_bf16 v[68:71], v[148:151], v[206:209], v[68:71]
	s_barrier
	s_add_i32 s76, s67, s53
	s_add_u32 s98, s34, s12
	s_addc_u32 s99, s35, s13
	s_add_u32 s100, s50, s12
	s_addc_u32 s101, s51, s13
	s_mov_b32 m0, s76
	ds_read_b128 v[160:163], v225 offset:16384
	ds_read_b128 v[164:167], v225 offset:17408
	ds_read_b128 v[168:171], v225 offset:18432
	ds_read_b128 v[172:175], v225 offset:19456
	ds_read_b128 v[176:179], v225 offset:20480
	ds_read_b128 v[180:183], v225 offset:21504
	ds_read_b128 v[202:205], v225 offset:22528
	ds_read_b128 v[206:209], v225 offset:23552
	global_load_lds_dwordx4 v186, s[34:35]
	s_add_i32 m0, s76, 0x2000
	s_add_u32 s76, s34, 0xb0000
	s_addc_u32 s77, s35, 0
	s_add_i32 s78, s68, s53
	global_load_lds_dwordx4 v190, s[34:35]
	s_mov_b32 m0, s78
	s_nop 0
	global_load_lds_dwordx4 v186, s[76:77]
	s_add_i32 m0, s78, 0x2000
	s_nop 0
	global_load_lds_dwordx4 v190, s[76:77]
	s_mov_b32 m0, s54
	s_nop 0
	global_load_lds_dwordx4 v184, s[50:51]
	s_mov_b32 m0, s55
	s_nop 0
	global_load_lds_dwordx4 v188, s[50:51]
	s_waitcnt vmcnt(8)
	s_waitcnt lgkmcnt(0)
	s_barrier
	v_mfma_f32_16x16x32_bf16 v[60:63], v[96:99], v[160:163], v[60:63]
	v_mfma_f32_16x16x32_bf16 v[56:59], v[120:123], v[160:163], v[56:59]
	v_mfma_f32_16x16x32_bf16 v[40:43], v[120:123], v[168:171], v[40:43]
	v_mfma_f32_16x16x32_bf16 v[44:47], v[96:99], v[168:171], v[44:47]
	v_mfma_f32_16x16x32_bf16 v[28:31], v[96:99], v[176:179], v[28:31]
	v_mfma_f32_16x16x32_bf16 v[24:27], v[120:123], v[176:179], v[24:27]
	v_mfma_f32_16x16x32_bf16 v[8:11], v[120:123], v[202:205], v[8:11]
	v_mfma_f32_16x16x32_bf16 v[12:15], v[96:99], v[202:205], v[12:15]
	v_mfma_f32_16x16x32_bf16 v[60:63], v[108:111], v[164:167], v[60:63]
	v_mfma_f32_16x16x32_bf16 v[56:59], v[128:131], v[164:167], v[56:59]
	v_mfma_f32_16x16x32_bf16 v[40:43], v[128:131], v[172:175], v[40:43]
	v_mfma_f32_16x16x32_bf16 v[44:47], v[108:111], v[172:175], v[44:47]
	v_mfma_f32_16x16x32_bf16 v[28:31], v[108:111], v[180:183], v[28:31]
	v_mfma_f32_16x16x32_bf16 v[24:27], v[128:131], v[180:183], v[24:27]
	v_mfma_f32_16x16x32_bf16 v[8:11], v[128:131], v[206:209], v[8:11]
	v_mfma_f32_16x16x32_bf16 v[12:15], v[108:111], v[206:209], v[12:15]
	v_mfma_f32_16x16x32_bf16 v[52:55], v[144:147], v[160:163], v[52:55]
	v_mfma_f32_16x16x32_bf16 v[48:51], v[152:155], v[160:163], v[48:51]
	v_mfma_f32_16x16x32_bf16 v[32:35], v[152:155], v[168:171], v[32:35]
	v_mfma_f32_16x16x32_bf16 v[36:39], v[144:147], v[168:171], v[36:39]
	v_mfma_f32_16x16x32_bf16 v[20:23], v[144:147], v[176:179], v[20:23]
	v_mfma_f32_16x16x32_bf16 v[16:19], v[152:155], v[176:179], v[16:19]
	v_mfma_f32_16x16x32_bf16 v[0:3], v[152:155], v[202:205], v[0:3]
	v_mfma_f32_16x16x32_bf16 v[4:7], v[144:147], v[202:205], v[4:7]
	v_mfma_f32_16x16x32_bf16 v[52:55], v[148:151], v[164:167], v[52:55]
	v_mfma_f32_16x16x32_bf16 v[48:51], v[156:159], v[164:167], v[48:51]
	v_mfma_f32_16x16x32_bf16 v[32:35], v[156:159], v[172:175], v[32:35]
	v_mfma_f32_16x16x32_bf16 v[36:39], v[148:151], v[172:175], v[36:39]
	v_mfma_f32_16x16x32_bf16 v[20:23], v[148:151], v[180:183], v[20:23]
	v_mfma_f32_16x16x32_bf16 v[16:19], v[156:159], v[180:183], v[16:19]
	v_mfma_f32_16x16x32_bf16 v[0:3], v[156:159], v[206:209], v[0:3]
	v_mfma_f32_16x16x32_bf16 v[4:7], v[148:151], v[206:209], v[4:7]
	s_barrier
; #define PG8_STAGE(bufoff, gbase, voff) do { _Pragma("unroll") for (int _i = 0; _i < 2; ++_i) \
;         __builtin_amdgcn_global_load_lds((const unsigned*)((const char*)(gbase) + (voff)[_i]), (PG8_LAS unsigned*)(lds + (bufoff) + ldsw + _i * 8192), 16, 0, 0); } while (0)
; #define PG8_LDA(dst, b, h) do { _Pragma("unroll") for (int m = 0; m < 4; ++m) _Pragma("unroll") for (int k = 0; k < 2; ++k) dst[m][k] = *(const PG8_LAS bf16x8*)(lds + PG8_SA(b, h) + aoff + m * 2048 + k * 1024); } while (0)
; #define PG8_LDB(dst, b, h) do { _Pragma("unroll") for (int n = 0; n < 2; ++n) _Pragma("unroll") for (int k = 0; k < 2; ++k) dst[n][k] = *(const PG8_LAS bf16x8*)(lds + PG8_SB(b, h) + boff + n * 2048 + k * 1024); } while (0)
; #define PG8_MMA(ai, bj, At, Bt) do { __builtin_amdgcn_s_setprio(1); _Pragma("unroll") for (int m = 0; m < 4; ++m) _Pragma("unroll") for (int n = 0; n < 2; ++n) _Pragma("unroll") for (int k = 0; k < 2; ++k) \
;         acc[ai][bj][m][n] = __builtin_amdgcn_mfma_f32_16x16x32_bf16(Bt[n][k], At[m][k], acc[ai][bj][m][n], 0, 0, 0); __builtin_amdgcn_s_setprio(0); } while (0)
; #define PG8_WAIT_V(n) asm volatile("s_waitcnt vmcnt(" #n ")" ::: "memory")
; #define PG8_WAIT_L(n) asm volatile("s_waitcnt lgkmcnt(" #n ")" ::: "memory")
; #define PG8_BAR __builtin_amdgcn_s_barrier()
; #define PG8_SCHED __builtin_amdgcn_sched_barrier(0)
; template <class Epi, class Sched, bool ALIGN_EPI = false, bool SP2 = false>
; __device__ __forceinline__ void gemm_phase(PG8_LAS unsigned char* lds, const Gemm g, const Sched& S, const Epi& E) {
;     ...
;             PG8_LDB(B0, 1, 0); PG8_LDB(B1, 1, 1); PG8_SCHED; PG8_LDA(At, 1, 0); PG8_STAGE(PG8_SA(0, 1), a2 + hstep, voffA);
;             PG8_WAIT_V(8); PG8_WAIT_L(0); PG8_BAR; PG8_MMA(0, 0, At, B0); PG8_MMA(0, 1, At, B1); PG8_BAR; PG8_SCHED;
;             PG8_LDA(At, 1, 1); PG8_STAGE(PG8_SB(1, 0), b3, voffB); PG8_STAGE(PG8_SB(1, 1), b3 + hstep, voffB); PG8_STAGE(PG8_SA(1, 0), a3, voffA);
;             PG8_WAIT_V(8); PG8_WAIT_L(0); PG8_BAR; PG8_MMA(1, 0, At, B0); PG8_MMA(1, 1, At, B1); PG8_BAR; PG8_SCHED;
;     ...
;         if constexpr (ALIGN_EPI) { if (wr == 0) PG8_BAR; }
	s_add_i32 s76, 0, 0x18000
	s_add_i32 s77, 0, 0x1c000
	v_add_u32_e32 v128, s76, v221
	v_add_u32_e32 v156, s77, v221
	ds_read_b128 v[96:99], v128
	ds_read_b128 v[108:111], v128 offset:1024
	ds_read_b128 v[120:123], v128 offset:2048
	ds_read_b128 v[128:131], v128 offset:3072
	ds_read_b128 v[144:147], v156
	ds_read_b128 v[148:151], v156 offset:1024
	ds_read_b128 v[152:155], v156 offset:2048
	ds_read_b128 v[156:159], v156 offset:3072
	s_add_u32 s50, s50, 0xb0000
	s_addc_u32 s51, s51, 0
	s_mov_b32 m0, s56
	ds_read_b128 v[160:163], v225 offset:32768
	ds_read_b128 v[164:167], v225 offset:33792
	ds_read_b128 v[168:171], v225 offset:34816
	ds_read_b128 v[172:175], v225 offset:35840
	ds_read_b128 v[176:179], v225 offset:36864
	ds_read_b128 v[180:183], v225 offset:37888
	ds_read_b128 v[202:205], v225 offset:38912
	ds_read_b128 v[206:209], v225 offset:39936
	global_load_lds_dwordx4 v184, s[50:51]
	s_mov_b32 m0, s57
	s_nop 0
	global_load_lds_dwordx4 v188, s[50:51]
	s_waitcnt vmcnt(8)
	s_waitcnt lgkmcnt(0)
	s_barrier
	v_mfma_f32_16x16x32_bf16 v[140:143], v[96:99], v[160:163], v[140:143]
	v_mfma_f32_16x16x32_bf16 v[136:139], v[120:123], v[160:163], v[136:139]
	v_mfma_f32_16x16x32_bf16 v[112:115], v[120:123], v[168:171], v[112:115]
	v_mfma_f32_16x16x32_bf16 v[116:119], v[96:99], v[168:171], v[116:119]
	v_mfma_f32_16x16x32_bf16 v[92:95], v[96:99], v[176:179], v[92:95]
	v_mfma_f32_16x16x32_bf16 v[88:91], v[120:123], v[176:179], v[88:91]
	v_mfma_f32_16x16x32_bf16 v[72:75], v[120:123], v[202:205], v[72:75]
	v_mfma_f32_16x16x32_bf16 v[76:79], v[96:99], v[202:205], v[76:79]
	v_mfma_f32_16x16x32_bf16 v[140:143], v[108:111], v[164:167], v[140:143]
	v_mfma_f32_16x16x32_bf16 v[136:139], v[128:131], v[164:167], v[136:139]
	v_mfma_f32_16x16x32_bf16 v[112:115], v[128:131], v[172:175], v[112:115]
	v_mfma_f32_16x16x32_bf16 v[116:119], v[108:111], v[172:175], v[116:119]
	v_mfma_f32_16x16x32_bf16 v[92:95], v[108:111], v[180:183], v[92:95]
	v_mfma_f32_16x16x32_bf16 v[88:91], v[128:131], v[180:183], v[88:91]
	v_mfma_f32_16x16x32_bf16 v[72:75], v[128:131], v[206:209], v[72:75]
	v_mfma_f32_16x16x32_bf16 v[76:79], v[108:111], v[206:209], v[76:79]
	v_mfma_f32_16x16x32_bf16 v[132:135], v[144:147], v[160:163], v[132:135]
	v_mfma_f32_16x16x32_bf16 v[124:127], v[152:155], v[160:163], v[124:127]
	v_mfma_f32_16x16x32_bf16 v[100:103], v[152:155], v[168:171], v[100:103]
	v_mfma_f32_16x16x32_bf16 v[104:107], v[144:147], v[168:171], v[104:107]
	v_mfma_f32_16x16x32_bf16 v[84:87], v[144:147], v[176:179], v[84:87]
	v_mfma_f32_16x16x32_bf16 v[80:83], v[152:155], v[176:179], v[80:83]
	v_mfma_f32_16x16x32_bf16 v[64:67], v[152:155], v[202:205], v[64:67]
	v_mfma_f32_16x16x32_bf16 v[68:71], v[144:147], v[202:205], v[68:71]
	v_mfma_f32_16x16x32_bf16 v[132:135], v[148:151], v[164:167], v[132:135]
	v_mfma_f32_16x16x32_bf16 v[124:127], v[156:159], v[164:167], v[124:127]
	v_mfma_f32_16x16x32_bf16 v[100:103], v[156:159], v[172:175], v[100:103]
	v_mfma_f32_16x16x32_bf16 v[104:107], v[148:151], v[172:175], v[104:107]
	v_mfma_f32_16x16x32_bf16 v[84:87], v[148:151], v[180:183], v[84:87]
	v_mfma_f32_16x16x32_bf16 v[80:83], v[156:159], v[180:183], v[80:83]
	v_mfma_f32_16x16x32_bf16 v[64:67], v[156:159], v[206:209], v[64:67]
	v_mfma_f32_16x16x32_bf16 v[68:71], v[148:151], v[206:209], v[68:71]
	s_barrier
	s_add_i32 s50, s76, s53
	s_mov_b32 m0, s50
	ds_read_b128 v[160:163], v225 offset:49152
	ds_read_b128 v[164:167], v225 offset:50176
	ds_read_b128 v[168:171], v225 offset:51200
	ds_read_b128 v[172:175], v225 offset:52224
	ds_read_b128 v[176:179], v225 offset:53248
	ds_read_b128 v[180:183], v225 offset:54272
	ds_read_b128 v[202:205], v225 offset:55296
	ds_read_b128 v[206:209], v225 offset:56320
	global_load_lds_dwordx4 v186, s[98:99]
	s_add_i32 m0, s50, 0x2000
	s_add_u32 s34, s34, 0xb0080
	s_addc_u32 s35, s35, 0
	s_add_i32 s50, s77, s53
	global_load_lds_dwordx4 v190, s[98:99]
	s_mov_b32 m0, s50
	s_nop 0
	global_load_lds_dwordx4 v186, s[34:35]
	s_add_i32 m0, s50, 0x2000
	s_nop 0
	global_load_lds_dwordx4 v190, s[34:35]
	s_mov_b32 m0, s62
	s_nop 0
	global_load_lds_dwordx4 v184, s[100:101]
	s_mov_b32 m0, s63
	s_nop 0
	global_load_lds_dwordx4 v188, s[100:101]
	s_waitcnt vmcnt(8)
	s_waitcnt lgkmcnt(0)
	s_barrier
	v_mfma_f32_16x16x32_bf16 v[60:63], v[96:99], v[160:163], v[60:63]
	v_mfma_f32_16x16x32_bf16 v[56:59], v[120:123], v[160:163], v[56:59]
	v_mfma_f32_16x16x32_bf16 v[40:43], v[120:123], v[168:171], v[40:43]
	v_mfma_f32_16x16x32_bf16 v[44:47], v[96:99], v[168:171], v[44:47]
	v_mfma_f32_16x16x32_bf16 v[28:31], v[96:99], v[176:179], v[28:31]
	v_mfma_f32_16x16x32_bf16 v[24:27], v[120:123], v[176:179], v[24:27]
	v_mfma_f32_16x16x32_bf16 v[8:11], v[120:123], v[202:205], v[8:11]
	v_mfma_f32_16x16x32_bf16 v[12:15], v[96:99], v[202:205], v[12:15]
	v_mfma_f32_16x16x32_bf16 v[60:63], v[108:111], v[164:167], v[60:63]
	v_mfma_f32_16x16x32_bf16 v[56:59], v[128:131], v[164:167], v[56:59]
	v_mfma_f32_16x16x32_bf16 v[40:43], v[128:131], v[172:175], v[40:43]
	v_mfma_f32_16x16x32_bf16 v[44:47], v[108:111], v[172:175], v[44:47]
	v_mfma_f32_16x16x32_bf16 v[28:31], v[108:111], v[180:183], v[28:31]
	v_mfma_f32_16x16x32_bf16 v[24:27], v[128:131], v[180:183], v[24:27]
	v_mfma_f32_16x16x32_bf16 v[8:11], v[128:131], v[206:209], v[8:11]
	v_mfma_f32_16x16x32_bf16 v[12:15], v[108:111], v[206:209], v[12:15]
	v_mfma_f32_16x16x32_bf16 v[52:55], v[144:147], v[160:163], v[52:55]
	v_mfma_f32_16x16x32_bf16 v[48:51], v[152:155], v[160:163], v[48:51]
	v_mfma_f32_16x16x32_bf16 v[32:35], v[152:155], v[168:171], v[32:35]
	v_mfma_f32_16x16x32_bf16 v[36:39], v[144:147], v[168:171], v[36:39]
	v_mfma_f32_16x16x32_bf16 v[20:23], v[144:147], v[176:179], v[20:23]
	v_mfma_f32_16x16x32_bf16 v[16:19], v[152:155], v[176:179], v[16:19]
	v_mfma_f32_16x16x32_bf16 v[0:3], v[152:155], v[202:205], v[0:3]
	v_mfma_f32_16x16x32_bf16 v[4:7], v[144:147], v[202:205], v[4:7]
	v_mfma_f32_16x16x32_bf16 v[52:55], v[148:151], v[164:167], v[52:55]
	v_mfma_f32_16x16x32_bf16 v[48:51], v[156:159], v[164:167], v[48:51]
	v_mfma_f32_16x16x32_bf16 v[32:35], v[156:159], v[172:175], v[32:35]
	v_mfma_f32_16x16x32_bf16 v[36:39], v[148:151], v[172:175], v[36:39]
	v_mfma_f32_16x16x32_bf16 v[20:23], v[148:151], v[180:183], v[20:23]
	v_mfma_f32_16x16x32_bf16 v[16:19], v[156:159], v[180:183], v[16:19]
	v_mfma_f32_16x16x32_bf16 v[0:3], v[156:159], v[206:209], v[0:3]
	v_mfma_f32_16x16x32_bf16 v[4:7], v[148:151], v[206:209], v[4:7]
	s_barrier
	s_add_i32 s75, s75, 2
	s_add_u32 s20, s20, 0x100
	s_addc_u32 s21, s21, 0
	s_add_u32 s73, s73, 0x100
	s_addc_u32 s74, s74, 0
	s_cmp_gt_u32 s75, 41
	s_cbranch_scc0 .LBB0_309
	s_and_b64 vcc, exec, s[14:15]
	s_cbranch_vccz .LBB0_312
	s_barrier

; #define PG8_STAGE(bufoff, gbase, voff) do { _Pragma("unroll") for (int _i = 0; _i < 2; ++_i) \
;         __builtin_amdgcn_global_load_lds((const unsigned*)((const char*)(gbase) + (voff)[_i]), (PG8_LAS unsigned*)(lds + (bufoff) + ldsw + _i * 8192), 16, 0, 0); } while (0)
; #define PG8_LDA(dst, b, h) do { _Pragma("unroll") for (int m = 0; m < 4; ++m) _Pragma("unroll") for (int k = 0; k < 2; ++k) dst[m][k] = *(const PG8_LAS bf16x8*)(lds + PG8_SA(b, h) + aoff + m * 2048 + k * 1024); } while (0)
; template <class Epi, class Sched, bool ALIGN_EPI = false, bool SP2 = false>
; __device__ __forceinline__ void gemm_phase(PG8_LAS unsigned char* lds, const Gemm g, const Sched& S, const Epi& E) {
;     ...
;         const bool has_next = S.next(ui + 1, nxt);
;         const char* nA = has_next ? (const char*)g.A + (size_t)nxt.pm * tstep : cA; const char* nB = has_next ? (const char*)g.Bt + (size_t)nxt.pn * tstep : cB;
;         for (int t = 0; t < nt; t += 2) {
;             const bool last = (t == nt - 2);
;             const char* a1 = cA + (size_t)(t + 1) * kstep;
;             const char* a2 = last ? nA : cA + (size_t)(t + 2) * kstep; const char* b2 = last ? nB : cB + (size_t)(t + 2) * kstep;
;             const char* a3 = a2 + kstep; const char* b3 = b2 + kstep;
;             if (last && has_next) S.a_ready(nxt);
;             if constexpr (SP2) {
;             PG8_LDB(B0, 0, 0); PG8_LDB(B1, 0, 1); PG8_SCHED; PG8_LDA(At, 0, 0); PG8_STAGE(PG8_SA(1, 1), a1 + hstep, voffA);
;             PG8_WAIT_V(8); PG8_WAIT_L(0); PG8_BAR; PG8_MMA(0, 0, At, B0); PG8_MMA(0, 1, At, B1); PG8_BAR; PG8_SCHED;
;             PG8_LDA(At, 0, 1); PG8_STAGE(PG8_SB(0, 0), b2, voffB); PG8_STAGE(PG8_SB(0, 1), b2 + hstep, voffB); PG8_STAGE(PG8_SA(0, 0), a2, voffA);
;             PG8_WAIT_V(8); PG8_WAIT_L(0); PG8_BAR; PG8_MMA(1, 0, At, B0); PG8_MMA(1, 1, At, B1); PG8_BAR; PG8_SCHED;
;             PG8_LDB(B0, 1, 0); PG8_LDB(B1, 1, 1); PG8_SCHED; PG8_LDA(At, 1, 0); PG8_STAGE(PG8_SA(0, 1), a2 + hstep, voffA);
;             PG8_WAIT_V(8); PG8_WAIT_L(0); PG8_BAR; PG8_MMA(0, 0, At, B0); PG8_MMA(0, 1, At, B1); PG8_BAR; PG8_SCHED;
;             PG8_LDA(At, 1, 1); PG8_STAGE(PG8_SB(1, 0), b3, voffB); PG8_STAGE(PG8_SB(1, 1), b3 + hstep, voffB); PG8_STAGE(PG8_SA(1, 0), a3, voffA);
;             PG8_WAIT_V(8); PG8_WAIT_L(0); PG8_BAR; PG8_MMA(1, 0, At, B0); PG8_MMA(1, 1, At, B1); PG8_BAR; PG8_SCHED;
.LBB0_413:
	s_ashr_i32 s43, s42, 31
	s_lshl_b64 s[48:49], s[42:43], 19
	s_add_u32 s48, s36, s48
	s_addc_u32 s49, s37, s49
	s_and_b64 s[50:51], s[4:5], exec
	s_cselect_b32 s43, s49, s21
	s_cselect_b32 s78, s48, s20
	s_ashr_i32 s19, s18, 31
	s_lshl_b64 s[50:51], s[18:19], 19
	s_add_u32 s50, s61, s50
	s_addc_u32 s51, s62, s51
	s_and_b64 s[54:55], s[4:5], exec
	s_cselect_b32 s19, s51, s53
	s_cselect_b32 s79, s50, s52
	s_add_u32 s20, s20, 0x40080
	s_addc_u32 s21, s21, 0
	s_add_u32 s80, s52, 0x100
	s_addc_u32 s81, s53, 0
	s_mov_b32 s84, -2
	ds_read_b128 v[146:149], v165
	ds_read_b128 v[150:153], v165 offset:1024
	ds_read_b128 v[154:157], v165 offset:2048
	ds_read_b128 v[168:171], v165 offset:3072
	ds_read_b128 v[172:175], v166
	ds_read_b128 v[176:179], v166 offset:1024
	ds_read_b128 v[180:183], v166 offset:2048
	ds_read_b128 v[184:187], v166 offset:3072
	s_add_u32 s52, s20, 0xfffc0080
	s_addc_u32 s53, s21, -1
	s_cmp_eq_u32 s84, 12
	s_cselect_b32 s55, s43, s53
	s_cselect_b32 s54, s78, s52
	s_cselect_b32 s53, s19, s81
	s_cselect_b32 s52, s79, s80
	s_add_i32 m0, s35, 0xc000
	ds_read_b128 v[188:191], v167
	ds_read_b128 v[192:195], v167 offset:1024
	ds_read_b128 v[198:201], v167 offset:2048
	ds_read_b128 v[202:205], v167 offset:3072
	ds_read_b128 v[206:209], v167 offset:4096
	ds_read_b128 v[210:213], v167 offset:5120
	ds_read_b128 v[214:217], v167 offset:6144
	ds_read_b128 v[218:221], v167 offset:7168
	global_load_lds_dwordx4 v138, s[20:21]
	s_add_i32 m0, s35, 0xe000
	s_nop 0
	global_load_lds_dwordx4 v140, s[20:21]
	s_waitcnt vmcnt(8)
	s_waitcnt lgkmcnt(0)
	s_barrier
	v_mfma_f32_16x16x32_bf16 v[124:127], v[146:149], v[188:191], 0
	v_mfma_f32_16x16x32_bf16 v[120:123], v[154:157], v[188:191], 0
	v_mfma_f32_16x16x32_bf16 v[104:107], v[154:157], v[198:201], 0
	v_mfma_f32_16x16x32_bf16 v[108:111], v[146:149], v[198:201], 0
	v_mfma_f32_16x16x32_bf16 v[92:95], v[146:149], v[206:209], 0
	v_mfma_f32_16x16x32_bf16 v[88:91], v[154:157], v[206:209], 0
	v_mfma_f32_16x16x32_bf16 v[72:75], v[154:157], v[214:217], 0
	v_mfma_f32_16x16x32_bf16 v[76:79], v[146:149], v[214:217], 0
	v_mfma_f32_16x16x32_bf16 v[124:127], v[150:153], v[192:195], v[124:127]
	v_mfma_f32_16x16x32_bf16 v[120:123], v[168:171], v[192:195], v[120:123]
	v_mfma_f32_16x16x32_bf16 v[104:107], v[168:171], v[202:205], v[104:107]
	v_mfma_f32_16x16x32_bf16 v[108:111], v[150:153], v[202:205], v[108:111]
	v_mfma_f32_16x16x32_bf16 v[92:95], v[150:153], v[210:213], v[92:95]
	v_mfma_f32_16x16x32_bf16 v[88:91], v[168:171], v[210:213], v[88:91]
	v_mfma_f32_16x16x32_bf16 v[72:75], v[168:171], v[218:221], v[72:75]
	v_mfma_f32_16x16x32_bf16 v[76:79], v[150:153], v[218:221], v[76:79]
	v_mfma_f32_16x16x32_bf16 v[116:119], v[172:175], v[188:191], 0
	v_mfma_f32_16x16x32_bf16 v[112:115], v[180:183], v[188:191], 0
	v_mfma_f32_16x16x32_bf16 v[96:99], v[180:183], v[198:201], 0
	v_mfma_f32_16x16x32_bf16 v[100:103], v[172:175], v[198:201], 0
	v_mfma_f32_16x16x32_bf16 v[84:87], v[172:175], v[206:209], 0
	v_mfma_f32_16x16x32_bf16 v[80:83], v[180:183], v[206:209], 0
	v_mfma_f32_16x16x32_bf16 v[64:67], v[180:183], v[214:217], 0
	v_mfma_f32_16x16x32_bf16 v[68:71], v[172:175], v[214:217], 0
	v_mfma_f32_16x16x32_bf16 v[116:119], v[176:179], v[192:195], v[116:119]
	v_mfma_f32_16x16x32_bf16 v[112:115], v[184:187], v[192:195], v[112:115]
	v_mfma_f32_16x16x32_bf16 v[96:99], v[184:187], v[202:205], v[96:99]
	v_mfma_f32_16x16x32_bf16 v[100:103], v[176:179], v[202:205], v[100:103]
	v_mfma_f32_16x16x32_bf16 v[84:87], v[176:179], v[210:213], v[84:87]
	v_mfma_f32_16x16x32_bf16 v[80:83], v[184:187], v[210:213], v[80:83]
	v_mfma_f32_16x16x32_bf16 v[64:67], v[184:187], v[218:221], v[64:67]
	v_mfma_f32_16x16x32_bf16 v[68:71], v[176:179], v[218:221], v[68:71]
	s_barrier
	s_add_i32 s85, s72, s63
	s_add_u32 s98, s52, s8
	s_addc_u32 s99, s53, s9
	s_add_u32 s100, s54, s8
	s_addc_u32 s101, s55, s9
	s_mov_b32 m0, s85
	ds_read_b128 v[188:191], v167 offset:16384
	ds_read_b128 v[192:195], v167 offset:17408
	ds_read_b128 v[198:201], v167 offset:18432
	ds_read_b128 v[202:205], v167 offset:19456
	ds_read_b128 v[206:209], v167 offset:20480
	ds_read_b128 v[210:213], v167 offset:21504
	ds_read_b128 v[214:217], v167 offset:22528
	ds_read_b128 v[218:221], v167 offset:23552
	global_load_lds_dwordx4 v132, s[52:53]
	s_add_i32 m0, s85, 0x2000
	s_add_u32 s86, s52, 0x40000
	s_addc_u32 s87, s53, 0
	s_add_i32 s85, s73, s63
	global_load_lds_dwordx4 v128, s[52:53]
	s_mov_b32 m0, s85
	s_nop 0
	global_load_lds_dwordx4 v132, s[86:87]
	s_add_i32 m0, s85, 0x2000
	s_nop 0
	global_load_lds_dwordx4 v128, s[86:87]
	s_mov_b32 m0, s35
	s_nop 0
	global_load_lds_dwordx4 v134, s[54:55]
	s_mov_b32 m0, s65
	s_nop 0
	global_load_lds_dwordx4 v130, s[54:55]
	s_waitcnt vmcnt(8)
	s_waitcnt lgkmcnt(0)
	s_barrier
; #define PG8_STAGE(bufoff, gbase, voff) do { _Pragma("unroll") for (int _i = 0; _i < 2; ++_i) \
;         __builtin_amdgcn_global_load_lds((const unsigned*)((const char*)(gbase) + (voff)[_i]), (PG8_LAS unsigned*)(lds + (bufoff) + ldsw + _i * 8192), 16, 0, 0); } while (0)
; #define PG8_LDA(dst, b, h) do { _Pragma("unroll") for (int m = 0; m < 4; ++m) _Pragma("unroll") for (int k = 0; k < 2; ++k) dst[m][k] = *(const PG8_LAS bf16x8*)(lds + PG8_SA(b, h) + aoff + m * 2048 + k * 1024); } while (0)
; #define PG8_LDB(dst, b, h) do { _Pragma("unroll") for (int n = 0; n < 2; ++n) _Pragma("unroll") for (int k = 0; k < 2; ++k) dst[n][k] = *(const PG8_LAS bf16x8*)(lds + PG8_SB(b, h) + boff + n * 2048 + k * 1024); } while (0)
; #define PG8_MMA(ai, bj, At, Bt) do { __builtin_amdgcn_s_setprio(1); _Pragma("unroll") for (int m = 0; m < 4; ++m) _Pragma("unroll") for (int n = 0; n < 2; ++n) _Pragma("unroll") for (int k = 0; k < 2; ++k) \
;         acc[ai][bj][m][n] = __builtin_amdgcn_mfma_f32_16x16x32_bf16(Bt[n][k], At[m][k], acc[ai][bj][m][n], 0, 0, 0); __builtin_amdgcn_s_setprio(0); } while (0)
; #define PG8_WAIT_V(n) asm volatile("s_waitcnt vmcnt(" #n ")" ::: "memory")
; #define PG8_WAIT_L(n) asm volatile("s_waitcnt lgkmcnt(" #n ")" ::: "memory")
; #define PG8_BAR __builtin_amdgcn_s_barrier()
; #define PG8_SCHED __builtin_amdgcn_sched_barrier(0)
; template <class Epi, class Sched, bool ALIGN_EPI = false, bool SP2 = false>
; __device__ __forceinline__ void gemm_phase(PG8_LAS unsigned char* lds, const Gemm g, const Sched& S, const Epi& E) {
;     ...
;             PG8_LDB(B0, 0, 0); PG8_LDB(B1, 0, 1); PG8_SCHED; PG8_LDA(At, 0, 0); PG8_STAGE(PG8_SA(1, 1), a1 + hstep, voffA);
;             PG8_WAIT_V(8); PG8_WAIT_L(0); PG8_BAR; PG8_MMA(0, 0, At, B0); PG8_MMA(0, 1, At, B1); PG8_BAR; PG8_SCHED;
;             PG8_LDA(At, 0, 1); PG8_STAGE(PG8_SB(0, 0), b2, voffB); PG8_STAGE(PG8_SB(0, 1), b2 + hstep, voffB); PG8_STAGE(PG8_SA(0, 0), a2, voffA);
;             PG8_WAIT_V(8); PG8_WAIT_L(0); PG8_BAR; PG8_MMA(1, 0, At, B0); PG8_MMA(1, 1, At, B1); PG8_BAR; PG8_SCHED;
;             PG8_LDB(B0, 1, 0); PG8_LDB(B1, 1, 1); PG8_SCHED; PG8_LDA(At, 1, 0); PG8_STAGE(PG8_SA(0, 1), a2 + hstep, voffA);
;             PG8_WAIT_V(8); PG8_WAIT_L(0); PG8_BAR; PG8_MMA(0, 0, At, B0); PG8_MMA(0, 1, At, B1); PG8_BAR; PG8_SCHED;
	v_mfma_f32_16x16x32_bf16 v[60:63], v[146:149], v[188:191], 0
	v_mfma_f32_16x16x32_bf16 v[56:59], v[154:157], v[188:191], 0
	v_mfma_f32_16x16x32_bf16 v[40:43], v[154:157], v[198:201], 0
	v_mfma_f32_16x16x32_bf16 v[44:47], v[146:149], v[198:201], 0
	v_mfma_f32_16x16x32_bf16 v[28:31], v[146:149], v[206:209], 0
	v_mfma_f32_16x16x32_bf16 v[24:27], v[154:157], v[206:209], 0
	v_mfma_f32_16x16x32_bf16 v[8:11], v[154:157], v[214:217], 0
	v_mfma_f32_16x16x32_bf16 v[12:15], v[146:149], v[214:217], 0
	v_mfma_f32_16x16x32_bf16 v[60:63], v[150:153], v[192:195], v[60:63]
	v_mfma_f32_16x16x32_bf16 v[56:59], v[168:171], v[192:195], v[56:59]
	v_mfma_f32_16x16x32_bf16 v[40:43], v[168:171], v[202:205], v[40:43]
	v_mfma_f32_16x16x32_bf16 v[44:47], v[150:153], v[202:205], v[44:47]
	v_mfma_f32_16x16x32_bf16 v[28:31], v[150:153], v[210:213], v[28:31]
	v_mfma_f32_16x16x32_bf16 v[24:27], v[168:171], v[210:213], v[24:27]
	v_mfma_f32_16x16x32_bf16 v[8:11], v[168:171], v[218:221], v[8:11]
	v_mfma_f32_16x16x32_bf16 v[12:15], v[150:153], v[218:221], v[12:15]
	v_mfma_f32_16x16x32_bf16 v[52:55], v[172:175], v[188:191], 0
	v_mfma_f32_16x16x32_bf16 v[48:51], v[180:183], v[188:191], 0
	v_mfma_f32_16x16x32_bf16 v[32:35], v[180:183], v[198:201], 0
	v_mfma_f32_16x16x32_bf16 v[36:39], v[172:175], v[198:201], 0
	v_mfma_f32_16x16x32_bf16 v[20:23], v[172:175], v[206:209], 0
	v_mfma_f32_16x16x32_bf16 v[16:19], v[180:183], v[206:209], 0
	v_mfma_f32_16x16x32_bf16 v[0:3], v[180:183], v[214:217], 0
	v_mfma_f32_16x16x32_bf16 v[4:7], v[172:175], v[214:217], 0
	v_mfma_f32_16x16x32_bf16 v[52:55], v[176:179], v[192:195], v[52:55]
	v_mfma_f32_16x16x32_bf16 v[48:51], v[184:187], v[192:195], v[48:51]
	v_mfma_f32_16x16x32_bf16 v[32:35], v[184:187], v[202:205], v[32:35]
	v_mfma_f32_16x16x32_bf16 v[36:39], v[176:179], v[202:205], v[36:39]
	v_mfma_f32_16x16x32_bf16 v[20:23], v[176:179], v[210:213], v[20:23]
	v_mfma_f32_16x16x32_bf16 v[16:19], v[184:187], v[210:213], v[16:19]
	v_mfma_f32_16x16x32_bf16 v[0:3], v[184:187], v[218:221], v[0:3]
	v_mfma_f32_16x16x32_bf16 v[4:7], v[176:179], v[218:221], v[4:7]
	s_barrier
	s_add_i32 s85, 0, 0x18000
	v_add_u32_e32 v136, s85, v161
	s_add_i32 s86, 0, 0x1c000
	ds_read_b128 v[146:149], v136
	ds_read_b128 v[150:153], v136 offset:1024
	ds_read_b128 v[154:157], v136 offset:2048
	ds_read_b128 v[168:171], v136 offset:3072
	v_add_u32_e32 v136, s86, v161
	ds_read_b128 v[172:175], v136
	ds_read_b128 v[176:179], v136 offset:1024
	ds_read_b128 v[180:183], v136 offset:2048
	ds_read_b128 v[184:187], v136 offset:3072
	s_add_u32 s54, s54, 0x40000
	s_addc_u32 s55, s55, 0
	s_mov_b32 m0, s66
	ds_read_b128 v[188:191], v167 offset:32768
	ds_read_b128 v[192:195], v167 offset:33792
	ds_read_b128 v[198:201], v167 offset:34816
	ds_read_b128 v[202:205], v167 offset:35840
	ds_read_b128 v[206:209], v167 offset:36864
	ds_read_b128 v[210:213], v167 offset:37888
	ds_read_b128 v[214:217], v167 offset:38912
	ds_read_b128 v[218:221], v167 offset:39936
	global_load_lds_dwordx4 v134, s[54:55]
	s_mov_b32 m0, s67
	s_nop 0
	global_load_lds_dwordx4 v130, s[54:55]
	s_waitcnt vmcnt(8)
	s_waitcnt lgkmcnt(0)
	s_barrier
	v_mfma_f32_16x16x32_bf16 v[124:127], v[146:149], v[188:191], v[124:127]
	v_mfma_f32_16x16x32_bf16 v[120:123], v[154:157], v[188:191], v[120:123]
	v_mfma_f32_16x16x32_bf16 v[104:107], v[154:157], v[198:201], v[104:107]
	v_mfma_f32_16x16x32_bf16 v[108:111], v[146:149], v[198:201], v[108:111]
	v_mfma_f32_16x16x32_bf16 v[92:95], v[146:149], v[206:209], v[92:95]
	v_mfma_f32_16x16x32_bf16 v[88:91], v[154:157], v[206:209], v[88:91]
	v_mfma_f32_16x16x32_bf16 v[72:75], v[154:157], v[214:217], v[72:75]
	v_mfma_f32_16x16x32_bf16 v[76:79], v[146:149], v[214:217], v[76:79]
	v_mfma_f32_16x16x32_bf16 v[124:127], v[150:153], v[192:195], v[124:127]
	v_mfma_f32_16x16x32_bf16 v[120:123], v[168:171], v[192:195], v[120:123]
	v_mfma_f32_16x16x32_bf16 v[104:107], v[168:171], v[202:205], v[104:107]
	v_mfma_f32_16x16x32_bf16 v[108:111], v[150:153], v[202:205], v[108:111]
	v_mfma_f32_16x16x32_bf16 v[92:95], v[150:153], v[210:213], v[92:95]
	v_mfma_f32_16x16x32_bf16 v[88:91], v[168:171], v[210:213], v[88:91]
	v_mfma_f32_16x16x32_bf16 v[72:75], v[168:171], v[218:221], v[72:75]
	v_mfma_f32_16x16x32_bf16 v[76:79], v[150:153], v[218:221], v[76:79]
	v_mfma_f32_16x16x32_bf16 v[116:119], v[172:175], v[188:191], v[116:119]
	v_mfma_f32_16x16x32_bf16 v[112:115], v[180:183], v[188:191], v[112:115]
	v_mfma_f32_16x16x32_bf16 v[96:99], v[180:183], v[198:201], v[96:99]
	v_mfma_f32_16x16x32_bf16 v[100:103], v[172:175], v[198:201], v[100:103]
	v_mfma_f32_16x16x32_bf16 v[84:87], v[172:175], v[206:209], v[84:87]
	v_mfma_f32_16x16x32_bf16 v[80:83], v[180:183], v[206:209], v[80:83]
	v_mfma_f32_16x16x32_bf16 v[64:67], v[180:183], v[214:217], v[64:67]
	v_mfma_f32_16x16x32_bf16 v[68:71], v[172:175], v[214:217], v[68:71]
	v_mfma_f32_16x16x32_bf16 v[116:119], v[176:179], v[192:195], v[116:119]
	v_mfma_f32_16x16x32_bf16 v[112:115], v[184:187], v[192:195], v[112:115]
	v_mfma_f32_16x16x32_bf16 v[96:99], v[184:187], v[202:205], v[96:99]
	v_mfma_f32_16x16x32_bf16 v[100:103], v[176:179], v[202:205], v[100:103]
	v_mfma_f32_16x16x32_bf16 v[84:87], v[176:179], v[210:213], v[84:87]
	v_mfma_f32_16x16x32_bf16 v[80:83], v[184:187], v[210:213], v[80:83]
	v_mfma_f32_16x16x32_bf16 v[64:67], v[184:187], v[218:221], v[64:67]
	v_mfma_f32_16x16x32_bf16 v[68:71], v[176:179], v[218:221], v[68:71]
	s_barrier
; #define PG8_STAGE(bufoff, gbase, voff) do { _Pragma("unroll") for (int _i = 0; _i < 2; ++_i) \
;         __builtin_amdgcn_global_load_lds((const unsigned*)((const char*)(gbase) + (voff)[_i]), (PG8_LAS unsigned*)(lds + (bufoff) + ldsw + _i * 8192), 16, 0, 0); } while (0)
; #define PG8_LDA(dst, b, h) do { _Pragma("unroll") for (int m = 0; m < 4; ++m) _Pragma("unroll") for (int k = 0; k < 2; ++k) dst[m][k] = *(const PG8_LAS bf16x8*)(lds + PG8_SA(b, h) + aoff + m * 2048 + k * 1024); } while (0)
; #define PG8_LDB(dst, b, h) do { _Pragma("unroll") for (int n = 0; n < 2; ++n) _Pragma("unroll") for (int k = 0; k < 2; ++k) dst[n][k] = *(const PG8_LAS bf16x8*)(lds + PG8_SB(b, h) + boff + n * 2048 + k * 1024); } while (0)
; #define PG8_MMA(ai, bj, At, Bt) do { __builtin_amdgcn_s_setprio(1); _Pragma("unroll") for (int m = 0; m < 4; ++m) _Pragma("unroll") for (int n = 0; n < 2; ++n) _Pragma("unroll") for (int k = 0; k < 2; ++k) \
;         acc[ai][bj][m][n] = __builtin_amdgcn_mfma_f32_16x16x32_bf16(Bt[n][k], At[m][k], acc[ai][bj][m][n], 0, 0, 0); __builtin_amdgcn_s_setprio(0); } while (0)
; #define PG8_WAIT_V(n) asm volatile("s_waitcnt vmcnt(" #n ")" ::: "memory")
; #define PG8_WAIT_L(n) asm volatile("s_waitcnt lgkmcnt(" #n ")" ::: "memory")
; #define PG8_BAR __builtin_amdgcn_s_barrier()
; #define PG8_SCHED __builtin_amdgcn_sched_barrier(0)
; template <class Epi, class Sched, bool ALIGN_EPI = false, bool SP2 = false>
; __device__ __forceinline__ void gemm_phase(PG8_LAS unsigned char* lds, const Gemm g, const Sched& S, const Epi& E) {
;     ...
;             PG8_LDB(B0, 0, 0); PG8_LDB(B1, 0, 1); PG8_SCHED; PG8_LDA(At, 0, 0); PG8_STAGE(PG8_SA(1, 1), a1 + hstep, voffA);
;             PG8_WAIT_V(8); PG8_WAIT_L(0); PG8_BAR; PG8_MMA(0, 0, At, B0); PG8_MMA(0, 1, At, B1); PG8_BAR; PG8_SCHED;
;             PG8_LDA(At, 0, 1); PG8_STAGE(PG8_SB(0, 0), b2, voffB); PG8_STAGE(PG8_SB(0, 1), b2 + hstep, voffB); PG8_STAGE(PG8_SA(0, 0), a2, voffA);
;             PG8_WAIT_V(8); PG8_WAIT_L(0); PG8_BAR; PG8_MMA(1, 0, At, B0); PG8_MMA(1, 1, At, B1); PG8_BAR; PG8_SCHED;
;     ...
;             PG8_LDA(At, 1, 1); PG8_STAGE(PG8_SB(1, 0), b3, voffB); PG8_STAGE(PG8_SB(1, 1), b3 + hstep, voffB); PG8_STAGE(PG8_SA(1, 0), a3, voffA);
;             PG8_WAIT_V(8); PG8_WAIT_L(0); PG8_BAR; PG8_MMA(1, 0, At, B0); PG8_MMA(1, 1, At, B1); PG8_BAR; PG8_SCHED;
	s_add_i32 s54, s85, s63
	s_mov_b32 m0, s54
	ds_read_b128 v[188:191], v167 offset:49152
	ds_read_b128 v[192:195], v167 offset:50176
	ds_read_b128 v[198:201], v167 offset:51200
	ds_read_b128 v[202:205], v167 offset:52224
	ds_read_b128 v[206:209], v167 offset:53248
	ds_read_b128 v[210:213], v167 offset:54272
	ds_read_b128 v[214:217], v167 offset:55296
	ds_read_b128 v[218:221], v167 offset:56320
	global_load_lds_dwordx4 v132, s[98:99]
	s_add_i32 m0, s54, 0x2000
	s_add_u32 s52, s52, 0x40080
	s_addc_u32 s53, s53, 0
	s_add_i32 s54, s86, s63
	global_load_lds_dwordx4 v128, s[98:99]
	s_mov_b32 m0, s54
	s_nop 0
	global_load_lds_dwordx4 v132, s[52:53]
	s_add_i32 m0, s54, 0x2000
	s_nop 0
	global_load_lds_dwordx4 v128, s[52:53]
	s_mov_b32 m0, s69
	s_nop 0
	global_load_lds_dwordx4 v134, s[100:101]
	s_mov_b32 m0, s70
	s_nop 0
	global_load_lds_dwordx4 v130, s[100:101]
	s_waitcnt vmcnt(8)
	s_waitcnt lgkmcnt(0)
	s_barrier
	v_mfma_f32_16x16x32_bf16 v[60:63], v[146:149], v[188:191], v[60:63]
	v_mfma_f32_16x16x32_bf16 v[56:59], v[154:157], v[188:191], v[56:59]
	v_mfma_f32_16x16x32_bf16 v[40:43], v[154:157], v[198:201], v[40:43]
	v_mfma_f32_16x16x32_bf16 v[44:47], v[146:149], v[198:201], v[44:47]
	v_mfma_f32_16x16x32_bf16 v[28:31], v[146:149], v[206:209], v[28:31]
	v_mfma_f32_16x16x32_bf16 v[24:27], v[154:157], v[206:209], v[24:27]
	v_mfma_f32_16x16x32_bf16 v[8:11], v[154:157], v[214:217], v[8:11]
	v_mfma_f32_16x16x32_bf16 v[12:15], v[146:149], v[214:217], v[12:15]
	v_mfma_f32_16x16x32_bf16 v[60:63], v[150:153], v[192:195], v[60:63]
	v_mfma_f32_16x16x32_bf16 v[56:59], v[168:171], v[192:195], v[56:59]
	v_mfma_f32_16x16x32_bf16 v[40:43], v[168:171], v[202:205], v[40:43]
	v_mfma_f32_16x16x32_bf16 v[44:47], v[150:153], v[202:205], v[44:47]
	v_mfma_f32_16x16x32_bf16 v[28:31], v[150:153], v[210:213], v[28:31]
	v_mfma_f32_16x16x32_bf16 v[24:27], v[168:171], v[210:213], v[24:27]
	v_mfma_f32_16x16x32_bf16 v[8:11], v[168:171], v[218:221], v[8:11]
	v_mfma_f32_16x16x32_bf16 v[12:15], v[150:153], v[218:221], v[12:15]
	v_mfma_f32_16x16x32_bf16 v[52:55], v[172:175], v[188:191], v[52:55]
	v_mfma_f32_16x16x32_bf16 v[48:51], v[180:183], v[188:191], v[48:51]
	v_mfma_f32_16x16x32_bf16 v[32:35], v[180:183], v[198:201], v[32:35]
	v_mfma_f32_16x16x32_bf16 v[36:39], v[172:175], v[198:201], v[36:39]
	v_mfma_f32_16x16x32_bf16 v[20:23], v[172:175], v[206:209], v[20:23]
	v_mfma_f32_16x16x32_bf16 v[16:19], v[180:183], v[206:209], v[16:19]
	v_mfma_f32_16x16x32_bf16 v[0:3], v[180:183], v[214:217], v[0:3]
	v_mfma_f32_16x16x32_bf16 v[4:7], v[172:175], v[214:217], v[4:7]
	v_mfma_f32_16x16x32_bf16 v[52:55], v[176:179], v[192:195], v[52:55]
	v_mfma_f32_16x16x32_bf16 v[48:51], v[184:187], v[192:195], v[48:51]
	v_mfma_f32_16x16x32_bf16 v[32:35], v[184:187], v[202:205], v[32:35]
	v_mfma_f32_16x16x32_bf16 v[36:39], v[176:179], v[202:205], v[36:39]
	v_mfma_f32_16x16x32_bf16 v[20:23], v[176:179], v[210:213], v[20:23]
	v_mfma_f32_16x16x32_bf16 v[16:19], v[184:187], v[210:213], v[16:19]
	v_mfma_f32_16x16x32_bf16 v[0:3], v[184:187], v[218:221], v[0:3]
	v_mfma_f32_16x16x32_bf16 v[4:7], v[176:179], v[218:221], v[4:7]
	s_barrier
	s_add_i32 s84, s84, 2
	s_add_u32 s20, s20, 0x100
	s_addc_u32 s21, s21, 0
	s_add_u32 s80, s80, 0x100
	s_addc_u32 s81, s81, 0
	s_cmp_gt_u32 s84, 13
.LBB0_414:
	ds_read_b128 v[146:149], v165
	ds_read_b128 v[150:153], v165 offset:1024
	ds_read_b128 v[154:157], v165 offset:2048
	ds_read_b128 v[168:171], v165 offset:3072
	ds_read_b128 v[172:175], v166
	ds_read_b128 v[176:179], v166 offset:1024
	ds_read_b128 v[180:183], v166 offset:2048
	ds_read_b128 v[184:187], v166 offset:3072
	s_add_u32 s52, s20, 0xfffc0080
	s_addc_u32 s53, s21, -1
	s_cmp_eq_u32 s84, 12
	s_cselect_b32 s55, s43, s53
	s_cselect_b32 s54, s78, s52
	s_cselect_b32 s53, s19, s81
	s_cselect_b32 s52, s79, s80
	s_add_i32 m0, s35, 0xc000
	ds_read_b128 v[188:191], v167
	ds_read_b128 v[192:195], v167 offset:1024
	ds_read_b128 v[198:201], v167 offset:2048
	ds_read_b128 v[202:205], v167 offset:3072
	ds_read_b128 v[206:209], v167 offset:4096
	ds_read_b128 v[210:213], v167 offset:5120
	ds_read_b128 v[214:217], v167 offset:6144
	ds_read_b128 v[218:221], v167 offset:7168
	global_load_lds_dwordx4 v138, s[20:21]
	s_add_i32 m0, s35, 0xe000
	s_nop 0
	global_load_lds_dwordx4 v140, s[20:21]
	s_waitcnt vmcnt(8)
	s_waitcnt lgkmcnt(0)
	s_barrier
	v_mfma_f32_16x16x32_bf16 v[124:127], v[146:149], v[188:191], v[124:127]
	v_mfma_f32_16x16x32_bf16 v[120:123], v[154:157], v[188:191], v[120:123]
	v_mfma_f32_16x16x32_bf16 v[104:107], v[154:157], v[198:201], v[104:107]
	v_mfma_f32_16x16x32_bf16 v[108:111], v[146:149], v[198:201], v[108:111]
	v_mfma_f32_16x16x32_bf16 v[92:95], v[146:149], v[206:209], v[92:95]
	v_mfma_f32_16x16x32_bf16 v[88:91], v[154:157], v[206:209], v[88:91]
	v_mfma_f32_16x16x32_bf16 v[72:75], v[154:157], v[214:217], v[72:75]
	v_mfma_f32_16x16x32_bf16 v[76:79], v[146:149], v[214:217], v[76:79]
	v_mfma_f32_16x16x32_bf16 v[124:127], v[150:153], v[192:195], v[124:127]
	v_mfma_f32_16x16x32_bf16 v[120:123], v[168:171], v[192:195], v[120:123]
	v_mfma_f32_16x16x32_bf16 v[104:107], v[168:171], v[202:205], v[104:107]
	v_mfma_f32_16x16x32_bf16 v[108:111], v[150:153], v[202:205], v[108:111]
	v_mfma_f32_16x16x32_bf16 v[92:95], v[150:153], v[210:213], v[92:95]
	v_mfma_f32_16x16x32_bf16 v[88:91], v[168:171], v[210:213], v[88:91]
	v_mfma_f32_16x16x32_bf16 v[72:75], v[168:171], v[218:221], v[72:75]
	v_mfma_f32_16x16x32_bf16 v[76:79], v[150:153], v[218:221], v[76:79]
	v_mfma_f32_16x16x32_bf16 v[116:119], v[172:175], v[188:191], v[116:119]
	v_mfma_f32_16x16x32_bf16 v[112:115], v[180:183], v[188:191], v[112:115]
	v_mfma_f32_16x16x32_bf16 v[96:99], v[180:183], v[198:201], v[96:99]
	v_mfma_f32_16x16x32_bf16 v[100:103], v[172:175], v[198:201], v[100:103]
	v_mfma_f32_16x16x32_bf16 v[84:87], v[172:175], v[206:209], v[84:87]
	v_mfma_f32_16x16x32_bf16 v[80:83], v[180:183], v[206:209], v[80:83]
	v_mfma_f32_16x16x32_bf16 v[64:67], v[180:183], v[214:217], v[64:67]
	v_mfma_f32_16x16x32_bf16 v[68:71], v[172:175], v[214:217], v[68:71]
	v_mfma_f32_16x16x32_bf16 v[116:119], v[176:179], v[192:195], v[116:119]
	v_mfma_f32_16x16x32_bf16 v[112:115], v[184:187], v[192:195], v[112:115]
	v_mfma_f32_16x16x32_bf16 v[96:99], v[184:187], v[202:205], v[96:99]
	v_mfma_f32_16x16x32_bf16 v[100:103], v[176:179], v[202:205], v[100:103]
	v_mfma_f32_16x16x32_bf16 v[84:87], v[176:179], v[210:213], v[84:87]
	v_mfma_f32_16x16x32_bf16 v[80:83], v[184:187], v[210:213], v[80:83]
	v_mfma_f32_16x16x32_bf16 v[64:67], v[184:187], v[218:221], v[64:67]
	v_mfma_f32_16x16x32_bf16 v[68:71], v[176:179], v[218:221], v[68:71]
	s_barrier
; #define PG8_STAGE(bufoff, gbase, voff) do { _Pragma("unroll") for (int _i = 0; _i < 2; ++_i) \
;         __builtin_amdgcn_global_load_lds((const unsigned*)((const char*)(gbase) + (voff)[_i]), (PG8_LAS unsigned*)(lds + (bufoff) + ldsw + _i * 8192), 16, 0, 0); } while (0)
; #define PG8_LDA(dst, b, h) do { _Pragma("unroll") for (int m = 0; m < 4; ++m) _Pragma("unroll") for (int k = 0; k < 2; ++k) dst[m][k] = *(const PG8_LAS bf16x8*)(lds + PG8_SA(b, h) + aoff + m * 2048 + k * 1024); } while (0)
; #define PG8_LDB(dst, b, h) do { _Pragma("unroll") for (int n = 0; n < 2; ++n) _Pragma("unroll") for (int k = 0; k < 2; ++k) dst[n][k] = *(const PG8_LAS bf16x8*)(lds + PG8_SB(b, h) + boff + n * 2048 + k * 1024); } while (0)
; #define PG8_MMA(ai, bj, At, Bt) do { __builtin_amdgcn_s_setprio(1); _Pragma("unroll") for (int m = 0; m < 4; ++m) _Pragma("unroll") for (int n = 0; n < 2; ++n) _Pragma("unroll") for (int k = 0; k < 2; ++k) \
;         acc[ai][bj][m][n] = __builtin_amdgcn_mfma_f32_16x16x32_bf16(Bt[n][k], At[m][k], acc[ai][bj][m][n], 0, 0, 0); __builtin_amdgcn_s_setprio(0); } while (0)
; #define PG8_WAIT_V(n) asm volatile("s_waitcnt vmcnt(" #n ")" ::: "memory")
; #define PG8_WAIT_L(n) asm volatile("s_waitcnt lgkmcnt(" #n ")" ::: "memory")
; #define PG8_BAR __builtin_amdgcn_s_barrier()
; #define PG8_SCHED __builtin_amdgcn_sched_barrier(0)
; template <class Epi, class Sched, bool ALIGN_EPI = false, bool SP2 = false>
; __device__ __forceinline__ void gemm_phase(PG8_LAS unsigned char* lds, const Gemm g, const Sched& S, const Epi& E) {
;     ...
;             PG8_LDA(At, 0, 1); PG8_STAGE(PG8_SB(0, 0), b2, voffB); PG8_STAGE(PG8_SB(0, 1), b2 + hstep, voffB); PG8_STAGE(PG8_SA(0, 0), a2, voffA);
;             PG8_WAIT_V(8); PG8_WAIT_L(0); PG8_BAR; PG8_MMA(1, 0, At, B0); PG8_MMA(1, 1, At, B1); PG8_BAR; PG8_SCHED;
;             PG8_LDB(B0, 1, 0); PG8_LDB(B1, 1, 1); PG8_SCHED; PG8_LDA(At, 1, 0); PG8_STAGE(PG8_SA(0, 1), a2 + hstep, voffA);
;             PG8_WAIT_V(8); PG8_WAIT_L(0); PG8_BAR; PG8_MMA(0, 0, At, B0); PG8_MMA(0, 1, At, B1); PG8_BAR; PG8_SCHED;
	s_add_i32 s85, s72, s63
	s_add_u32 s98, s52, s8
	s_addc_u32 s99, s53, s9
	s_add_u32 s100, s54, s8
	s_addc_u32 s101, s55, s9
	s_mov_b32 m0, s85
	ds_read_b128 v[188:191], v167 offset:16384
	ds_read_b128 v[192:195], v167 offset:17408
	ds_read_b128 v[198:201], v167 offset:18432
	ds_read_b128 v[202:205], v167 offset:19456
	ds_read_b128 v[206:209], v167 offset:20480
	ds_read_b128 v[210:213], v167 offset:21504
	ds_read_b128 v[214:217], v167 offset:22528
	ds_read_b128 v[218:221], v167 offset:23552
	global_load_lds_dwordx4 v132, s[52:53]
	s_add_i32 m0, s85, 0x2000
	s_add_u32 s86, s52, 0x40000
	s_addc_u32 s87, s53, 0
	s_add_i32 s85, s73, s63
	global_load_lds_dwordx4 v128, s[52:53]
	s_mov_b32 m0, s85
	s_nop 0
	global_load_lds_dwordx4 v132, s[86:87]
	s_add_i32 m0, s85, 0x2000
	s_nop 0
	global_load_lds_dwordx4 v128, s[86:87]
	s_mov_b32 m0, s35
	s_nop 0
	global_load_lds_dwordx4 v134, s[54:55]
	s_mov_b32 m0, s65
	s_nop 0
	global_load_lds_dwordx4 v130, s[54:55]
	s_waitcnt vmcnt(8)
	s_waitcnt lgkmcnt(0)
	s_barrier
	v_mfma_f32_16x16x32_bf16 v[60:63], v[146:149], v[188:191], v[60:63]
	v_mfma_f32_16x16x32_bf16 v[56:59], v[154:157], v[188:191], v[56:59]
	v_mfma_f32_16x16x32_bf16 v[40:43], v[154:157], v[198:201], v[40:43]
	v_mfma_f32_16x16x32_bf16 v[44:47], v[146:149], v[198:201], v[44:47]
	v_mfma_f32_16x16x32_bf16 v[28:31], v[146:149], v[206:209], v[28:31]
	v_mfma_f32_16x16x32_bf16 v[24:27], v[154:157], v[206:209], v[24:27]
	v_mfma_f32_16x16x32_bf16 v[8:11], v[154:157], v[214:217], v[8:11]
	v_mfma_f32_16x16x32_bf16 v[12:15], v[146:149], v[214:217], v[12:15]
	v_mfma_f32_16x16x32_bf16 v[60:63], v[150:153], v[192:195], v[60:63]
	v_mfma_f32_16x16x32_bf16 v[56:59], v[168:171], v[192:195], v[56:59]
	v_mfma_f32_16x16x32_bf16 v[40:43], v[168:171], v[202:205], v[40:43]
	v_mfma_f32_16x16x32_bf16 v[44:47], v[150:153], v[202:205], v[44:47]
	v_mfma_f32_16x16x32_bf16 v[28:31], v[150:153], v[210:213], v[28:31]
	v_mfma_f32_16x16x32_bf16 v[24:27], v[168:171], v[210:213], v[24:27]
	v_mfma_f32_16x16x32_bf16 v[8:11], v[168:171], v[218:221], v[8:11]
	v_mfma_f32_16x16x32_bf16 v[12:15], v[150:153], v[218:221], v[12:15]
	v_mfma_f32_16x16x32_bf16 v[52:55], v[172:175], v[188:191], v[52:55]
	v_mfma_f32_16x16x32_bf16 v[48:51], v[180:183], v[188:191], v[48:51]
	v_mfma_f32_16x16x32_bf16 v[32:35], v[180:183], v[198:201], v[32:35]
	v_mfma_f32_16x16x32_bf16 v[36:39], v[172:175], v[198:201], v[36:39]
	v_mfma_f32_16x16x32_bf16 v[20:23], v[172:175], v[206:209], v[20:23]
	v_mfma_f32_16x16x32_bf16 v[16:19], v[180:183], v[206:209], v[16:19]
	v_mfma_f32_16x16x32_bf16 v[0:3], v[180:183], v[214:217], v[0:3]
	v_mfma_f32_16x16x32_bf16 v[4:7], v[172:175], v[214:217], v[4:7]
	v_mfma_f32_16x16x32_bf16 v[52:55], v[176:179], v[192:195], v[52:55]
	v_mfma_f32_16x16x32_bf16 v[48:51], v[184:187], v[192:195], v[48:51]
	v_mfma_f32_16x16x32_bf16 v[32:35], v[184:187], v[202:205], v[32:35]
	v_mfma_f32_16x16x32_bf16 v[36:39], v[176:179], v[202:205], v[36:39]
	v_mfma_f32_16x16x32_bf16 v[20:23], v[176:179], v[210:213], v[20:23]
	v_mfma_f32_16x16x32_bf16 v[16:19], v[184:187], v[210:213], v[16:19]
	v_mfma_f32_16x16x32_bf16 v[0:3], v[184:187], v[218:221], v[0:3]
	v_mfma_f32_16x16x32_bf16 v[4:7], v[176:179], v[218:221], v[4:7]
	s_barrier
	s_add_i32 s85, 0, 0x18000
	v_add_u32_e32 v136, s85, v161
	s_add_i32 s86, 0, 0x1c000
	ds_read_b128 v[146:149], v136
	ds_read_b128 v[150:153], v136 offset:1024
	ds_read_b128 v[154:157], v136 offset:2048
	ds_read_b128 v[168:171], v136 offset:3072
	v_add_u32_e32 v136, s86, v161
	ds_read_b128 v[172:175], v136
	ds_read_b128 v[176:179], v136 offset:1024
	ds_read_b128 v[180:183], v136 offset:2048
	ds_read_b128 v[184:187], v136 offset:3072
	s_add_u32 s54, s54, 0x40000
	s_addc_u32 s55, s55, 0
	s_mov_b32 m0, s66
	ds_read_b128 v[188:191], v167 offset:32768
	ds_read_b128 v[192:195], v167 offset:33792
	ds_read_b128 v[198:201], v167 offset:34816
	ds_read_b128 v[202:205], v167 offset:35840
	ds_read_b128 v[206:209], v167 offset:36864
	ds_read_b128 v[210:213], v167 offset:37888
	ds_read_b128 v[214:217], v167 offset:38912
	ds_read_b128 v[218:221], v167 offset:39936
	global_load_lds_dwordx4 v134, s[54:55]
	s_mov_b32 m0, s67
	s_nop 0
	global_load_lds_dwordx4 v130, s[54:55]
	s_waitcnt vmcnt(8)
	s_waitcnt lgkmcnt(0)
	s_barrier
; #define PG8_STAGE(bufoff, gbase, voff) do { _Pragma("unroll") for (int _i = 0; _i < 2; ++_i) \
;         __builtin_amdgcn_global_load_lds((const unsigned*)((const char*)(gbase) + (voff)[_i]), (PG8_LAS unsigned*)(lds + (bufoff) + ldsw + _i * 8192), 16, 0, 0); } while (0)
; #define PG8_LDA(dst, b, h) do { _Pragma("unroll") for (int m = 0; m < 4; ++m) _Pragma("unroll") for (int k = 0; k < 2; ++k) dst[m][k] = *(const PG8_LAS bf16x8*)(lds + PG8_SA(b, h) + aoff + m * 2048 + k * 1024); } while (0)
; #define PG8_LDB(dst, b, h) do { _Pragma("unroll") for (int n = 0; n < 2; ++n) _Pragma("unroll") for (int k = 0; k < 2; ++k) dst[n][k] = *(const PG8_LAS bf16x8*)(lds + PG8_SB(b, h) + boff + n * 2048 + k * 1024); } while (0)
; #define PG8_MMA(ai, bj, At, Bt) do { __builtin_amdgcn_s_setprio(1); _Pragma("unroll") for (int m = 0; m < 4; ++m) _Pragma("unroll") for (int n = 0; n < 2; ++n) _Pragma("unroll") for (int k = 0; k < 2; ++k) \
;         acc[ai][bj][m][n] = __builtin_amdgcn_mfma_f32_16x16x32_bf16(Bt[n][k], At[m][k], acc[ai][bj][m][n], 0, 0, 0); __builtin_amdgcn_s_setprio(0); } while (0)
; #define PG8_WAIT_V(n) asm volatile("s_waitcnt vmcnt(" #n ")" ::: "memory")
; #define PG8_WAIT_L(n) asm volatile("s_waitcnt lgkmcnt(" #n ")" ::: "memory")
; #define PG8_BAR __builtin_amdgcn_s_barrier()
; #define PG8_SCHED __builtin_amdgcn_sched_barrier(0)
; template <class Epi, class Sched, bool ALIGN_EPI = false, bool SP2 = false>
; __device__ __forceinline__ void gemm_phase(PG8_LAS unsigned char* lds, const Gemm g, const Sched& S, const Epi& E) {
;     ...
;             PG8_LDB(B0, 1, 0); PG8_LDB(B1, 1, 1); PG8_SCHED; PG8_LDA(At, 1, 0); PG8_STAGE(PG8_SA(0, 1), a2 + hstep, voffA);
;             PG8_WAIT_V(8); PG8_WAIT_L(0); PG8_BAR; PG8_MMA(0, 0, At, B0); PG8_MMA(0, 1, At, B1); PG8_BAR; PG8_SCHED;
;             PG8_LDA(At, 1, 1); PG8_STAGE(PG8_SB(1, 0), b3, voffB); PG8_STAGE(PG8_SB(1, 1), b3 + hstep, voffB); PG8_STAGE(PG8_SA(1, 0), a3, voffA);
;             PG8_WAIT_V(8); PG8_WAIT_L(0); PG8_BAR; PG8_MMA(1, 0, At, B0); PG8_MMA(1, 1, At, B1); PG8_BAR; PG8_SCHED;
	v_mfma_f32_16x16x32_bf16 v[124:127], v[146:149], v[188:191], v[124:127]
	v_mfma_f32_16x16x32_bf16 v[120:123], v[154:157], v[188:191], v[120:123]
	v_mfma_f32_16x16x32_bf16 v[104:107], v[154:157], v[198:201], v[104:107]
	v_mfma_f32_16x16x32_bf16 v[108:111], v[146:149], v[198:201], v[108:111]
	v_mfma_f32_16x16x32_bf16 v[92:95], v[146:149], v[206:209], v[92:95]
	v_mfma_f32_16x16x32_bf16 v[88:91], v[154:157], v[206:209], v[88:91]
	v_mfma_f32_16x16x32_bf16 v[72:75], v[154:157], v[214:217], v[72:75]
	v_mfma_f32_16x16x32_bf16 v[76:79], v[146:149], v[214:217], v[76:79]
	v_mfma_f32_16x16x32_bf16 v[124:127], v[150:153], v[192:195], v[124:127]
	v_mfma_f32_16x16x32_bf16 v[120:123], v[168:171], v[192:195], v[120:123]
	v_mfma_f32_16x16x32_bf16 v[104:107], v[168:171], v[202:205], v[104:107]
	v_mfma_f32_16x16x32_bf16 v[108:111], v[150:153], v[202:205], v[108:111]
	v_mfma_f32_16x16x32_bf16 v[92:95], v[150:153], v[210:213], v[92:95]
	v_mfma_f32_16x16x32_bf16 v[88:91], v[168:171], v[210:213], v[88:91]
	v_mfma_f32_16x16x32_bf16 v[72:75], v[168:171], v[218:221], v[72:75]
	v_mfma_f32_16x16x32_bf16 v[76:79], v[150:153], v[218:221], v[76:79]
	v_mfma_f32_16x16x32_bf16 v[116:119], v[172:175], v[188:191], v[116:119]
	v_mfma_f32_16x16x32_bf16 v[112:115], v[180:183], v[188:191], v[112:115]
	v_mfma_f32_16x16x32_bf16 v[96:99], v[180:183], v[198:201], v[96:99]
	v_mfma_f32_16x16x32_bf16 v[100:103], v[172:175], v[198:201], v[100:103]
	v_mfma_f32_16x16x32_bf16 v[84:87], v[172:175], v[206:209], v[84:87]
	v_mfma_f32_16x16x32_bf16 v[80:83], v[180:183], v[206:209], v[80:83]
	v_mfma_f32_16x16x32_bf16 v[64:67], v[180:183], v[214:217], v[64:67]
	v_mfma_f32_16x16x32_bf16 v[68:71], v[172:175], v[214:217], v[68:71]
	v_mfma_f32_16x16x32_bf16 v[116:119], v[176:179], v[192:195], v[116:119]
	v_mfma_f32_16x16x32_bf16 v[112:115], v[184:187], v[192:195], v[112:115]
	v_mfma_f32_16x16x32_bf16 v[96:99], v[184:187], v[202:205], v[96:99]
	v_mfma_f32_16x16x32_bf16 v[100:103], v[176:179], v[202:205], v[100:103]
	v_mfma_f32_16x16x32_bf16 v[84:87], v[176:179], v[210:213], v[84:87]
	v_mfma_f32_16x16x32_bf16 v[80:83], v[184:187], v[210:213], v[80:83]
	v_mfma_f32_16x16x32_bf16 v[64:67], v[184:187], v[218:221], v[64:67]
	v_mfma_f32_16x16x32_bf16 v[68:71], v[176:179], v[218:221], v[68:71]
	s_barrier
	s_add_i32 s54, s85, s63
	s_mov_b32 m0, s54
	ds_read_b128 v[188:191], v167 offset:49152
	ds_read_b128 v[192:195], v167 offset:50176
	ds_read_b128 v[198:201], v167 offset:51200
	ds_read_b128 v[202:205], v167 offset:52224
	ds_read_b128 v[206:209], v167 offset:53248
	ds_read_b128 v[210:213], v167 offset:54272
	ds_read_b128 v[214:217], v167 offset:55296
	ds_read_b128 v[218:221], v167 offset:56320
	global_load_lds_dwordx4 v132, s[98:99]
	s_add_i32 m0, s54, 0x2000
	s_add_u32 s52, s52, 0x40080
	s_addc_u32 s53, s53, 0
	s_add_i32 s54, s86, s63
	global_load_lds_dwordx4 v128, s[98:99]
	s_mov_b32 m0, s54
	s_nop 0
	global_load_lds_dwordx4 v132, s[52:53]
	s_add_i32 m0, s54, 0x2000
	s_nop 0
	global_load_lds_dwordx4 v128, s[52:53]
	s_mov_b32 m0, s69
	s_nop 0
	global_load_lds_dwordx4 v134, s[100:101]
	s_mov_b32 m0, s70
	s_nop 0
	global_load_lds_dwordx4 v130, s[100:101]
	s_waitcnt vmcnt(8)
	s_waitcnt lgkmcnt(0)
	s_barrier
	v_mfma_f32_16x16x32_bf16 v[60:63], v[146:149], v[188:191], v[60:63]
	v_mfma_f32_16x16x32_bf16 v[56:59], v[154:157], v[188:191], v[56:59]
	v_mfma_f32_16x16x32_bf16 v[40:43], v[154:157], v[198:201], v[40:43]
	v_mfma_f32_16x16x32_bf16 v[44:47], v[146:149], v[198:201], v[44:47]
	v_mfma_f32_16x16x32_bf16 v[28:31], v[146:149], v[206:209], v[28:31]
	v_mfma_f32_16x16x32_bf16 v[24:27], v[154:157], v[206:209], v[24:27]
	v_mfma_f32_16x16x32_bf16 v[8:11], v[154:157], v[214:217], v[8:11]
	v_mfma_f32_16x16x32_bf16 v[12:15], v[146:149], v[214:217], v[12:15]
	v_mfma_f32_16x16x32_bf16 v[60:63], v[150:153], v[192:195], v[60:63]
	v_mfma_f32_16x16x32_bf16 v[56:59], v[168:171], v[192:195], v[56:59]
	v_mfma_f32_16x16x32_bf16 v[40:43], v[168:171], v[202:205], v[40:43]
	v_mfma_f32_16x16x32_bf16 v[44:47], v[150:153], v[202:205], v[44:47]
	v_mfma_f32_16x16x32_bf16 v[28:31], v[150:153], v[210:213], v[28:31]
	v_mfma_f32_16x16x32_bf16 v[24:27], v[168:171], v[210:213], v[24:27]
	v_mfma_f32_16x16x32_bf16 v[8:11], v[168:171], v[218:221], v[8:11]
	v_mfma_f32_16x16x32_bf16 v[12:15], v[150:153], v[218:221], v[12:15]
	v_mfma_f32_16x16x32_bf16 v[52:55], v[172:175], v[188:191], v[52:55]
	v_mfma_f32_16x16x32_bf16 v[48:51], v[180:183], v[188:191], v[48:51]
	v_mfma_f32_16x16x32_bf16 v[32:35], v[180:183], v[198:201], v[32:35]
	v_mfma_f32_16x16x32_bf16 v[36:39], v[172:175], v[198:201], v[36:39]
	v_mfma_f32_16x16x32_bf16 v[20:23], v[172:175], v[206:209], v[20:23]
	v_mfma_f32_16x16x32_bf16 v[16:19], v[180:183], v[206:209], v[16:19]
	v_mfma_f32_16x16x32_bf16 v[0:3], v[180:183], v[214:217], v[0:3]
	v_mfma_f32_16x16x32_bf16 v[4:7], v[172:175], v[214:217], v[4:7]
	v_mfma_f32_16x16x32_bf16 v[52:55], v[176:179], v[192:195], v[52:55]
	v_mfma_f32_16x16x32_bf16 v[48:51], v[184:187], v[192:195], v[48:51]
	v_mfma_f32_16x16x32_bf16 v[32:35], v[184:187], v[202:205], v[32:35]
	v_mfma_f32_16x16x32_bf16 v[36:39], v[176:179], v[202:205], v[36:39]
	v_mfma_f32_16x16x32_bf16 v[20:23], v[176:179], v[210:213], v[20:23]
	v_mfma_f32_16x16x32_bf16 v[16:19], v[184:187], v[210:213], v[16:19]
	v_mfma_f32_16x16x32_bf16 v[0:3], v[184:187], v[218:221], v[0:3]
	v_mfma_f32_16x16x32_bf16 v[4:7], v[176:179], v[218:221], v[4:7]
	s_barrier
	s_add_i32 s84, s84, 2
	s_add_u32 s20, s20, 0x100
	s_addc_u32 s21, s21, 0
	s_add_u32 s80, s80, 0x100
	s_addc_u32 s81, s81, 0
	s_cmp_gt_u32 s84, 13
	s_cbranch_scc0 .LBB0_414
	v_readlane_b32 s101, v249, 49
	s_nop 3
	s_cmp_eq_u32 s101, 0
	s_cbranch_scc1 .Ldw_done_0
	s_add_u32 s98, s28, 0x183500
	s_addc_u32 s99, s29, 0
	v_mov_b32_e32 v251, 0
	s_mov_b32 s100, 0

; #define PG8_STAGE(bufoff, gbase, voff) do { _Pragma("unroll") for (int _i = 0; _i < 2; ++_i) \
;         __builtin_amdgcn_global_load_lds((const unsigned*)((const char*)(gbase) + (voff)[_i]), (PG8_LAS unsigned*)(lds + (bufoff) + ldsw + _i * 8192), 16, 0, 0); } while (0)
; #define PG8_LDA(dst, b, h) do { _Pragma("unroll") for (int m = 0; m < 4; ++m) _Pragma("unroll") for (int k = 0; k < 2; ++k) dst[m][k] = *(const PG8_LAS bf16x8*)(lds + PG8_SA(b, h) + aoff + m * 2048 + k * 1024); } while (0)
; template <class Epi, class Sched, bool ALIGN_EPI = false, bool SP2 = false>
; __device__ __forceinline__ void gemm_phase(PG8_LAS unsigned char* lds, const Gemm g, const Sched& S, const Epi& E) {
;     ...
;         const bool has_next = S.next(ui + 1, nxt);
;         const char* nA = has_next ? (const char*)g.A + (size_t)nxt.pm * tstep : cA; const char* nB = has_next ? (const char*)g.Bt + (size_t)nxt.pn * tstep : cB;
;         for (int t = 0; t < nt; t += 2) {
;             const bool last = (t == nt - 2);
;             const char* a1 = cA + (size_t)(t + 1) * kstep;
;             const char* a2 = last ? nA : cA + (size_t)(t + 2) * kstep; const char* b2 = last ? nB : cB + (size_t)(t + 2) * kstep;
;             const char* a3 = a2 + kstep; const char* b3 = b2 + kstep;
;             if (last && has_next) S.a_ready(nxt);
;             if constexpr (SP2) {
;             PG8_LDB(B0, 0, 0); PG8_LDB(B1, 0, 1); PG8_SCHED; PG8_LDA(At, 0, 0); PG8_STAGE(PG8_SA(1, 1), a1 + hstep, voffA);
;             PG8_WAIT_V(8); PG8_WAIT_L(0); PG8_BAR; PG8_MMA(0, 0, At, B0); PG8_MMA(0, 1, At, B1); PG8_BAR; PG8_SCHED;
;             PG8_LDA(At, 0, 1); PG8_STAGE(PG8_SB(0, 0), b2, voffB); PG8_STAGE(PG8_SB(0, 1), b2 + hstep, voffB); PG8_STAGE(PG8_SA(0, 0), a2, voffA);
;             PG8_WAIT_V(8); PG8_WAIT_L(0); PG8_BAR; PG8_MMA(1, 0, At, B0); PG8_MMA(1, 1, At, B1); PG8_BAR; PG8_SCHED;
;             PG8_LDB(B0, 1, 0); PG8_LDB(B1, 1, 1); PG8_SCHED; PG8_LDA(At, 1, 0); PG8_STAGE(PG8_SA(0, 1), a2 + hstep, voffA);
;             PG8_WAIT_V(8); PG8_WAIT_L(0); PG8_BAR; PG8_MMA(0, 0, At, B0); PG8_MMA(0, 1, At, B1); PG8_BAR; PG8_SCHED;
;             PG8_LDA(At, 1, 1); PG8_STAGE(PG8_SB(1, 0), b3, voffB); PG8_STAGE(PG8_SB(1, 1), b3 + hstep, voffB); PG8_STAGE(PG8_SA(1, 0), a3, voffA);
;             PG8_WAIT_V(8); PG8_WAIT_L(0); PG8_BAR; PG8_MMA(1, 0, At, B0); PG8_MMA(1, 1, At, B1); PG8_BAR; PG8_SCHED;
.LBB0_623:
	s_ashr_i32 s17, s16, 31
	s_lshl_b64 s[18:19], s[16:17], 18
	s_add_u32 s18, s0, s18
	s_addc_u32 s19, s1, s19
	s_and_b64 s[38:39], s[4:5], exec
	s_cselect_b32 s17, s19, s21
	s_cselect_b32 s63, s18, s20
	s_ashr_i32 s15, s14, 31
	s_lshl_b64 s[38:39], s[14:15], 18
	s_add_u32 s38, s33, s38
	s_addc_u32 s39, s50, s39
	s_and_b64 s[48:49], s[4:5], exec
	s_cselect_b32 s15, s39, s47
	s_cselect_b32 s64, s38, s46
	s_add_u32 s20, s20, 0x20080
	s_addc_u32 s21, s21, 0
	s_add_u32 s65, s46, 0x100
	s_addc_u32 s66, s47, 0
	s_mov_b32 s67, -2
	ds_read_b128 v[112:115], v167
	ds_read_b128 v[116:119], v167 offset:1024
	ds_read_b128 v[152:155], v167 offset:2048
	ds_read_b128 v[156:159], v167 offset:3072
	ds_read_b128 v[160:163], v168
	ds_read_b128 v[170:173], v168 offset:1024
	ds_read_b128 v[174:177], v168 offset:2048
	ds_read_b128 v[178:181], v168 offset:3072
	s_add_u32 s46, s20, 0xfffe0080
	s_addc_u32 s47, s21, -1
	s_cmp_eq_u32 s67, 4
	s_cselect_b32 s49, s17, s47
	s_cselect_b32 s48, s63, s46
	s_cselect_b32 s47, s15, s66
	s_cselect_b32 s46, s64, s65
	s_add_i32 m0, s35, 0xc000
	ds_read_b128 v[182:185], v169
	ds_read_b128 v[186:189], v169 offset:1024
	ds_read_b128 v[190:193], v169 offset:2048
	ds_read_b128 v[198:201], v169 offset:3072
	ds_read_b128 v[202:205], v169 offset:4096
	ds_read_b128 v[206:209], v169 offset:5120
	ds_read_b128 v[210:213], v169 offset:6144
	ds_read_b128 v[214:217], v169 offset:7168
	global_load_lds_dwordx4 v144, s[20:21]
	s_add_i32 m0, s35, 0xe000
	s_nop 0
	global_load_lds_dwordx4 v146, s[20:21]
	s_waitcnt vmcnt(8)
	s_waitcnt lgkmcnt(0)
	s_barrier
	v_mfma_f32_16x16x32_bf16 v[132:135], v[112:115], v[182:185], 0
	v_mfma_f32_16x16x32_bf16 v[128:131], v[152:155], v[182:185], 0
	v_mfma_f32_16x16x32_bf16 v[120:123], v[152:155], v[190:193], 0
	v_mfma_f32_16x16x32_bf16 v[124:127], v[112:115], v[190:193], 0
	v_mfma_f32_16x16x32_bf16 v[108:111], v[112:115], v[202:205], 0
	v_mfma_f32_16x16x32_bf16 v[104:107], v[152:155], v[202:205], 0
	v_mfma_f32_16x16x32_bf16 v[96:99], v[152:155], v[210:213], 0
	v_mfma_f32_16x16x32_bf16 v[100:103], v[112:115], v[210:213], 0
	v_mfma_f32_16x16x32_bf16 v[132:135], v[116:119], v[186:189], v[132:135]
	v_mfma_f32_16x16x32_bf16 v[128:131], v[156:159], v[186:189], v[128:131]
	v_mfma_f32_16x16x32_bf16 v[120:123], v[156:159], v[198:201], v[120:123]
	v_mfma_f32_16x16x32_bf16 v[124:127], v[116:119], v[198:201], v[124:127]
	v_mfma_f32_16x16x32_bf16 v[108:111], v[116:119], v[206:209], v[108:111]
	v_mfma_f32_16x16x32_bf16 v[104:107], v[156:159], v[206:209], v[104:107]
	v_mfma_f32_16x16x32_bf16 v[96:99], v[156:159], v[214:217], v[96:99]
	v_mfma_f32_16x16x32_bf16 v[100:103], v[116:119], v[214:217], v[100:103]
	v_mfma_f32_16x16x32_bf16 v[60:63], v[160:163], v[182:185], 0
	v_mfma_f32_16x16x32_bf16 v[56:59], v[174:177], v[182:185], 0
	v_mfma_f32_16x16x32_bf16 v[48:51], v[174:177], v[190:193], 0
	v_mfma_f32_16x16x32_bf16 v[52:55], v[160:163], v[190:193], 0
	v_mfma_f32_16x16x32_bf16 v[44:47], v[160:163], v[202:205], 0
	v_mfma_f32_16x16x32_bf16 v[40:43], v[174:177], v[202:205], 0
	v_mfma_f32_16x16x32_bf16 v[32:35], v[174:177], v[210:213], 0
	v_mfma_f32_16x16x32_bf16 v[36:39], v[160:163], v[210:213], 0
	v_mfma_f32_16x16x32_bf16 v[60:63], v[170:173], v[186:189], v[60:63]
	v_mfma_f32_16x16x32_bf16 v[56:59], v[178:181], v[186:189], v[56:59]
	v_mfma_f32_16x16x32_bf16 v[48:51], v[178:181], v[198:201], v[48:51]
	v_mfma_f32_16x16x32_bf16 v[52:55], v[170:173], v[198:201], v[52:55]
	v_mfma_f32_16x16x32_bf16 v[44:47], v[170:173], v[206:209], v[44:47]
	v_mfma_f32_16x16x32_bf16 v[40:43], v[178:181], v[206:209], v[40:43]
	v_mfma_f32_16x16x32_bf16 v[32:35], v[178:181], v[214:217], v[32:35]
	v_mfma_f32_16x16x32_bf16 v[36:39], v[170:173], v[214:217], v[36:39]
	s_barrier
	s_add_i32 s68, s60, s51
	s_add_u32 s98, s46, s10
	s_addc_u32 s99, s47, s11
	s_add_u32 s100, s48, s10
	s_addc_u32 s101, s49, s11
	s_mov_b32 m0, s68
	ds_read_b128 v[182:185], v169 offset:16384
	ds_read_b128 v[186:189], v169 offset:17408
	ds_read_b128 v[190:193], v169 offset:18432
	ds_read_b128 v[198:201], v169 offset:19456
	ds_read_b128 v[202:205], v169 offset:20480
	ds_read_b128 v[206:209], v169 offset:21504
	ds_read_b128 v[210:213], v169 offset:22528
	ds_read_b128 v[214:217], v169 offset:23552
	global_load_lds_dwordx4 v138, s[46:47]
	s_add_i32 m0, s68, 0x2000
	s_add_u32 s68, s46, 0x20000
	s_addc_u32 s69, s47, 0
	s_add_i32 s70, s61, s51
	global_load_lds_dwordx4 v142, s[46:47]
	s_mov_b32 m0, s70
	s_nop 0
	global_load_lds_dwordx4 v138, s[68:69]
	s_add_i32 m0, s70, 0x2000
	s_nop 0
	global_load_lds_dwordx4 v142, s[68:69]
	s_mov_b32 m0, s35
	s_nop 0
	global_load_lds_dwordx4 v136, s[48:49]
	s_mov_b32 m0, s52
	s_nop 0
	global_load_lds_dwordx4 v140, s[48:49]
	s_waitcnt vmcnt(8)
	s_waitcnt lgkmcnt(0)
	s_barrier
; #define PG8_STAGE(bufoff, gbase, voff) do { _Pragma("unroll") for (int _i = 0; _i < 2; ++_i) \
;         __builtin_amdgcn_global_load_lds((const unsigned*)((const char*)(gbase) + (voff)[_i]), (PG8_LAS unsigned*)(lds + (bufoff) + ldsw + _i * 8192), 16, 0, 0); } while (0)
; #define PG8_LDA(dst, b, h) do { _Pragma("unroll") for (int m = 0; m < 4; ++m) _Pragma("unroll") for (int k = 0; k < 2; ++k) dst[m][k] = *(const PG8_LAS bf16x8*)(lds + PG8_SA(b, h) + aoff + m * 2048 + k * 1024); } while (0)
; #define PG8_LDB(dst, b, h) do { _Pragma("unroll") for (int n = 0; n < 2; ++n) _Pragma("unroll") for (int k = 0; k < 2; ++k) dst[n][k] = *(const PG8_LAS bf16x8*)(lds + PG8_SB(b, h) + boff + n * 2048 + k * 1024); } while (0)
; #define PG8_MMA(ai, bj, At, Bt) do { __builtin_amdgcn_s_setprio(1); _Pragma("unroll") for (int m = 0; m < 4; ++m) _Pragma("unroll") for (int n = 0; n < 2; ++n) _Pragma("unroll") for (int k = 0; k < 2; ++k) \
;         acc[ai][bj][m][n] = __builtin_amdgcn_mfma_f32_16x16x32_bf16(Bt[n][k], At[m][k], acc[ai][bj][m][n], 0, 0, 0); __builtin_amdgcn_s_setprio(0); } while (0)
; #define PG8_WAIT_V(n) asm volatile("s_waitcnt vmcnt(" #n ")" ::: "memory")
; #define PG8_WAIT_L(n) asm volatile("s_waitcnt lgkmcnt(" #n ")" ::: "memory")
; #define PG8_BAR __builtin_amdgcn_s_barrier()
; #define PG8_SCHED __builtin_amdgcn_sched_barrier(0)
; template <class Epi, class Sched, bool ALIGN_EPI = false, bool SP2 = false>
; __device__ __forceinline__ void gemm_phase(PG8_LAS unsigned char* lds, const Gemm g, const Sched& S, const Epi& E) {
;     ...
;             PG8_LDA(At, 0, 1); PG8_STAGE(PG8_SB(0, 0), b2, voffB); PG8_STAGE(PG8_SB(0, 1), b2 + hstep, voffB); PG8_STAGE(PG8_SA(0, 0), a2, voffA);
;             PG8_WAIT_V(8); PG8_WAIT_L(0); PG8_BAR; PG8_MMA(1, 0, At, B0); PG8_MMA(1, 1, At, B1); PG8_BAR; PG8_SCHED;
;             PG8_LDB(B0, 1, 0); PG8_LDB(B1, 1, 1); PG8_SCHED; PG8_LDA(At, 1, 0); PG8_STAGE(PG8_SA(0, 1), a2 + hstep, voffA);
;             PG8_WAIT_V(8); PG8_WAIT_L(0); PG8_BAR; PG8_MMA(0, 0, At, B0); PG8_MMA(0, 1, At, B1); PG8_BAR; PG8_SCHED;
	v_mfma_f32_16x16x32_bf16 v[92:95], v[112:115], v[182:185], 0
	v_mfma_f32_16x16x32_bf16 v[88:91], v[152:155], v[182:185], 0
	v_mfma_f32_16x16x32_bf16 v[80:83], v[152:155], v[190:193], 0
	v_mfma_f32_16x16x32_bf16 v[84:87], v[112:115], v[190:193], 0
	v_mfma_f32_16x16x32_bf16 v[76:79], v[112:115], v[202:205], 0
	v_mfma_f32_16x16x32_bf16 v[72:75], v[152:155], v[202:205], 0
	v_mfma_f32_16x16x32_bf16 v[64:67], v[152:155], v[210:213], 0
	v_mfma_f32_16x16x32_bf16 v[68:71], v[112:115], v[210:213], 0
	v_mfma_f32_16x16x32_bf16 v[92:95], v[116:119], v[186:189], v[92:95]
	v_mfma_f32_16x16x32_bf16 v[88:91], v[156:159], v[186:189], v[88:91]
	v_mfma_f32_16x16x32_bf16 v[80:83], v[156:159], v[198:201], v[80:83]
	v_mfma_f32_16x16x32_bf16 v[84:87], v[116:119], v[198:201], v[84:87]
	v_mfma_f32_16x16x32_bf16 v[76:79], v[116:119], v[206:209], v[76:79]
	v_mfma_f32_16x16x32_bf16 v[72:75], v[156:159], v[206:209], v[72:75]
	v_mfma_f32_16x16x32_bf16 v[64:67], v[156:159], v[214:217], v[64:67]
	v_mfma_f32_16x16x32_bf16 v[68:71], v[116:119], v[214:217], v[68:71]
	v_mfma_f32_16x16x32_bf16 v[28:31], v[160:163], v[182:185], 0
	v_mfma_f32_16x16x32_bf16 v[24:27], v[174:177], v[182:185], 0
	v_mfma_f32_16x16x32_bf16 v[16:19], v[174:177], v[190:193], 0
	v_mfma_f32_16x16x32_bf16 v[20:23], v[160:163], v[190:193], 0
	v_mfma_f32_16x16x32_bf16 v[12:15], v[160:163], v[202:205], 0
	v_mfma_f32_16x16x32_bf16 v[8:11], v[174:177], v[202:205], 0
	v_mfma_f32_16x16x32_bf16 v[0:3], v[174:177], v[210:213], 0
	v_mfma_f32_16x16x32_bf16 v[4:7], v[160:163], v[210:213], 0
	v_mfma_f32_16x16x32_bf16 v[28:31], v[170:173], v[186:189], v[28:31]
	v_mfma_f32_16x16x32_bf16 v[24:27], v[178:181], v[186:189], v[24:27]
	v_mfma_f32_16x16x32_bf16 v[16:19], v[178:181], v[198:201], v[16:19]
	v_mfma_f32_16x16x32_bf16 v[20:23], v[170:173], v[198:201], v[20:23]
	v_mfma_f32_16x16x32_bf16 v[12:15], v[170:173], v[206:209], v[12:15]
	v_mfma_f32_16x16x32_bf16 v[8:11], v[178:181], v[206:209], v[8:11]
	v_mfma_f32_16x16x32_bf16 v[0:3], v[178:181], v[214:217], v[0:3]
	v_mfma_f32_16x16x32_bf16 v[4:7], v[170:173], v[214:217], v[4:7]
	s_barrier
	s_add_i32 s68, 0, 0x18000
	s_add_i32 s69, 0, 0x1c000
	v_add_u32_e32 v156, s68, v165
	v_add_u32_e32 v178, s69, v165
	ds_read_b128 v[112:115], v156
	ds_read_b128 v[116:119], v156 offset:1024
	ds_read_b128 v[152:155], v156 offset:2048
	ds_read_b128 v[156:159], v156 offset:3072
	ds_read_b128 v[160:163], v178
	ds_read_b128 v[170:173], v178 offset:1024
	ds_read_b128 v[174:177], v178 offset:2048
	ds_read_b128 v[178:181], v178 offset:3072
	s_add_u32 s48, s48, 0x20000
	s_addc_u32 s49, s49, 0
	s_mov_b32 m0, s53
	ds_read_b128 v[182:185], v169 offset:32768
	ds_read_b128 v[186:189], v169 offset:33792
	ds_read_b128 v[190:193], v169 offset:34816
	ds_read_b128 v[198:201], v169 offset:35840
	ds_read_b128 v[202:205], v169 offset:36864
	ds_read_b128 v[206:209], v169 offset:37888
	ds_read_b128 v[210:213], v169 offset:38912
	ds_read_b128 v[214:217], v169 offset:39936
	global_load_lds_dwordx4 v136, s[48:49]
	s_mov_b32 m0, s54
	s_nop 0
	global_load_lds_dwordx4 v140, s[48:49]
	s_waitcnt vmcnt(8)
	s_waitcnt lgkmcnt(0)
	s_barrier
	v_mfma_f32_16x16x32_bf16 v[132:135], v[112:115], v[182:185], v[132:135]
	v_mfma_f32_16x16x32_bf16 v[128:131], v[152:155], v[182:185], v[128:131]
	v_mfma_f32_16x16x32_bf16 v[120:123], v[152:155], v[190:193], v[120:123]
	v_mfma_f32_16x16x32_bf16 v[124:127], v[112:115], v[190:193], v[124:127]
	v_mfma_f32_16x16x32_bf16 v[108:111], v[112:115], v[202:205], v[108:111]
	v_mfma_f32_16x16x32_bf16 v[104:107], v[152:155], v[202:205], v[104:107]
	v_mfma_f32_16x16x32_bf16 v[96:99], v[152:155], v[210:213], v[96:99]
	v_mfma_f32_16x16x32_bf16 v[100:103], v[112:115], v[210:213], v[100:103]
	v_mfma_f32_16x16x32_bf16 v[132:135], v[116:119], v[186:189], v[132:135]
	v_mfma_f32_16x16x32_bf16 v[128:131], v[156:159], v[186:189], v[128:131]
	v_mfma_f32_16x16x32_bf16 v[120:123], v[156:159], v[198:201], v[120:123]
	v_mfma_f32_16x16x32_bf16 v[124:127], v[116:119], v[198:201], v[124:127]
	v_mfma_f32_16x16x32_bf16 v[108:111], v[116:119], v[206:209], v[108:111]
	v_mfma_f32_16x16x32_bf16 v[104:107], v[156:159], v[206:209], v[104:107]
	v_mfma_f32_16x16x32_bf16 v[96:99], v[156:159], v[214:217], v[96:99]
	v_mfma_f32_16x16x32_bf16 v[100:103], v[116:119], v[214:217], v[100:103]
	v_mfma_f32_16x16x32_bf16 v[60:63], v[160:163], v[182:185], v[60:63]
	v_mfma_f32_16x16x32_bf16 v[56:59], v[174:177], v[182:185], v[56:59]
	v_mfma_f32_16x16x32_bf16 v[48:51], v[174:177], v[190:193], v[48:51]
	v_mfma_f32_16x16x32_bf16 v[52:55], v[160:163], v[190:193], v[52:55]
	v_mfma_f32_16x16x32_bf16 v[44:47], v[160:163], v[202:205], v[44:47]
	v_mfma_f32_16x16x32_bf16 v[40:43], v[174:177], v[202:205], v[40:43]
	v_mfma_f32_16x16x32_bf16 v[32:35], v[174:177], v[210:213], v[32:35]
	v_mfma_f32_16x16x32_bf16 v[36:39], v[160:163], v[210:213], v[36:39]
	v_mfma_f32_16x16x32_bf16 v[60:63], v[170:173], v[186:189], v[60:63]
	v_mfma_f32_16x16x32_bf16 v[56:59], v[178:181], v[186:189], v[56:59]
	v_mfma_f32_16x16x32_bf16 v[48:51], v[178:181], v[198:201], v[48:51]
	v_mfma_f32_16x16x32_bf16 v[52:55], v[170:173], v[198:201], v[52:55]
	v_mfma_f32_16x16x32_bf16 v[44:47], v[170:173], v[206:209], v[44:47]
	v_mfma_f32_16x16x32_bf16 v[40:43], v[178:181], v[206:209], v[40:43]
	v_mfma_f32_16x16x32_bf16 v[32:35], v[178:181], v[214:217], v[32:35]
	v_mfma_f32_16x16x32_bf16 v[36:39], v[170:173], v[214:217], v[36:39]
	s_barrier
; #define PG8_STAGE(bufoff, gbase, voff) do { _Pragma("unroll") for (int _i = 0; _i < 2; ++_i) \
;         __builtin_amdgcn_global_load_lds((const unsigned*)((const char*)(gbase) + (voff)[_i]), (PG8_LAS unsigned*)(lds + (bufoff) + ldsw + _i * 8192), 16, 0, 0); } while (0)
; #define PG8_LDA(dst, b, h) do { _Pragma("unroll") for (int m = 0; m < 4; ++m) _Pragma("unroll") for (int k = 0; k < 2; ++k) dst[m][k] = *(const PG8_LAS bf16x8*)(lds + PG8_SA(b, h) + aoff + m * 2048 + k * 1024); } while (0)
; #define PG8_LDB(dst, b, h) do { _Pragma("unroll") for (int n = 0; n < 2; ++n) _Pragma("unroll") for (int k = 0; k < 2; ++k) dst[n][k] = *(const PG8_LAS bf16x8*)(lds + PG8_SB(b, h) + boff + n * 2048 + k * 1024); } while (0)
; #define PG8_MMA(ai, bj, At, Bt) do { __builtin_amdgcn_s_setprio(1); _Pragma("unroll") for (int m = 0; m < 4; ++m) _Pragma("unroll") for (int n = 0; n < 2; ++n) _Pragma("unroll") for (int k = 0; k < 2; ++k) \
;         acc[ai][bj][m][n] = __builtin_amdgcn_mfma_f32_16x16x32_bf16(Bt[n][k], At[m][k], acc[ai][bj][m][n], 0, 0, 0); __builtin_amdgcn_s_setprio(0); } while (0)
; #define PG8_WAIT_V(n) asm volatile("s_waitcnt vmcnt(" #n ")" ::: "memory")
; #define PG8_WAIT_L(n) asm volatile("s_waitcnt lgkmcnt(" #n ")" ::: "memory")
; #define PG8_BAR __builtin_amdgcn_s_barrier()
; #define PG8_SCHED __builtin_amdgcn_sched_barrier(0)
; template <class Epi, class Sched, bool ALIGN_EPI = false, bool SP2 = false>
; __device__ __forceinline__ void gemm_phase(PG8_LAS unsigned char* lds, const Gemm g, const Sched& S, const Epi& E) {
;     ...
;             PG8_LDB(B0, 0, 0); PG8_LDB(B1, 0, 1); PG8_SCHED; PG8_LDA(At, 0, 0); PG8_STAGE(PG8_SA(1, 1), a1 + hstep, voffA);
;             PG8_WAIT_V(8); PG8_WAIT_L(0); PG8_BAR; PG8_MMA(0, 0, At, B0); PG8_MMA(0, 1, At, B1); PG8_BAR; PG8_SCHED;
;             PG8_LDA(At, 0, 1); PG8_STAGE(PG8_SB(0, 0), b2, voffB); PG8_STAGE(PG8_SB(0, 1), b2 + hstep, voffB); PG8_STAGE(PG8_SA(0, 0), a2, voffA);
;             PG8_WAIT_V(8); PG8_WAIT_L(0); PG8_BAR; PG8_MMA(1, 0, At, B0); PG8_MMA(1, 1, At, B1); PG8_BAR; PG8_SCHED;
;     ...
;             PG8_LDA(At, 1, 1); PG8_STAGE(PG8_SB(1, 0), b3, voffB); PG8_STAGE(PG8_SB(1, 1), b3 + hstep, voffB); PG8_STAGE(PG8_SA(1, 0), a3, voffA);
;             PG8_WAIT_V(8); PG8_WAIT_L(0); PG8_BAR; PG8_MMA(1, 0, At, B0); PG8_MMA(1, 1, At, B1); PG8_BAR; PG8_SCHED;
	s_add_i32 s48, s68, s51
	s_mov_b32 m0, s48
	ds_read_b128 v[182:185], v169 offset:49152
	ds_read_b128 v[186:189], v169 offset:50176
	ds_read_b128 v[190:193], v169 offset:51200
	ds_read_b128 v[198:201], v169 offset:52224
	ds_read_b128 v[202:205], v169 offset:53248
	ds_read_b128 v[206:209], v169 offset:54272
	ds_read_b128 v[210:213], v169 offset:55296
	ds_read_b128 v[214:217], v169 offset:56320
	global_load_lds_dwordx4 v138, s[98:99]
	s_add_i32 m0, s48, 0x2000
	s_add_u32 s46, s46, 0x20080
	s_addc_u32 s47, s47, 0
	s_add_i32 s48, s69, s51
	global_load_lds_dwordx4 v142, s[98:99]
	s_mov_b32 m0, s48
	s_nop 0
	global_load_lds_dwordx4 v138, s[46:47]
	s_add_i32 m0, s48, 0x2000
	s_nop 0
	global_load_lds_dwordx4 v142, s[46:47]
	s_mov_b32 m0, s56
	s_nop 0
	global_load_lds_dwordx4 v136, s[100:101]
	s_mov_b32 m0, s57
	s_nop 0
	global_load_lds_dwordx4 v140, s[100:101]
	s_waitcnt vmcnt(8)
	s_waitcnt lgkmcnt(0)
	s_barrier
	v_mfma_f32_16x16x32_bf16 v[92:95], v[112:115], v[182:185], v[92:95]
	v_mfma_f32_16x16x32_bf16 v[88:91], v[152:155], v[182:185], v[88:91]
	v_mfma_f32_16x16x32_bf16 v[80:83], v[152:155], v[190:193], v[80:83]
	v_mfma_f32_16x16x32_bf16 v[84:87], v[112:115], v[190:193], v[84:87]
	v_mfma_f32_16x16x32_bf16 v[76:79], v[112:115], v[202:205], v[76:79]
	v_mfma_f32_16x16x32_bf16 v[72:75], v[152:155], v[202:205], v[72:75]
	v_mfma_f32_16x16x32_bf16 v[64:67], v[152:155], v[210:213], v[64:67]
	v_mfma_f32_16x16x32_bf16 v[68:71], v[112:115], v[210:213], v[68:71]
	v_mfma_f32_16x16x32_bf16 v[92:95], v[116:119], v[186:189], v[92:95]
	v_mfma_f32_16x16x32_bf16 v[88:91], v[156:159], v[186:189], v[88:91]
	v_mfma_f32_16x16x32_bf16 v[80:83], v[156:159], v[198:201], v[80:83]
	v_mfma_f32_16x16x32_bf16 v[84:87], v[116:119], v[198:201], v[84:87]
	v_mfma_f32_16x16x32_bf16 v[76:79], v[116:119], v[206:209], v[76:79]
	v_mfma_f32_16x16x32_bf16 v[72:75], v[156:159], v[206:209], v[72:75]
	v_mfma_f32_16x16x32_bf16 v[64:67], v[156:159], v[214:217], v[64:67]
	v_mfma_f32_16x16x32_bf16 v[68:71], v[116:119], v[214:217], v[68:71]
	v_mfma_f32_16x16x32_bf16 v[28:31], v[160:163], v[182:185], v[28:31]
	v_mfma_f32_16x16x32_bf16 v[24:27], v[174:177], v[182:185], v[24:27]
	v_mfma_f32_16x16x32_bf16 v[16:19], v[174:177], v[190:193], v[16:19]
	v_mfma_f32_16x16x32_bf16 v[20:23], v[160:163], v[190:193], v[20:23]
	v_mfma_f32_16x16x32_bf16 v[12:15], v[160:163], v[202:205], v[12:15]
	v_mfma_f32_16x16x32_bf16 v[8:11], v[174:177], v[202:205], v[8:11]
	v_mfma_f32_16x16x32_bf16 v[0:3], v[174:177], v[210:213], v[0:3]
	v_mfma_f32_16x16x32_bf16 v[4:7], v[160:163], v[210:213], v[4:7]
	v_mfma_f32_16x16x32_bf16 v[28:31], v[170:173], v[186:189], v[28:31]
	v_mfma_f32_16x16x32_bf16 v[24:27], v[178:181], v[186:189], v[24:27]
	v_mfma_f32_16x16x32_bf16 v[16:19], v[178:181], v[198:201], v[16:19]
	v_mfma_f32_16x16x32_bf16 v[20:23], v[170:173], v[198:201], v[20:23]
	v_mfma_f32_16x16x32_bf16 v[12:15], v[170:173], v[206:209], v[12:15]
	v_mfma_f32_16x16x32_bf16 v[8:11], v[178:181], v[206:209], v[8:11]
	v_mfma_f32_16x16x32_bf16 v[0:3], v[178:181], v[214:217], v[0:3]
	v_mfma_f32_16x16x32_bf16 v[4:7], v[170:173], v[214:217], v[4:7]
	s_barrier
	s_add_i32 s67, s67, 2
	s_add_u32 s20, s20, 0x100
	s_addc_u32 s21, s21, 0
	s_add_u32 s65, s65, 0x100
	s_addc_u32 s66, s66, 0
	s_cmp_gt_u32 s67, 5
.LBB0_624:
	ds_read_b128 v[112:115], v167
	ds_read_b128 v[116:119], v167 offset:1024
	ds_read_b128 v[152:155], v167 offset:2048
	ds_read_b128 v[156:159], v167 offset:3072
	ds_read_b128 v[160:163], v168
	ds_read_b128 v[170:173], v168 offset:1024
	ds_read_b128 v[174:177], v168 offset:2048
	ds_read_b128 v[178:181], v168 offset:3072
	s_add_u32 s46, s20, 0xfffe0080
	s_addc_u32 s47, s21, -1
	s_cmp_eq_u32 s67, 4
	s_cselect_b32 s49, s17, s47
	s_cselect_b32 s48, s63, s46
	s_cselect_b32 s47, s15, s66
	s_cselect_b32 s46, s64, s65
	s_add_i32 m0, s35, 0xc000
	ds_read_b128 v[182:185], v169
	ds_read_b128 v[186:189], v169 offset:1024
	ds_read_b128 v[190:193], v169 offset:2048
	ds_read_b128 v[198:201], v169 offset:3072
	ds_read_b128 v[202:205], v169 offset:4096
	ds_read_b128 v[206:209], v169 offset:5120
	ds_read_b128 v[210:213], v169 offset:6144
	ds_read_b128 v[214:217], v169 offset:7168
	global_load_lds_dwordx4 v144, s[20:21]
	s_add_i32 m0, s35, 0xe000
	s_nop 0
	global_load_lds_dwordx4 v146, s[20:21]
	s_waitcnt vmcnt(8)
	s_waitcnt lgkmcnt(0)
	s_barrier
	v_mfma_f32_16x16x32_bf16 v[132:135], v[112:115], v[182:185], v[132:135]
	v_mfma_f32_16x16x32_bf16 v[128:131], v[152:155], v[182:185], v[128:131]
	v_mfma_f32_16x16x32_bf16 v[120:123], v[152:155], v[190:193], v[120:123]
	v_mfma_f32_16x16x32_bf16 v[124:127], v[112:115], v[190:193], v[124:127]
	v_mfma_f32_16x16x32_bf16 v[108:111], v[112:115], v[202:205], v[108:111]
	v_mfma_f32_16x16x32_bf16 v[104:107], v[152:155], v[202:205], v[104:107]
	v_mfma_f32_16x16x32_bf16 v[96:99], v[152:155], v[210:213], v[96:99]
	v_mfma_f32_16x16x32_bf16 v[100:103], v[112:115], v[210:213], v[100:103]
	v_mfma_f32_16x16x32_bf16 v[132:135], v[116:119], v[186:189], v[132:135]
	v_mfma_f32_16x16x32_bf16 v[128:131], v[156:159], v[186:189], v[128:131]
	v_mfma_f32_16x16x32_bf16 v[120:123], v[156:159], v[198:201], v[120:123]
	v_mfma_f32_16x16x32_bf16 v[124:127], v[116:119], v[198:201], v[124:127]
	v_mfma_f32_16x16x32_bf16 v[108:111], v[116:119], v[206:209], v[108:111]
	v_mfma_f32_16x16x32_bf16 v[104:107], v[156:159], v[206:209], v[104:107]
	v_mfma_f32_16x16x32_bf16 v[96:99], v[156:159], v[214:217], v[96:99]
	v_mfma_f32_16x16x32_bf16 v[100:103], v[116:119], v[214:217], v[100:103]
	v_mfma_f32_16x16x32_bf16 v[60:63], v[160:163], v[182:185], v[60:63]
	v_mfma_f32_16x16x32_bf16 v[56:59], v[174:177], v[182:185], v[56:59]
	v_mfma_f32_16x16x32_bf16 v[48:51], v[174:177], v[190:193], v[48:51]
	v_mfma_f32_16x16x32_bf16 v[52:55], v[160:163], v[190:193], v[52:55]
	v_mfma_f32_16x16x32_bf16 v[44:47], v[160:163], v[202:205], v[44:47]
	v_mfma_f32_16x16x32_bf16 v[40:43], v[174:177], v[202:205], v[40:43]
	v_mfma_f32_16x16x32_bf16 v[32:35], v[174:177], v[210:213], v[32:35]
	v_mfma_f32_16x16x32_bf16 v[36:39], v[160:163], v[210:213], v[36:39]
	v_mfma_f32_16x16x32_bf16 v[60:63], v[170:173], v[186:189], v[60:63]
	v_mfma_f32_16x16x32_bf16 v[56:59], v[178:181], v[186:189], v[56:59]
	v_mfma_f32_16x16x32_bf16 v[48:51], v[178:181], v[198:201], v[48:51]
	v_mfma_f32_16x16x32_bf16 v[52:55], v[170:173], v[198:201], v[52:55]
	v_mfma_f32_16x16x32_bf16 v[44:47], v[170:173], v[206:209], v[44:47]
	v_mfma_f32_16x16x32_bf16 v[40:43], v[178:181], v[206:209], v[40:43]
	v_mfma_f32_16x16x32_bf16 v[32:35], v[178:181], v[214:217], v[32:35]
	v_mfma_f32_16x16x32_bf16 v[36:39], v[170:173], v[214:217], v[36:39]
	s_barrier
; #define PG8_STAGE(bufoff, gbase, voff) do { _Pragma("unroll") for (int _i = 0; _i < 2; ++_i) \
;         __builtin_amdgcn_global_load_lds((const unsigned*)((const char*)(gbase) + (voff)[_i]), (PG8_LAS unsigned*)(lds + (bufoff) + ldsw + _i * 8192), 16, 0, 0); } while (0)
; #define PG8_LDA(dst, b, h) do { _Pragma("unroll") for (int m = 0; m < 4; ++m) _Pragma("unroll") for (int k = 0; k < 2; ++k) dst[m][k] = *(const PG8_LAS bf16x8*)(lds + PG8_SA(b, h) + aoff + m * 2048 + k * 1024); } while (0)
; #define PG8_LDB(dst, b, h) do { _Pragma("unroll") for (int n = 0; n < 2; ++n) _Pragma("unroll") for (int k = 0; k < 2; ++k) dst[n][k] = *(const PG8_LAS bf16x8*)(lds + PG8_SB(b, h) + boff + n * 2048 + k * 1024); } while (0)
; #define PG8_MMA(ai, bj, At, Bt) do { __builtin_amdgcn_s_setprio(1); _Pragma("unroll") for (int m = 0; m < 4; ++m) _Pragma("unroll") for (int n = 0; n < 2; ++n) _Pragma("unroll") for (int k = 0; k < 2; ++k) \
;         acc[ai][bj][m][n] = __builtin_amdgcn_mfma_f32_16x16x32_bf16(Bt[n][k], At[m][k], acc[ai][bj][m][n], 0, 0, 0); __builtin_amdgcn_s_setprio(0); } while (0)
; #define PG8_WAIT_V(n) asm volatile("s_waitcnt vmcnt(" #n ")" ::: "memory")
; #define PG8_WAIT_L(n) asm volatile("s_waitcnt lgkmcnt(" #n ")" ::: "memory")
; #define PG8_BAR __builtin_amdgcn_s_barrier()
; #define PG8_SCHED __builtin_amdgcn_sched_barrier(0)
; template <class Epi, class Sched, bool ALIGN_EPI = false, bool SP2 = false>
; __device__ __forceinline__ void gemm_phase(PG8_LAS unsigned char* lds, const Gemm g, const Sched& S, const Epi& E) {
;     ...
;             PG8_LDA(At, 0, 1); PG8_STAGE(PG8_SB(0, 0), b2, voffB); PG8_STAGE(PG8_SB(0, 1), b2 + hstep, voffB); PG8_STAGE(PG8_SA(0, 0), a2, voffA);
;             PG8_WAIT_V(8); PG8_WAIT_L(0); PG8_BAR; PG8_MMA(1, 0, At, B0); PG8_MMA(1, 1, At, B1); PG8_BAR; PG8_SCHED;
;             PG8_LDB(B0, 1, 0); PG8_LDB(B1, 1, 1); PG8_SCHED; PG8_LDA(At, 1, 0); PG8_STAGE(PG8_SA(0, 1), a2 + hstep, voffA);
;             PG8_WAIT_V(8); PG8_WAIT_L(0); PG8_BAR; PG8_MMA(0, 0, At, B0); PG8_MMA(0, 1, At, B1); PG8_BAR; PG8_SCHED;
	s_add_i32 s68, s60, s51
	s_add_u32 s98, s46, s10
	s_addc_u32 s99, s47, s11
	s_add_u32 s100, s48, s10
	s_addc_u32 s101, s49, s11
	s_mov_b32 m0, s68
	ds_read_b128 v[182:185], v169 offset:16384
	ds_read_b128 v[186:189], v169 offset:17408
	ds_read_b128 v[190:193], v169 offset:18432
	ds_read_b128 v[198:201], v169 offset:19456
	ds_read_b128 v[202:205], v169 offset:20480
	ds_read_b128 v[206:209], v169 offset:21504
	ds_read_b128 v[210:213], v169 offset:22528
	ds_read_b128 v[214:217], v169 offset:23552
	global_load_lds_dwordx4 v138, s[46:47]
	s_add_i32 m0, s68, 0x2000
	s_add_u32 s68, s46, 0x20000
	s_addc_u32 s69, s47, 0
	s_add_i32 s70, s61, s51
	global_load_lds_dwordx4 v142, s[46:47]
	s_mov_b32 m0, s70
	s_nop 0
	global_load_lds_dwordx4 v138, s[68:69]
	s_add_i32 m0, s70, 0x2000
	s_nop 0
	global_load_lds_dwordx4 v142, s[68:69]
	s_mov_b32 m0, s35
	s_nop 0
	global_load_lds_dwordx4 v136, s[48:49]
	s_mov_b32 m0, s52
	s_nop 0
	global_load_lds_dwordx4 v140, s[48:49]
	s_waitcnt vmcnt(8)
	s_waitcnt lgkmcnt(0)
	s_barrier
	v_mfma_f32_16x16x32_bf16 v[92:95], v[112:115], v[182:185], v[92:95]
	v_mfma_f32_16x16x32_bf16 v[88:91], v[152:155], v[182:185], v[88:91]
	v_mfma_f32_16x16x32_bf16 v[80:83], v[152:155], v[190:193], v[80:83]
	v_mfma_f32_16x16x32_bf16 v[84:87], v[112:115], v[190:193], v[84:87]
	v_mfma_f32_16x16x32_bf16 v[76:79], v[112:115], v[202:205], v[76:79]
	v_mfma_f32_16x16x32_bf16 v[72:75], v[152:155], v[202:205], v[72:75]
	v_mfma_f32_16x16x32_bf16 v[64:67], v[152:155], v[210:213], v[64:67]
	v_mfma_f32_16x16x32_bf16 v[68:71], v[112:115], v[210:213], v[68:71]
	v_mfma_f32_16x16x32_bf16 v[92:95], v[116:119], v[186:189], v[92:95]
	v_mfma_f32_16x16x32_bf16 v[88:91], v[156:159], v[186:189], v[88:91]
	v_mfma_f32_16x16x32_bf16 v[80:83], v[156:159], v[198:201], v[80:83]
	v_mfma_f32_16x16x32_bf16 v[84:87], v[116:119], v[198:201], v[84:87]
	v_mfma_f32_16x16x32_bf16 v[76:79], v[116:119], v[206:209], v[76:79]
	v_mfma_f32_16x16x32_bf16 v[72:75], v[156:159], v[206:209], v[72:75]
	v_mfma_f32_16x16x32_bf16 v[64:67], v[156:159], v[214:217], v[64:67]
	v_mfma_f32_16x16x32_bf16 v[68:71], v[116:119], v[214:217], v[68:71]
	v_mfma_f32_16x16x32_bf16 v[28:31], v[160:163], v[182:185], v[28:31]
	v_mfma_f32_16x16x32_bf16 v[24:27], v[174:177], v[182:185], v[24:27]
	v_mfma_f32_16x16x32_bf16 v[16:19], v[174:177], v[190:193], v[16:19]
	v_mfma_f32_16x16x32_bf16 v[20:23], v[160:163], v[190:193], v[20:23]
	v_mfma_f32_16x16x32_bf16 v[12:15], v[160:163], v[202:205], v[12:15]
	v_mfma_f32_16x16x32_bf16 v[8:11], v[174:177], v[202:205], v[8:11]
	v_mfma_f32_16x16x32_bf16 v[0:3], v[174:177], v[210:213], v[0:3]
	v_mfma_f32_16x16x32_bf16 v[4:7], v[160:163], v[210:213], v[4:7]
	v_mfma_f32_16x16x32_bf16 v[28:31], v[170:173], v[186:189], v[28:31]
	v_mfma_f32_16x16x32_bf16 v[24:27], v[178:181], v[186:189], v[24:27]
	v_mfma_f32_16x16x32_bf16 v[16:19], v[178:181], v[198:201], v[16:19]
	v_mfma_f32_16x16x32_bf16 v[20:23], v[170:173], v[198:201], v[20:23]
	v_mfma_f32_16x16x32_bf16 v[12:15], v[170:173], v[206:209], v[12:15]
	v_mfma_f32_16x16x32_bf16 v[8:11], v[178:181], v[206:209], v[8:11]
	v_mfma_f32_16x16x32_bf16 v[0:3], v[178:181], v[214:217], v[0:3]
	v_mfma_f32_16x16x32_bf16 v[4:7], v[170:173], v[214:217], v[4:7]
	s_barrier
	s_add_i32 s68, 0, 0x18000
	s_add_i32 s69, 0, 0x1c000
	v_add_u32_e32 v156, s68, v165
	v_add_u32_e32 v178, s69, v165
	ds_read_b128 v[112:115], v156
	ds_read_b128 v[116:119], v156 offset:1024
	ds_read_b128 v[152:155], v156 offset:2048
	ds_read_b128 v[156:159], v156 offset:3072
	ds_read_b128 v[160:163], v178
	ds_read_b128 v[170:173], v178 offset:1024
	ds_read_b128 v[174:177], v178 offset:2048
	ds_read_b128 v[178:181], v178 offset:3072
	s_add_u32 s48, s48, 0x20000
	s_addc_u32 s49, s49, 0
	s_mov_b32 m0, s53
	ds_read_b128 v[182:185], v169 offset:32768
	ds_read_b128 v[186:189], v169 offset:33792
	ds_read_b128 v[190:193], v169 offset:34816
	ds_read_b128 v[198:201], v169 offset:35840
	ds_read_b128 v[202:205], v169 offset:36864
	ds_read_b128 v[206:209], v169 offset:37888
	ds_read_b128 v[210:213], v169 offset:38912
	ds_read_b128 v[214:217], v169 offset:39936
	global_load_lds_dwordx4 v136, s[48:49]
	s_mov_b32 m0, s54
	s_nop 0
	global_load_lds_dwordx4 v140, s[48:49]
	s_waitcnt vmcnt(8)
	s_waitcnt lgkmcnt(0)
	s_barrier
; #define PG8_STAGE(bufoff, gbase, voff) do { _Pragma("unroll") for (int _i = 0; _i < 2; ++_i) \
;         __builtin_amdgcn_global_load_lds((const unsigned*)((const char*)(gbase) + (voff)[_i]), (PG8_LAS unsigned*)(lds + (bufoff) + ldsw + _i * 8192), 16, 0, 0); } while (0)
; #define PG8_LDA(dst, b, h) do { _Pragma("unroll") for (int m = 0; m < 4; ++m) _Pragma("unroll") for (int k = 0; k < 2; ++k) dst[m][k] = *(const PG8_LAS bf16x8*)(lds + PG8_SA(b, h) + aoff + m * 2048 + k * 1024); } while (0)
; #define PG8_LDB(dst, b, h) do { _Pragma("unroll") for (int n = 0; n < 2; ++n) _Pragma("unroll") for (int k = 0; k < 2; ++k) dst[n][k] = *(const PG8_LAS bf16x8*)(lds + PG8_SB(b, h) + boff + n * 2048 + k * 1024); } while (0)
; #define PG8_MMA(ai, bj, At, Bt) do { __builtin_amdgcn_s_setprio(1); _Pragma("unroll") for (int m = 0; m < 4; ++m) _Pragma("unroll") for (int n = 0; n < 2; ++n) _Pragma("unroll") for (int k = 0; k < 2; ++k) \
;         acc[ai][bj][m][n] = __builtin_amdgcn_mfma_f32_16x16x32_bf16(Bt[n][k], At[m][k], acc[ai][bj][m][n], 0, 0, 0); __builtin_amdgcn_s_setprio(0); } while (0)
; #define PG8_WAIT_V(n) asm volatile("s_waitcnt vmcnt(" #n ")" ::: "memory")
; #define PG8_WAIT_L(n) asm volatile("s_waitcnt lgkmcnt(" #n ")" ::: "memory")
; #define PG8_BAR __builtin_amdgcn_s_barrier()
; #define PG8_SCHED __builtin_amdgcn_sched_barrier(0)
; template <class Epi, class Sched, bool ALIGN_EPI = false, bool SP2 = false>
; __device__ __forceinline__ void gemm_phase(PG8_LAS unsigned char* lds, const Gemm g, const Sched& S, const Epi& E) {
;     ...
;             PG8_LDB(B0, 1, 0); PG8_LDB(B1, 1, 1); PG8_SCHED; PG8_LDA(At, 1, 0); PG8_STAGE(PG8_SA(0, 1), a2 + hstep, voffA);
;             PG8_WAIT_V(8); PG8_WAIT_L(0); PG8_BAR; PG8_MMA(0, 0, At, B0); PG8_MMA(0, 1, At, B1); PG8_BAR; PG8_SCHED;
;             PG8_LDA(At, 1, 1); PG8_STAGE(PG8_SB(1, 0), b3, voffB); PG8_STAGE(PG8_SB(1, 1), b3 + hstep, voffB); PG8_STAGE(PG8_SA(1, 0), a3, voffA);
;             PG8_WAIT_V(8); PG8_WAIT_L(0); PG8_BAR; PG8_MMA(1, 0, At, B0); PG8_MMA(1, 1, At, B1); PG8_BAR; PG8_SCHED;
;     ...
;         if constexpr (ALIGN_EPI) { if (wr == 0) PG8_BAR; }
	v_mfma_f32_16x16x32_bf16 v[132:135], v[112:115], v[182:185], v[132:135]
	v_mfma_f32_16x16x32_bf16 v[128:131], v[152:155], v[182:185], v[128:131]
	v_mfma_f32_16x16x32_bf16 v[120:123], v[152:155], v[190:193], v[120:123]
	v_mfma_f32_16x16x32_bf16 v[124:127], v[112:115], v[190:193], v[124:127]
	v_mfma_f32_16x16x32_bf16 v[108:111], v[112:115], v[202:205], v[108:111]
	v_mfma_f32_16x16x32_bf16 v[104:107], v[152:155], v[202:205], v[104:107]
	v_mfma_f32_16x16x32_bf16 v[96:99], v[152:155], v[210:213], v[96:99]
	v_mfma_f32_16x16x32_bf16 v[100:103], v[112:115], v[210:213], v[100:103]
	v_mfma_f32_16x16x32_bf16 v[132:135], v[116:119], v[186:189], v[132:135]
	v_mfma_f32_16x16x32_bf16 v[128:131], v[156:159], v[186:189], v[128:131]
	v_mfma_f32_16x16x32_bf16 v[120:123], v[156:159], v[198:201], v[120:123]
	v_mfma_f32_16x16x32_bf16 v[124:127], v[116:119], v[198:201], v[124:127]
	v_mfma_f32_16x16x32_bf16 v[108:111], v[116:119], v[206:209], v[108:111]
	v_mfma_f32_16x16x32_bf16 v[104:107], v[156:159], v[206:209], v[104:107]
	v_mfma_f32_16x16x32_bf16 v[96:99], v[156:159], v[214:217], v[96:99]
	v_mfma_f32_16x16x32_bf16 v[100:103], v[116:119], v[214:217], v[100:103]
	v_mfma_f32_16x16x32_bf16 v[60:63], v[160:163], v[182:185], v[60:63]
	v_mfma_f32_16x16x32_bf16 v[56:59], v[174:177], v[182:185], v[56:59]
	v_mfma_f32_16x16x32_bf16 v[48:51], v[174:177], v[190:193], v[48:51]
	v_mfma_f32_16x16x32_bf16 v[52:55], v[160:163], v[190:193], v[52:55]
	v_mfma_f32_16x16x32_bf16 v[44:47], v[160:163], v[202:205], v[44:47]
	v_mfma_f32_16x16x32_bf16 v[40:43], v[174:177], v[202:205], v[40:43]
	v_mfma_f32_16x16x32_bf16 v[32:35], v[174:177], v[210:213], v[32:35]
	v_mfma_f32_16x16x32_bf16 v[36:39], v[160:163], v[210:213], v[36:39]
	v_mfma_f32_16x16x32_bf16 v[60:63], v[170:173], v[186:189], v[60:63]
	v_mfma_f32_16x16x32_bf16 v[56:59], v[178:181], v[186:189], v[56:59]
	v_mfma_f32_16x16x32_bf16 v[48:51], v[178:181], v[198:201], v[48:51]
	v_mfma_f32_16x16x32_bf16 v[52:55], v[170:173], v[198:201], v[52:55]
	v_mfma_f32_16x16x32_bf16 v[44:47], v[170:173], v[206:209], v[44:47]
	v_mfma_f32_16x16x32_bf16 v[40:43], v[178:181], v[206:209], v[40:43]
	v_mfma_f32_16x16x32_bf16 v[32:35], v[178:181], v[214:217], v[32:35]
	v_mfma_f32_16x16x32_bf16 v[36:39], v[170:173], v[214:217], v[36:39]
	s_barrier
	s_add_i32 s48, s68, s51
	s_mov_b32 m0, s48
	ds_read_b128 v[182:185], v169 offset:49152
	ds_read_b128 v[186:189], v169 offset:50176
	ds_read_b128 v[190:193], v169 offset:51200
	ds_read_b128 v[198:201], v169 offset:52224
	ds_read_b128 v[202:205], v169 offset:53248
	ds_read_b128 v[206:209], v169 offset:54272
	ds_read_b128 v[210:213], v169 offset:55296
	ds_read_b128 v[214:217], v169 offset:56320
	global_load_lds_dwordx4 v138, s[98:99]
	s_add_i32 m0, s48, 0x2000
	s_add_u32 s46, s46, 0x20080
	s_addc_u32 s47, s47, 0
	s_add_i32 s48, s69, s51
	global_load_lds_dwordx4 v142, s[98:99]
	s_mov_b32 m0, s48
	s_nop 0
	global_load_lds_dwordx4 v138, s[46:47]
	s_add_i32 m0, s48, 0x2000
	s_nop 0
	global_load_lds_dwordx4 v142, s[46:47]
	s_mov_b32 m0, s56
	s_nop 0
	global_load_lds_dwordx4 v136, s[100:101]
	s_mov_b32 m0, s57
	s_nop 0
	global_load_lds_dwordx4 v140, s[100:101]
	s_waitcnt vmcnt(8)
	s_waitcnt lgkmcnt(0)
	s_barrier
	v_mfma_f32_16x16x32_bf16 v[92:95], v[112:115], v[182:185], v[92:95]
	v_mfma_f32_16x16x32_bf16 v[88:91], v[152:155], v[182:185], v[88:91]
	v_mfma_f32_16x16x32_bf16 v[80:83], v[152:155], v[190:193], v[80:83]
	v_mfma_f32_16x16x32_bf16 v[84:87], v[112:115], v[190:193], v[84:87]
	v_mfma_f32_16x16x32_bf16 v[76:79], v[112:115], v[202:205], v[76:79]
	v_mfma_f32_16x16x32_bf16 v[72:75], v[152:155], v[202:205], v[72:75]
	v_mfma_f32_16x16x32_bf16 v[64:67], v[152:155], v[210:213], v[64:67]
	v_mfma_f32_16x16x32_bf16 v[68:71], v[112:115], v[210:213], v[68:71]
	v_mfma_f32_16x16x32_bf16 v[92:95], v[116:119], v[186:189], v[92:95]
	v_mfma_f32_16x16x32_bf16 v[88:91], v[156:159], v[186:189], v[88:91]
	v_mfma_f32_16x16x32_bf16 v[80:83], v[156:159], v[198:201], v[80:83]
	v_mfma_f32_16x16x32_bf16 v[84:87], v[116:119], v[198:201], v[84:87]
	v_mfma_f32_16x16x32_bf16 v[76:79], v[116:119], v[206:209], v[76:79]
	v_mfma_f32_16x16x32_bf16 v[72:75], v[156:159], v[206:209], v[72:75]
	v_mfma_f32_16x16x32_bf16 v[64:67], v[156:159], v[214:217], v[64:67]
	v_mfma_f32_16x16x32_bf16 v[68:71], v[116:119], v[214:217], v[68:71]
	v_mfma_f32_16x16x32_bf16 v[28:31], v[160:163], v[182:185], v[28:31]
	v_mfma_f32_16x16x32_bf16 v[24:27], v[174:177], v[182:185], v[24:27]
	v_mfma_f32_16x16x32_bf16 v[16:19], v[174:177], v[190:193], v[16:19]
	v_mfma_f32_16x16x32_bf16 v[20:23], v[160:163], v[190:193], v[20:23]
	v_mfma_f32_16x16x32_bf16 v[12:15], v[160:163], v[202:205], v[12:15]
	v_mfma_f32_16x16x32_bf16 v[8:11], v[174:177], v[202:205], v[8:11]
	v_mfma_f32_16x16x32_bf16 v[0:3], v[174:177], v[210:213], v[0:3]
	v_mfma_f32_16x16x32_bf16 v[4:7], v[160:163], v[210:213], v[4:7]
	v_mfma_f32_16x16x32_bf16 v[28:31], v[170:173], v[186:189], v[28:31]
	v_mfma_f32_16x16x32_bf16 v[24:27], v[178:181], v[186:189], v[24:27]
	v_mfma_f32_16x16x32_bf16 v[16:19], v[178:181], v[198:201], v[16:19]
	v_mfma_f32_16x16x32_bf16 v[20:23], v[170:173], v[198:201], v[20:23]
	v_mfma_f32_16x16x32_bf16 v[12:15], v[170:173], v[206:209], v[12:15]
	v_mfma_f32_16x16x32_bf16 v[8:11], v[178:181], v[206:209], v[8:11]
	v_mfma_f32_16x16x32_bf16 v[0:3], v[178:181], v[214:217], v[0:3]
	v_mfma_f32_16x16x32_bf16 v[4:7], v[170:173], v[214:217], v[4:7]
	s_barrier
	s_add_i32 s67, s67, 2
	s_add_u32 s20, s20, 0x100
	s_addc_u32 s21, s21, 0
	s_add_u32 s65, s65, 0x100
	s_addc_u32 s66, s66, 0
	s_cmp_gt_u32 s67, 5
	s_cbranch_scc0 .LBB0_624
	s_and_b64 vcc, exec, s[12:13]
	s_cbranch_vccz .LBB0_627
	s_barrier

; #define PG8_STAGE(bufoff, gbase, voff) do { _Pragma("unroll") for (int _i = 0; _i < 2; ++_i) \
;         __builtin_amdgcn_global_load_lds((const unsigned*)((const char*)(gbase) + (voff)[_i]), (PG8_LAS unsigned*)(lds + (bufoff) + ldsw + _i * 8192), 16, 0, 0); } while (0)
; #define PG8_LDA(dst, b, h) do { _Pragma("unroll") for (int m = 0; m < 4; ++m) _Pragma("unroll") for (int k = 0; k < 2; ++k) dst[m][k] = *(const PG8_LAS bf16x8*)(lds + PG8_SA(b, h) + aoff + m * 2048 + k * 1024); } while (0)
; template <class Epi, class Sched, bool ALIGN_EPI = false, bool SP2 = false>
; __device__ __forceinline__ void gemm_phase(PG8_LAS unsigned char* lds, const Gemm g, const Sched& S, const Epi& E) {
;     ...
;         const bool has_next = S.next(ui + 1, nxt);
;         const char* nA = has_next ? (const char*)g.A + (size_t)nxt.pm * tstep : cA; const char* nB = has_next ? (const char*)g.Bt + (size_t)nxt.pn * tstep : cB;
;         for (int t = 0; t < nt; t += 2) {
;             const bool last = (t == nt - 2);
;             const char* a1 = cA + (size_t)(t + 1) * kstep;
;             const char* a2 = last ? nA : cA + (size_t)(t + 2) * kstep; const char* b2 = last ? nB : cB + (size_t)(t + 2) * kstep;
;             const char* a3 = a2 + kstep; const char* b3 = b2 + kstep;
;             if (last && has_next) S.a_ready(nxt);
;             if constexpr (SP2) {
;             PG8_LDB(B0, 0, 0); PG8_LDB(B1, 0, 1); PG8_SCHED; PG8_LDA(At, 0, 0); PG8_STAGE(PG8_SA(1, 1), a1 + hstep, voffA);
;             PG8_WAIT_V(8); PG8_WAIT_L(0); PG8_BAR; PG8_MMA(0, 0, At, B0); PG8_MMA(0, 1, At, B1); PG8_BAR; PG8_SCHED;
;             PG8_LDA(At, 0, 1); PG8_STAGE(PG8_SB(0, 0), b2, voffB); PG8_STAGE(PG8_SB(0, 1), b2 + hstep, voffB); PG8_STAGE(PG8_SA(0, 0), a2, voffA);
;             PG8_WAIT_V(8); PG8_WAIT_L(0); PG8_BAR; PG8_MMA(1, 0, At, B0); PG8_MMA(1, 1, At, B1); PG8_BAR; PG8_SCHED;
;             PG8_LDB(B0, 1, 0); PG8_LDB(B1, 1, 1); PG8_SCHED; PG8_LDA(At, 1, 0); PG8_STAGE(PG8_SA(0, 1), a2 + hstep, voffA);
;             PG8_WAIT_V(8); PG8_WAIT_L(0); PG8_BAR; PG8_MMA(0, 0, At, B0); PG8_MMA(0, 1, At, B1); PG8_BAR; PG8_SCHED;
;             PG8_LDA(At, 1, 1); PG8_STAGE(PG8_SB(1, 0), b3, voffB); PG8_STAGE(PG8_SB(1, 1), b3 + hstep, voffB); PG8_STAGE(PG8_SA(1, 0), a3, voffA);
;             PG8_WAIT_V(8); PG8_WAIT_L(0); PG8_BAR; PG8_MMA(1, 0, At, B0); PG8_MMA(1, 1, At, B1); PG8_BAR; PG8_SCHED;
.LBB0_704:
	s_ashr_i32 s47, s46, 31
	s_lshl_b64 s[48:49], s[46:47], 19
	s_add_u32 s48, s42, s48
	s_addc_u32 s49, s43, s49
	s_and_b64 s[50:51], s[6:7], exec
	s_cselect_b32 s35, s49, s21
	s_cselect_b32 s47, s48, s20
	s_ashr_i32 s45, s44, 31
	s_lshl_b64 s[50:51], s[44:45], 19
	s_add_u32 s50, s3, s50
	s_addc_u32 s51, s33, s51
	s_and_b64 s[56:57], s[6:7], exec
	s_cselect_b32 s45, s51, s55
	s_cselect_b32 s73, s50, s54
	s_add_u32 s20, s20, 0x40080
	s_addc_u32 s21, s21, 0
	s_add_u32 s74, s54, 0x100
	s_addc_u32 s75, s55, 0
	s_mov_b32 s76, -2
	s_waitcnt lgkmcnt(0)
	ds_read_b128 v[96:99], v223
	ds_read_b128 v[108:111], v223 offset:1024
	ds_read_b128 v[120:123], v223 offset:2048
	ds_read_b128 v[128:131], v223 offset:3072
	ds_read_b128 v[144:147], v224
	ds_read_b128 v[148:151], v224 offset:1024
	ds_read_b128 v[152:155], v224 offset:2048
	ds_read_b128 v[156:159], v224 offset:3072
	s_add_u32 s54, s20, 0xfffc0080
	s_addc_u32 s55, s21, -1
	s_cmp_eq_u32 s76, 12
	s_cselect_b32 s57, s35, s55
	s_cselect_b32 s56, s47, s54
	s_cselect_b32 s55, s45, s75
	s_cselect_b32 s54, s73, s74
	s_add_i32 m0, s53, 0xc000
	ds_read_b128 v[160:163], v225
	ds_read_b128 v[164:167], v225 offset:1024
	ds_read_b128 v[168:171], v225 offset:2048
	ds_read_b128 v[172:175], v225 offset:3072
	ds_read_b128 v[176:179], v225 offset:4096
	ds_read_b128 v[180:183], v225 offset:5120
	ds_read_b128 v[202:205], v225 offset:6144
	ds_read_b128 v[206:209], v225 offset:7168
	global_load_lds_dwordx4 v192, s[20:21]
	s_add_i32 m0, s53, 0xe000
	s_nop 0
	global_load_lds_dwordx4 v194, s[20:21]
	s_waitcnt vmcnt(8)
	s_waitcnt lgkmcnt(0)
	s_barrier
	v_mfma_f32_16x16x32_bf16 v[140:143], v[96:99], v[160:163], 0
	v_mfma_f32_16x16x32_bf16 v[136:139], v[120:123], v[160:163], 0
	v_mfma_f32_16x16x32_bf16 v[112:115], v[120:123], v[168:171], 0
	v_mfma_f32_16x16x32_bf16 v[116:119], v[96:99], v[168:171], 0
	v_mfma_f32_16x16x32_bf16 v[92:95], v[96:99], v[176:179], 0
	v_mfma_f32_16x16x32_bf16 v[88:91], v[120:123], v[176:179], 0
	v_mfma_f32_16x16x32_bf16 v[72:75], v[120:123], v[202:205], 0
	v_mfma_f32_16x16x32_bf16 v[76:79], v[96:99], v[202:205], 0
	v_mfma_f32_16x16x32_bf16 v[140:143], v[108:111], v[164:167], v[140:143]
	v_mfma_f32_16x16x32_bf16 v[136:139], v[128:131], v[164:167], v[136:139]
	v_mfma_f32_16x16x32_bf16 v[112:115], v[128:131], v[172:175], v[112:115]
	v_mfma_f32_16x16x32_bf16 v[116:119], v[108:111], v[172:175], v[116:119]
	v_mfma_f32_16x16x32_bf16 v[92:95], v[108:111], v[180:183], v[92:95]
	v_mfma_f32_16x16x32_bf16 v[88:91], v[128:131], v[180:183], v[88:91]
	v_mfma_f32_16x16x32_bf16 v[72:75], v[128:131], v[206:209], v[72:75]
	v_mfma_f32_16x16x32_bf16 v[76:79], v[108:111], v[206:209], v[76:79]
	v_mfma_f32_16x16x32_bf16 v[132:135], v[144:147], v[160:163], 0
	v_mfma_f32_16x16x32_bf16 v[124:127], v[152:155], v[160:163], 0
	v_mfma_f32_16x16x32_bf16 v[100:103], v[152:155], v[168:171], 0
	v_mfma_f32_16x16x32_bf16 v[104:107], v[144:147], v[168:171], 0
	v_mfma_f32_16x16x32_bf16 v[84:87], v[144:147], v[176:179], 0
	v_mfma_f32_16x16x32_bf16 v[80:83], v[152:155], v[176:179], 0
	v_mfma_f32_16x16x32_bf16 v[64:67], v[152:155], v[202:205], 0
	v_mfma_f32_16x16x32_bf16 v[68:71], v[144:147], v[202:205], 0
	v_mfma_f32_16x16x32_bf16 v[132:135], v[148:151], v[164:167], v[132:135]
	v_mfma_f32_16x16x32_bf16 v[124:127], v[156:159], v[164:167], v[124:127]
	v_mfma_f32_16x16x32_bf16 v[100:103], v[156:159], v[172:175], v[100:103]
	v_mfma_f32_16x16x32_bf16 v[104:107], v[148:151], v[172:175], v[104:107]
	v_mfma_f32_16x16x32_bf16 v[84:87], v[148:151], v[180:183], v[84:87]
	v_mfma_f32_16x16x32_bf16 v[80:83], v[156:159], v[180:183], v[80:83]
	v_mfma_f32_16x16x32_bf16 v[64:67], v[156:159], v[206:209], v[64:67]
	v_mfma_f32_16x16x32_bf16 v[68:71], v[148:151], v[206:209], v[68:71]
	s_barrier
	s_add_i32 s77, s71, s58
	s_add_u32 s98, s54, s12
	s_addc_u32 s99, s55, s13
	s_add_u32 s100, s56, s12
	s_addc_u32 s101, s57, s13
	s_mov_b32 m0, s77
	ds_read_b128 v[160:163], v225 offset:16384
	ds_read_b128 v[164:167], v225 offset:17408
	ds_read_b128 v[168:171], v225 offset:18432
	ds_read_b128 v[172:175], v225 offset:19456
	ds_read_b128 v[176:179], v225 offset:20480
	ds_read_b128 v[180:183], v225 offset:21504
	ds_read_b128 v[202:205], v225 offset:22528
	ds_read_b128 v[206:209], v225 offset:23552
	global_load_lds_dwordx4 v186, s[54:55]
	s_add_i32 m0, s77, 0x2000
	s_add_u32 s78, s54, 0x40000
	s_addc_u32 s79, s55, 0
	s_add_i32 s77, s72, s58
	global_load_lds_dwordx4 v190, s[54:55]
	s_mov_b32 m0, s77
	s_nop 0
	global_load_lds_dwordx4 v186, s[78:79]
	s_add_i32 m0, s77, 0x2000
	s_nop 0
	global_load_lds_dwordx4 v190, s[78:79]
	s_mov_b32 m0, s53
	s_nop 0
	global_load_lds_dwordx4 v184, s[56:57]
	s_mov_b32 m0, s59
	s_nop 0
	global_load_lds_dwordx4 v188, s[56:57]
	s_waitcnt vmcnt(8)
	s_waitcnt lgkmcnt(0)
	s_barrier
; #define PG8_STAGE(bufoff, gbase, voff) do { _Pragma("unroll") for (int _i = 0; _i < 2; ++_i) \
;         __builtin_amdgcn_global_load_lds((const unsigned*)((const char*)(gbase) + (voff)[_i]), (PG8_LAS unsigned*)(lds + (bufoff) + ldsw + _i * 8192), 16, 0, 0); } while (0)
; #define PG8_LDA(dst, b, h) do { _Pragma("unroll") for (int m = 0; m < 4; ++m) _Pragma("unroll") for (int k = 0; k < 2; ++k) dst[m][k] = *(const PG8_LAS bf16x8*)(lds + PG8_SA(b, h) + aoff + m * 2048 + k * 1024); } while (0)
; #define PG8_LDB(dst, b, h) do { _Pragma("unroll") for (int n = 0; n < 2; ++n) _Pragma("unroll") for (int k = 0; k < 2; ++k) dst[n][k] = *(const PG8_LAS bf16x8*)(lds + PG8_SB(b, h) + boff + n * 2048 + k * 1024); } while (0)
; #define PG8_MMA(ai, bj, At, Bt) do { __builtin_amdgcn_s_setprio(1); _Pragma("unroll") for (int m = 0; m < 4; ++m) _Pragma("unroll") for (int n = 0; n < 2; ++n) _Pragma("unroll") for (int k = 0; k < 2; ++k) \
;         acc[ai][bj][m][n] = __builtin_amdgcn_mfma_f32_16x16x32_bf16(Bt[n][k], At[m][k], acc[ai][bj][m][n], 0, 0, 0); __builtin_amdgcn_s_setprio(0); } while (0)
; #define PG8_WAIT_V(n) asm volatile("s_waitcnt vmcnt(" #n ")" ::: "memory")
; #define PG8_WAIT_L(n) asm volatile("s_waitcnt lgkmcnt(" #n ")" ::: "memory")
; #define PG8_BAR __builtin_amdgcn_s_barrier()
; #define PG8_SCHED __builtin_amdgcn_sched_barrier(0)
; template <class Epi, class Sched, bool ALIGN_EPI = false, bool SP2 = false>
; __device__ __forceinline__ void gemm_phase(PG8_LAS unsigned char* lds, const Gemm g, const Sched& S, const Epi& E) {
;     ...
;             PG8_LDA(At, 0, 1); PG8_STAGE(PG8_SB(0, 0), b2, voffB); PG8_STAGE(PG8_SB(0, 1), b2 + hstep, voffB); PG8_STAGE(PG8_SA(0, 0), a2, voffA);
;             PG8_WAIT_V(8); PG8_WAIT_L(0); PG8_BAR; PG8_MMA(1, 0, At, B0); PG8_MMA(1, 1, At, B1); PG8_BAR; PG8_SCHED;
;             PG8_LDB(B0, 1, 0); PG8_LDB(B1, 1, 1); PG8_SCHED; PG8_LDA(At, 1, 0); PG8_STAGE(PG8_SA(0, 1), a2 + hstep, voffA);
;             PG8_WAIT_V(8); PG8_WAIT_L(0); PG8_BAR; PG8_MMA(0, 0, At, B0); PG8_MMA(0, 1, At, B1); PG8_BAR; PG8_SCHED;
	v_mfma_f32_16x16x32_bf16 v[60:63], v[96:99], v[160:163], 0
	v_mfma_f32_16x16x32_bf16 v[56:59], v[120:123], v[160:163], 0
	v_mfma_f32_16x16x32_bf16 v[40:43], v[120:123], v[168:171], 0
	v_mfma_f32_16x16x32_bf16 v[44:47], v[96:99], v[168:171], 0
	v_mfma_f32_16x16x32_bf16 v[28:31], v[96:99], v[176:179], 0
	v_mfma_f32_16x16x32_bf16 v[24:27], v[120:123], v[176:179], 0
	v_mfma_f32_16x16x32_bf16 v[8:11], v[120:123], v[202:205], 0
	v_mfma_f32_16x16x32_bf16 v[12:15], v[96:99], v[202:205], 0
	v_mfma_f32_16x16x32_bf16 v[60:63], v[108:111], v[164:167], v[60:63]
	v_mfma_f32_16x16x32_bf16 v[56:59], v[128:131], v[164:167], v[56:59]
	v_mfma_f32_16x16x32_bf16 v[40:43], v[128:131], v[172:175], v[40:43]
	v_mfma_f32_16x16x32_bf16 v[44:47], v[108:111], v[172:175], v[44:47]
	v_mfma_f32_16x16x32_bf16 v[28:31], v[108:111], v[180:183], v[28:31]
	v_mfma_f32_16x16x32_bf16 v[24:27], v[128:131], v[180:183], v[24:27]
	v_mfma_f32_16x16x32_bf16 v[8:11], v[128:131], v[206:209], v[8:11]
	v_mfma_f32_16x16x32_bf16 v[12:15], v[108:111], v[206:209], v[12:15]
	v_mfma_f32_16x16x32_bf16 v[52:55], v[144:147], v[160:163], 0
	v_mfma_f32_16x16x32_bf16 v[48:51], v[152:155], v[160:163], 0
	v_mfma_f32_16x16x32_bf16 v[32:35], v[152:155], v[168:171], 0
	v_mfma_f32_16x16x32_bf16 v[36:39], v[144:147], v[168:171], 0
	v_mfma_f32_16x16x32_bf16 v[20:23], v[144:147], v[176:179], 0
	v_mfma_f32_16x16x32_bf16 v[16:19], v[152:155], v[176:179], 0
	v_mfma_f32_16x16x32_bf16 v[0:3], v[152:155], v[202:205], 0
	v_mfma_f32_16x16x32_bf16 v[4:7], v[144:147], v[202:205], 0
	v_mfma_f32_16x16x32_bf16 v[52:55], v[148:151], v[164:167], v[52:55]
	v_mfma_f32_16x16x32_bf16 v[48:51], v[156:159], v[164:167], v[48:51]
	v_mfma_f32_16x16x32_bf16 v[32:35], v[156:159], v[172:175], v[32:35]
	v_mfma_f32_16x16x32_bf16 v[36:39], v[148:151], v[172:175], v[36:39]
	v_mfma_f32_16x16x32_bf16 v[20:23], v[148:151], v[180:183], v[20:23]
	v_mfma_f32_16x16x32_bf16 v[16:19], v[156:159], v[180:183], v[16:19]
	v_mfma_f32_16x16x32_bf16 v[0:3], v[156:159], v[206:209], v[0:3]
	v_mfma_f32_16x16x32_bf16 v[4:7], v[148:151], v[206:209], v[4:7]
	s_barrier
	s_add_i32 s77, 0, 0x18000
	s_add_i32 s78, 0, 0x1c000
	v_add_u32_e32 v128, s77, v221
	v_add_u32_e32 v156, s78, v221
	ds_read_b128 v[96:99], v128
	ds_read_b128 v[108:111], v128 offset:1024
	ds_read_b128 v[120:123], v128 offset:2048
	ds_read_b128 v[128:131], v128 offset:3072
	ds_read_b128 v[144:147], v156
	ds_read_b128 v[148:151], v156 offset:1024
	ds_read_b128 v[152:155], v156 offset:2048
	ds_read_b128 v[156:159], v156 offset:3072
	s_add_u32 s56, s56, 0x40000
	s_addc_u32 s57, s57, 0
	s_mov_b32 m0, s60
	ds_read_b128 v[160:163], v225 offset:32768
	ds_read_b128 v[164:167], v225 offset:33792
	ds_read_b128 v[168:171], v225 offset:34816
	ds_read_b128 v[172:175], v225 offset:35840
	ds_read_b128 v[176:179], v225 offset:36864
	ds_read_b128 v[180:183], v225 offset:37888
	ds_read_b128 v[202:205], v225 offset:38912
	ds_read_b128 v[206:209], v225 offset:39936
	global_load_lds_dwordx4 v184, s[56:57]
	s_mov_b32 m0, s61
	s_nop 0
	global_load_lds_dwordx4 v188, s[56:57]
	s_waitcnt vmcnt(8)
	s_waitcnt lgkmcnt(0)
	s_barrier
	v_mfma_f32_16x16x32_bf16 v[140:143], v[96:99], v[160:163], v[140:143]
	v_mfma_f32_16x16x32_bf16 v[136:139], v[120:123], v[160:163], v[136:139]
	v_mfma_f32_16x16x32_bf16 v[112:115], v[120:123], v[168:171], v[112:115]
	v_mfma_f32_16x16x32_bf16 v[116:119], v[96:99], v[168:171], v[116:119]
	v_mfma_f32_16x16x32_bf16 v[92:95], v[96:99], v[176:179], v[92:95]
	v_mfma_f32_16x16x32_bf16 v[88:91], v[120:123], v[176:179], v[88:91]
	v_mfma_f32_16x16x32_bf16 v[72:75], v[120:123], v[202:205], v[72:75]
	v_mfma_f32_16x16x32_bf16 v[76:79], v[96:99], v[202:205], v[76:79]
	v_mfma_f32_16x16x32_bf16 v[140:143], v[108:111], v[164:167], v[140:143]
	v_mfma_f32_16x16x32_bf16 v[136:139], v[128:131], v[164:167], v[136:139]
	v_mfma_f32_16x16x32_bf16 v[112:115], v[128:131], v[172:175], v[112:115]
	v_mfma_f32_16x16x32_bf16 v[116:119], v[108:111], v[172:175], v[116:119]
	v_mfma_f32_16x16x32_bf16 v[92:95], v[108:111], v[180:183], v[92:95]
	v_mfma_f32_16x16x32_bf16 v[88:91], v[128:131], v[180:183], v[88:91]
	v_mfma_f32_16x16x32_bf16 v[72:75], v[128:131], v[206:209], v[72:75]
	v_mfma_f32_16x16x32_bf16 v[76:79], v[108:111], v[206:209], v[76:79]
	v_mfma_f32_16x16x32_bf16 v[132:135], v[144:147], v[160:163], v[132:135]
	v_mfma_f32_16x16x32_bf16 v[124:127], v[152:155], v[160:163], v[124:127]
	v_mfma_f32_16x16x32_bf16 v[100:103], v[152:155], v[168:171], v[100:103]
	v_mfma_f32_16x16x32_bf16 v[104:107], v[144:147], v[168:171], v[104:107]
	v_mfma_f32_16x16x32_bf16 v[84:87], v[144:147], v[176:179], v[84:87]
	v_mfma_f32_16x16x32_bf16 v[80:83], v[152:155], v[176:179], v[80:83]
	v_mfma_f32_16x16x32_bf16 v[64:67], v[152:155], v[202:205], v[64:67]
	v_mfma_f32_16x16x32_bf16 v[68:71], v[144:147], v[202:205], v[68:71]
	v_mfma_f32_16x16x32_bf16 v[132:135], v[148:151], v[164:167], v[132:135]
	v_mfma_f32_16x16x32_bf16 v[124:127], v[156:159], v[164:167], v[124:127]
	v_mfma_f32_16x16x32_bf16 v[100:103], v[156:159], v[172:175], v[100:103]
	v_mfma_f32_16x16x32_bf16 v[104:107], v[148:151], v[172:175], v[104:107]
	v_mfma_f32_16x16x32_bf16 v[84:87], v[148:151], v[180:183], v[84:87]
	v_mfma_f32_16x16x32_bf16 v[80:83], v[156:159], v[180:183], v[80:83]
	v_mfma_f32_16x16x32_bf16 v[64:67], v[156:159], v[206:209], v[64:67]
	v_mfma_f32_16x16x32_bf16 v[68:71], v[148:151], v[206:209], v[68:71]
	s_barrier
; #define PG8_STAGE(bufoff, gbase, voff) do { _Pragma("unroll") for (int _i = 0; _i < 2; ++_i) \
;         __builtin_amdgcn_global_load_lds((const unsigned*)((const char*)(gbase) + (voff)[_i]), (PG8_LAS unsigned*)(lds + (bufoff) + ldsw + _i * 8192), 16, 0, 0); } while (0)
; #define PG8_LDA(dst, b, h) do { _Pragma("unroll") for (int m = 0; m < 4; ++m) _Pragma("unroll") for (int k = 0; k < 2; ++k) dst[m][k] = *(const PG8_LAS bf16x8*)(lds + PG8_SA(b, h) + aoff + m * 2048 + k * 1024); } while (0)
; #define PG8_LDB(dst, b, h) do { _Pragma("unroll") for (int n = 0; n < 2; ++n) _Pragma("unroll") for (int k = 0; k < 2; ++k) dst[n][k] = *(const PG8_LAS bf16x8*)(lds + PG8_SB(b, h) + boff + n * 2048 + k * 1024); } while (0)
; #define PG8_MMA(ai, bj, At, Bt) do { __builtin_amdgcn_s_setprio(1); _Pragma("unroll") for (int m = 0; m < 4; ++m) _Pragma("unroll") for (int n = 0; n < 2; ++n) _Pragma("unroll") for (int k = 0; k < 2; ++k) \
;         acc[ai][bj][m][n] = __builtin_amdgcn_mfma_f32_16x16x32_bf16(Bt[n][k], At[m][k], acc[ai][bj][m][n], 0, 0, 0); __builtin_amdgcn_s_setprio(0); } while (0)
; #define PG8_WAIT_V(n) asm volatile("s_waitcnt vmcnt(" #n ")" ::: "memory")
; template <class Epi, class Sched, bool ALIGN_EPI = false, bool SP2 = false>
; __device__ __forceinline__ void gemm_phase(PG8_LAS unsigned char* lds, const Gemm g, const Sched& S, const Epi& E) {
;     ...
;             PG8_LDB(B0, 0, 0); PG8_LDB(B1, 0, 1); PG8_SCHED; PG8_LDA(At, 0, 0); PG8_STAGE(PG8_SA(1, 1), a1 + hstep, voffA);
;             PG8_WAIT_V(8); PG8_WAIT_L(0); PG8_BAR; PG8_MMA(0, 0, At, B0); PG8_MMA(0, 1, At, B1); PG8_BAR; PG8_SCHED;
;             PG8_LDA(At, 0, 1); PG8_STAGE(PG8_SB(0, 0), b2, voffB); PG8_STAGE(PG8_SB(0, 1), b2 + hstep, voffB); PG8_STAGE(PG8_SA(0, 0), a2, voffA);
;             PG8_WAIT_V(8); PG8_WAIT_L(0); PG8_BAR; PG8_MMA(1, 0, At, B0); PG8_MMA(1, 1, At, B1); PG8_BAR; PG8_SCHED;
;             PG8_LDB(B0, 1, 0); PG8_LDB(B1, 1, 1); PG8_SCHED; PG8_LDA(At, 1, 0); PG8_STAGE(PG8_SA(0, 1), a2 + hstep, voffA);
;             PG8_WAIT_V(8); PG8_WAIT_L(0); PG8_BAR; PG8_MMA(0, 0, At, B0); PG8_MMA(0, 1, At, B1); PG8_BAR; PG8_SCHED;
;             PG8_LDA(At, 1, 1); PG8_STAGE(PG8_SB(1, 0), b3, voffB); PG8_STAGE(PG8_SB(1, 1), b3 + hstep, voffB); PG8_STAGE(PG8_SA(1, 0), a3, voffA);
;             PG8_WAIT_V(8); PG8_WAIT_L(0); PG8_BAR; PG8_MMA(1, 0, At, B0); PG8_MMA(1, 1, At, B1); PG8_BAR; PG8_SCHED;
	s_add_i32 s56, s77, s58
	s_mov_b32 m0, s56
	ds_read_b128 v[160:163], v225 offset:49152
	ds_read_b128 v[164:167], v225 offset:50176
	ds_read_b128 v[168:171], v225 offset:51200
	ds_read_b128 v[172:175], v225 offset:52224
	ds_read_b128 v[176:179], v225 offset:53248
	ds_read_b128 v[180:183], v225 offset:54272
	ds_read_b128 v[202:205], v225 offset:55296
	ds_read_b128 v[206:209], v225 offset:56320
	global_load_lds_dwordx4 v186, s[98:99]
	s_add_i32 m0, s56, 0x2000
	s_add_u32 s54, s54, 0x40080
	s_addc_u32 s55, s55, 0
	s_add_i32 s56, s78, s58
	global_load_lds_dwordx4 v190, s[98:99]
	s_mov_b32 m0, s56
	s_nop 0
	global_load_lds_dwordx4 v186, s[54:55]
	s_add_i32 m0, s56, 0x2000
	s_nop 0
	global_load_lds_dwordx4 v190, s[54:55]
	s_mov_b32 m0, s66
	s_nop 0
	global_load_lds_dwordx4 v184, s[100:101]
	s_mov_b32 m0, s67
	s_nop 0
	global_load_lds_dwordx4 v188, s[100:101]
	s_waitcnt vmcnt(8)
	s_waitcnt lgkmcnt(0)
	s_barrier
	v_mfma_f32_16x16x32_bf16 v[60:63], v[96:99], v[160:163], v[60:63]
	v_mfma_f32_16x16x32_bf16 v[56:59], v[120:123], v[160:163], v[56:59]
	v_mfma_f32_16x16x32_bf16 v[40:43], v[120:123], v[168:171], v[40:43]
	v_mfma_f32_16x16x32_bf16 v[44:47], v[96:99], v[168:171], v[44:47]
	v_mfma_f32_16x16x32_bf16 v[28:31], v[96:99], v[176:179], v[28:31]
	v_mfma_f32_16x16x32_bf16 v[24:27], v[120:123], v[176:179], v[24:27]
	v_mfma_f32_16x16x32_bf16 v[8:11], v[120:123], v[202:205], v[8:11]
	v_mfma_f32_16x16x32_bf16 v[12:15], v[96:99], v[202:205], v[12:15]
	v_mfma_f32_16x16x32_bf16 v[60:63], v[108:111], v[164:167], v[60:63]
	v_mfma_f32_16x16x32_bf16 v[56:59], v[128:131], v[164:167], v[56:59]
	v_mfma_f32_16x16x32_bf16 v[40:43], v[128:131], v[172:175], v[40:43]
	v_mfma_f32_16x16x32_bf16 v[44:47], v[108:111], v[172:175], v[44:47]
	v_mfma_f32_16x16x32_bf16 v[28:31], v[108:111], v[180:183], v[28:31]
	v_mfma_f32_16x16x32_bf16 v[24:27], v[128:131], v[180:183], v[24:27]
	v_mfma_f32_16x16x32_bf16 v[8:11], v[128:131], v[206:209], v[8:11]
	v_mfma_f32_16x16x32_bf16 v[12:15], v[108:111], v[206:209], v[12:15]
	v_mfma_f32_16x16x32_bf16 v[52:55], v[144:147], v[160:163], v[52:55]
	v_mfma_f32_16x16x32_bf16 v[48:51], v[152:155], v[160:163], v[48:51]
	v_mfma_f32_16x16x32_bf16 v[32:35], v[152:155], v[168:171], v[32:35]
	v_mfma_f32_16x16x32_bf16 v[36:39], v[144:147], v[168:171], v[36:39]
	v_mfma_f32_16x16x32_bf16 v[20:23], v[144:147], v[176:179], v[20:23]
	v_mfma_f32_16x16x32_bf16 v[16:19], v[152:155], v[176:179], v[16:19]
	v_mfma_f32_16x16x32_bf16 v[0:3], v[152:155], v[202:205], v[0:3]
	v_mfma_f32_16x16x32_bf16 v[4:7], v[144:147], v[202:205], v[4:7]
	v_mfma_f32_16x16x32_bf16 v[52:55], v[148:151], v[164:167], v[52:55]
	v_mfma_f32_16x16x32_bf16 v[48:51], v[156:159], v[164:167], v[48:51]
	v_mfma_f32_16x16x32_bf16 v[32:35], v[156:159], v[172:175], v[32:35]
	v_mfma_f32_16x16x32_bf16 v[36:39], v[148:151], v[172:175], v[36:39]
	v_mfma_f32_16x16x32_bf16 v[20:23], v[148:151], v[180:183], v[20:23]
	v_mfma_f32_16x16x32_bf16 v[16:19], v[156:159], v[180:183], v[16:19]
	v_mfma_f32_16x16x32_bf16 v[0:3], v[156:159], v[206:209], v[0:3]
	v_mfma_f32_16x16x32_bf16 v[4:7], v[148:151], v[206:209], v[4:7]
	s_barrier
	s_add_i32 s76, s76, 2
	s_add_u32 s20, s20, 0x100
	s_addc_u32 s21, s21, 0
	s_add_u32 s74, s74, 0x100
	s_addc_u32 s75, s75, 0
	s_cmp_gt_u32 s76, 13
.LBB0_705:
	ds_read_b128 v[96:99], v223
	ds_read_b128 v[108:111], v223 offset:1024
	ds_read_b128 v[120:123], v223 offset:2048
	ds_read_b128 v[128:131], v223 offset:3072
	ds_read_b128 v[144:147], v224
	ds_read_b128 v[148:151], v224 offset:1024
	ds_read_b128 v[152:155], v224 offset:2048
	ds_read_b128 v[156:159], v224 offset:3072
	s_add_u32 s54, s20, 0xfffc0080
	s_addc_u32 s55, s21, -1
	s_cmp_eq_u32 s76, 12
	s_cselect_b32 s57, s35, s55
	s_cselect_b32 s56, s47, s54
	s_cselect_b32 s55, s45, s75
	s_cselect_b32 s54, s73, s74
	s_add_i32 m0, s53, 0xc000
	ds_read_b128 v[160:163], v225
	ds_read_b128 v[164:167], v225 offset:1024
	ds_read_b128 v[168:171], v225 offset:2048
	ds_read_b128 v[172:175], v225 offset:3072
	ds_read_b128 v[176:179], v225 offset:4096
	ds_read_b128 v[180:183], v225 offset:5120
	ds_read_b128 v[202:205], v225 offset:6144
	ds_read_b128 v[206:209], v225 offset:7168
	global_load_lds_dwordx4 v192, s[20:21]
	s_add_i32 m0, s53, 0xe000
	s_nop 0
	global_load_lds_dwordx4 v194, s[20:21]
	s_waitcnt vmcnt(8)
	s_waitcnt lgkmcnt(0)
	s_barrier
	v_mfma_f32_16x16x32_bf16 v[140:143], v[96:99], v[160:163], v[140:143]
	v_mfma_f32_16x16x32_bf16 v[136:139], v[120:123], v[160:163], v[136:139]
	v_mfma_f32_16x16x32_bf16 v[112:115], v[120:123], v[168:171], v[112:115]
	v_mfma_f32_16x16x32_bf16 v[116:119], v[96:99], v[168:171], v[116:119]
	v_mfma_f32_16x16x32_bf16 v[92:95], v[96:99], v[176:179], v[92:95]
	v_mfma_f32_16x16x32_bf16 v[88:91], v[120:123], v[176:179], v[88:91]
	v_mfma_f32_16x16x32_bf16 v[72:75], v[120:123], v[202:205], v[72:75]
	v_mfma_f32_16x16x32_bf16 v[76:79], v[96:99], v[202:205], v[76:79]
	v_mfma_f32_16x16x32_bf16 v[140:143], v[108:111], v[164:167], v[140:143]
	v_mfma_f32_16x16x32_bf16 v[136:139], v[128:131], v[164:167], v[136:139]
	v_mfma_f32_16x16x32_bf16 v[112:115], v[128:131], v[172:175], v[112:115]
	v_mfma_f32_16x16x32_bf16 v[116:119], v[108:111], v[172:175], v[116:119]
	v_mfma_f32_16x16x32_bf16 v[92:95], v[108:111], v[180:183], v[92:95]
	v_mfma_f32_16x16x32_bf16 v[88:91], v[128:131], v[180:183], v[88:91]
	v_mfma_f32_16x16x32_bf16 v[72:75], v[128:131], v[206:209], v[72:75]
	v_mfma_f32_16x16x32_bf16 v[76:79], v[108:111], v[206:209], v[76:79]
	v_mfma_f32_16x16x32_bf16 v[132:135], v[144:147], v[160:163], v[132:135]
	v_mfma_f32_16x16x32_bf16 v[124:127], v[152:155], v[160:163], v[124:127]
	v_mfma_f32_16x16x32_bf16 v[100:103], v[152:155], v[168:171], v[100:103]
	v_mfma_f32_16x16x32_bf16 v[104:107], v[144:147], v[168:171], v[104:107]
	v_mfma_f32_16x16x32_bf16 v[84:87], v[144:147], v[176:179], v[84:87]
	v_mfma_f32_16x16x32_bf16 v[80:83], v[152:155], v[176:179], v[80:83]
	v_mfma_f32_16x16x32_bf16 v[64:67], v[152:155], v[202:205], v[64:67]
	v_mfma_f32_16x16x32_bf16 v[68:71], v[144:147], v[202:205], v[68:71]
	v_mfma_f32_16x16x32_bf16 v[132:135], v[148:151], v[164:167], v[132:135]
	v_mfma_f32_16x16x32_bf16 v[124:127], v[156:159], v[164:167], v[124:127]
	v_mfma_f32_16x16x32_bf16 v[100:103], v[156:159], v[172:175], v[100:103]
	v_mfma_f32_16x16x32_bf16 v[104:107], v[148:151], v[172:175], v[104:107]
	v_mfma_f32_16x16x32_bf16 v[84:87], v[148:151], v[180:183], v[84:87]
	v_mfma_f32_16x16x32_bf16 v[80:83], v[156:159], v[180:183], v[80:83]
	v_mfma_f32_16x16x32_bf16 v[64:67], v[156:159], v[206:209], v[64:67]
	v_mfma_f32_16x16x32_bf16 v[68:71], v[148:151], v[206:209], v[68:71]
	s_barrier
; #define PG8_STAGE(bufoff, gbase, voff) do { _Pragma("unroll") for (int _i = 0; _i < 2; ++_i) \
;         __builtin_amdgcn_global_load_lds((const unsigned*)((const char*)(gbase) + (voff)[_i]), (PG8_LAS unsigned*)(lds + (bufoff) + ldsw + _i * 8192), 16, 0, 0); } while (0)
; #define PG8_LDA(dst, b, h) do { _Pragma("unroll") for (int m = 0; m < 4; ++m) _Pragma("unroll") for (int k = 0; k < 2; ++k) dst[m][k] = *(const PG8_LAS bf16x8*)(lds + PG8_SA(b, h) + aoff + m * 2048 + k * 1024); } while (0)
; #define PG8_LDB(dst, b, h) do { _Pragma("unroll") for (int n = 0; n < 2; ++n) _Pragma("unroll") for (int k = 0; k < 2; ++k) dst[n][k] = *(const PG8_LAS bf16x8*)(lds + PG8_SB(b, h) + boff + n * 2048 + k * 1024); } while (0)
; #define PG8_MMA(ai, bj, At, Bt) do { __builtin_amdgcn_s_setprio(1); _Pragma("unroll") for (int m = 0; m < 4; ++m) _Pragma("unroll") for (int n = 0; n < 2; ++n) _Pragma("unroll") for (int k = 0; k < 2; ++k) \
;         acc[ai][bj][m][n] = __builtin_amdgcn_mfma_f32_16x16x32_bf16(Bt[n][k], At[m][k], acc[ai][bj][m][n], 0, 0, 0); __builtin_amdgcn_s_setprio(0); } while (0)
; #define PG8_WAIT_V(n) asm volatile("s_waitcnt vmcnt(" #n ")" ::: "memory")
; #define PG8_WAIT_L(n) asm volatile("s_waitcnt lgkmcnt(" #n ")" ::: "memory")
; #define PG8_BAR __builtin_amdgcn_s_barrier()
; #define PG8_SCHED __builtin_amdgcn_sched_barrier(0)
; template <class Epi, class Sched, bool ALIGN_EPI = false, bool SP2 = false>
; __device__ __forceinline__ void gemm_phase(PG8_LAS unsigned char* lds, const Gemm g, const Sched& S, const Epi& E) {
;     ...
;             PG8_LDA(At, 0, 1); PG8_STAGE(PG8_SB(0, 0), b2, voffB); PG8_STAGE(PG8_SB(0, 1), b2 + hstep, voffB); PG8_STAGE(PG8_SA(0, 0), a2, voffA);
;             PG8_WAIT_V(8); PG8_WAIT_L(0); PG8_BAR; PG8_MMA(1, 0, At, B0); PG8_MMA(1, 1, At, B1); PG8_BAR; PG8_SCHED;
;             PG8_LDB(B0, 1, 0); PG8_LDB(B1, 1, 1); PG8_SCHED; PG8_LDA(At, 1, 0); PG8_STAGE(PG8_SA(0, 1), a2 + hstep, voffA);
;             PG8_WAIT_V(8); PG8_WAIT_L(0); PG8_BAR; PG8_MMA(0, 0, At, B0); PG8_MMA(0, 1, At, B1); PG8_BAR; PG8_SCHED;
	s_add_i32 s77, s71, s58
	s_add_u32 s98, s54, s12
	s_addc_u32 s99, s55, s13
	s_add_u32 s100, s56, s12
	s_addc_u32 s101, s57, s13
	s_mov_b32 m0, s77
	ds_read_b128 v[160:163], v225 offset:16384
	ds_read_b128 v[164:167], v225 offset:17408
	ds_read_b128 v[168:171], v225 offset:18432
	ds_read_b128 v[172:175], v225 offset:19456
	ds_read_b128 v[176:179], v225 offset:20480
	ds_read_b128 v[180:183], v225 offset:21504
	ds_read_b128 v[202:205], v225 offset:22528
	ds_read_b128 v[206:209], v225 offset:23552
	global_load_lds_dwordx4 v186, s[54:55]
	s_add_i32 m0, s77, 0x2000
	s_add_u32 s78, s54, 0x40000
	s_addc_u32 s79, s55, 0
	s_add_i32 s77, s72, s58
	global_load_lds_dwordx4 v190, s[54:55]
	s_mov_b32 m0, s77
	s_nop 0
	global_load_lds_dwordx4 v186, s[78:79]
	s_add_i32 m0, s77, 0x2000
	s_nop 0
	global_load_lds_dwordx4 v190, s[78:79]
	s_mov_b32 m0, s53
	s_nop 0
	global_load_lds_dwordx4 v184, s[56:57]
	s_mov_b32 m0, s59
	s_nop 0
	global_load_lds_dwordx4 v188, s[56:57]
	s_waitcnt vmcnt(8)
	s_waitcnt lgkmcnt(0)
	s_barrier
	v_mfma_f32_16x16x32_bf16 v[60:63], v[96:99], v[160:163], v[60:63]
	v_mfma_f32_16x16x32_bf16 v[56:59], v[120:123], v[160:163], v[56:59]
	v_mfma_f32_16x16x32_bf16 v[40:43], v[120:123], v[168:171], v[40:43]
	v_mfma_f32_16x16x32_bf16 v[44:47], v[96:99], v[168:171], v[44:47]
	v_mfma_f32_16x16x32_bf16 v[28:31], v[96:99], v[176:179], v[28:31]
	v_mfma_f32_16x16x32_bf16 v[24:27], v[120:123], v[176:179], v[24:27]
	v_mfma_f32_16x16x32_bf16 v[8:11], v[120:123], v[202:205], v[8:11]
	v_mfma_f32_16x16x32_bf16 v[12:15], v[96:99], v[202:205], v[12:15]
	v_mfma_f32_16x16x32_bf16 v[60:63], v[108:111], v[164:167], v[60:63]
	v_mfma_f32_16x16x32_bf16 v[56:59], v[128:131], v[164:167], v[56:59]
	v_mfma_f32_16x16x32_bf16 v[40:43], v[128:131], v[172:175], v[40:43]
	v_mfma_f32_16x16x32_bf16 v[44:47], v[108:111], v[172:175], v[44:47]
	v_mfma_f32_16x16x32_bf16 v[28:31], v[108:111], v[180:183], v[28:31]
	v_mfma_f32_16x16x32_bf16 v[24:27], v[128:131], v[180:183], v[24:27]
	v_mfma_f32_16x16x32_bf16 v[8:11], v[128:131], v[206:209], v[8:11]
	v_mfma_f32_16x16x32_bf16 v[12:15], v[108:111], v[206:209], v[12:15]
	v_mfma_f32_16x16x32_bf16 v[52:55], v[144:147], v[160:163], v[52:55]
	v_mfma_f32_16x16x32_bf16 v[48:51], v[152:155], v[160:163], v[48:51]
	v_mfma_f32_16x16x32_bf16 v[32:35], v[152:155], v[168:171], v[32:35]
	v_mfma_f32_16x16x32_bf16 v[36:39], v[144:147], v[168:171], v[36:39]
	v_mfma_f32_16x16x32_bf16 v[20:23], v[144:147], v[176:179], v[20:23]
	v_mfma_f32_16x16x32_bf16 v[16:19], v[152:155], v[176:179], v[16:19]
	v_mfma_f32_16x16x32_bf16 v[0:3], v[152:155], v[202:205], v[0:3]
	v_mfma_f32_16x16x32_bf16 v[4:7], v[144:147], v[202:205], v[4:7]
	v_mfma_f32_16x16x32_bf16 v[52:55], v[148:151], v[164:167], v[52:55]
	v_mfma_f32_16x16x32_bf16 v[48:51], v[156:159], v[164:167], v[48:51]
	v_mfma_f32_16x16x32_bf16 v[32:35], v[156:159], v[172:175], v[32:35]
	v_mfma_f32_16x16x32_bf16 v[36:39], v[148:151], v[172:175], v[36:39]
	v_mfma_f32_16x16x32_bf16 v[20:23], v[148:151], v[180:183], v[20:23]
	v_mfma_f32_16x16x32_bf16 v[16:19], v[156:159], v[180:183], v[16:19]
	v_mfma_f32_16x16x32_bf16 v[0:3], v[156:159], v[206:209], v[0:3]
	v_mfma_f32_16x16x32_bf16 v[4:7], v[148:151], v[206:209], v[4:7]
	s_barrier
	s_add_i32 s77, 0, 0x18000
	s_add_i32 s78, 0, 0x1c000
	v_add_u32_e32 v128, s77, v221
	v_add_u32_e32 v156, s78, v221
	ds_read_b128 v[96:99], v128
	ds_read_b128 v[108:111], v128 offset:1024
	ds_read_b128 v[120:123], v128 offset:2048
	ds_read_b128 v[128:131], v128 offset:3072
	ds_read_b128 v[144:147], v156
	ds_read_b128 v[148:151], v156 offset:1024
	ds_read_b128 v[152:155], v156 offset:2048
	ds_read_b128 v[156:159], v156 offset:3072
	s_add_u32 s56, s56, 0x40000
	s_addc_u32 s57, s57, 0
	s_mov_b32 m0, s60
	ds_read_b128 v[160:163], v225 offset:32768
	ds_read_b128 v[164:167], v225 offset:33792
	ds_read_b128 v[168:171], v225 offset:34816
	ds_read_b128 v[172:175], v225 offset:35840
	ds_read_b128 v[176:179], v225 offset:36864
	ds_read_b128 v[180:183], v225 offset:37888
	ds_read_b128 v[202:205], v225 offset:38912
	ds_read_b128 v[206:209], v225 offset:39936
	global_load_lds_dwordx4 v184, s[56:57]
	s_mov_b32 m0, s61
	s_nop 0
	global_load_lds_dwordx4 v188, s[56:57]
	s_waitcnt vmcnt(8)
	s_waitcnt lgkmcnt(0)
	s_barrier
; #define PG8_STAGE(bufoff, gbase, voff) do { _Pragma("unroll") for (int _i = 0; _i < 2; ++_i) \
;         __builtin_amdgcn_global_load_lds((const unsigned*)((const char*)(gbase) + (voff)[_i]), (PG8_LAS unsigned*)(lds + (bufoff) + ldsw + _i * 8192), 16, 0, 0); } while (0)
; #define PG8_LDA(dst, b, h) do { _Pragma("unroll") for (int m = 0; m < 4; ++m) _Pragma("unroll") for (int k = 0; k < 2; ++k) dst[m][k] = *(const PG8_LAS bf16x8*)(lds + PG8_SA(b, h) + aoff + m * 2048 + k * 1024); } while (0)
; #define PG8_MMA(ai, bj, At, Bt) do { __builtin_amdgcn_s_setprio(1); _Pragma("unroll") for (int m = 0; m < 4; ++m) _Pragma("unroll") for (int n = 0; n < 2; ++n) _Pragma("unroll") for (int k = 0; k < 2; ++k) \
;         acc[ai][bj][m][n] = __builtin_amdgcn_mfma_f32_16x16x32_bf16(Bt[n][k], At[m][k], acc[ai][bj][m][n], 0, 0, 0); __builtin_amdgcn_s_setprio(0); } while (0)
; #define PG8_WAIT_V(n) asm volatile("s_waitcnt vmcnt(" #n ")" ::: "memory")
; #define PG8_WAIT_L(n) asm volatile("s_waitcnt lgkmcnt(" #n ")" ::: "memory")
; #define PG8_BAR __builtin_amdgcn_s_barrier()
; #define PG8_SCHED __builtin_amdgcn_sched_barrier(0)
; template <class Epi, class Sched, bool ALIGN_EPI = false, bool SP2 = false>
; __device__ __forceinline__ void gemm_phase(PG8_LAS unsigned char* lds, const Gemm g, const Sched& S, const Epi& E) {
;     ...
;             PG8_WAIT_V(8); PG8_WAIT_L(0); PG8_BAR; PG8_MMA(0, 0, At, B0); PG8_MMA(0, 1, At, B1); PG8_BAR; PG8_SCHED;
;             PG8_LDA(At, 1, 1); PG8_STAGE(PG8_SB(1, 0), b3, voffB); PG8_STAGE(PG8_SB(1, 1), b3 + hstep, voffB); PG8_STAGE(PG8_SA(1, 0), a3, voffA);
;             PG8_WAIT_V(8); PG8_WAIT_L(0); PG8_BAR; PG8_MMA(1, 0, At, B0); PG8_MMA(1, 1, At, B1); PG8_BAR; PG8_SCHED;
;     ...
;         if constexpr (ALIGN_EPI) { if (wr == 0) PG8_BAR; }
	v_mfma_f32_16x16x32_bf16 v[140:143], v[96:99], v[160:163], v[140:143]
	v_mfma_f32_16x16x32_bf16 v[136:139], v[120:123], v[160:163], v[136:139]
	v_mfma_f32_16x16x32_bf16 v[112:115], v[120:123], v[168:171], v[112:115]
	v_mfma_f32_16x16x32_bf16 v[116:119], v[96:99], v[168:171], v[116:119]
	v_mfma_f32_16x16x32_bf16 v[92:95], v[96:99], v[176:179], v[92:95]
	v_mfma_f32_16x16x32_bf16 v[88:91], v[120:123], v[176:179], v[88:91]
	v_mfma_f32_16x16x32_bf16 v[72:75], v[120:123], v[202:205], v[72:75]
	v_mfma_f32_16x16x32_bf16 v[76:79], v[96:99], v[202:205], v[76:79]
	v_mfma_f32_16x16x32_bf16 v[140:143], v[108:111], v[164:167], v[140:143]
	v_mfma_f32_16x16x32_bf16 v[136:139], v[128:131], v[164:167], v[136:139]
	v_mfma_f32_16x16x32_bf16 v[112:115], v[128:131], v[172:175], v[112:115]
	v_mfma_f32_16x16x32_bf16 v[116:119], v[108:111], v[172:175], v[116:119]
	v_mfma_f32_16x16x32_bf16 v[92:95], v[108:111], v[180:183], v[92:95]
	v_mfma_f32_16x16x32_bf16 v[88:91], v[128:131], v[180:183], v[88:91]
	v_mfma_f32_16x16x32_bf16 v[72:75], v[128:131], v[206:209], v[72:75]
	v_mfma_f32_16x16x32_bf16 v[76:79], v[108:111], v[206:209], v[76:79]
	v_mfma_f32_16x16x32_bf16 v[132:135], v[144:147], v[160:163], v[132:135]
	v_mfma_f32_16x16x32_bf16 v[124:127], v[152:155], v[160:163], v[124:127]
	v_mfma_f32_16x16x32_bf16 v[100:103], v[152:155], v[168:171], v[100:103]
	v_mfma_f32_16x16x32_bf16 v[104:107], v[144:147], v[168:171], v[104:107]
	v_mfma_f32_16x16x32_bf16 v[84:87], v[144:147], v[176:179], v[84:87]
	v_mfma_f32_16x16x32_bf16 v[80:83], v[152:155], v[176:179], v[80:83]
	v_mfma_f32_16x16x32_bf16 v[64:67], v[152:155], v[202:205], v[64:67]
	v_mfma_f32_16x16x32_bf16 v[68:71], v[144:147], v[202:205], v[68:71]
	v_mfma_f32_16x16x32_bf16 v[132:135], v[148:151], v[164:167], v[132:135]
	v_mfma_f32_16x16x32_bf16 v[124:127], v[156:159], v[164:167], v[124:127]
	v_mfma_f32_16x16x32_bf16 v[100:103], v[156:159], v[172:175], v[100:103]
	v_mfma_f32_16x16x32_bf16 v[104:107], v[148:151], v[172:175], v[104:107]
	v_mfma_f32_16x16x32_bf16 v[84:87], v[148:151], v[180:183], v[84:87]
	v_mfma_f32_16x16x32_bf16 v[80:83], v[156:159], v[180:183], v[80:83]
	v_mfma_f32_16x16x32_bf16 v[64:67], v[156:159], v[206:209], v[64:67]
	v_mfma_f32_16x16x32_bf16 v[68:71], v[148:151], v[206:209], v[68:71]
	s_barrier
	s_add_i32 s56, s77, s58
	s_mov_b32 m0, s56
	ds_read_b128 v[160:163], v225 offset:49152
	ds_read_b128 v[164:167], v225 offset:50176
	ds_read_b128 v[168:171], v225 offset:51200
	ds_read_b128 v[172:175], v225 offset:52224
	ds_read_b128 v[176:179], v225 offset:53248
	ds_read_b128 v[180:183], v225 offset:54272
	ds_read_b128 v[202:205], v225 offset:55296
	ds_read_b128 v[206:209], v225 offset:56320
	global_load_lds_dwordx4 v186, s[98:99]
	s_add_i32 m0, s56, 0x2000
	s_add_u32 s54, s54, 0x40080
	s_addc_u32 s55, s55, 0
	s_add_i32 s56, s78, s58
	global_load_lds_dwordx4 v190, s[98:99]
	s_mov_b32 m0, s56
	s_nop 0
	global_load_lds_dwordx4 v186, s[54:55]
	s_add_i32 m0, s56, 0x2000
	s_nop 0
	global_load_lds_dwordx4 v190, s[54:55]
	s_mov_b32 m0, s66
	s_nop 0
	global_load_lds_dwordx4 v184, s[100:101]
	s_mov_b32 m0, s67
	s_nop 0
	global_load_lds_dwordx4 v188, s[100:101]
	s_waitcnt vmcnt(8)
	s_waitcnt lgkmcnt(0)
	s_barrier
	v_mfma_f32_16x16x32_bf16 v[60:63], v[96:99], v[160:163], v[60:63]
	v_mfma_f32_16x16x32_bf16 v[56:59], v[120:123], v[160:163], v[56:59]
	v_mfma_f32_16x16x32_bf16 v[40:43], v[120:123], v[168:171], v[40:43]
	v_mfma_f32_16x16x32_bf16 v[44:47], v[96:99], v[168:171], v[44:47]
	v_mfma_f32_16x16x32_bf16 v[28:31], v[96:99], v[176:179], v[28:31]
	v_mfma_f32_16x16x32_bf16 v[24:27], v[120:123], v[176:179], v[24:27]
	v_mfma_f32_16x16x32_bf16 v[8:11], v[120:123], v[202:205], v[8:11]
	v_mfma_f32_16x16x32_bf16 v[12:15], v[96:99], v[202:205], v[12:15]
	v_mfma_f32_16x16x32_bf16 v[60:63], v[108:111], v[164:167], v[60:63]
	v_mfma_f32_16x16x32_bf16 v[56:59], v[128:131], v[164:167], v[56:59]
	v_mfma_f32_16x16x32_bf16 v[40:43], v[128:131], v[172:175], v[40:43]
	v_mfma_f32_16x16x32_bf16 v[44:47], v[108:111], v[172:175], v[44:47]
	v_mfma_f32_16x16x32_bf16 v[28:31], v[108:111], v[180:183], v[28:31]
	v_mfma_f32_16x16x32_bf16 v[24:27], v[128:131], v[180:183], v[24:27]
	v_mfma_f32_16x16x32_bf16 v[8:11], v[128:131], v[206:209], v[8:11]
	v_mfma_f32_16x16x32_bf16 v[12:15], v[108:111], v[206:209], v[12:15]
	v_mfma_f32_16x16x32_bf16 v[52:55], v[144:147], v[160:163], v[52:55]
	v_mfma_f32_16x16x32_bf16 v[48:51], v[152:155], v[160:163], v[48:51]
	v_mfma_f32_16x16x32_bf16 v[32:35], v[152:155], v[168:171], v[32:35]
	v_mfma_f32_16x16x32_bf16 v[36:39], v[144:147], v[168:171], v[36:39]
	v_mfma_f32_16x16x32_bf16 v[20:23], v[144:147], v[176:179], v[20:23]
	v_mfma_f32_16x16x32_bf16 v[16:19], v[152:155], v[176:179], v[16:19]
	v_mfma_f32_16x16x32_bf16 v[0:3], v[152:155], v[202:205], v[0:3]
	v_mfma_f32_16x16x32_bf16 v[4:7], v[144:147], v[202:205], v[4:7]
	v_mfma_f32_16x16x32_bf16 v[52:55], v[148:151], v[164:167], v[52:55]
	v_mfma_f32_16x16x32_bf16 v[48:51], v[156:159], v[164:167], v[48:51]
	v_mfma_f32_16x16x32_bf16 v[32:35], v[156:159], v[172:175], v[32:35]
	v_mfma_f32_16x16x32_bf16 v[36:39], v[148:151], v[172:175], v[36:39]
	v_mfma_f32_16x16x32_bf16 v[20:23], v[148:151], v[180:183], v[20:23]
	v_mfma_f32_16x16x32_bf16 v[16:19], v[156:159], v[180:183], v[16:19]
	v_mfma_f32_16x16x32_bf16 v[0:3], v[156:159], v[206:209], v[0:3]
	v_mfma_f32_16x16x32_bf16 v[4:7], v[148:151], v[206:209], v[4:7]
	s_barrier
	s_add_i32 s76, s76, 2
	s_add_u32 s20, s20, 0x100
	s_addc_u32 s21, s21, 0
	s_add_u32 s74, s74, 0x100
	s_addc_u32 s75, s75, 0
	s_cmp_gt_u32 s76, 13
	s_cbranch_scc0 .LBB0_705
	s_and_b64 vcc, exec, s[14:15]
	s_cbranch_vccz .LBB0_708
	s_barrier

; #define PG8_STAGE(bufoff, gbase, voff) do { _Pragma("unroll") for (int _i = 0; _i < 2; ++_i) \
;         __builtin_amdgcn_global_load_lds((const unsigned*)((const char*)(gbase) + (voff)[_i]), (PG8_LAS unsigned*)(lds + (bufoff) + ldsw + _i * 8192), 16, 0, 0); } while (0)
; #define PG8_LDA(dst, b, h) do { _Pragma("unroll") for (int m = 0; m < 4; ++m) _Pragma("unroll") for (int k = 0; k < 2; ++k) dst[m][k] = *(const PG8_LAS bf16x8*)(lds + PG8_SA(b, h) + aoff + m * 2048 + k * 1024); } while (0)
; #define PG8_LDB(dst, b, h) do { _Pragma("unroll") for (int n = 0; n < 2; ++n) _Pragma("unroll") for (int k = 0; k < 2; ++k) dst[n][k] = *(const PG8_LAS bf16x8*)(lds + PG8_SB(b, h) + boff + n * 2048 + k * 1024); } while (0)
; #define PG8_WAIT_V(n) asm volatile("s_waitcnt vmcnt(" #n ")" ::: "memory")
; #define PG8_WAIT_L(n) asm volatile("s_waitcnt lgkmcnt(" #n ")" ::: "memory")
; #define PG8_BAR __builtin_amdgcn_s_barrier()
; #define PG8_SCHED __builtin_amdgcn_sched_barrier(0)
; template <class Epi, class Sched, bool ALIGN_EPI = false, bool SP2 = false>
; __device__ __forceinline__ void gemm_phase(PG8_LAS unsigned char* lds, const Gemm g, const Sched& S, const Epi& E) {
;     ...
;         const char* nA = has_next ? (const char*)g.A + (size_t)nxt.pm * tstep : cA; const char* nB = has_next ? (const char*)g.Bt + (size_t)nxt.pn * tstep : cB;
;         for (int t = 0; t < nt; t += 2) {
;             const bool last = (t == nt - 2);
;             const char* a1 = cA + (size_t)(t + 1) * kstep;
;             const char* a2 = last ? nA : cA + (size_t)(t + 2) * kstep; const char* b2 = last ? nB : cB + (size_t)(t + 2) * kstep;
;             const char* a3 = a2 + kstep; const char* b3 = b2 + kstep;
;             if (last && has_next) S.a_ready(nxt);
;             if constexpr (SP2) {
;             PG8_LDB(B0, 0, 0); PG8_LDB(B1, 0, 1); PG8_SCHED; PG8_LDA(At, 0, 0); PG8_STAGE(PG8_SA(1, 1), a1 + hstep, voffA);
;             PG8_WAIT_V(8); PG8_WAIT_L(0); PG8_BAR; PG8_MMA(0, 0, At, B0); PG8_MMA(0, 1, At, B1); PG8_BAR; PG8_SCHED;
;             PG8_LDA(At, 0, 1); PG8_STAGE(PG8_SB(0, 0), b2, voffB); PG8_STAGE(PG8_SB(0, 1), b2 + hstep, voffB); PG8_STAGE(PG8_SA(0, 0), a2, voffA);
;             PG8_WAIT_V(8); PG8_WAIT_L(0); PG8_BAR; PG8_MMA(1, 0, At, B0); PG8_MMA(1, 1, At, B1); PG8_BAR; PG8_SCHED;
.LBB0_809:
	s_ashr_i32 s15, s14, 31
	s_lshl_b64 s[16:17], s[14:15], 19
	s_add_u32 s16, s36, s16
	s_addc_u32 s17, s37, s17
	s_and_b64 s[18:19], s[4:5], exec
	s_cselect_b32 s15, s17, s21
	s_cselect_b32 s65, s16, s20
	s_ashr_i32 s13, s12, 31
	s_lshl_b64 s[18:19], s[12:13], 19
	s_add_u32 s18, s50, s18
	s_addc_u32 s19, s51, s19
	s_and_b64 s[44:45], s[4:5], exec
	s_cselect_b32 s13, s19, s39
	s_cselect_b32 s66, s18, s38
	s_add_u32 s20, s20, 0x40080
	s_addc_u32 s21, s21, 0
	s_add_u32 s67, s38, 0x100
	s_addc_u32 s68, s39, 0
	s_mov_b32 s69, -2
	ds_read_b128 v[154:157], v150
	ds_read_b128 v[158:161], v150 offset:1024
	ds_read_b128 v[162:165], v150 offset:2048
	ds_read_b128 v[166:169], v150 offset:3072
	ds_read_b128 v[170:173], v151
	ds_read_b128 v[174:177], v151 offset:1024
	ds_read_b128 v[178:181], v151 offset:2048
	ds_read_b128 v[182:185], v151 offset:3072
	s_add_u32 s38, s20, 0xfffc0080
	s_addc_u32 s39, s21, -1
	s_cmp_eq_u32 s69, 12
	s_cselect_b32 s45, s15, s39
	s_cselect_b32 s44, s65, s38
	s_cselect_b32 s39, s13, s68
	s_cselect_b32 s38, s66, s67
	s_add_i32 m0, s35, 0xc000
	ds_read_b128 v[186:189], v152
	ds_read_b128 v[190:193], v152 offset:1024
	ds_read_b128 v[198:201], v152 offset:2048
	ds_read_b128 v[202:205], v152 offset:3072
	ds_read_b128 v[206:209], v152 offset:4096
	ds_read_b128 v[210:213], v152 offset:5120
	ds_read_b128 v[214:217], v152 offset:6144
	ds_read_b128 v[218:221], v152 offset:7168
	global_load_lds_dwordx4 v136, s[20:21]
	s_add_i32 m0, s35, 0xe000
	s_nop 0
	global_load_lds_dwordx4 v138, s[20:21]
	s_waitcnt vmcnt(8)
	s_waitcnt lgkmcnt(0)
	s_barrier
	v_mfma_f32_16x16x32_bf16 v[124:127], v[154:157], v[186:189], 0
	v_mfma_f32_16x16x32_bf16 v[116:119], v[162:165], v[186:189], 0
	v_mfma_f32_16x16x32_bf16 v[100:103], v[162:165], v[198:201], 0
	v_mfma_f32_16x16x32_bf16 v[108:111], v[154:157], v[198:201], 0
	v_mfma_f32_16x16x32_bf16 v[92:95], v[154:157], v[206:209], 0
	v_mfma_f32_16x16x32_bf16 v[84:87], v[162:165], v[206:209], 0
	v_mfma_f32_16x16x32_bf16 v[68:71], v[162:165], v[214:217], 0
	v_mfma_f32_16x16x32_bf16 v[76:79], v[154:157], v[214:217], 0
	v_mfma_f32_16x16x32_bf16 v[124:127], v[158:161], v[190:193], v[124:127]
	v_mfma_f32_16x16x32_bf16 v[116:119], v[166:169], v[190:193], v[116:119]
	v_mfma_f32_16x16x32_bf16 v[100:103], v[166:169], v[202:205], v[100:103]
	v_mfma_f32_16x16x32_bf16 v[108:111], v[158:161], v[202:205], v[108:111]
	v_mfma_f32_16x16x32_bf16 v[92:95], v[158:161], v[210:213], v[92:95]
	v_mfma_f32_16x16x32_bf16 v[84:87], v[166:169], v[210:213], v[84:87]
	v_mfma_f32_16x16x32_bf16 v[68:71], v[166:169], v[218:221], v[68:71]
	v_mfma_f32_16x16x32_bf16 v[76:79], v[158:161], v[218:221], v[76:79]
	v_mfma_f32_16x16x32_bf16 v[120:123], v[170:173], v[186:189], 0
	v_mfma_f32_16x16x32_bf16 v[112:115], v[178:181], v[186:189], 0
	v_mfma_f32_16x16x32_bf16 v[96:99], v[178:181], v[198:201], 0
	v_mfma_f32_16x16x32_bf16 v[104:107], v[170:173], v[198:201], 0
	v_mfma_f32_16x16x32_bf16 v[88:91], v[170:173], v[206:209], 0
	v_mfma_f32_16x16x32_bf16 v[80:83], v[178:181], v[206:209], 0
	v_mfma_f32_16x16x32_bf16 v[64:67], v[178:181], v[214:217], 0
	v_mfma_f32_16x16x32_bf16 v[72:75], v[170:173], v[214:217], 0
	v_mfma_f32_16x16x32_bf16 v[120:123], v[174:177], v[190:193], v[120:123]
	v_mfma_f32_16x16x32_bf16 v[112:115], v[182:185], v[190:193], v[112:115]
	v_mfma_f32_16x16x32_bf16 v[96:99], v[182:185], v[202:205], v[96:99]
	v_mfma_f32_16x16x32_bf16 v[104:107], v[174:177], v[202:205], v[104:107]
	v_mfma_f32_16x16x32_bf16 v[88:91], v[174:177], v[210:213], v[88:91]
	v_mfma_f32_16x16x32_bf16 v[80:83], v[182:185], v[210:213], v[80:83]
	v_mfma_f32_16x16x32_bf16 v[64:67], v[182:185], v[218:221], v[64:67]
	v_mfma_f32_16x16x32_bf16 v[72:75], v[174:177], v[218:221], v[72:75]
	s_barrier
	s_add_i32 s70, s60, s52
	s_add_u32 s98, s38, s8
	s_addc_u32 s99, s39, s9
	s_add_u32 s100, s44, s8
	s_addc_u32 s101, s45, s9
	s_mov_b32 m0, s70
	ds_read_b128 v[186:189], v152 offset:16384
	ds_read_b128 v[190:193], v152 offset:17408
	ds_read_b128 v[198:201], v152 offset:18432
	ds_read_b128 v[202:205], v152 offset:19456
	ds_read_b128 v[206:209], v152 offset:20480
	ds_read_b128 v[210:213], v152 offset:21504
	ds_read_b128 v[214:217], v152 offset:22528
	ds_read_b128 v[218:221], v152 offset:23552
	global_load_lds_dwordx4 v132, s[38:39]
	s_add_i32 m0, s70, 0x2000
	s_add_u32 s70, s38, 0x40000
	s_addc_u32 s71, s39, 0
	s_add_i32 s72, s61, s52
	global_load_lds_dwordx4 v128, s[38:39]
	s_mov_b32 m0, s72
	s_nop 0
	global_load_lds_dwordx4 v132, s[70:71]
	s_add_i32 m0, s72, 0x2000
	s_nop 0
	global_load_lds_dwordx4 v128, s[70:71]
	s_mov_b32 m0, s35
	s_nop 0
	global_load_lds_dwordx4 v134, s[44:45]
	s_mov_b32 m0, s54
	s_nop 0
	global_load_lds_dwordx4 v130, s[44:45]
	s_waitcnt vmcnt(8)
	s_waitcnt lgkmcnt(0)
	s_barrier
; #define PG8_STAGE(bufoff, gbase, voff) do { _Pragma("unroll") for (int _i = 0; _i < 2; ++_i) \
;         __builtin_amdgcn_global_load_lds((const unsigned*)((const char*)(gbase) + (voff)[_i]), (PG8_LAS unsigned*)(lds + (bufoff) + ldsw + _i * 8192), 16, 0, 0); } while (0)
; #define PG8_LDA(dst, b, h) do { _Pragma("unroll") for (int m = 0; m < 4; ++m) _Pragma("unroll") for (int k = 0; k < 2; ++k) dst[m][k] = *(const PG8_LAS bf16x8*)(lds + PG8_SA(b, h) + aoff + m * 2048 + k * 1024); } while (0)
; #define PG8_LDB(dst, b, h) do { _Pragma("unroll") for (int n = 0; n < 2; ++n) _Pragma("unroll") for (int k = 0; k < 2; ++k) dst[n][k] = *(const PG8_LAS bf16x8*)(lds + PG8_SB(b, h) + boff + n * 2048 + k * 1024); } while (0)
; #define PG8_MMA(ai, bj, At, Bt) do { __builtin_amdgcn_s_setprio(1); _Pragma("unroll") for (int m = 0; m < 4; ++m) _Pragma("unroll") for (int n = 0; n < 2; ++n) _Pragma("unroll") for (int k = 0; k < 2; ++k) \
;         acc[ai][bj][m][n] = __builtin_amdgcn_mfma_f32_16x16x32_bf16(Bt[n][k], At[m][k], acc[ai][bj][m][n], 0, 0, 0); __builtin_amdgcn_s_setprio(0); } while (0)
; #define PG8_WAIT_V(n) asm volatile("s_waitcnt vmcnt(" #n ")" ::: "memory")
; #define PG8_WAIT_L(n) asm volatile("s_waitcnt lgkmcnt(" #n ")" ::: "memory")
; #define PG8_BAR __builtin_amdgcn_s_barrier()
; #define PG8_SCHED __builtin_amdgcn_sched_barrier(0)
; template <class Epi, class Sched, bool ALIGN_EPI = false, bool SP2 = false>
; __device__ __forceinline__ void gemm_phase(PG8_LAS unsigned char* lds, const Gemm g, const Sched& S, const Epi& E) {
;     ...
;             PG8_WAIT_V(8); PG8_WAIT_L(0); PG8_BAR; PG8_MMA(1, 0, At, B0); PG8_MMA(1, 1, At, B1); PG8_BAR; PG8_SCHED;
;             PG8_LDB(B0, 1, 0); PG8_LDB(B1, 1, 1); PG8_SCHED; PG8_LDA(At, 1, 0); PG8_STAGE(PG8_SA(0, 1), a2 + hstep, voffA);
;             PG8_WAIT_V(8); PG8_WAIT_L(0); PG8_BAR; PG8_MMA(0, 0, At, B0); PG8_MMA(0, 1, At, B1); PG8_BAR; PG8_SCHED;
	v_mfma_f32_16x16x32_bf16 v[60:63], v[154:157], v[186:189], 0
	v_mfma_f32_16x16x32_bf16 v[52:55], v[162:165], v[186:189], 0
	v_mfma_f32_16x16x32_bf16 v[36:39], v[162:165], v[198:201], 0
	v_mfma_f32_16x16x32_bf16 v[44:47], v[154:157], v[198:201], 0
	v_mfma_f32_16x16x32_bf16 v[28:31], v[154:157], v[206:209], 0
	v_mfma_f32_16x16x32_bf16 v[20:23], v[162:165], v[206:209], 0
	v_mfma_f32_16x16x32_bf16 v[4:7], v[162:165], v[214:217], 0
	v_mfma_f32_16x16x32_bf16 v[12:15], v[154:157], v[214:217], 0
	v_mfma_f32_16x16x32_bf16 v[60:63], v[158:161], v[190:193], v[60:63]
	v_mfma_f32_16x16x32_bf16 v[52:55], v[166:169], v[190:193], v[52:55]
	v_mfma_f32_16x16x32_bf16 v[36:39], v[166:169], v[202:205], v[36:39]
	v_mfma_f32_16x16x32_bf16 v[44:47], v[158:161], v[202:205], v[44:47]
	v_mfma_f32_16x16x32_bf16 v[28:31], v[158:161], v[210:213], v[28:31]
	v_mfma_f32_16x16x32_bf16 v[20:23], v[166:169], v[210:213], v[20:23]
	v_mfma_f32_16x16x32_bf16 v[4:7], v[166:169], v[218:221], v[4:7]
	v_mfma_f32_16x16x32_bf16 v[12:15], v[158:161], v[218:221], v[12:15]
	v_mfma_f32_16x16x32_bf16 v[56:59], v[170:173], v[186:189], 0
	v_mfma_f32_16x16x32_bf16 v[48:51], v[178:181], v[186:189], 0
	v_mfma_f32_16x16x32_bf16 v[32:35], v[178:181], v[198:201], 0
	v_mfma_f32_16x16x32_bf16 v[40:43], v[170:173], v[198:201], 0
	v_mfma_f32_16x16x32_bf16 v[24:27], v[170:173], v[206:209], 0
	v_mfma_f32_16x16x32_bf16 v[16:19], v[178:181], v[206:209], 0
	v_mfma_f32_16x16x32_bf16 v[0:3], v[178:181], v[214:217], 0
	v_mfma_f32_16x16x32_bf16 v[8:11], v[170:173], v[214:217], 0
	v_mfma_f32_16x16x32_bf16 v[56:59], v[174:177], v[190:193], v[56:59]
	v_mfma_f32_16x16x32_bf16 v[48:51], v[182:185], v[190:193], v[48:51]
	v_mfma_f32_16x16x32_bf16 v[32:35], v[182:185], v[202:205], v[32:35]
	v_mfma_f32_16x16x32_bf16 v[40:43], v[174:177], v[202:205], v[40:43]
	v_mfma_f32_16x16x32_bf16 v[24:27], v[174:177], v[210:213], v[24:27]
	v_mfma_f32_16x16x32_bf16 v[16:19], v[182:185], v[210:213], v[16:19]
	v_mfma_f32_16x16x32_bf16 v[0:3], v[182:185], v[218:221], v[0:3]
	v_mfma_f32_16x16x32_bf16 v[8:11], v[174:177], v[218:221], v[8:11]
	s_barrier
	s_add_i32 s70, 0, 0x18000
	v_add_u32_e32 v153, s70, v147
	s_add_i32 s71, 0, 0x1c000
	ds_read_b128 v[154:157], v153
	ds_read_b128 v[158:161], v153 offset:1024
	ds_read_b128 v[162:165], v153 offset:2048
	ds_read_b128 v[166:169], v153 offset:3072
	v_add_u32_e32 v153, s71, v147
	ds_read_b128 v[170:173], v153
	ds_read_b128 v[174:177], v153 offset:1024
	ds_read_b128 v[178:181], v153 offset:2048
	ds_read_b128 v[182:185], v153 offset:3072
	s_add_u32 s44, s44, 0x40000
	s_addc_u32 s45, s45, 0
	s_mov_b32 m0, s55
	ds_read_b128 v[186:189], v152 offset:32768
	ds_read_b128 v[190:193], v152 offset:33792
	ds_read_b128 v[198:201], v152 offset:34816
	ds_read_b128 v[202:205], v152 offset:35840
	ds_read_b128 v[206:209], v152 offset:36864
	ds_read_b128 v[210:213], v152 offset:37888
	ds_read_b128 v[214:217], v152 offset:38912
	ds_read_b128 v[218:221], v152 offset:39936
	global_load_lds_dwordx4 v134, s[44:45]
	s_mov_b32 m0, s56
	s_nop 0
	global_load_lds_dwordx4 v130, s[44:45]
	s_waitcnt vmcnt(8)
	s_waitcnt lgkmcnt(0)
	s_barrier
	v_mfma_f32_16x16x32_bf16 v[124:127], v[154:157], v[186:189], v[124:127]
	v_mfma_f32_16x16x32_bf16 v[116:119], v[162:165], v[186:189], v[116:119]
	v_mfma_f32_16x16x32_bf16 v[100:103], v[162:165], v[198:201], v[100:103]
	v_mfma_f32_16x16x32_bf16 v[108:111], v[154:157], v[198:201], v[108:111]
	v_mfma_f32_16x16x32_bf16 v[92:95], v[154:157], v[206:209], v[92:95]
	v_mfma_f32_16x16x32_bf16 v[84:87], v[162:165], v[206:209], v[84:87]
	v_mfma_f32_16x16x32_bf16 v[68:71], v[162:165], v[214:217], v[68:71]
	v_mfma_f32_16x16x32_bf16 v[76:79], v[154:157], v[214:217], v[76:79]
	v_mfma_f32_16x16x32_bf16 v[124:127], v[158:161], v[190:193], v[124:127]
	v_mfma_f32_16x16x32_bf16 v[116:119], v[166:169], v[190:193], v[116:119]
	v_mfma_f32_16x16x32_bf16 v[100:103], v[166:169], v[202:205], v[100:103]
	v_mfma_f32_16x16x32_bf16 v[108:111], v[158:161], v[202:205], v[108:111]
	v_mfma_f32_16x16x32_bf16 v[92:95], v[158:161], v[210:213], v[92:95]
	v_mfma_f32_16x16x32_bf16 v[84:87], v[166:169], v[210:213], v[84:87]
	v_mfma_f32_16x16x32_bf16 v[68:71], v[166:169], v[218:221], v[68:71]
	v_mfma_f32_16x16x32_bf16 v[76:79], v[158:161], v[218:221], v[76:79]
	v_mfma_f32_16x16x32_bf16 v[120:123], v[170:173], v[186:189], v[120:123]
	v_mfma_f32_16x16x32_bf16 v[112:115], v[178:181], v[186:189], v[112:115]
	v_mfma_f32_16x16x32_bf16 v[96:99], v[178:181], v[198:201], v[96:99]
	v_mfma_f32_16x16x32_bf16 v[104:107], v[170:173], v[198:201], v[104:107]
	v_mfma_f32_16x16x32_bf16 v[88:91], v[170:173], v[206:209], v[88:91]
	v_mfma_f32_16x16x32_bf16 v[80:83], v[178:181], v[206:209], v[80:83]
	v_mfma_f32_16x16x32_bf16 v[64:67], v[178:181], v[214:217], v[64:67]
	v_mfma_f32_16x16x32_bf16 v[72:75], v[170:173], v[214:217], v[72:75]
	v_mfma_f32_16x16x32_bf16 v[120:123], v[174:177], v[190:193], v[120:123]
	v_mfma_f32_16x16x32_bf16 v[112:115], v[182:185], v[190:193], v[112:115]
	v_mfma_f32_16x16x32_bf16 v[96:99], v[182:185], v[202:205], v[96:99]
	v_mfma_f32_16x16x32_bf16 v[104:107], v[174:177], v[202:205], v[104:107]
	v_mfma_f32_16x16x32_bf16 v[88:91], v[174:177], v[210:213], v[88:91]
	v_mfma_f32_16x16x32_bf16 v[80:83], v[182:185], v[210:213], v[80:83]
	v_mfma_f32_16x16x32_bf16 v[64:67], v[182:185], v[218:221], v[64:67]
	v_mfma_f32_16x16x32_bf16 v[72:75], v[174:177], v[218:221], v[72:75]
	s_barrier
; #define PG8_STAGE(bufoff, gbase, voff) do { _Pragma("unroll") for (int _i = 0; _i < 2; ++_i) \
;         __builtin_amdgcn_global_load_lds((const unsigned*)((const char*)(gbase) + (voff)[_i]), (PG8_LAS unsigned*)(lds + (bufoff) + ldsw + _i * 8192), 16, 0, 0); } while (0)
; #define PG8_LDA(dst, b, h) do { _Pragma("unroll") for (int m = 0; m < 4; ++m) _Pragma("unroll") for (int k = 0; k < 2; ++k) dst[m][k] = *(const PG8_LAS bf16x8*)(lds + PG8_SA(b, h) + aoff + m * 2048 + k * 1024); } while (0)
; #define PG8_LDB(dst, b, h) do { _Pragma("unroll") for (int n = 0; n < 2; ++n) _Pragma("unroll") for (int k = 0; k < 2; ++k) dst[n][k] = *(const PG8_LAS bf16x8*)(lds + PG8_SB(b, h) + boff + n * 2048 + k * 1024); } while (0)
; #define PG8_MMA(ai, bj, At, Bt) do { __builtin_amdgcn_s_setprio(1); _Pragma("unroll") for (int m = 0; m < 4; ++m) _Pragma("unroll") for (int n = 0; n < 2; ++n) _Pragma("unroll") for (int k = 0; k < 2; ++k) \
;         acc[ai][bj][m][n] = __builtin_amdgcn_mfma_f32_16x16x32_bf16(Bt[n][k], At[m][k], acc[ai][bj][m][n], 0, 0, 0); __builtin_amdgcn_s_setprio(0); } while (0)
; #define PG8_WAIT_V(n) asm volatile("s_waitcnt vmcnt(" #n ")" ::: "memory")
; template <class Epi, class Sched, bool ALIGN_EPI = false, bool SP2 = false>
; __device__ __forceinline__ void gemm_phase(PG8_LAS unsigned char* lds, const Gemm g, const Sched& S, const Epi& E) {
;     ...
;             PG8_LDB(B0, 0, 0); PG8_LDB(B1, 0, 1); PG8_SCHED; PG8_LDA(At, 0, 0); PG8_STAGE(PG8_SA(1, 1), a1 + hstep, voffA);
;             PG8_WAIT_V(8); PG8_WAIT_L(0); PG8_BAR; PG8_MMA(0, 0, At, B0); PG8_MMA(0, 1, At, B1); PG8_BAR; PG8_SCHED;
;             PG8_LDA(At, 0, 1); PG8_STAGE(PG8_SB(0, 0), b2, voffB); PG8_STAGE(PG8_SB(0, 1), b2 + hstep, voffB); PG8_STAGE(PG8_SA(0, 0), a2, voffA);
;             PG8_WAIT_V(8); PG8_WAIT_L(0); PG8_BAR; PG8_MMA(1, 0, At, B0); PG8_MMA(1, 1, At, B1); PG8_BAR; PG8_SCHED;
;             PG8_LDB(B0, 1, 0); PG8_LDB(B1, 1, 1); PG8_SCHED; PG8_LDA(At, 1, 0); PG8_STAGE(PG8_SA(0, 1), a2 + hstep, voffA);
;             PG8_WAIT_V(8); PG8_WAIT_L(0); PG8_BAR; PG8_MMA(0, 0, At, B0); PG8_MMA(0, 1, At, B1); PG8_BAR; PG8_SCHED;
;             PG8_LDA(At, 1, 1); PG8_STAGE(PG8_SB(1, 0), b3, voffB); PG8_STAGE(PG8_SB(1, 1), b3 + hstep, voffB); PG8_STAGE(PG8_SA(1, 0), a3, voffA);
;             PG8_WAIT_V(8); PG8_WAIT_L(0); PG8_BAR; PG8_MMA(1, 0, At, B0); PG8_MMA(1, 1, At, B1); PG8_BAR; PG8_SCHED;
	s_add_i32 s44, s70, s52
	s_mov_b32 m0, s44
	ds_read_b128 v[186:189], v152 offset:49152
	ds_read_b128 v[190:193], v152 offset:50176
	ds_read_b128 v[198:201], v152 offset:51200
	ds_read_b128 v[202:205], v152 offset:52224
	ds_read_b128 v[206:209], v152 offset:53248
	ds_read_b128 v[210:213], v152 offset:54272
	ds_read_b128 v[214:217], v152 offset:55296
	ds_read_b128 v[218:221], v152 offset:56320
	global_load_lds_dwordx4 v132, s[98:99]
	s_add_i32 m0, s44, 0x2000
	s_add_u32 s38, s38, 0x40080
	s_addc_u32 s39, s39, 0
	s_add_i32 s44, s71, s52
	global_load_lds_dwordx4 v128, s[98:99]
	s_mov_b32 m0, s44
	s_nop 0
	global_load_lds_dwordx4 v132, s[38:39]
	s_add_i32 m0, s44, 0x2000
	s_nop 0
	global_load_lds_dwordx4 v128, s[38:39]
	s_mov_b32 m0, s58
	s_nop 0
	global_load_lds_dwordx4 v134, s[100:101]
	s_mov_b32 m0, s59
	s_nop 0
	global_load_lds_dwordx4 v130, s[100:101]
	s_waitcnt vmcnt(8)
	s_waitcnt lgkmcnt(0)
	s_barrier
	v_mfma_f32_16x16x32_bf16 v[60:63], v[154:157], v[186:189], v[60:63]
	v_mfma_f32_16x16x32_bf16 v[52:55], v[162:165], v[186:189], v[52:55]
	v_mfma_f32_16x16x32_bf16 v[36:39], v[162:165], v[198:201], v[36:39]
	v_mfma_f32_16x16x32_bf16 v[44:47], v[154:157], v[198:201], v[44:47]
	v_mfma_f32_16x16x32_bf16 v[28:31], v[154:157], v[206:209], v[28:31]
	v_mfma_f32_16x16x32_bf16 v[20:23], v[162:165], v[206:209], v[20:23]
	v_mfma_f32_16x16x32_bf16 v[4:7], v[162:165], v[214:217], v[4:7]
	v_mfma_f32_16x16x32_bf16 v[12:15], v[154:157], v[214:217], v[12:15]
	v_mfma_f32_16x16x32_bf16 v[60:63], v[158:161], v[190:193], v[60:63]
	v_mfma_f32_16x16x32_bf16 v[52:55], v[166:169], v[190:193], v[52:55]
	v_mfma_f32_16x16x32_bf16 v[36:39], v[166:169], v[202:205], v[36:39]
	v_mfma_f32_16x16x32_bf16 v[44:47], v[158:161], v[202:205], v[44:47]
	v_mfma_f32_16x16x32_bf16 v[28:31], v[158:161], v[210:213], v[28:31]
	v_mfma_f32_16x16x32_bf16 v[20:23], v[166:169], v[210:213], v[20:23]
	v_mfma_f32_16x16x32_bf16 v[4:7], v[166:169], v[218:221], v[4:7]
	v_mfma_f32_16x16x32_bf16 v[12:15], v[158:161], v[218:221], v[12:15]
	v_mfma_f32_16x16x32_bf16 v[56:59], v[170:173], v[186:189], v[56:59]
	v_mfma_f32_16x16x32_bf16 v[48:51], v[178:181], v[186:189], v[48:51]
	v_mfma_f32_16x16x32_bf16 v[32:35], v[178:181], v[198:201], v[32:35]
	v_mfma_f32_16x16x32_bf16 v[40:43], v[170:173], v[198:201], v[40:43]
	v_mfma_f32_16x16x32_bf16 v[24:27], v[170:173], v[206:209], v[24:27]
	v_mfma_f32_16x16x32_bf16 v[16:19], v[178:181], v[206:209], v[16:19]
	v_mfma_f32_16x16x32_bf16 v[0:3], v[178:181], v[214:217], v[0:3]
	v_mfma_f32_16x16x32_bf16 v[8:11], v[170:173], v[214:217], v[8:11]
	v_mfma_f32_16x16x32_bf16 v[56:59], v[174:177], v[190:193], v[56:59]
	v_mfma_f32_16x16x32_bf16 v[48:51], v[182:185], v[190:193], v[48:51]
	v_mfma_f32_16x16x32_bf16 v[32:35], v[182:185], v[202:205], v[32:35]
	v_mfma_f32_16x16x32_bf16 v[40:43], v[174:177], v[202:205], v[40:43]
	v_mfma_f32_16x16x32_bf16 v[24:27], v[174:177], v[210:213], v[24:27]
	v_mfma_f32_16x16x32_bf16 v[16:19], v[182:185], v[210:213], v[16:19]
	v_mfma_f32_16x16x32_bf16 v[0:3], v[182:185], v[218:221], v[0:3]
	v_mfma_f32_16x16x32_bf16 v[8:11], v[174:177], v[218:221], v[8:11]
	s_barrier
	s_add_i32 s69, s69, 2
	s_add_u32 s20, s20, 0x100
	s_addc_u32 s21, s21, 0
	s_add_u32 s67, s67, 0x100
	s_addc_u32 s68, s68, 0
	s_cmp_gt_u32 s69, 13
.LBB0_810:
	ds_read_b128 v[154:157], v150
	ds_read_b128 v[158:161], v150 offset:1024
	ds_read_b128 v[162:165], v150 offset:2048
	ds_read_b128 v[166:169], v150 offset:3072
	ds_read_b128 v[170:173], v151
	ds_read_b128 v[174:177], v151 offset:1024
	ds_read_b128 v[178:181], v151 offset:2048
	ds_read_b128 v[182:185], v151 offset:3072
	s_add_u32 s38, s20, 0xfffc0080
	s_addc_u32 s39, s21, -1
	s_cmp_eq_u32 s69, 12
	s_cselect_b32 s45, s15, s39
	s_cselect_b32 s44, s65, s38
	s_cselect_b32 s39, s13, s68
	s_cselect_b32 s38, s66, s67
	s_add_i32 m0, s35, 0xc000
	ds_read_b128 v[186:189], v152
	ds_read_b128 v[190:193], v152 offset:1024
	ds_read_b128 v[198:201], v152 offset:2048
	ds_read_b128 v[202:205], v152 offset:3072
	ds_read_b128 v[206:209], v152 offset:4096
	ds_read_b128 v[210:213], v152 offset:5120
	ds_read_b128 v[214:217], v152 offset:6144
	ds_read_b128 v[218:221], v152 offset:7168
	global_load_lds_dwordx4 v136, s[20:21]
	s_add_i32 m0, s35, 0xe000
	s_nop 0
	global_load_lds_dwordx4 v138, s[20:21]
	s_waitcnt vmcnt(8)
	s_waitcnt lgkmcnt(0)
	s_barrier
	v_mfma_f32_16x16x32_bf16 v[124:127], v[154:157], v[186:189], v[124:127]
	v_mfma_f32_16x16x32_bf16 v[116:119], v[162:165], v[186:189], v[116:119]
	v_mfma_f32_16x16x32_bf16 v[100:103], v[162:165], v[198:201], v[100:103]
	v_mfma_f32_16x16x32_bf16 v[108:111], v[154:157], v[198:201], v[108:111]
	v_mfma_f32_16x16x32_bf16 v[92:95], v[154:157], v[206:209], v[92:95]
	v_mfma_f32_16x16x32_bf16 v[84:87], v[162:165], v[206:209], v[84:87]
	v_mfma_f32_16x16x32_bf16 v[68:71], v[162:165], v[214:217], v[68:71]
	v_mfma_f32_16x16x32_bf16 v[76:79], v[154:157], v[214:217], v[76:79]
	v_mfma_f32_16x16x32_bf16 v[124:127], v[158:161], v[190:193], v[124:127]
	v_mfma_f32_16x16x32_bf16 v[116:119], v[166:169], v[190:193], v[116:119]
	v_mfma_f32_16x16x32_bf16 v[100:103], v[166:169], v[202:205], v[100:103]
	v_mfma_f32_16x16x32_bf16 v[108:111], v[158:161], v[202:205], v[108:111]
	v_mfma_f32_16x16x32_bf16 v[92:95], v[158:161], v[210:213], v[92:95]
	v_mfma_f32_16x16x32_bf16 v[84:87], v[166:169], v[210:213], v[84:87]
	v_mfma_f32_16x16x32_bf16 v[68:71], v[166:169], v[218:221], v[68:71]
	v_mfma_f32_16x16x32_bf16 v[76:79], v[158:161], v[218:221], v[76:79]
	v_mfma_f32_16x16x32_bf16 v[120:123], v[170:173], v[186:189], v[120:123]
	v_mfma_f32_16x16x32_bf16 v[112:115], v[178:181], v[186:189], v[112:115]
	v_mfma_f32_16x16x32_bf16 v[96:99], v[178:181], v[198:201], v[96:99]
	v_mfma_f32_16x16x32_bf16 v[104:107], v[170:173], v[198:201], v[104:107]
	v_mfma_f32_16x16x32_bf16 v[88:91], v[170:173], v[206:209], v[88:91]
	v_mfma_f32_16x16x32_bf16 v[80:83], v[178:181], v[206:209], v[80:83]
	v_mfma_f32_16x16x32_bf16 v[64:67], v[178:181], v[214:217], v[64:67]
	v_mfma_f32_16x16x32_bf16 v[72:75], v[170:173], v[214:217], v[72:75]
	v_mfma_f32_16x16x32_bf16 v[120:123], v[174:177], v[190:193], v[120:123]
	v_mfma_f32_16x16x32_bf16 v[112:115], v[182:185], v[190:193], v[112:115]
	v_mfma_f32_16x16x32_bf16 v[96:99], v[182:185], v[202:205], v[96:99]
	v_mfma_f32_16x16x32_bf16 v[104:107], v[174:177], v[202:205], v[104:107]
	v_mfma_f32_16x16x32_bf16 v[88:91], v[174:177], v[210:213], v[88:91]
	v_mfma_f32_16x16x32_bf16 v[80:83], v[182:185], v[210:213], v[80:83]
	v_mfma_f32_16x16x32_bf16 v[64:67], v[182:185], v[218:221], v[64:67]
	v_mfma_f32_16x16x32_bf16 v[72:75], v[174:177], v[218:221], v[72:75]
	s_barrier
; #define PG8_STAGE(bufoff, gbase, voff) do { _Pragma("unroll") for (int _i = 0; _i < 2; ++_i) \
;         __builtin_amdgcn_global_load_lds((const unsigned*)((const char*)(gbase) + (voff)[_i]), (PG8_LAS unsigned*)(lds + (bufoff) + ldsw + _i * 8192), 16, 0, 0); } while (0)
; #define PG8_LDA(dst, b, h) do { _Pragma("unroll") for (int m = 0; m < 4; ++m) _Pragma("unroll") for (int k = 0; k < 2; ++k) dst[m][k] = *(const PG8_LAS bf16x8*)(lds + PG8_SA(b, h) + aoff + m * 2048 + k * 1024); } while (0)
; #define PG8_LDB(dst, b, h) do { _Pragma("unroll") for (int n = 0; n < 2; ++n) _Pragma("unroll") for (int k = 0; k < 2; ++k) dst[n][k] = *(const PG8_LAS bf16x8*)(lds + PG8_SB(b, h) + boff + n * 2048 + k * 1024); } while (0)
; #define PG8_MMA(ai, bj, At, Bt) do { __builtin_amdgcn_s_setprio(1); _Pragma("unroll") for (int m = 0; m < 4; ++m) _Pragma("unroll") for (int n = 0; n < 2; ++n) _Pragma("unroll") for (int k = 0; k < 2; ++k) \
;         acc[ai][bj][m][n] = __builtin_amdgcn_mfma_f32_16x16x32_bf16(Bt[n][k], At[m][k], acc[ai][bj][m][n], 0, 0, 0); __builtin_amdgcn_s_setprio(0); } while (0)
; #define PG8_WAIT_V(n) asm volatile("s_waitcnt vmcnt(" #n ")" ::: "memory")
; #define PG8_WAIT_L(n) asm volatile("s_waitcnt lgkmcnt(" #n ")" ::: "memory")
; #define PG8_BAR __builtin_amdgcn_s_barrier()
; #define PG8_SCHED __builtin_amdgcn_sched_barrier(0)
; template <class Epi, class Sched, bool ALIGN_EPI = false, bool SP2 = false>
; __device__ __forceinline__ void gemm_phase(PG8_LAS unsigned char* lds, const Gemm g, const Sched& S, const Epi& E) {
;     ...
;             PG8_LDA(At, 0, 1); PG8_STAGE(PG8_SB(0, 0), b2, voffB); PG8_STAGE(PG8_SB(0, 1), b2 + hstep, voffB); PG8_STAGE(PG8_SA(0, 0), a2, voffA);
;             PG8_WAIT_V(8); PG8_WAIT_L(0); PG8_BAR; PG8_MMA(1, 0, At, B0); PG8_MMA(1, 1, At, B1); PG8_BAR; PG8_SCHED;
;             PG8_LDB(B0, 1, 0); PG8_LDB(B1, 1, 1); PG8_SCHED; PG8_LDA(At, 1, 0); PG8_STAGE(PG8_SA(0, 1), a2 + hstep, voffA);
;             PG8_WAIT_V(8); PG8_WAIT_L(0); PG8_BAR; PG8_MMA(0, 0, At, B0); PG8_MMA(0, 1, At, B1); PG8_BAR; PG8_SCHED;
	s_add_i32 s70, s60, s52
	s_add_u32 s98, s38, s8
	s_addc_u32 s99, s39, s9
	s_add_u32 s100, s44, s8
	s_addc_u32 s101, s45, s9
	s_mov_b32 m0, s70
	ds_read_b128 v[186:189], v152 offset:16384
	ds_read_b128 v[190:193], v152 offset:17408
	ds_read_b128 v[198:201], v152 offset:18432
	ds_read_b128 v[202:205], v152 offset:19456
	ds_read_b128 v[206:209], v152 offset:20480
	ds_read_b128 v[210:213], v152 offset:21504
	ds_read_b128 v[214:217], v152 offset:22528
	ds_read_b128 v[218:221], v152 offset:23552
	global_load_lds_dwordx4 v132, s[38:39]
	s_add_i32 m0, s70, 0x2000
	s_add_u32 s70, s38, 0x40000
	s_addc_u32 s71, s39, 0
	s_add_i32 s72, s61, s52
	global_load_lds_dwordx4 v128, s[38:39]
	s_mov_b32 m0, s72
	s_nop 0
	global_load_lds_dwordx4 v132, s[70:71]
	s_add_i32 m0, s72, 0x2000
	s_nop 0
	global_load_lds_dwordx4 v128, s[70:71]
	s_mov_b32 m0, s35
	s_nop 0
	global_load_lds_dwordx4 v134, s[44:45]
	s_mov_b32 m0, s54
	s_nop 0
	global_load_lds_dwordx4 v130, s[44:45]
	s_waitcnt vmcnt(8)
	s_waitcnt lgkmcnt(0)
	s_barrier
	v_mfma_f32_16x16x32_bf16 v[60:63], v[154:157], v[186:189], v[60:63]
	v_mfma_f32_16x16x32_bf16 v[52:55], v[162:165], v[186:189], v[52:55]
	v_mfma_f32_16x16x32_bf16 v[36:39], v[162:165], v[198:201], v[36:39]
	v_mfma_f32_16x16x32_bf16 v[44:47], v[154:157], v[198:201], v[44:47]
	v_mfma_f32_16x16x32_bf16 v[28:31], v[154:157], v[206:209], v[28:31]
	v_mfma_f32_16x16x32_bf16 v[20:23], v[162:165], v[206:209], v[20:23]
	v_mfma_f32_16x16x32_bf16 v[4:7], v[162:165], v[214:217], v[4:7]
	v_mfma_f32_16x16x32_bf16 v[12:15], v[154:157], v[214:217], v[12:15]
	v_mfma_f32_16x16x32_bf16 v[60:63], v[158:161], v[190:193], v[60:63]
	v_mfma_f32_16x16x32_bf16 v[52:55], v[166:169], v[190:193], v[52:55]
	v_mfma_f32_16x16x32_bf16 v[36:39], v[166:169], v[202:205], v[36:39]
	v_mfma_f32_16x16x32_bf16 v[44:47], v[158:161], v[202:205], v[44:47]
	v_mfma_f32_16x16x32_bf16 v[28:31], v[158:161], v[210:213], v[28:31]
	v_mfma_f32_16x16x32_bf16 v[20:23], v[166:169], v[210:213], v[20:23]
	v_mfma_f32_16x16x32_bf16 v[4:7], v[166:169], v[218:221], v[4:7]
	v_mfma_f32_16x16x32_bf16 v[12:15], v[158:161], v[218:221], v[12:15]
	v_mfma_f32_16x16x32_bf16 v[56:59], v[170:173], v[186:189], v[56:59]
	v_mfma_f32_16x16x32_bf16 v[48:51], v[178:181], v[186:189], v[48:51]
	v_mfma_f32_16x16x32_bf16 v[32:35], v[178:181], v[198:201], v[32:35]
	v_mfma_f32_16x16x32_bf16 v[40:43], v[170:173], v[198:201], v[40:43]
	v_mfma_f32_16x16x32_bf16 v[24:27], v[170:173], v[206:209], v[24:27]
	v_mfma_f32_16x16x32_bf16 v[16:19], v[178:181], v[206:209], v[16:19]
	v_mfma_f32_16x16x32_bf16 v[0:3], v[178:181], v[214:217], v[0:3]
	v_mfma_f32_16x16x32_bf16 v[8:11], v[170:173], v[214:217], v[8:11]
	v_mfma_f32_16x16x32_bf16 v[56:59], v[174:177], v[190:193], v[56:59]
	v_mfma_f32_16x16x32_bf16 v[48:51], v[182:185], v[190:193], v[48:51]
	v_mfma_f32_16x16x32_bf16 v[32:35], v[182:185], v[202:205], v[32:35]
	v_mfma_f32_16x16x32_bf16 v[40:43], v[174:177], v[202:205], v[40:43]
	v_mfma_f32_16x16x32_bf16 v[24:27], v[174:177], v[210:213], v[24:27]
	v_mfma_f32_16x16x32_bf16 v[16:19], v[182:185], v[210:213], v[16:19]
	v_mfma_f32_16x16x32_bf16 v[0:3], v[182:185], v[218:221], v[0:3]
	v_mfma_f32_16x16x32_bf16 v[8:11], v[174:177], v[218:221], v[8:11]
	s_barrier
	s_add_i32 s70, 0, 0x18000
	v_add_u32_e32 v153, s70, v147
	s_add_i32 s71, 0, 0x1c000
	ds_read_b128 v[154:157], v153
	ds_read_b128 v[158:161], v153 offset:1024
	ds_read_b128 v[162:165], v153 offset:2048
	ds_read_b128 v[166:169], v153 offset:3072
	v_add_u32_e32 v153, s71, v147
	ds_read_b128 v[170:173], v153
	ds_read_b128 v[174:177], v153 offset:1024
	ds_read_b128 v[178:181], v153 offset:2048
	ds_read_b128 v[182:185], v153 offset:3072
	s_add_u32 s44, s44, 0x40000
	s_addc_u32 s45, s45, 0
	s_mov_b32 m0, s55
	ds_read_b128 v[186:189], v152 offset:32768
	ds_read_b128 v[190:193], v152 offset:33792
	ds_read_b128 v[198:201], v152 offset:34816
	ds_read_b128 v[202:205], v152 offset:35840
	ds_read_b128 v[206:209], v152 offset:36864
	ds_read_b128 v[210:213], v152 offset:37888
	ds_read_b128 v[214:217], v152 offset:38912
	ds_read_b128 v[218:221], v152 offset:39936
	global_load_lds_dwordx4 v134, s[44:45]
	s_mov_b32 m0, s56
	s_nop 0
	global_load_lds_dwordx4 v130, s[44:45]
	s_waitcnt vmcnt(8)
	s_waitcnt lgkmcnt(0)
	s_barrier
; #define PG8_STAGE(bufoff, gbase, voff) do { _Pragma("unroll") for (int _i = 0; _i < 2; ++_i) \
;         __builtin_amdgcn_global_load_lds((const unsigned*)((const char*)(gbase) + (voff)[_i]), (PG8_LAS unsigned*)(lds + (bufoff) + ldsw + _i * 8192), 16, 0, 0); } while (0)
; #define PG8_LDA(dst, b, h) do { _Pragma("unroll") for (int m = 0; m < 4; ++m) _Pragma("unroll") for (int k = 0; k < 2; ++k) dst[m][k] = *(const PG8_LAS bf16x8*)(lds + PG8_SA(b, h) + aoff + m * 2048 + k * 1024); } while (0)
; #define PG8_MMA(ai, bj, At, Bt) do { __builtin_amdgcn_s_setprio(1); _Pragma("unroll") for (int m = 0; m < 4; ++m) _Pragma("unroll") for (int n = 0; n < 2; ++n) _Pragma("unroll") for (int k = 0; k < 2; ++k) \
;         acc[ai][bj][m][n] = __builtin_amdgcn_mfma_f32_16x16x32_bf16(Bt[n][k], At[m][k], acc[ai][bj][m][n], 0, 0, 0); __builtin_amdgcn_s_setprio(0); } while (0)
; #define PG8_WAIT_V(n) asm volatile("s_waitcnt vmcnt(" #n ")" ::: "memory")
; #define PG8_WAIT_L(n) asm volatile("s_waitcnt lgkmcnt(" #n ")" ::: "memory")
; #define PG8_BAR __builtin_amdgcn_s_barrier()
; #define PG8_SCHED __builtin_amdgcn_sched_barrier(0)
; template <class Epi, class Sched, bool ALIGN_EPI = false, bool SP2 = false>
; __device__ __forceinline__ void gemm_phase(PG8_LAS unsigned char* lds, const Gemm g, const Sched& S, const Epi& E) {
;     ...
;             PG8_WAIT_V(8); PG8_WAIT_L(0); PG8_BAR; PG8_MMA(0, 0, At, B0); PG8_MMA(0, 1, At, B1); PG8_BAR; PG8_SCHED;
;             PG8_LDA(At, 1, 1); PG8_STAGE(PG8_SB(1, 0), b3, voffB); PG8_STAGE(PG8_SB(1, 1), b3 + hstep, voffB); PG8_STAGE(PG8_SA(1, 0), a3, voffA);
;             PG8_WAIT_V(8); PG8_WAIT_L(0); PG8_BAR; PG8_MMA(1, 0, At, B0); PG8_MMA(1, 1, At, B1); PG8_BAR; PG8_SCHED;
	v_mfma_f32_16x16x32_bf16 v[124:127], v[154:157], v[186:189], v[124:127]
	v_mfma_f32_16x16x32_bf16 v[116:119], v[162:165], v[186:189], v[116:119]
	v_mfma_f32_16x16x32_bf16 v[100:103], v[162:165], v[198:201], v[100:103]
	v_mfma_f32_16x16x32_bf16 v[108:111], v[154:157], v[198:201], v[108:111]
	v_mfma_f32_16x16x32_bf16 v[92:95], v[154:157], v[206:209], v[92:95]
	v_mfma_f32_16x16x32_bf16 v[84:87], v[162:165], v[206:209], v[84:87]
	v_mfma_f32_16x16x32_bf16 v[68:71], v[162:165], v[214:217], v[68:71]
	v_mfma_f32_16x16x32_bf16 v[76:79], v[154:157], v[214:217], v[76:79]
	v_mfma_f32_16x16x32_bf16 v[124:127], v[158:161], v[190:193], v[124:127]
	v_mfma_f32_16x16x32_bf16 v[116:119], v[166:169], v[190:193], v[116:119]
	v_mfma_f32_16x16x32_bf16 v[100:103], v[166:169], v[202:205], v[100:103]
	v_mfma_f32_16x16x32_bf16 v[108:111], v[158:161], v[202:205], v[108:111]
	v_mfma_f32_16x16x32_bf16 v[92:95], v[158:161], v[210:213], v[92:95]
	v_mfma_f32_16x16x32_bf16 v[84:87], v[166:169], v[210:213], v[84:87]
	v_mfma_f32_16x16x32_bf16 v[68:71], v[166:169], v[218:221], v[68:71]
	v_mfma_f32_16x16x32_bf16 v[76:79], v[158:161], v[218:221], v[76:79]
	v_mfma_f32_16x16x32_bf16 v[120:123], v[170:173], v[186:189], v[120:123]
	v_mfma_f32_16x16x32_bf16 v[112:115], v[178:181], v[186:189], v[112:115]
	v_mfma_f32_16x16x32_bf16 v[96:99], v[178:181], v[198:201], v[96:99]
	v_mfma_f32_16x16x32_bf16 v[104:107], v[170:173], v[198:201], v[104:107]
	v_mfma_f32_16x16x32_bf16 v[88:91], v[170:173], v[206:209], v[88:91]
	v_mfma_f32_16x16x32_bf16 v[80:83], v[178:181], v[206:209], v[80:83]
	v_mfma_f32_16x16x32_bf16 v[64:67], v[178:181], v[214:217], v[64:67]
	v_mfma_f32_16x16x32_bf16 v[72:75], v[170:173], v[214:217], v[72:75]
	v_mfma_f32_16x16x32_bf16 v[120:123], v[174:177], v[190:193], v[120:123]
	v_mfma_f32_16x16x32_bf16 v[112:115], v[182:185], v[190:193], v[112:115]
	v_mfma_f32_16x16x32_bf16 v[96:99], v[182:185], v[202:205], v[96:99]
	v_mfma_f32_16x16x32_bf16 v[104:107], v[174:177], v[202:205], v[104:107]
	v_mfma_f32_16x16x32_bf16 v[88:91], v[174:177], v[210:213], v[88:91]
	v_mfma_f32_16x16x32_bf16 v[80:83], v[182:185], v[210:213], v[80:83]
	v_mfma_f32_16x16x32_bf16 v[64:67], v[182:185], v[218:221], v[64:67]
	v_mfma_f32_16x16x32_bf16 v[72:75], v[174:177], v[218:221], v[72:75]
	s_barrier
	s_add_i32 s44, s70, s52
	s_mov_b32 m0, s44
	ds_read_b128 v[186:189], v152 offset:49152
	ds_read_b128 v[190:193], v152 offset:50176
	ds_read_b128 v[198:201], v152 offset:51200
	ds_read_b128 v[202:205], v152 offset:52224
	ds_read_b128 v[206:209], v152 offset:53248
	ds_read_b128 v[210:213], v152 offset:54272
	ds_read_b128 v[214:217], v152 offset:55296
	ds_read_b128 v[218:221], v152 offset:56320
	global_load_lds_dwordx4 v132, s[98:99]
	s_add_i32 m0, s44, 0x2000
	s_add_u32 s38, s38, 0x40080
	s_addc_u32 s39, s39, 0
	s_add_i32 s44, s71, s52
	global_load_lds_dwordx4 v128, s[98:99]
	s_mov_b32 m0, s44
	s_nop 0
	global_load_lds_dwordx4 v132, s[38:39]
	s_add_i32 m0, s44, 0x2000
	s_nop 0
	global_load_lds_dwordx4 v128, s[38:39]
	s_mov_b32 m0, s58
	s_nop 0
	global_load_lds_dwordx4 v134, s[100:101]
	s_mov_b32 m0, s59
	s_nop 0
	global_load_lds_dwordx4 v130, s[100:101]
	s_waitcnt vmcnt(8)
	s_waitcnt lgkmcnt(0)
	s_barrier
	v_mfma_f32_16x16x32_bf16 v[60:63], v[154:157], v[186:189], v[60:63]
	v_mfma_f32_16x16x32_bf16 v[52:55], v[162:165], v[186:189], v[52:55]
	v_mfma_f32_16x16x32_bf16 v[36:39], v[162:165], v[198:201], v[36:39]
	v_mfma_f32_16x16x32_bf16 v[44:47], v[154:157], v[198:201], v[44:47]
	v_mfma_f32_16x16x32_bf16 v[28:31], v[154:157], v[206:209], v[28:31]
	v_mfma_f32_16x16x32_bf16 v[20:23], v[162:165], v[206:209], v[20:23]
	v_mfma_f32_16x16x32_bf16 v[4:7], v[162:165], v[214:217], v[4:7]
	v_mfma_f32_16x16x32_bf16 v[12:15], v[154:157], v[214:217], v[12:15]
	v_mfma_f32_16x16x32_bf16 v[60:63], v[158:161], v[190:193], v[60:63]
	v_mfma_f32_16x16x32_bf16 v[52:55], v[166:169], v[190:193], v[52:55]
	v_mfma_f32_16x16x32_bf16 v[36:39], v[166:169], v[202:205], v[36:39]
	v_mfma_f32_16x16x32_bf16 v[44:47], v[158:161], v[202:205], v[44:47]
	v_mfma_f32_16x16x32_bf16 v[28:31], v[158:161], v[210:213], v[28:31]
	v_mfma_f32_16x16x32_bf16 v[20:23], v[166:169], v[210:213], v[20:23]
	v_mfma_f32_16x16x32_bf16 v[4:7], v[166:169], v[218:221], v[4:7]
	v_mfma_f32_16x16x32_bf16 v[12:15], v[158:161], v[218:221], v[12:15]
	v_mfma_f32_16x16x32_bf16 v[56:59], v[170:173], v[186:189], v[56:59]
	v_mfma_f32_16x16x32_bf16 v[48:51], v[178:181], v[186:189], v[48:51]
	v_mfma_f32_16x16x32_bf16 v[32:35], v[178:181], v[198:201], v[32:35]
	v_mfma_f32_16x16x32_bf16 v[40:43], v[170:173], v[198:201], v[40:43]
	v_mfma_f32_16x16x32_bf16 v[24:27], v[170:173], v[206:209], v[24:27]
	v_mfma_f32_16x16x32_bf16 v[16:19], v[178:181], v[206:209], v[16:19]
	v_mfma_f32_16x16x32_bf16 v[0:3], v[178:181], v[214:217], v[0:3]
	v_mfma_f32_16x16x32_bf16 v[8:11], v[170:173], v[214:217], v[8:11]
	v_mfma_f32_16x16x32_bf16 v[56:59], v[174:177], v[190:193], v[56:59]
	v_mfma_f32_16x16x32_bf16 v[48:51], v[182:185], v[190:193], v[48:51]
	v_mfma_f32_16x16x32_bf16 v[32:35], v[182:185], v[202:205], v[32:35]
	v_mfma_f32_16x16x32_bf16 v[40:43], v[174:177], v[202:205], v[40:43]
	v_mfma_f32_16x16x32_bf16 v[24:27], v[174:177], v[210:213], v[24:27]
	v_mfma_f32_16x16x32_bf16 v[16:19], v[182:185], v[210:213], v[16:19]
	v_mfma_f32_16x16x32_bf16 v[0:3], v[182:185], v[218:221], v[0:3]
	v_mfma_f32_16x16x32_bf16 v[8:11], v[174:177], v[218:221], v[8:11]
	s_barrier
	s_add_i32 s69, s69, 2
	s_add_u32 s20, s20, 0x100
	s_addc_u32 s21, s21, 0
	s_add_u32 s67, s67, 0x100
	s_addc_u32 s68, s68, 0
	s_cmp_gt_u32 s69, 13
	s_cbranch_scc0 .LBB0_810
	v_readlane_b32 s101, v249, 49
	s_nop 3
	s_cmp_eq_u32 s101, 0
	s_cbranch_scc1 .Ldw_done_1
	s_add_u32 s98, s28, 0x183500
	s_addc_u32 s99, s29, 0
	v_mov_b32_e32 v251, 0
	s_mov_b32 s100, 0

; #define PG8_STAGE(bufoff, gbase, voff) do { _Pragma("unroll") for (int _i = 0; _i < 2; ++_i) \
;         __builtin_amdgcn_global_load_lds((const unsigned*)((const char*)(gbase) + (voff)[_i]), (PG8_LAS unsigned*)(lds + (bufoff) + ldsw + _i * 8192), 16, 0, 0); } while (0)
; #define PG8_LDA(dst, b, h) do { _Pragma("unroll") for (int m = 0; m < 4; ++m) _Pragma("unroll") for (int k = 0; k < 2; ++k) dst[m][k] = *(const PG8_LAS bf16x8*)(lds + PG8_SA(b, h) + aoff + m * 2048 + k * 1024); } while (0)
; #define PG8_LDB(dst, b, h) do { _Pragma("unroll") for (int n = 0; n < 2; ++n) _Pragma("unroll") for (int k = 0; k < 2; ++k) dst[n][k] = *(const PG8_LAS bf16x8*)(lds + PG8_SB(b, h) + boff + n * 2048 + k * 1024); } while (0)
; #define PG8_WAIT_V(n) asm volatile("s_waitcnt vmcnt(" #n ")" ::: "memory")
; #define PG8_WAIT_L(n) asm volatile("s_waitcnt lgkmcnt(" #n ")" ::: "memory")
; #define PG8_BAR __builtin_amdgcn_s_barrier()
; #define PG8_SCHED __builtin_amdgcn_sched_barrier(0)
; template <class Epi, class Sched, bool ALIGN_EPI = false, bool SP2 = false>
; __device__ __forceinline__ void gemm_phase(PG8_LAS unsigned char* lds, const Gemm g, const Sched& S, const Epi& E) {
;     ...
;         const char* nA = has_next ? (const char*)g.A + (size_t)nxt.pm * tstep : cA; const char* nB = has_next ? (const char*)g.Bt + (size_t)nxt.pn * tstep : cB;
;         for (int t = 0; t < nt; t += 2) {
;             const bool last = (t == nt - 2);
;             const char* a1 = cA + (size_t)(t + 1) * kstep;
;             const char* a2 = last ? nA : cA + (size_t)(t + 2) * kstep; const char* b2 = last ? nB : cB + (size_t)(t + 2) * kstep;
;             const char* a3 = a2 + kstep; const char* b3 = b2 + kstep;
;             if (last && has_next) S.a_ready(nxt);
;             if constexpr (SP2) {
;             PG8_LDB(B0, 0, 0); PG8_LDB(B1, 0, 1); PG8_SCHED; PG8_LDA(At, 0, 0); PG8_STAGE(PG8_SA(1, 1), a1 + hstep, voffA);
;             PG8_WAIT_V(8); PG8_WAIT_L(0); PG8_BAR; PG8_MMA(0, 0, At, B0); PG8_MMA(0, 1, At, B1); PG8_BAR; PG8_SCHED;
;             PG8_LDA(At, 0, 1); PG8_STAGE(PG8_SB(0, 0), b2, voffB); PG8_STAGE(PG8_SB(0, 1), b2 + hstep, voffB); PG8_STAGE(PG8_SA(0, 0), a2, voffA);
;             PG8_WAIT_V(8); PG8_WAIT_L(0); PG8_BAR; PG8_MMA(1, 0, At, B0); PG8_MMA(1, 1, At, B1); PG8_BAR; PG8_SCHED;
.LBB0_894:
	s_add_u32 s20, s20, 0xb0080
	s_addc_u32 s21, s21, 0
	s_add_u32 s70, s34, 0x100
	s_addc_u32 s71, s35, 0
	s_mov_b32 s72, -2
	s_waitcnt lgkmcnt(0)
	ds_read_b128 v[96:99], v223
	ds_read_b128 v[108:111], v223 offset:1024
	ds_read_b128 v[120:123], v223 offset:2048
	ds_read_b128 v[128:131], v223 offset:3072
	ds_read_b128 v[144:147], v224
	ds_read_b128 v[148:151], v224 offset:1024
	ds_read_b128 v[152:155], v224 offset:2048
	ds_read_b128 v[156:159], v224 offset:3072
	s_add_u32 s34, s20, 0xfff50080
	s_addc_u32 s35, s21, -1
	s_cmp_eq_u32 s72, 40
	s_cselect_b32 s49, s1, s35
	s_cselect_b32 s48, s0, s34
	s_cselect_b32 s35, s47, s71
	s_cselect_b32 s34, s46, s70
	s_add_i32 m0, s51, 0xc000
	ds_read_b128 v[160:163], v225
	ds_read_b128 v[164:167], v225 offset:1024
	ds_read_b128 v[168:171], v225 offset:2048
	ds_read_b128 v[172:175], v225 offset:3072
	ds_read_b128 v[176:179], v225 offset:4096
	ds_read_b128 v[180:183], v225 offset:5120
	ds_read_b128 v[202:205], v225 offset:6144
	ds_read_b128 v[206:209], v225 offset:7168
	global_load_lds_dwordx4 v192, s[20:21]
	s_add_i32 m0, s51, 0xe000
	s_nop 0
	global_load_lds_dwordx4 v194, s[20:21]
	s_waitcnt vmcnt(8)
	s_waitcnt lgkmcnt(0)
	s_barrier
	v_mfma_f32_16x16x32_bf16 v[140:143], v[96:99], v[160:163], 0
	v_mfma_f32_16x16x32_bf16 v[136:139], v[120:123], v[160:163], 0
	v_mfma_f32_16x16x32_bf16 v[112:115], v[120:123], v[168:171], 0
	v_mfma_f32_16x16x32_bf16 v[116:119], v[96:99], v[168:171], 0
	v_mfma_f32_16x16x32_bf16 v[92:95], v[96:99], v[176:179], 0
	v_mfma_f32_16x16x32_bf16 v[88:91], v[120:123], v[176:179], 0
	v_mfma_f32_16x16x32_bf16 v[72:75], v[120:123], v[202:205], 0
	v_mfma_f32_16x16x32_bf16 v[76:79], v[96:99], v[202:205], 0
	v_mfma_f32_16x16x32_bf16 v[140:143], v[108:111], v[164:167], v[140:143]
	v_mfma_f32_16x16x32_bf16 v[136:139], v[128:131], v[164:167], v[136:139]
	v_mfma_f32_16x16x32_bf16 v[112:115], v[128:131], v[172:175], v[112:115]
	v_mfma_f32_16x16x32_bf16 v[116:119], v[108:111], v[172:175], v[116:119]
	v_mfma_f32_16x16x32_bf16 v[92:95], v[108:111], v[180:183], v[92:95]
	v_mfma_f32_16x16x32_bf16 v[88:91], v[128:131], v[180:183], v[88:91]
	v_mfma_f32_16x16x32_bf16 v[72:75], v[128:131], v[206:209], v[72:75]
	v_mfma_f32_16x16x32_bf16 v[76:79], v[108:111], v[206:209], v[76:79]
	v_mfma_f32_16x16x32_bf16 v[132:135], v[144:147], v[160:163], 0
	v_mfma_f32_16x16x32_bf16 v[124:127], v[152:155], v[160:163], 0
	v_mfma_f32_16x16x32_bf16 v[100:103], v[152:155], v[168:171], 0
	v_mfma_f32_16x16x32_bf16 v[104:107], v[144:147], v[168:171], 0
	v_mfma_f32_16x16x32_bf16 v[84:87], v[144:147], v[176:179], 0
	v_mfma_f32_16x16x32_bf16 v[80:83], v[152:155], v[176:179], 0
	v_mfma_f32_16x16x32_bf16 v[64:67], v[152:155], v[202:205], 0
	v_mfma_f32_16x16x32_bf16 v[68:71], v[144:147], v[202:205], 0
	v_mfma_f32_16x16x32_bf16 v[132:135], v[148:151], v[164:167], v[132:135]
	v_mfma_f32_16x16x32_bf16 v[124:127], v[156:159], v[164:167], v[124:127]
	v_mfma_f32_16x16x32_bf16 v[100:103], v[156:159], v[172:175], v[100:103]
	v_mfma_f32_16x16x32_bf16 v[104:107], v[148:151], v[172:175], v[104:107]
	v_mfma_f32_16x16x32_bf16 v[84:87], v[148:151], v[180:183], v[84:87]
	v_mfma_f32_16x16x32_bf16 v[80:83], v[156:159], v[180:183], v[80:83]
	v_mfma_f32_16x16x32_bf16 v[64:67], v[156:159], v[206:209], v[64:67]
	v_mfma_f32_16x16x32_bf16 v[68:71], v[148:151], v[206:209], v[68:71]
	s_barrier
	s_add_i32 s73, s64, s50
	s_add_u32 s98, s34, s12
	s_addc_u32 s99, s35, s13
	s_add_u32 s100, s48, s12
	s_addc_u32 s101, s49, s13
	s_mov_b32 m0, s73
	ds_read_b128 v[160:163], v225 offset:16384
	ds_read_b128 v[164:167], v225 offset:17408
	ds_read_b128 v[168:171], v225 offset:18432
	ds_read_b128 v[172:175], v225 offset:19456
	ds_read_b128 v[176:179], v225 offset:20480
	ds_read_b128 v[180:183], v225 offset:21504
	ds_read_b128 v[202:205], v225 offset:22528
	ds_read_b128 v[206:209], v225 offset:23552
	global_load_lds_dwordx4 v186, s[34:35]
	s_add_i32 m0, s73, 0x2000
	s_add_u32 s74, s34, 0xb0000
	s_addc_u32 s75, s35, 0
	s_add_i32 s73, s65, s50
	global_load_lds_dwordx4 v190, s[34:35]
	s_mov_b32 m0, s73
	s_nop 0
	global_load_lds_dwordx4 v186, s[74:75]
	s_add_i32 m0, s73, 0x2000
	s_nop 0
	global_load_lds_dwordx4 v190, s[74:75]
	s_mov_b32 m0, s51
	s_nop 0
	global_load_lds_dwordx4 v184, s[48:49]
	s_mov_b32 m0, s52
	s_nop 0
	global_load_lds_dwordx4 v188, s[48:49]
	s_waitcnt vmcnt(8)
	s_waitcnt lgkmcnt(0)
	s_barrier
	v_mfma_f32_16x16x32_bf16 v[60:63], v[96:99], v[160:163], 0
	v_mfma_f32_16x16x32_bf16 v[56:59], v[120:123], v[160:163], 0
	v_mfma_f32_16x16x32_bf16 v[40:43], v[120:123], v[168:171], 0
	v_mfma_f32_16x16x32_bf16 v[44:47], v[96:99], v[168:171], 0
	v_mfma_f32_16x16x32_bf16 v[28:31], v[96:99], v[176:179], 0
	v_mfma_f32_16x16x32_bf16 v[24:27], v[120:123], v[176:179], 0
	v_mfma_f32_16x16x32_bf16 v[8:11], v[120:123], v[202:205], 0
	v_mfma_f32_16x16x32_bf16 v[12:15], v[96:99], v[202:205], 0
	v_mfma_f32_16x16x32_bf16 v[60:63], v[108:111], v[164:167], v[60:63]
	v_mfma_f32_16x16x32_bf16 v[56:59], v[128:131], v[164:167], v[56:59]
	v_mfma_f32_16x16x32_bf16 v[40:43], v[128:131], v[172:175], v[40:43]
	v_mfma_f32_16x16x32_bf16 v[44:47], v[108:111], v[172:175], v[44:47]
	v_mfma_f32_16x16x32_bf16 v[28:31], v[108:111], v[180:183], v[28:31]
	v_mfma_f32_16x16x32_bf16 v[24:27], v[128:131], v[180:183], v[24:27]
	v_mfma_f32_16x16x32_bf16 v[8:11], v[128:131], v[206:209], v[8:11]
	v_mfma_f32_16x16x32_bf16 v[12:15], v[108:111], v[206:209], v[12:15]
	v_mfma_f32_16x16x32_bf16 v[52:55], v[144:147], v[160:163], 0
	v_mfma_f32_16x16x32_bf16 v[48:51], v[152:155], v[160:163], 0
	v_mfma_f32_16x16x32_bf16 v[32:35], v[152:155], v[168:171], 0
	v_mfma_f32_16x16x32_bf16 v[36:39], v[144:147], v[168:171], 0
	v_mfma_f32_16x16x32_bf16 v[20:23], v[144:147], v[176:179], 0
	v_mfma_f32_16x16x32_bf16 v[16:19], v[152:155], v[176:179], 0
	v_mfma_f32_16x16x32_bf16 v[0:3], v[152:155], v[202:205], 0
	v_mfma_f32_16x16x32_bf16 v[4:7], v[144:147], v[202:205], 0
	v_mfma_f32_16x16x32_bf16 v[52:55], v[148:151], v[164:167], v[52:55]
	v_mfma_f32_16x16x32_bf16 v[48:51], v[156:159], v[164:167], v[48:51]
	v_mfma_f32_16x16x32_bf16 v[32:35], v[156:159], v[172:175], v[32:35]
	v_mfma_f32_16x16x32_bf16 v[36:39], v[148:151], v[172:175], v[36:39]
	v_mfma_f32_16x16x32_bf16 v[20:23], v[148:151], v[180:183], v[20:23]
	v_mfma_f32_16x16x32_bf16 v[16:19], v[156:159], v[180:183], v[16:19]
	v_mfma_f32_16x16x32_bf16 v[0:3], v[156:159], v[206:209], v[0:3]
	v_mfma_f32_16x16x32_bf16 v[4:7], v[148:151], v[206:209], v[4:7]
	s_barrier
; #define PG8_STAGE(bufoff, gbase, voff) do { _Pragma("unroll") for (int _i = 0; _i < 2; ++_i) \
;         __builtin_amdgcn_global_load_lds((const unsigned*)((const char*)(gbase) + (voff)[_i]), (PG8_LAS unsigned*)(lds + (bufoff) + ldsw + _i * 8192), 16, 0, 0); } while (0)
; #define PG8_LDA(dst, b, h) do { _Pragma("unroll") for (int m = 0; m < 4; ++m) _Pragma("unroll") for (int k = 0; k < 2; ++k) dst[m][k] = *(const PG8_LAS bf16x8*)(lds + PG8_SA(b, h) + aoff + m * 2048 + k * 1024); } while (0)
; #define PG8_LDB(dst, b, h) do { _Pragma("unroll") for (int n = 0; n < 2; ++n) _Pragma("unroll") for (int k = 0; k < 2; ++k) dst[n][k] = *(const PG8_LAS bf16x8*)(lds + PG8_SB(b, h) + boff + n * 2048 + k * 1024); } while (0)
; #define PG8_MMA(ai, bj, At, Bt) do { __builtin_amdgcn_s_setprio(1); _Pragma("unroll") for (int m = 0; m < 4; ++m) _Pragma("unroll") for (int n = 0; n < 2; ++n) _Pragma("unroll") for (int k = 0; k < 2; ++k) \
;         acc[ai][bj][m][n] = __builtin_amdgcn_mfma_f32_16x16x32_bf16(Bt[n][k], At[m][k], acc[ai][bj][m][n], 0, 0, 0); __builtin_amdgcn_s_setprio(0); } while (0)
; #define PG8_WAIT_V(n) asm volatile("s_waitcnt vmcnt(" #n ")" ::: "memory")
; #define PG8_WAIT_L(n) asm volatile("s_waitcnt lgkmcnt(" #n ")" ::: "memory")
; #define PG8_BAR __builtin_amdgcn_s_barrier()
; #define PG8_SCHED __builtin_amdgcn_sched_barrier(0)
; template <class Epi, class Sched, bool ALIGN_EPI = false, bool SP2 = false>
; __device__ __forceinline__ void gemm_phase(PG8_LAS unsigned char* lds, const Gemm g, const Sched& S, const Epi& E) {
;     ...
;             PG8_LDB(B0, 1, 0); PG8_LDB(B1, 1, 1); PG8_SCHED; PG8_LDA(At, 1, 0); PG8_STAGE(PG8_SA(0, 1), a2 + hstep, voffA);
;             PG8_WAIT_V(8); PG8_WAIT_L(0); PG8_BAR; PG8_MMA(0, 0, At, B0); PG8_MMA(0, 1, At, B1); PG8_BAR; PG8_SCHED;
;             PG8_LDA(At, 1, 1); PG8_STAGE(PG8_SB(1, 0), b3, voffB); PG8_STAGE(PG8_SB(1, 1), b3 + hstep, voffB); PG8_STAGE(PG8_SA(1, 0), a3, voffA);
;             PG8_WAIT_V(8); PG8_WAIT_L(0); PG8_BAR; PG8_MMA(1, 0, At, B0); PG8_MMA(1, 1, At, B1); PG8_BAR; PG8_SCHED;
	s_add_i32 s73, 0, 0x18000
	s_add_i32 s74, 0, 0x1c000
	v_add_u32_e32 v128, s73, v221
	v_add_u32_e32 v156, s74, v221
	ds_read_b128 v[96:99], v128
	ds_read_b128 v[108:111], v128 offset:1024
	ds_read_b128 v[120:123], v128 offset:2048
	ds_read_b128 v[128:131], v128 offset:3072
	ds_read_b128 v[144:147], v156
	ds_read_b128 v[148:151], v156 offset:1024
	ds_read_b128 v[152:155], v156 offset:2048
	ds_read_b128 v[156:159], v156 offset:3072
	s_add_u32 s48, s48, 0xb0000
	s_addc_u32 s49, s49, 0
	s_mov_b32 m0, s53
	ds_read_b128 v[160:163], v225 offset:32768
	ds_read_b128 v[164:167], v225 offset:33792
	ds_read_b128 v[168:171], v225 offset:34816
	ds_read_b128 v[172:175], v225 offset:35840
	ds_read_b128 v[176:179], v225 offset:36864
	ds_read_b128 v[180:183], v225 offset:37888
	ds_read_b128 v[202:205], v225 offset:38912
	ds_read_b128 v[206:209], v225 offset:39936
	global_load_lds_dwordx4 v184, s[48:49]
	s_mov_b32 m0, s54
	s_nop 0
	global_load_lds_dwordx4 v188, s[48:49]
	s_waitcnt vmcnt(8)
	s_waitcnt lgkmcnt(0)
	s_barrier
	v_mfma_f32_16x16x32_bf16 v[140:143], v[96:99], v[160:163], v[140:143]
	v_mfma_f32_16x16x32_bf16 v[136:139], v[120:123], v[160:163], v[136:139]
	v_mfma_f32_16x16x32_bf16 v[112:115], v[120:123], v[168:171], v[112:115]
	v_mfma_f32_16x16x32_bf16 v[116:119], v[96:99], v[168:171], v[116:119]
	v_mfma_f32_16x16x32_bf16 v[92:95], v[96:99], v[176:179], v[92:95]
	v_mfma_f32_16x16x32_bf16 v[88:91], v[120:123], v[176:179], v[88:91]
	v_mfma_f32_16x16x32_bf16 v[72:75], v[120:123], v[202:205], v[72:75]
	v_mfma_f32_16x16x32_bf16 v[76:79], v[96:99], v[202:205], v[76:79]
	v_mfma_f32_16x16x32_bf16 v[140:143], v[108:111], v[164:167], v[140:143]
	v_mfma_f32_16x16x32_bf16 v[136:139], v[128:131], v[164:167], v[136:139]
	v_mfma_f32_16x16x32_bf16 v[112:115], v[128:131], v[172:175], v[112:115]
	v_mfma_f32_16x16x32_bf16 v[116:119], v[108:111], v[172:175], v[116:119]
	v_mfma_f32_16x16x32_bf16 v[92:95], v[108:111], v[180:183], v[92:95]
	v_mfma_f32_16x16x32_bf16 v[88:91], v[128:131], v[180:183], v[88:91]
	v_mfma_f32_16x16x32_bf16 v[72:75], v[128:131], v[206:209], v[72:75]
	v_mfma_f32_16x16x32_bf16 v[76:79], v[108:111], v[206:209], v[76:79]
	v_mfma_f32_16x16x32_bf16 v[132:135], v[144:147], v[160:163], v[132:135]
	v_mfma_f32_16x16x32_bf16 v[124:127], v[152:155], v[160:163], v[124:127]
	v_mfma_f32_16x16x32_bf16 v[100:103], v[152:155], v[168:171], v[100:103]
	v_mfma_f32_16x16x32_bf16 v[104:107], v[144:147], v[168:171], v[104:107]
	v_mfma_f32_16x16x32_bf16 v[84:87], v[144:147], v[176:179], v[84:87]
	v_mfma_f32_16x16x32_bf16 v[80:83], v[152:155], v[176:179], v[80:83]
	v_mfma_f32_16x16x32_bf16 v[64:67], v[152:155], v[202:205], v[64:67]
	v_mfma_f32_16x16x32_bf16 v[68:71], v[144:147], v[202:205], v[68:71]
	v_mfma_f32_16x16x32_bf16 v[132:135], v[148:151], v[164:167], v[132:135]
	v_mfma_f32_16x16x32_bf16 v[124:127], v[156:159], v[164:167], v[124:127]
	v_mfma_f32_16x16x32_bf16 v[100:103], v[156:159], v[172:175], v[100:103]
	v_mfma_f32_16x16x32_bf16 v[104:107], v[148:151], v[172:175], v[104:107]
	v_mfma_f32_16x16x32_bf16 v[84:87], v[148:151], v[180:183], v[84:87]
	v_mfma_f32_16x16x32_bf16 v[80:83], v[156:159], v[180:183], v[80:83]
	v_mfma_f32_16x16x32_bf16 v[64:67], v[156:159], v[206:209], v[64:67]
	v_mfma_f32_16x16x32_bf16 v[68:71], v[148:151], v[206:209], v[68:71]
	s_barrier
	s_add_i32 s48, s73, s50
	s_mov_b32 m0, s48
	ds_read_b128 v[160:163], v225 offset:49152
	ds_read_b128 v[164:167], v225 offset:50176
	ds_read_b128 v[168:171], v225 offset:51200
	ds_read_b128 v[172:175], v225 offset:52224
	ds_read_b128 v[176:179], v225 offset:53248
	ds_read_b128 v[180:183], v225 offset:54272
	ds_read_b128 v[202:205], v225 offset:55296
	ds_read_b128 v[206:209], v225 offset:56320
	global_load_lds_dwordx4 v186, s[98:99]
	s_add_i32 m0, s48, 0x2000
	s_add_u32 s34, s34, 0xb0080
	s_addc_u32 s35, s35, 0
	s_add_i32 s48, s74, s50
	global_load_lds_dwordx4 v190, s[98:99]
	s_mov_b32 m0, s48
	s_nop 0
	global_load_lds_dwordx4 v186, s[34:35]
	s_add_i32 m0, s48, 0x2000
	s_nop 0
	global_load_lds_dwordx4 v190, s[34:35]
	s_mov_b32 m0, s59
	s_nop 0
	global_load_lds_dwordx4 v184, s[100:101]
	s_mov_b32 m0, s60
	s_nop 0
	global_load_lds_dwordx4 v188, s[100:101]
	s_waitcnt vmcnt(8)
	s_waitcnt lgkmcnt(0)
	s_barrier
	v_mfma_f32_16x16x32_bf16 v[60:63], v[96:99], v[160:163], v[60:63]
	v_mfma_f32_16x16x32_bf16 v[56:59], v[120:123], v[160:163], v[56:59]
	v_mfma_f32_16x16x32_bf16 v[40:43], v[120:123], v[168:171], v[40:43]
	v_mfma_f32_16x16x32_bf16 v[44:47], v[96:99], v[168:171], v[44:47]
	v_mfma_f32_16x16x32_bf16 v[28:31], v[96:99], v[176:179], v[28:31]
	v_mfma_f32_16x16x32_bf16 v[24:27], v[120:123], v[176:179], v[24:27]
	v_mfma_f32_16x16x32_bf16 v[8:11], v[120:123], v[202:205], v[8:11]
	v_mfma_f32_16x16x32_bf16 v[12:15], v[96:99], v[202:205], v[12:15]
	v_mfma_f32_16x16x32_bf16 v[60:63], v[108:111], v[164:167], v[60:63]
	v_mfma_f32_16x16x32_bf16 v[56:59], v[128:131], v[164:167], v[56:59]
	v_mfma_f32_16x16x32_bf16 v[40:43], v[128:131], v[172:175], v[40:43]
	v_mfma_f32_16x16x32_bf16 v[44:47], v[108:111], v[172:175], v[44:47]
	v_mfma_f32_16x16x32_bf16 v[28:31], v[108:111], v[180:183], v[28:31]
	v_mfma_f32_16x16x32_bf16 v[24:27], v[128:131], v[180:183], v[24:27]
	v_mfma_f32_16x16x32_bf16 v[8:11], v[128:131], v[206:209], v[8:11]
	v_mfma_f32_16x16x32_bf16 v[12:15], v[108:111], v[206:209], v[12:15]
	v_mfma_f32_16x16x32_bf16 v[52:55], v[144:147], v[160:163], v[52:55]
	v_mfma_f32_16x16x32_bf16 v[48:51], v[152:155], v[160:163], v[48:51]
	v_mfma_f32_16x16x32_bf16 v[32:35], v[152:155], v[168:171], v[32:35]
	v_mfma_f32_16x16x32_bf16 v[36:39], v[144:147], v[168:171], v[36:39]
	v_mfma_f32_16x16x32_bf16 v[20:23], v[144:147], v[176:179], v[20:23]
	v_mfma_f32_16x16x32_bf16 v[16:19], v[152:155], v[176:179], v[16:19]
	v_mfma_f32_16x16x32_bf16 v[0:3], v[152:155], v[202:205], v[0:3]
	v_mfma_f32_16x16x32_bf16 v[4:7], v[144:147], v[202:205], v[4:7]
	v_mfma_f32_16x16x32_bf16 v[52:55], v[148:151], v[164:167], v[52:55]
	v_mfma_f32_16x16x32_bf16 v[48:51], v[156:159], v[164:167], v[48:51]
	v_mfma_f32_16x16x32_bf16 v[32:35], v[156:159], v[172:175], v[32:35]
	v_mfma_f32_16x16x32_bf16 v[36:39], v[148:151], v[172:175], v[36:39]
	v_mfma_f32_16x16x32_bf16 v[20:23], v[148:151], v[180:183], v[20:23]
	v_mfma_f32_16x16x32_bf16 v[16:19], v[156:159], v[180:183], v[16:19]
	v_mfma_f32_16x16x32_bf16 v[0:3], v[156:159], v[206:209], v[0:3]
	v_mfma_f32_16x16x32_bf16 v[4:7], v[148:151], v[206:209], v[4:7]
	s_barrier
	s_add_i32 s72, s72, 2
	s_add_u32 s20, s20, 0x100
	s_addc_u32 s21, s21, 0
	s_add_u32 s70, s70, 0x100
	s_addc_u32 s71, s71, 0
	s_cmp_gt_u32 s72, 41
; #define PG8_STAGE(bufoff, gbase, voff) do { _Pragma("unroll") for (int _i = 0; _i < 2; ++_i) \
;         __builtin_amdgcn_global_load_lds((const unsigned*)((const char*)(gbase) + (voff)[_i]), (PG8_LAS unsigned*)(lds + (bufoff) + ldsw + _i * 8192), 16, 0, 0); } while (0)
; #define PG8_LDA(dst, b, h) do { _Pragma("unroll") for (int m = 0; m < 4; ++m) _Pragma("unroll") for (int k = 0; k < 2; ++k) dst[m][k] = *(const PG8_LAS bf16x8*)(lds + PG8_SA(b, h) + aoff + m * 2048 + k * 1024); } while (0)
; #define PG8_LDB(dst, b, h) do { _Pragma("unroll") for (int n = 0; n < 2; ++n) _Pragma("unroll") for (int k = 0; k < 2; ++k) dst[n][k] = *(const PG8_LAS bf16x8*)(lds + PG8_SB(b, h) + boff + n * 2048 + k * 1024); } while (0)
; #define PG8_MMA(ai, bj, At, Bt) do { __builtin_amdgcn_s_setprio(1); _Pragma("unroll") for (int m = 0; m < 4; ++m) _Pragma("unroll") for (int n = 0; n < 2; ++n) _Pragma("unroll") for (int k = 0; k < 2; ++k) \
;         acc[ai][bj][m][n] = __builtin_amdgcn_mfma_f32_16x16x32_bf16(Bt[n][k], At[m][k], acc[ai][bj][m][n], 0, 0, 0); __builtin_amdgcn_s_setprio(0); } while (0)
; #define PG8_WAIT_V(n) asm volatile("s_waitcnt vmcnt(" #n ")" ::: "memory")
; #define PG8_WAIT_L(n) asm volatile("s_waitcnt lgkmcnt(" #n ")" ::: "memory")
; #define PG8_BAR __builtin_amdgcn_s_barrier()
; #define PG8_SCHED __builtin_amdgcn_sched_barrier(0)
; template <class Epi, class Sched, bool ALIGN_EPI = false, bool SP2 = false>
; __device__ __forceinline__ void gemm_phase(PG8_LAS unsigned char* lds, const Gemm g, const Sched& S, const Epi& E) {
;     ...
;             PG8_LDB(B0, 0, 0); PG8_LDB(B1, 0, 1); PG8_SCHED; PG8_LDA(At, 0, 0); PG8_STAGE(PG8_SA(1, 1), a1 + hstep, voffA);
;             PG8_WAIT_V(8); PG8_WAIT_L(0); PG8_BAR; PG8_MMA(0, 0, At, B0); PG8_MMA(0, 1, At, B1); PG8_BAR; PG8_SCHED;
;             PG8_LDA(At, 0, 1); PG8_STAGE(PG8_SB(0, 0), b2, voffB); PG8_STAGE(PG8_SB(0, 1), b2 + hstep, voffB); PG8_STAGE(PG8_SA(0, 0), a2, voffA);
;             PG8_WAIT_V(8); PG8_WAIT_L(0); PG8_BAR; PG8_MMA(1, 0, At, B0); PG8_MMA(1, 1, At, B1); PG8_BAR; PG8_SCHED;
.LBB0_895:
	ds_read_b128 v[96:99], v223
	ds_read_b128 v[108:111], v223 offset:1024
	ds_read_b128 v[120:123], v223 offset:2048
	ds_read_b128 v[128:131], v223 offset:3072
	ds_read_b128 v[144:147], v224
	ds_read_b128 v[148:151], v224 offset:1024
	ds_read_b128 v[152:155], v224 offset:2048
	ds_read_b128 v[156:159], v224 offset:3072
	s_add_u32 s34, s20, 0xfff50080
	s_addc_u32 s35, s21, -1
	s_cmp_eq_u32 s72, 40
	s_cselect_b32 s49, s1, s35
	s_cselect_b32 s48, s0, s34
	s_cselect_b32 s35, s47, s71
	s_cselect_b32 s34, s46, s70
	s_add_i32 m0, s51, 0xc000
	ds_read_b128 v[160:163], v225
	ds_read_b128 v[164:167], v225 offset:1024
	ds_read_b128 v[168:171], v225 offset:2048
	ds_read_b128 v[172:175], v225 offset:3072
	ds_read_b128 v[176:179], v225 offset:4096
	ds_read_b128 v[180:183], v225 offset:5120
	ds_read_b128 v[202:205], v225 offset:6144
	ds_read_b128 v[206:209], v225 offset:7168
	global_load_lds_dwordx4 v192, s[20:21]
	s_add_i32 m0, s51, 0xe000
	s_nop 0
	global_load_lds_dwordx4 v194, s[20:21]
	s_waitcnt vmcnt(8)
	s_waitcnt lgkmcnt(0)
	s_barrier
	v_mfma_f32_16x16x32_bf16 v[140:143], v[96:99], v[160:163], v[140:143]
	v_mfma_f32_16x16x32_bf16 v[136:139], v[120:123], v[160:163], v[136:139]
	v_mfma_f32_16x16x32_bf16 v[112:115], v[120:123], v[168:171], v[112:115]
	v_mfma_f32_16x16x32_bf16 v[116:119], v[96:99], v[168:171], v[116:119]
	v_mfma_f32_16x16x32_bf16 v[92:95], v[96:99], v[176:179], v[92:95]
	v_mfma_f32_16x16x32_bf16 v[88:91], v[120:123], v[176:179], v[88:91]
	v_mfma_f32_16x16x32_bf16 v[72:75], v[120:123], v[202:205], v[72:75]
	v_mfma_f32_16x16x32_bf16 v[76:79], v[96:99], v[202:205], v[76:79]
	v_mfma_f32_16x16x32_bf16 v[140:143], v[108:111], v[164:167], v[140:143]
	v_mfma_f32_16x16x32_bf16 v[136:139], v[128:131], v[164:167], v[136:139]
	v_mfma_f32_16x16x32_bf16 v[112:115], v[128:131], v[172:175], v[112:115]
	v_mfma_f32_16x16x32_bf16 v[116:119], v[108:111], v[172:175], v[116:119]
	v_mfma_f32_16x16x32_bf16 v[92:95], v[108:111], v[180:183], v[92:95]
	v_mfma_f32_16x16x32_bf16 v[88:91], v[128:131], v[180:183], v[88:91]
	v_mfma_f32_16x16x32_bf16 v[72:75], v[128:131], v[206:209], v[72:75]
	v_mfma_f32_16x16x32_bf16 v[76:79], v[108:111], v[206:209], v[76:79]
	v_mfma_f32_16x16x32_bf16 v[132:135], v[144:147], v[160:163], v[132:135]
	v_mfma_f32_16x16x32_bf16 v[124:127], v[152:155], v[160:163], v[124:127]
	v_mfma_f32_16x16x32_bf16 v[100:103], v[152:155], v[168:171], v[100:103]
	v_mfma_f32_16x16x32_bf16 v[104:107], v[144:147], v[168:171], v[104:107]
	v_mfma_f32_16x16x32_bf16 v[84:87], v[144:147], v[176:179], v[84:87]
	v_mfma_f32_16x16x32_bf16 v[80:83], v[152:155], v[176:179], v[80:83]
	v_mfma_f32_16x16x32_bf16 v[64:67], v[152:155], v[202:205], v[64:67]
	v_mfma_f32_16x16x32_bf16 v[68:71], v[144:147], v[202:205], v[68:71]
	v_mfma_f32_16x16x32_bf16 v[132:135], v[148:151], v[164:167], v[132:135]
	v_mfma_f32_16x16x32_bf16 v[124:127], v[156:159], v[164:167], v[124:127]
	v_mfma_f32_16x16x32_bf16 v[100:103], v[156:159], v[172:175], v[100:103]
	v_mfma_f32_16x16x32_bf16 v[104:107], v[148:151], v[172:175], v[104:107]
	v_mfma_f32_16x16x32_bf16 v[84:87], v[148:151], v[180:183], v[84:87]
	v_mfma_f32_16x16x32_bf16 v[80:83], v[156:159], v[180:183], v[80:83]
	v_mfma_f32_16x16x32_bf16 v[64:67], v[156:159], v[206:209], v[64:67]
	v_mfma_f32_16x16x32_bf16 v[68:71], v[148:151], v[206:209], v[68:71]
	s_barrier
	s_add_i32 s73, s64, s50
	s_add_u32 s98, s34, s12
	s_addc_u32 s99, s35, s13
	s_add_u32 s100, s48, s12
	s_addc_u32 s101, s49, s13
	s_mov_b32 m0, s73
	ds_read_b128 v[160:163], v225 offset:16384
	ds_read_b128 v[164:167], v225 offset:17408
	ds_read_b128 v[168:171], v225 offset:18432
	ds_read_b128 v[172:175], v225 offset:19456
	ds_read_b128 v[176:179], v225 offset:20480
	ds_read_b128 v[180:183], v225 offset:21504
	ds_read_b128 v[202:205], v225 offset:22528
	ds_read_b128 v[206:209], v225 offset:23552
	global_load_lds_dwordx4 v186, s[34:35]
	s_add_i32 m0, s73, 0x2000
	s_add_u32 s74, s34, 0xb0000
	s_addc_u32 s75, s35, 0
	s_add_i32 s73, s65, s50
	global_load_lds_dwordx4 v190, s[34:35]
	s_mov_b32 m0, s73
	s_nop 0
	global_load_lds_dwordx4 v186, s[74:75]
	s_add_i32 m0, s73, 0x2000
	s_nop 0
	global_load_lds_dwordx4 v190, s[74:75]
	s_mov_b32 m0, s51
	s_nop 0
	global_load_lds_dwordx4 v184, s[48:49]
	s_mov_b32 m0, s52
	s_nop 0
	global_load_lds_dwordx4 v188, s[48:49]
	s_waitcnt vmcnt(8)
	s_waitcnt lgkmcnt(0)
	s_barrier
	v_mfma_f32_16x16x32_bf16 v[60:63], v[96:99], v[160:163], v[60:63]
	v_mfma_f32_16x16x32_bf16 v[56:59], v[120:123], v[160:163], v[56:59]
	v_mfma_f32_16x16x32_bf16 v[40:43], v[120:123], v[168:171], v[40:43]
	v_mfma_f32_16x16x32_bf16 v[44:47], v[96:99], v[168:171], v[44:47]
	v_mfma_f32_16x16x32_bf16 v[28:31], v[96:99], v[176:179], v[28:31]
	v_mfma_f32_16x16x32_bf16 v[24:27], v[120:123], v[176:179], v[24:27]
	v_mfma_f32_16x16x32_bf16 v[8:11], v[120:123], v[202:205], v[8:11]
	v_mfma_f32_16x16x32_bf16 v[12:15], v[96:99], v[202:205], v[12:15]
	v_mfma_f32_16x16x32_bf16 v[60:63], v[108:111], v[164:167], v[60:63]
	v_mfma_f32_16x16x32_bf16 v[56:59], v[128:131], v[164:167], v[56:59]
	v_mfma_f32_16x16x32_bf16 v[40:43], v[128:131], v[172:175], v[40:43]
	v_mfma_f32_16x16x32_bf16 v[44:47], v[108:111], v[172:175], v[44:47]
	v_mfma_f32_16x16x32_bf16 v[28:31], v[108:111], v[180:183], v[28:31]
	v_mfma_f32_16x16x32_bf16 v[24:27], v[128:131], v[180:183], v[24:27]
	v_mfma_f32_16x16x32_bf16 v[8:11], v[128:131], v[206:209], v[8:11]
	v_mfma_f32_16x16x32_bf16 v[12:15], v[108:111], v[206:209], v[12:15]
	v_mfma_f32_16x16x32_bf16 v[52:55], v[144:147], v[160:163], v[52:55]
	v_mfma_f32_16x16x32_bf16 v[48:51], v[152:155], v[160:163], v[48:51]
	v_mfma_f32_16x16x32_bf16 v[32:35], v[152:155], v[168:171], v[32:35]
	v_mfma_f32_16x16x32_bf16 v[36:39], v[144:147], v[168:171], v[36:39]
	v_mfma_f32_16x16x32_bf16 v[20:23], v[144:147], v[176:179], v[20:23]
	v_mfma_f32_16x16x32_bf16 v[16:19], v[152:155], v[176:179], v[16:19]
	v_mfma_f32_16x16x32_bf16 v[0:3], v[152:155], v[202:205], v[0:3]
	v_mfma_f32_16x16x32_bf16 v[4:7], v[144:147], v[202:205], v[4:7]
	v_mfma_f32_16x16x32_bf16 v[52:55], v[148:151], v[164:167], v[52:55]
	v_mfma_f32_16x16x32_bf16 v[48:51], v[156:159], v[164:167], v[48:51]
	v_mfma_f32_16x16x32_bf16 v[32:35], v[156:159], v[172:175], v[32:35]
	v_mfma_f32_16x16x32_bf16 v[36:39], v[148:151], v[172:175], v[36:39]
	v_mfma_f32_16x16x32_bf16 v[20:23], v[148:151], v[180:183], v[20:23]
	v_mfma_f32_16x16x32_bf16 v[16:19], v[156:159], v[180:183], v[16:19]
	v_mfma_f32_16x16x32_bf16 v[0:3], v[156:159], v[206:209], v[0:3]
	v_mfma_f32_16x16x32_bf16 v[4:7], v[148:151], v[206:209], v[4:7]
	s_barrier
; #define PG8_STAGE(bufoff, gbase, voff) do { _Pragma("unroll") for (int _i = 0; _i < 2; ++_i) \
;         __builtin_amdgcn_global_load_lds((const unsigned*)((const char*)(gbase) + (voff)[_i]), (PG8_LAS unsigned*)(lds + (bufoff) + ldsw + _i * 8192), 16, 0, 0); } while (0)
; #define PG8_LDA(dst, b, h) do { _Pragma("unroll") for (int m = 0; m < 4; ++m) _Pragma("unroll") for (int k = 0; k < 2; ++k) dst[m][k] = *(const PG8_LAS bf16x8*)(lds + PG8_SA(b, h) + aoff + m * 2048 + k * 1024); } while (0)
; #define PG8_LDB(dst, b, h) do { _Pragma("unroll") for (int n = 0; n < 2; ++n) _Pragma("unroll") for (int k = 0; k < 2; ++k) dst[n][k] = *(const PG8_LAS bf16x8*)(lds + PG8_SB(b, h) + boff + n * 2048 + k * 1024); } while (0)
; #define PG8_MMA(ai, bj, At, Bt) do { __builtin_amdgcn_s_setprio(1); _Pragma("unroll") for (int m = 0; m < 4; ++m) _Pragma("unroll") for (int n = 0; n < 2; ++n) _Pragma("unroll") for (int k = 0; k < 2; ++k) \
;         acc[ai][bj][m][n] = __builtin_amdgcn_mfma_f32_16x16x32_bf16(Bt[n][k], At[m][k], acc[ai][bj][m][n], 0, 0, 0); __builtin_amdgcn_s_setprio(0); } while (0)
; #define PG8_WAIT_V(n) asm volatile("s_waitcnt vmcnt(" #n ")" ::: "memory")
; #define PG8_WAIT_L(n) asm volatile("s_waitcnt lgkmcnt(" #n ")" ::: "memory")
; #define PG8_BAR __builtin_amdgcn_s_barrier()
; #define PG8_SCHED __builtin_amdgcn_sched_barrier(0)
; template <class Epi, class Sched, bool ALIGN_EPI = false, bool SP2 = false>
; __device__ __forceinline__ void gemm_phase(PG8_LAS unsigned char* lds, const Gemm g, const Sched& S, const Epi& E) {
;     ...
;             PG8_LDB(B0, 1, 0); PG8_LDB(B1, 1, 1); PG8_SCHED; PG8_LDA(At, 1, 0); PG8_STAGE(PG8_SA(0, 1), a2 + hstep, voffA);
;             PG8_WAIT_V(8); PG8_WAIT_L(0); PG8_BAR; PG8_MMA(0, 0, At, B0); PG8_MMA(0, 1, At, B1); PG8_BAR; PG8_SCHED;
;             PG8_LDA(At, 1, 1); PG8_STAGE(PG8_SB(1, 0), b3, voffB); PG8_STAGE(PG8_SB(1, 1), b3 + hstep, voffB); PG8_STAGE(PG8_SA(1, 0), a3, voffA);
;             PG8_WAIT_V(8); PG8_WAIT_L(0); PG8_BAR; PG8_MMA(1, 0, At, B0); PG8_MMA(1, 1, At, B1); PG8_BAR; PG8_SCHED;
;     ...
;         if constexpr (ALIGN_EPI) { if (wr == 0) PG8_BAR; }
	s_add_i32 s73, 0, 0x18000
	s_add_i32 s74, 0, 0x1c000
	v_add_u32_e32 v128, s73, v221
	v_add_u32_e32 v156, s74, v221
	ds_read_b128 v[96:99], v128
	ds_read_b128 v[108:111], v128 offset:1024
	ds_read_b128 v[120:123], v128 offset:2048
	ds_read_b128 v[128:131], v128 offset:3072
	ds_read_b128 v[144:147], v156
	ds_read_b128 v[148:151], v156 offset:1024
	ds_read_b128 v[152:155], v156 offset:2048
	ds_read_b128 v[156:159], v156 offset:3072
	s_add_u32 s48, s48, 0xb0000
	s_addc_u32 s49, s49, 0
	s_mov_b32 m0, s53
	ds_read_b128 v[160:163], v225 offset:32768
	ds_read_b128 v[164:167], v225 offset:33792
	ds_read_b128 v[168:171], v225 offset:34816
	ds_read_b128 v[172:175], v225 offset:35840
	ds_read_b128 v[176:179], v225 offset:36864
	ds_read_b128 v[180:183], v225 offset:37888
	ds_read_b128 v[202:205], v225 offset:38912
	ds_read_b128 v[206:209], v225 offset:39936
	global_load_lds_dwordx4 v184, s[48:49]
	s_mov_b32 m0, s54
	s_nop 0
	global_load_lds_dwordx4 v188, s[48:49]
	s_waitcnt vmcnt(8)
	s_waitcnt lgkmcnt(0)
	s_barrier
	v_mfma_f32_16x16x32_bf16 v[140:143], v[96:99], v[160:163], v[140:143]
	v_mfma_f32_16x16x32_bf16 v[136:139], v[120:123], v[160:163], v[136:139]
	v_mfma_f32_16x16x32_bf16 v[112:115], v[120:123], v[168:171], v[112:115]
	v_mfma_f32_16x16x32_bf16 v[116:119], v[96:99], v[168:171], v[116:119]
	v_mfma_f32_16x16x32_bf16 v[92:95], v[96:99], v[176:179], v[92:95]
	v_mfma_f32_16x16x32_bf16 v[88:91], v[120:123], v[176:179], v[88:91]
	v_mfma_f32_16x16x32_bf16 v[72:75], v[120:123], v[202:205], v[72:75]
	v_mfma_f32_16x16x32_bf16 v[76:79], v[96:99], v[202:205], v[76:79]
	v_mfma_f32_16x16x32_bf16 v[140:143], v[108:111], v[164:167], v[140:143]
	v_mfma_f32_16x16x32_bf16 v[136:139], v[128:131], v[164:167], v[136:139]
	v_mfma_f32_16x16x32_bf16 v[112:115], v[128:131], v[172:175], v[112:115]
	v_mfma_f32_16x16x32_bf16 v[116:119], v[108:111], v[172:175], v[116:119]
	v_mfma_f32_16x16x32_bf16 v[92:95], v[108:111], v[180:183], v[92:95]
	v_mfma_f32_16x16x32_bf16 v[88:91], v[128:131], v[180:183], v[88:91]
	v_mfma_f32_16x16x32_bf16 v[72:75], v[128:131], v[206:209], v[72:75]
	v_mfma_f32_16x16x32_bf16 v[76:79], v[108:111], v[206:209], v[76:79]
	v_mfma_f32_16x16x32_bf16 v[132:135], v[144:147], v[160:163], v[132:135]
	v_mfma_f32_16x16x32_bf16 v[124:127], v[152:155], v[160:163], v[124:127]
	v_mfma_f32_16x16x32_bf16 v[100:103], v[152:155], v[168:171], v[100:103]
	v_mfma_f32_16x16x32_bf16 v[104:107], v[144:147], v[168:171], v[104:107]
	v_mfma_f32_16x16x32_bf16 v[84:87], v[144:147], v[176:179], v[84:87]
	v_mfma_f32_16x16x32_bf16 v[80:83], v[152:155], v[176:179], v[80:83]
	v_mfma_f32_16x16x32_bf16 v[64:67], v[152:155], v[202:205], v[64:67]
	v_mfma_f32_16x16x32_bf16 v[68:71], v[144:147], v[202:205], v[68:71]
	v_mfma_f32_16x16x32_bf16 v[132:135], v[148:151], v[164:167], v[132:135]
	v_mfma_f32_16x16x32_bf16 v[124:127], v[156:159], v[164:167], v[124:127]
	v_mfma_f32_16x16x32_bf16 v[100:103], v[156:159], v[172:175], v[100:103]
	v_mfma_f32_16x16x32_bf16 v[104:107], v[148:151], v[172:175], v[104:107]
	v_mfma_f32_16x16x32_bf16 v[84:87], v[148:151], v[180:183], v[84:87]
	v_mfma_f32_16x16x32_bf16 v[80:83], v[156:159], v[180:183], v[80:83]
	v_mfma_f32_16x16x32_bf16 v[64:67], v[156:159], v[206:209], v[64:67]
	v_mfma_f32_16x16x32_bf16 v[68:71], v[148:151], v[206:209], v[68:71]
	s_barrier
	s_add_i32 s48, s73, s50
	s_mov_b32 m0, s48
	ds_read_b128 v[160:163], v225 offset:49152
	ds_read_b128 v[164:167], v225 offset:50176
	ds_read_b128 v[168:171], v225 offset:51200
	ds_read_b128 v[172:175], v225 offset:52224
	ds_read_b128 v[176:179], v225 offset:53248
	ds_read_b128 v[180:183], v225 offset:54272
	ds_read_b128 v[202:205], v225 offset:55296
	ds_read_b128 v[206:209], v225 offset:56320
	global_load_lds_dwordx4 v186, s[98:99]
	s_add_i32 m0, s48, 0x2000
	s_add_u32 s34, s34, 0xb0080
	s_addc_u32 s35, s35, 0
	s_add_i32 s48, s74, s50
	global_load_lds_dwordx4 v190, s[98:99]
	s_mov_b32 m0, s48
	s_nop 0
	global_load_lds_dwordx4 v186, s[34:35]
	s_add_i32 m0, s48, 0x2000
	s_nop 0
	global_load_lds_dwordx4 v190, s[34:35]
	s_mov_b32 m0, s59
	s_nop 0
	global_load_lds_dwordx4 v184, s[100:101]
	s_mov_b32 m0, s60
	s_nop 0
	global_load_lds_dwordx4 v188, s[100:101]
	s_waitcnt vmcnt(8)
	s_waitcnt lgkmcnt(0)
	s_barrier
	v_mfma_f32_16x16x32_bf16 v[60:63], v[96:99], v[160:163], v[60:63]
	v_mfma_f32_16x16x32_bf16 v[56:59], v[120:123], v[160:163], v[56:59]
	v_mfma_f32_16x16x32_bf16 v[40:43], v[120:123], v[168:171], v[40:43]
	v_mfma_f32_16x16x32_bf16 v[44:47], v[96:99], v[168:171], v[44:47]
	v_mfma_f32_16x16x32_bf16 v[28:31], v[96:99], v[176:179], v[28:31]
	v_mfma_f32_16x16x32_bf16 v[24:27], v[120:123], v[176:179], v[24:27]
	v_mfma_f32_16x16x32_bf16 v[8:11], v[120:123], v[202:205], v[8:11]
	v_mfma_f32_16x16x32_bf16 v[12:15], v[96:99], v[202:205], v[12:15]
	v_mfma_f32_16x16x32_bf16 v[60:63], v[108:111], v[164:167], v[60:63]
	v_mfma_f32_16x16x32_bf16 v[56:59], v[128:131], v[164:167], v[56:59]
	v_mfma_f32_16x16x32_bf16 v[40:43], v[128:131], v[172:175], v[40:43]
	v_mfma_f32_16x16x32_bf16 v[44:47], v[108:111], v[172:175], v[44:47]
	v_mfma_f32_16x16x32_bf16 v[28:31], v[108:111], v[180:183], v[28:31]
	v_mfma_f32_16x16x32_bf16 v[24:27], v[128:131], v[180:183], v[24:27]
	v_mfma_f32_16x16x32_bf16 v[8:11], v[128:131], v[206:209], v[8:11]
	v_mfma_f32_16x16x32_bf16 v[12:15], v[108:111], v[206:209], v[12:15]
	v_mfma_f32_16x16x32_bf16 v[52:55], v[144:147], v[160:163], v[52:55]
	v_mfma_f32_16x16x32_bf16 v[48:51], v[152:155], v[160:163], v[48:51]
	v_mfma_f32_16x16x32_bf16 v[32:35], v[152:155], v[168:171], v[32:35]
	v_mfma_f32_16x16x32_bf16 v[36:39], v[144:147], v[168:171], v[36:39]
	v_mfma_f32_16x16x32_bf16 v[20:23], v[144:147], v[176:179], v[20:23]
	v_mfma_f32_16x16x32_bf16 v[16:19], v[152:155], v[176:179], v[16:19]
	v_mfma_f32_16x16x32_bf16 v[0:3], v[152:155], v[202:205], v[0:3]
	v_mfma_f32_16x16x32_bf16 v[4:7], v[144:147], v[202:205], v[4:7]
	v_mfma_f32_16x16x32_bf16 v[52:55], v[148:151], v[164:167], v[52:55]
	v_mfma_f32_16x16x32_bf16 v[48:51], v[156:159], v[164:167], v[48:51]
	v_mfma_f32_16x16x32_bf16 v[32:35], v[156:159], v[172:175], v[32:35]
	v_mfma_f32_16x16x32_bf16 v[36:39], v[148:151], v[172:175], v[36:39]
	v_mfma_f32_16x16x32_bf16 v[20:23], v[148:151], v[180:183], v[20:23]
	v_mfma_f32_16x16x32_bf16 v[16:19], v[156:159], v[180:183], v[16:19]
	v_mfma_f32_16x16x32_bf16 v[0:3], v[156:159], v[206:209], v[0:3]
	v_mfma_f32_16x16x32_bf16 v[4:7], v[148:151], v[206:209], v[4:7]
	s_barrier
	s_add_i32 s72, s72, 2
	s_add_u32 s20, s20, 0x100
	s_addc_u32 s21, s21, 0
	s_add_u32 s70, s70, 0x100
	s_addc_u32 s71, s71, 0
	s_cmp_gt_u32 s72, 41
	s_cbranch_scc0 .LBB0_895
	s_and_b64 vcc, exec, s[14:15]
	s_cbranch_vccz .LBB0_898
	s_barrier

; #define PG8_STAGE(bufoff, gbase, voff) do { _Pragma("unroll") for (int _i = 0; _i < 2; ++_i) \
;         __builtin_amdgcn_global_load_lds((const unsigned*)((const char*)(gbase) + (voff)[_i]), (PG8_LAS unsigned*)(lds + (bufoff) + ldsw + _i * 8192), 16, 0, 0); } while (0)
; #define PG8_LDA(dst, b, h) do { _Pragma("unroll") for (int m = 0; m < 4; ++m) _Pragma("unroll") for (int k = 0; k < 2; ++k) dst[m][k] = *(const PG8_LAS bf16x8*)(lds + PG8_SA(b, h) + aoff + m * 2048 + k * 1024); } while (0)
; #define PG8_LDB(dst, b, h) do { _Pragma("unroll") for (int n = 0; n < 2; ++n) _Pragma("unroll") for (int k = 0; k < 2; ++k) dst[n][k] = *(const PG8_LAS bf16x8*)(lds + PG8_SB(b, h) + boff + n * 2048 + k * 1024); } while (0)
; #define PG8_MMA(ai, bj, At, Bt) do { __builtin_amdgcn_s_setprio(1); _Pragma("unroll") for (int m = 0; m < 4; ++m) _Pragma("unroll") for (int n = 0; n < 2; ++n) _Pragma("unroll") for (int k = 0; k < 2; ++k) \
;         acc[ai][bj][m][n] = __builtin_amdgcn_mfma_f32_16x16x32_bf16(Bt[n][k], At[m][k], acc[ai][bj][m][n], 0, 0, 0); __builtin_amdgcn_s_setprio(0); } while (0)
; #define PG8_WAIT_V(n) asm volatile("s_waitcnt vmcnt(" #n ")" ::: "memory")
; #define PG8_WAIT_L(n) asm volatile("s_waitcnt lgkmcnt(" #n ")" ::: "memory")
; #define PG8_BAR __builtin_amdgcn_s_barrier()
; #define PG8_SCHED __builtin_amdgcn_sched_barrier(0)
; template <class Epi, class Sched, bool ALIGN_EPI = false, bool SP2 = false>
; __device__ __forceinline__ void gemm_phase(PG8_LAS unsigned char* lds, const Gemm g, const Sched& S, const Epi& E) {
;     ...
;             PG8_LDB(B0, 0, 0); PG8_LDB(B1, 0, 1); PG8_SCHED; PG8_LDA(At, 0, 0); PG8_STAGE(PG8_SA(1, 1), a1 + hstep, voffA);
;             PG8_WAIT_V(8); PG8_WAIT_L(0); PG8_BAR; PG8_MMA(0, 0, At, B0); PG8_MMA(0, 1, At, B1); PG8_BAR; PG8_SCHED;
;             PG8_LDA(At, 0, 1); PG8_STAGE(PG8_SB(0, 0), b2, voffB); PG8_STAGE(PG8_SB(0, 1), b2 + hstep, voffB); PG8_STAGE(PG8_SA(0, 0), a2, voffA);
;             PG8_WAIT_V(8); PG8_WAIT_L(0); PG8_BAR; PG8_MMA(1, 0, At, B0); PG8_MMA(1, 1, At, B1); PG8_BAR; PG8_SCHED;
.LBB0_1000:
	ds_read_b128 v[154:157], v150
	ds_read_b128 v[158:161], v150 offset:1024
	ds_read_b128 v[162:165], v150 offset:2048
	ds_read_b128 v[166:169], v150 offset:3072
	ds_read_b128 v[170:173], v151
	ds_read_b128 v[174:177], v151 offset:1024
	ds_read_b128 v[178:181], v151 offset:2048
	ds_read_b128 v[182:185], v151 offset:3072
	s_add_u32 s38, s20, 0xfffc0080
	s_addc_u32 s39, s21, -1
	s_cmp_eq_u32 s69, 12
	s_cselect_b32 s45, s15, s39
	s_cselect_b32 s44, s65, s38
	s_cselect_b32 s39, s13, s68
	s_cselect_b32 s38, s66, s67
	s_add_i32 m0, s35, 0xc000
	ds_read_b128 v[186:189], v152
	ds_read_b128 v[190:193], v152 offset:1024
	ds_read_b128 v[198:201], v152 offset:2048
	ds_read_b128 v[202:205], v152 offset:3072
	ds_read_b128 v[206:209], v152 offset:4096
	ds_read_b128 v[210:213], v152 offset:5120
	ds_read_b128 v[214:217], v152 offset:6144
	ds_read_b128 v[218:221], v152 offset:7168
	global_load_lds_dwordx4 v136, s[20:21]
	s_add_i32 m0, s35, 0xe000
	s_nop 0
	global_load_lds_dwordx4 v138, s[20:21]
	s_waitcnt vmcnt(8)
	s_waitcnt lgkmcnt(0)
	s_barrier
	v_mfma_f32_16x16x32_bf16 v[124:127], v[154:157], v[186:189], v[124:127]
	v_mfma_f32_16x16x32_bf16 v[116:119], v[162:165], v[186:189], v[116:119]
	v_mfma_f32_16x16x32_bf16 v[100:103], v[162:165], v[198:201], v[100:103]
	v_mfma_f32_16x16x32_bf16 v[108:111], v[154:157], v[198:201], v[108:111]
	v_mfma_f32_16x16x32_bf16 v[92:95], v[154:157], v[206:209], v[92:95]
	v_mfma_f32_16x16x32_bf16 v[84:87], v[162:165], v[206:209], v[84:87]
	v_mfma_f32_16x16x32_bf16 v[68:71], v[162:165], v[214:217], v[68:71]
	v_mfma_f32_16x16x32_bf16 v[76:79], v[154:157], v[214:217], v[76:79]
	v_mfma_f32_16x16x32_bf16 v[124:127], v[158:161], v[190:193], v[124:127]
	v_mfma_f32_16x16x32_bf16 v[116:119], v[166:169], v[190:193], v[116:119]
	v_mfma_f32_16x16x32_bf16 v[100:103], v[166:169], v[202:205], v[100:103]
	v_mfma_f32_16x16x32_bf16 v[108:111], v[158:161], v[202:205], v[108:111]
	v_mfma_f32_16x16x32_bf16 v[92:95], v[158:161], v[210:213], v[92:95]
	v_mfma_f32_16x16x32_bf16 v[84:87], v[166:169], v[210:213], v[84:87]
	v_mfma_f32_16x16x32_bf16 v[68:71], v[166:169], v[218:221], v[68:71]
	v_mfma_f32_16x16x32_bf16 v[76:79], v[158:161], v[218:221], v[76:79]
	v_mfma_f32_16x16x32_bf16 v[120:123], v[170:173], v[186:189], v[120:123]
	v_mfma_f32_16x16x32_bf16 v[112:115], v[178:181], v[186:189], v[112:115]
	v_mfma_f32_16x16x32_bf16 v[96:99], v[178:181], v[198:201], v[96:99]
	v_mfma_f32_16x16x32_bf16 v[104:107], v[170:173], v[198:201], v[104:107]
	v_mfma_f32_16x16x32_bf16 v[88:91], v[170:173], v[206:209], v[88:91]
	v_mfma_f32_16x16x32_bf16 v[80:83], v[178:181], v[206:209], v[80:83]
	v_mfma_f32_16x16x32_bf16 v[64:67], v[178:181], v[214:217], v[64:67]
	v_mfma_f32_16x16x32_bf16 v[72:75], v[170:173], v[214:217], v[72:75]
	v_mfma_f32_16x16x32_bf16 v[120:123], v[174:177], v[190:193], v[120:123]
	v_mfma_f32_16x16x32_bf16 v[112:115], v[182:185], v[190:193], v[112:115]
	v_mfma_f32_16x16x32_bf16 v[96:99], v[182:185], v[202:205], v[96:99]
	v_mfma_f32_16x16x32_bf16 v[104:107], v[174:177], v[202:205], v[104:107]
	v_mfma_f32_16x16x32_bf16 v[88:91], v[174:177], v[210:213], v[88:91]
	v_mfma_f32_16x16x32_bf16 v[80:83], v[182:185], v[210:213], v[80:83]
	v_mfma_f32_16x16x32_bf16 v[64:67], v[182:185], v[218:221], v[64:67]
	v_mfma_f32_16x16x32_bf16 v[72:75], v[174:177], v[218:221], v[72:75]
	s_barrier
	s_add_i32 s70, s60, s52
	s_add_u32 s98, s38, s8
	s_addc_u32 s99, s39, s9
	s_add_u32 s100, s44, s8
	s_addc_u32 s101, s45, s9
	s_mov_b32 m0, s70
	ds_read_b128 v[186:189], v152 offset:16384
	ds_read_b128 v[190:193], v152 offset:17408
	ds_read_b128 v[198:201], v152 offset:18432
	ds_read_b128 v[202:205], v152 offset:19456
	ds_read_b128 v[206:209], v152 offset:20480
	ds_read_b128 v[210:213], v152 offset:21504
	ds_read_b128 v[214:217], v152 offset:22528
	ds_read_b128 v[218:221], v152 offset:23552
	global_load_lds_dwordx4 v132, s[38:39]
	s_add_i32 m0, s70, 0x2000
	s_add_u32 s70, s38, 0x40000
	s_addc_u32 s71, s39, 0
	s_add_i32 s72, s61, s52
	global_load_lds_dwordx4 v128, s[38:39]
	s_mov_b32 m0, s72
	s_nop 0
	global_load_lds_dwordx4 v132, s[70:71]
	s_add_i32 m0, s72, 0x2000
	s_nop 0
	global_load_lds_dwordx4 v128, s[70:71]
	s_mov_b32 m0, s35
	s_nop 0
	global_load_lds_dwordx4 v134, s[44:45]
	s_mov_b32 m0, s54
	s_nop 0
	global_load_lds_dwordx4 v130, s[44:45]
	s_waitcnt vmcnt(8)
	s_waitcnt lgkmcnt(0)
	s_barrier
	v_mfma_f32_16x16x32_bf16 v[60:63], v[154:157], v[186:189], v[60:63]
	v_mfma_f32_16x16x32_bf16 v[52:55], v[162:165], v[186:189], v[52:55]
	v_mfma_f32_16x16x32_bf16 v[36:39], v[162:165], v[198:201], v[36:39]
	v_mfma_f32_16x16x32_bf16 v[44:47], v[154:157], v[198:201], v[44:47]
	v_mfma_f32_16x16x32_bf16 v[28:31], v[154:157], v[206:209], v[28:31]
	v_mfma_f32_16x16x32_bf16 v[20:23], v[162:165], v[206:209], v[20:23]
	v_mfma_f32_16x16x32_bf16 v[4:7], v[162:165], v[214:217], v[4:7]
	v_mfma_f32_16x16x32_bf16 v[12:15], v[154:157], v[214:217], v[12:15]
	v_mfma_f32_16x16x32_bf16 v[60:63], v[158:161], v[190:193], v[60:63]
	v_mfma_f32_16x16x32_bf16 v[52:55], v[166:169], v[190:193], v[52:55]
	v_mfma_f32_16x16x32_bf16 v[36:39], v[166:169], v[202:205], v[36:39]
	v_mfma_f32_16x16x32_bf16 v[44:47], v[158:161], v[202:205], v[44:47]
	v_mfma_f32_16x16x32_bf16 v[28:31], v[158:161], v[210:213], v[28:31]
	v_mfma_f32_16x16x32_bf16 v[20:23], v[166:169], v[210:213], v[20:23]
	v_mfma_f32_16x16x32_bf16 v[4:7], v[166:169], v[218:221], v[4:7]
	v_mfma_f32_16x16x32_bf16 v[12:15], v[158:161], v[218:221], v[12:15]
	v_mfma_f32_16x16x32_bf16 v[56:59], v[170:173], v[186:189], v[56:59]
	v_mfma_f32_16x16x32_bf16 v[48:51], v[178:181], v[186:189], v[48:51]
	v_mfma_f32_16x16x32_bf16 v[32:35], v[178:181], v[198:201], v[32:35]
	v_mfma_f32_16x16x32_bf16 v[40:43], v[170:173], v[198:201], v[40:43]
	v_mfma_f32_16x16x32_bf16 v[24:27], v[170:173], v[206:209], v[24:27]
	v_mfma_f32_16x16x32_bf16 v[16:19], v[178:181], v[206:209], v[16:19]
	v_mfma_f32_16x16x32_bf16 v[0:3], v[178:181], v[214:217], v[0:3]
	v_mfma_f32_16x16x32_bf16 v[8:11], v[170:173], v[214:217], v[8:11]
	v_mfma_f32_16x16x32_bf16 v[56:59], v[174:177], v[190:193], v[56:59]
	v_mfma_f32_16x16x32_bf16 v[48:51], v[182:185], v[190:193], v[48:51]
	v_mfma_f32_16x16x32_bf16 v[32:35], v[182:185], v[202:205], v[32:35]
	v_mfma_f32_16x16x32_bf16 v[40:43], v[174:177], v[202:205], v[40:43]
	v_mfma_f32_16x16x32_bf16 v[24:27], v[174:177], v[210:213], v[24:27]
	v_mfma_f32_16x16x32_bf16 v[16:19], v[182:185], v[210:213], v[16:19]
	v_mfma_f32_16x16x32_bf16 v[0:3], v[182:185], v[218:221], v[0:3]
	v_mfma_f32_16x16x32_bf16 v[8:11], v[174:177], v[218:221], v[8:11]
	s_barrier
; #define PG8_STAGE(bufoff, gbase, voff) do { _Pragma("unroll") for (int _i = 0; _i < 2; ++_i) \
;         __builtin_amdgcn_global_load_lds((const unsigned*)((const char*)(gbase) + (voff)[_i]), (PG8_LAS unsigned*)(lds + (bufoff) + ldsw + _i * 8192), 16, 0, 0); } while (0)
; #define PG8_LDA(dst, b, h) do { _Pragma("unroll") for (int m = 0; m < 4; ++m) _Pragma("unroll") for (int k = 0; k < 2; ++k) dst[m][k] = *(const PG8_LAS bf16x8*)(lds + PG8_SA(b, h) + aoff + m * 2048 + k * 1024); } while (0)
; #define PG8_LDB(dst, b, h) do { _Pragma("unroll") for (int n = 0; n < 2; ++n) _Pragma("unroll") for (int k = 0; k < 2; ++k) dst[n][k] = *(const PG8_LAS bf16x8*)(lds + PG8_SB(b, h) + boff + n * 2048 + k * 1024); } while (0)
; #define PG8_MMA(ai, bj, At, Bt) do { __builtin_amdgcn_s_setprio(1); _Pragma("unroll") for (int m = 0; m < 4; ++m) _Pragma("unroll") for (int n = 0; n < 2; ++n) _Pragma("unroll") for (int k = 0; k < 2; ++k) \
;         acc[ai][bj][m][n] = __builtin_amdgcn_mfma_f32_16x16x32_bf16(Bt[n][k], At[m][k], acc[ai][bj][m][n], 0, 0, 0); __builtin_amdgcn_s_setprio(0); } while (0)
; #define PG8_WAIT_V(n) asm volatile("s_waitcnt vmcnt(" #n ")" ::: "memory")
; #define PG8_WAIT_L(n) asm volatile("s_waitcnt lgkmcnt(" #n ")" ::: "memory")
; #define PG8_BAR __builtin_amdgcn_s_barrier()
; #define PG8_SCHED __builtin_amdgcn_sched_barrier(0)
; template <class Epi, class Sched, bool ALIGN_EPI = false, bool SP2 = false>
; __device__ __forceinline__ void gemm_phase(PG8_LAS unsigned char* lds, const Gemm g, const Sched& S, const Epi& E) {
;     ...
;             PG8_LDB(B0, 1, 0); PG8_LDB(B1, 1, 1); PG8_SCHED; PG8_LDA(At, 1, 0); PG8_STAGE(PG8_SA(0, 1), a2 + hstep, voffA);
;             PG8_WAIT_V(8); PG8_WAIT_L(0); PG8_BAR; PG8_MMA(0, 0, At, B0); PG8_MMA(0, 1, At, B1); PG8_BAR; PG8_SCHED;
;             PG8_LDA(At, 1, 1); PG8_STAGE(PG8_SB(1, 0), b3, voffB); PG8_STAGE(PG8_SB(1, 1), b3 + hstep, voffB); PG8_STAGE(PG8_SA(1, 0), a3, voffA);
;             PG8_WAIT_V(8); PG8_WAIT_L(0); PG8_BAR; PG8_MMA(1, 0, At, B0); PG8_MMA(1, 1, At, B1); PG8_BAR; PG8_SCHED;
;     ...
;         if constexpr (ALIGN_EPI) { if (wr == 0) PG8_BAR; }
	s_add_i32 s70, 0, 0x18000
	v_add_u32_e32 v153, s70, v147
	s_add_i32 s71, 0, 0x1c000
	ds_read_b128 v[154:157], v153
	ds_read_b128 v[158:161], v153 offset:1024
	ds_read_b128 v[162:165], v153 offset:2048
	ds_read_b128 v[166:169], v153 offset:3072
	v_add_u32_e32 v153, s71, v147
	ds_read_b128 v[170:173], v153
	ds_read_b128 v[174:177], v153 offset:1024
	ds_read_b128 v[178:181], v153 offset:2048
	ds_read_b128 v[182:185], v153 offset:3072
	s_add_u32 s44, s44, 0x40000
	s_addc_u32 s45, s45, 0
	s_mov_b32 m0, s55
	ds_read_b128 v[186:189], v152 offset:32768
	ds_read_b128 v[190:193], v152 offset:33792
	ds_read_b128 v[198:201], v152 offset:34816
	ds_read_b128 v[202:205], v152 offset:35840
	ds_read_b128 v[206:209], v152 offset:36864
	ds_read_b128 v[210:213], v152 offset:37888
	ds_read_b128 v[214:217], v152 offset:38912
	ds_read_b128 v[218:221], v152 offset:39936
	global_load_lds_dwordx4 v134, s[44:45]
	s_mov_b32 m0, s56
	s_nop 0
	global_load_lds_dwordx4 v130, s[44:45]
	s_waitcnt vmcnt(8)
	s_waitcnt lgkmcnt(0)
	s_barrier
	v_mfma_f32_16x16x32_bf16 v[124:127], v[154:157], v[186:189], v[124:127]
	v_mfma_f32_16x16x32_bf16 v[116:119], v[162:165], v[186:189], v[116:119]
	v_mfma_f32_16x16x32_bf16 v[100:103], v[162:165], v[198:201], v[100:103]
	v_mfma_f32_16x16x32_bf16 v[108:111], v[154:157], v[198:201], v[108:111]
	v_mfma_f32_16x16x32_bf16 v[92:95], v[154:157], v[206:209], v[92:95]
	v_mfma_f32_16x16x32_bf16 v[84:87], v[162:165], v[206:209], v[84:87]
	v_mfma_f32_16x16x32_bf16 v[68:71], v[162:165], v[214:217], v[68:71]
	v_mfma_f32_16x16x32_bf16 v[76:79], v[154:157], v[214:217], v[76:79]
	v_mfma_f32_16x16x32_bf16 v[124:127], v[158:161], v[190:193], v[124:127]
	v_mfma_f32_16x16x32_bf16 v[116:119], v[166:169], v[190:193], v[116:119]
	v_mfma_f32_16x16x32_bf16 v[100:103], v[166:169], v[202:205], v[100:103]
	v_mfma_f32_16x16x32_bf16 v[108:111], v[158:161], v[202:205], v[108:111]
	v_mfma_f32_16x16x32_bf16 v[92:95], v[158:161], v[210:213], v[92:95]
	v_mfma_f32_16x16x32_bf16 v[84:87], v[166:169], v[210:213], v[84:87]
	v_mfma_f32_16x16x32_bf16 v[68:71], v[166:169], v[218:221], v[68:71]
	v_mfma_f32_16x16x32_bf16 v[76:79], v[158:161], v[218:221], v[76:79]
	v_mfma_f32_16x16x32_bf16 v[120:123], v[170:173], v[186:189], v[120:123]
	v_mfma_f32_16x16x32_bf16 v[112:115], v[178:181], v[186:189], v[112:115]
	v_mfma_f32_16x16x32_bf16 v[96:99], v[178:181], v[198:201], v[96:99]
	v_mfma_f32_16x16x32_bf16 v[104:107], v[170:173], v[198:201], v[104:107]
	v_mfma_f32_16x16x32_bf16 v[88:91], v[170:173], v[206:209], v[88:91]
	v_mfma_f32_16x16x32_bf16 v[80:83], v[178:181], v[206:209], v[80:83]
	v_mfma_f32_16x16x32_bf16 v[64:67], v[178:181], v[214:217], v[64:67]
	v_mfma_f32_16x16x32_bf16 v[72:75], v[170:173], v[214:217], v[72:75]
	v_mfma_f32_16x16x32_bf16 v[120:123], v[174:177], v[190:193], v[120:123]
	v_mfma_f32_16x16x32_bf16 v[112:115], v[182:185], v[190:193], v[112:115]
	v_mfma_f32_16x16x32_bf16 v[96:99], v[182:185], v[202:205], v[96:99]
	v_mfma_f32_16x16x32_bf16 v[104:107], v[174:177], v[202:205], v[104:107]
	v_mfma_f32_16x16x32_bf16 v[88:91], v[174:177], v[210:213], v[88:91]
	v_mfma_f32_16x16x32_bf16 v[80:83], v[182:185], v[210:213], v[80:83]
	v_mfma_f32_16x16x32_bf16 v[64:67], v[182:185], v[218:221], v[64:67]
	v_mfma_f32_16x16x32_bf16 v[72:75], v[174:177], v[218:221], v[72:75]
	s_barrier
	s_add_i32 s44, s70, s52
	s_mov_b32 m0, s44
	ds_read_b128 v[186:189], v152 offset:49152
	ds_read_b128 v[190:193], v152 offset:50176
	ds_read_b128 v[198:201], v152 offset:51200
	ds_read_b128 v[202:205], v152 offset:52224
	ds_read_b128 v[206:209], v152 offset:53248
	ds_read_b128 v[210:213], v152 offset:54272
	ds_read_b128 v[214:217], v152 offset:55296
	ds_read_b128 v[218:221], v152 offset:56320
	global_load_lds_dwordx4 v132, s[98:99]
	s_add_i32 m0, s44, 0x2000
	s_add_u32 s38, s38, 0x40080
	s_addc_u32 s39, s39, 0
	s_add_i32 s44, s71, s52
	global_load_lds_dwordx4 v128, s[98:99]
	s_mov_b32 m0, s44
	s_nop 0
	global_load_lds_dwordx4 v132, s[38:39]
	s_add_i32 m0, s44, 0x2000
	s_nop 0
	global_load_lds_dwordx4 v128, s[38:39]
	s_mov_b32 m0, s58
	s_nop 0
	global_load_lds_dwordx4 v134, s[100:101]
	s_mov_b32 m0, s59
	s_nop 0
	global_load_lds_dwordx4 v130, s[100:101]
	s_waitcnt vmcnt(8)
	s_waitcnt lgkmcnt(0)
	s_barrier
	v_mfma_f32_16x16x32_bf16 v[60:63], v[154:157], v[186:189], v[60:63]
	v_mfma_f32_16x16x32_bf16 v[52:55], v[162:165], v[186:189], v[52:55]
	v_mfma_f32_16x16x32_bf16 v[36:39], v[162:165], v[198:201], v[36:39]
	v_mfma_f32_16x16x32_bf16 v[44:47], v[154:157], v[198:201], v[44:47]
	v_mfma_f32_16x16x32_bf16 v[28:31], v[154:157], v[206:209], v[28:31]
	v_mfma_f32_16x16x32_bf16 v[20:23], v[162:165], v[206:209], v[20:23]
	v_mfma_f32_16x16x32_bf16 v[4:7], v[162:165], v[214:217], v[4:7]
	v_mfma_f32_16x16x32_bf16 v[12:15], v[154:157], v[214:217], v[12:15]
	v_mfma_f32_16x16x32_bf16 v[60:63], v[158:161], v[190:193], v[60:63]
	v_mfma_f32_16x16x32_bf16 v[52:55], v[166:169], v[190:193], v[52:55]
	v_mfma_f32_16x16x32_bf16 v[36:39], v[166:169], v[202:205], v[36:39]
	v_mfma_f32_16x16x32_bf16 v[44:47], v[158:161], v[202:205], v[44:47]
	v_mfma_f32_16x16x32_bf16 v[28:31], v[158:161], v[210:213], v[28:31]
	v_mfma_f32_16x16x32_bf16 v[20:23], v[166:169], v[210:213], v[20:23]
	v_mfma_f32_16x16x32_bf16 v[4:7], v[166:169], v[218:221], v[4:7]
	v_mfma_f32_16x16x32_bf16 v[12:15], v[158:161], v[218:221], v[12:15]
	v_mfma_f32_16x16x32_bf16 v[56:59], v[170:173], v[186:189], v[56:59]
	v_mfma_f32_16x16x32_bf16 v[48:51], v[178:181], v[186:189], v[48:51]
	v_mfma_f32_16x16x32_bf16 v[32:35], v[178:181], v[198:201], v[32:35]
	v_mfma_f32_16x16x32_bf16 v[40:43], v[170:173], v[198:201], v[40:43]
	v_mfma_f32_16x16x32_bf16 v[24:27], v[170:173], v[206:209], v[24:27]
	v_mfma_f32_16x16x32_bf16 v[16:19], v[178:181], v[206:209], v[16:19]
	v_mfma_f32_16x16x32_bf16 v[0:3], v[178:181], v[214:217], v[0:3]
	v_mfma_f32_16x16x32_bf16 v[8:11], v[170:173], v[214:217], v[8:11]
	v_mfma_f32_16x16x32_bf16 v[56:59], v[174:177], v[190:193], v[56:59]
	v_mfma_f32_16x16x32_bf16 v[48:51], v[182:185], v[190:193], v[48:51]
	v_mfma_f32_16x16x32_bf16 v[32:35], v[182:185], v[202:205], v[32:35]
	v_mfma_f32_16x16x32_bf16 v[40:43], v[174:177], v[202:205], v[40:43]
	v_mfma_f32_16x16x32_bf16 v[24:27], v[174:177], v[210:213], v[24:27]
	v_mfma_f32_16x16x32_bf16 v[16:19], v[182:185], v[210:213], v[16:19]
	v_mfma_f32_16x16x32_bf16 v[0:3], v[182:185], v[218:221], v[0:3]
	v_mfma_f32_16x16x32_bf16 v[8:11], v[174:177], v[218:221], v[8:11]
	s_barrier
	s_add_i32 s69, s69, 2
	s_add_u32 s20, s20, 0x100
	s_addc_u32 s21, s21, 0
	s_add_u32 s67, s67, 0x100
	s_addc_u32 s68, s68, 0
	s_cmp_gt_u32 s69, 13
	s_cbranch_scc0 .LBB0_1000
	s_and_b64 vcc, exec, s[10:11]
	s_cbranch_vccz .LBB0_1003
	s_barrier

; #define PG8_STAGE(bufoff, gbase, voff) do { _Pragma("unroll") for (int _i = 0; _i < 2; ++_i) \
;         __builtin_amdgcn_global_load_lds((const unsigned*)((const char*)(gbase) + (voff)[_i]), (PG8_LAS unsigned*)(lds + (bufoff) + ldsw + _i * 8192), 16, 0, 0); } while (0)
; #define PG8_LDA(dst, b, h) do { _Pragma("unroll") for (int m = 0; m < 4; ++m) _Pragma("unroll") for (int k = 0; k < 2; ++k) dst[m][k] = *(const PG8_LAS bf16x8*)(lds + PG8_SA(b, h) + aoff + m * 2048 + k * 1024); } while (0)
; #define PG8_LDB(dst, b, h) do { _Pragma("unroll") for (int n = 0; n < 2; ++n) _Pragma("unroll") for (int k = 0; k < 2; ++k) dst[n][k] = *(const PG8_LAS bf16x8*)(lds + PG8_SB(b, h) + boff + n * 2048 + k * 1024); } while (0)
; #define PG8_WAIT_V(n) asm volatile("s_waitcnt vmcnt(" #n ")" ::: "memory")
; #define PG8_WAIT_L(n) asm volatile("s_waitcnt lgkmcnt(" #n ")" ::: "memory")
; #define PG8_BAR __builtin_amdgcn_s_barrier()
; #define PG8_SCHED __builtin_amdgcn_sched_barrier(0)
; template <class Epi, class Sched, bool ALIGN_EPI = false, bool SP2 = false>
; __device__ __forceinline__ void gemm_phase(PG8_LAS unsigned char* lds, const Gemm g, const Sched& S, const Epi& E) {
;     ...
;         const char* nA = has_next ? (const char*)g.A + (size_t)nxt.pm * tstep : cA; const char* nB = has_next ? (const char*)g.Bt + (size_t)nxt.pn * tstep : cB;
;         for (int t = 0; t < nt; t += 2) {
;             const bool last = (t == nt - 2);
;             const char* a1 = cA + (size_t)(t + 1) * kstep;
;             const char* a2 = last ? nA : cA + (size_t)(t + 2) * kstep; const char* b2 = last ? nB : cB + (size_t)(t + 2) * kstep;
;             const char* a3 = a2 + kstep; const char* b3 = b2 + kstep;
;             if (last && has_next) S.a_ready(nxt);
;             if constexpr (SP2) {
;             PG8_LDB(B0, 0, 0); PG8_LDB(B1, 0, 1); PG8_SCHED; PG8_LDA(At, 0, 0); PG8_STAGE(PG8_SA(1, 1), a1 + hstep, voffA);
;             PG8_WAIT_V(8); PG8_WAIT_L(0); PG8_BAR; PG8_MMA(0, 0, At, B0); PG8_MMA(0, 1, At, B1); PG8_BAR; PG8_SCHED;
;             PG8_LDA(At, 0, 1); PG8_STAGE(PG8_SB(0, 0), b2, voffB); PG8_STAGE(PG8_SB(0, 1), b2 + hstep, voffB); PG8_STAGE(PG8_SA(0, 0), a2, voffA);
;             PG8_WAIT_V(8); PG8_WAIT_L(0); PG8_BAR; PG8_MMA(1, 0, At, B0); PG8_MMA(1, 1, At, B1); PG8_BAR; PG8_SCHED;
.LBB0_1199:
	s_ashr_i32 s57, s56, 31
	s_lshl_b64 s[58:59], s[56:57], 19
	s_add_u32 s58, s36, s58
	s_addc_u32 s59, s37, s59
	s_and_b64 s[60:61], s[8:9], exec
	s_cselect_b32 s1, s59, s21
	s_cselect_b32 s57, s58, s20
	s_ashr_i32 s55, s54, 31
	s_lshl_b64 s[60:61], s[54:55], 19
	s_add_u32 s60, s68, s60
	s_addc_u32 s61, s69, s61
	s_and_b64 s[62:63], s[8:9], exec
	s_cselect_b32 s55, s61, s35
	s_cselect_b32 s85, s60, s34
	s_add_u32 s20, s20, 0x40080
	s_addc_u32 s21, s21, 0
	s_add_u32 s86, s34, 0x100
	s_addc_u32 s87, s35, 0
	s_mov_b32 s88, -2
	s_waitcnt lgkmcnt(0)
	ds_read_b128 v[140:143], v163
	ds_read_b128 v[168:171], v163 offset:1024
	ds_read_b128 v[172:175], v163 offset:2048
	ds_read_b128 v[176:179], v163 offset:3072
	ds_read_b128 v[180:183], v164
	ds_read_b128 v[184:187], v164 offset:1024
	ds_read_b128 v[188:191], v164 offset:2048
	ds_read_b128 v[192:195], v164 offset:3072
	s_add_u32 s34, s20, 0xfffc0080
	s_addc_u32 s35, s21, -1
	s_cmp_eq_u32 s88, 12
	s_cselect_b32 s63, s1, s35
	s_cselect_b32 s62, s57, s34
	s_cselect_b32 s35, s55, s87
	s_cselect_b32 s34, s85, s86
	s_add_i32 m0, s71, 0xc000
	ds_read_b128 v[198:201], v165
	ds_read_b128 v[202:205], v165 offset:1024
	ds_read_b128 v[206:209], v165 offset:2048
	ds_read_b128 v[210:213], v165 offset:3072
	ds_read_b128 v[214:217], v165 offset:4096
	ds_read_b128 v[218:221], v165 offset:5120
	ds_read_b128 v[222:225], v165 offset:6144
	ds_read_b128 v[226:229], v165 offset:7168
	global_load_lds_dwordx4 v132, s[20:21]
	s_add_i32 m0, s71, 0xe000
	s_nop 0
	global_load_lds_dwordx4 v134, s[20:21]
	s_waitcnt vmcnt(8)
	s_waitcnt lgkmcnt(0)
	s_barrier
	v_mfma_f32_16x16x32_bf16 v[124:127], v[140:143], v[198:201], 0
	v_mfma_f32_16x16x32_bf16 v[120:123], v[172:175], v[198:201], 0
	v_mfma_f32_16x16x32_bf16 v[104:107], v[172:175], v[206:209], 0
	v_mfma_f32_16x16x32_bf16 v[108:111], v[140:143], v[206:209], 0
	v_mfma_f32_16x16x32_bf16 v[92:95], v[140:143], v[214:217], 0
	v_mfma_f32_16x16x32_bf16 v[88:91], v[172:175], v[214:217], 0
	v_mfma_f32_16x16x32_bf16 v[72:75], v[172:175], v[222:225], 0
	v_mfma_f32_16x16x32_bf16 v[76:79], v[140:143], v[222:225], 0
	v_mfma_f32_16x16x32_bf16 v[124:127], v[168:171], v[202:205], v[124:127]
	v_mfma_f32_16x16x32_bf16 v[120:123], v[176:179], v[202:205], v[120:123]
	v_mfma_f32_16x16x32_bf16 v[104:107], v[176:179], v[210:213], v[104:107]
	v_mfma_f32_16x16x32_bf16 v[108:111], v[168:171], v[210:213], v[108:111]
	v_mfma_f32_16x16x32_bf16 v[92:95], v[168:171], v[218:221], v[92:95]
	v_mfma_f32_16x16x32_bf16 v[88:91], v[176:179], v[218:221], v[88:91]
	v_mfma_f32_16x16x32_bf16 v[72:75], v[176:179], v[226:229], v[72:75]
	v_mfma_f32_16x16x32_bf16 v[76:79], v[168:171], v[226:229], v[76:79]
	v_mfma_f32_16x16x32_bf16 v[116:119], v[180:183], v[198:201], 0
	v_mfma_f32_16x16x32_bf16 v[112:115], v[188:191], v[198:201], 0
	v_mfma_f32_16x16x32_bf16 v[96:99], v[188:191], v[206:209], 0
	v_mfma_f32_16x16x32_bf16 v[100:103], v[180:183], v[206:209], 0
	v_mfma_f32_16x16x32_bf16 v[84:87], v[180:183], v[214:217], 0
	v_mfma_f32_16x16x32_bf16 v[80:83], v[188:191], v[214:217], 0
	v_mfma_f32_16x16x32_bf16 v[64:67], v[188:191], v[222:225], 0
	v_mfma_f32_16x16x32_bf16 v[68:71], v[180:183], v[222:225], 0
	v_mfma_f32_16x16x32_bf16 v[116:119], v[184:187], v[202:205], v[116:119]
	v_mfma_f32_16x16x32_bf16 v[112:115], v[192:195], v[202:205], v[112:115]
	v_mfma_f32_16x16x32_bf16 v[96:99], v[192:195], v[210:213], v[96:99]
	v_mfma_f32_16x16x32_bf16 v[100:103], v[184:187], v[210:213], v[100:103]
	v_mfma_f32_16x16x32_bf16 v[84:87], v[184:187], v[218:221], v[84:87]
	v_mfma_f32_16x16x32_bf16 v[80:83], v[192:195], v[218:221], v[80:83]
	v_mfma_f32_16x16x32_bf16 v[64:67], v[192:195], v[226:229], v[64:67]
	v_mfma_f32_16x16x32_bf16 v[68:71], v[184:187], v[226:229], v[68:71]
	s_barrier
	s_add_i32 s89, s77, s70
	s_add_u32 s98, s34, s18
	s_addc_u32 s99, s35, s19
	s_add_u32 s100, s62, s18
	s_addc_u32 s101, s63, s19
	s_mov_b32 m0, s89
	ds_read_b128 v[198:201], v165 offset:16384
	ds_read_b128 v[202:205], v165 offset:17408
	ds_read_b128 v[206:209], v165 offset:18432
	ds_read_b128 v[210:213], v165 offset:19456
	ds_read_b128 v[214:217], v165 offset:20480
	ds_read_b128 v[218:221], v165 offset:21504
	ds_read_b128 v[222:225], v165 offset:22528
	ds_read_b128 v[226:229], v165 offset:23552
	global_load_lds_dwordx4 v146, s[34:35]
	s_add_i32 m0, s89, 0x2000
	s_add_u32 s90, s34, 0x40000
	s_addc_u32 s91, s35, 0
	s_add_i32 s89, s78, s70
	global_load_lds_dwordx4 v150, s[34:35]
	s_mov_b32 m0, s89
	s_nop 0
	global_load_lds_dwordx4 v146, s[90:91]
	s_add_i32 m0, s89, 0x2000
	s_nop 0
	global_load_lds_dwordx4 v150, s[90:91]
	s_mov_b32 m0, s71
	s_nop 0
	global_load_lds_dwordx4 v144, s[62:63]
	s_mov_b32 m0, s72
	s_nop 0
	global_load_lds_dwordx4 v148, s[62:63]
	s_waitcnt vmcnt(8)
	s_waitcnt lgkmcnt(0)
	s_barrier
; #define PG8_STAGE(bufoff, gbase, voff) do { _Pragma("unroll") for (int _i = 0; _i < 2; ++_i) \
;         __builtin_amdgcn_global_load_lds((const unsigned*)((const char*)(gbase) + (voff)[_i]), (PG8_LAS unsigned*)(lds + (bufoff) + ldsw + _i * 8192), 16, 0, 0); } while (0)
; #define PG8_LDA(dst, b, h) do { _Pragma("unroll") for (int m = 0; m < 4; ++m) _Pragma("unroll") for (int k = 0; k < 2; ++k) dst[m][k] = *(const PG8_LAS bf16x8*)(lds + PG8_SA(b, h) + aoff + m * 2048 + k * 1024); } while (0)
; #define PG8_LDB(dst, b, h) do { _Pragma("unroll") for (int n = 0; n < 2; ++n) _Pragma("unroll") for (int k = 0; k < 2; ++k) dst[n][k] = *(const PG8_LAS bf16x8*)(lds + PG8_SB(b, h) + boff + n * 2048 + k * 1024); } while (0)
; #define PG8_MMA(ai, bj, At, Bt) do { __builtin_amdgcn_s_setprio(1); _Pragma("unroll") for (int m = 0; m < 4; ++m) _Pragma("unroll") for (int n = 0; n < 2; ++n) _Pragma("unroll") for (int k = 0; k < 2; ++k) \
;         acc[ai][bj][m][n] = __builtin_amdgcn_mfma_f32_16x16x32_bf16(Bt[n][k], At[m][k], acc[ai][bj][m][n], 0, 0, 0); __builtin_amdgcn_s_setprio(0); } while (0)
; #define PG8_WAIT_V(n) asm volatile("s_waitcnt vmcnt(" #n ")" ::: "memory")
; #define PG8_WAIT_L(n) asm volatile("s_waitcnt lgkmcnt(" #n ")" ::: "memory")
; #define PG8_BAR __builtin_amdgcn_s_barrier()
; #define PG8_SCHED __builtin_amdgcn_sched_barrier(0)
; template <class Epi, class Sched, bool ALIGN_EPI = false, bool SP2 = false>
; __device__ __forceinline__ void gemm_phase(PG8_LAS unsigned char* lds, const Gemm g, const Sched& S, const Epi& E) {
;     ...
;             PG8_WAIT_V(8); PG8_WAIT_L(0); PG8_BAR; PG8_MMA(1, 0, At, B0); PG8_MMA(1, 1, At, B1); PG8_BAR; PG8_SCHED;
;             PG8_LDB(B0, 1, 0); PG8_LDB(B1, 1, 1); PG8_SCHED; PG8_LDA(At, 1, 0); PG8_STAGE(PG8_SA(0, 1), a2 + hstep, voffA);
;             PG8_WAIT_V(8); PG8_WAIT_L(0); PG8_BAR; PG8_MMA(0, 0, At, B0); PG8_MMA(0, 1, At, B1); PG8_BAR; PG8_SCHED;
	v_mfma_f32_16x16x32_bf16 v[60:63], v[140:143], v[198:201], 0
	v_mfma_f32_16x16x32_bf16 v[56:59], v[172:175], v[198:201], 0
	v_mfma_f32_16x16x32_bf16 v[40:43], v[172:175], v[206:209], 0
	v_mfma_f32_16x16x32_bf16 v[48:51], v[140:143], v[206:209], 0
	v_mfma_f32_16x16x32_bf16 v[32:35], v[140:143], v[214:217], 0
	v_mfma_f32_16x16x32_bf16 v[24:27], v[172:175], v[214:217], 0
	v_mfma_f32_16x16x32_bf16 v[8:11], v[172:175], v[222:225], 0
	v_mfma_f32_16x16x32_bf16 v[16:19], v[140:143], v[222:225], 0
	v_mfma_f32_16x16x32_bf16 v[60:63], v[168:171], v[202:205], v[60:63]
	v_mfma_f32_16x16x32_bf16 v[56:59], v[176:179], v[202:205], v[56:59]
	v_mfma_f32_16x16x32_bf16 v[40:43], v[176:179], v[210:213], v[40:43]
	v_mfma_f32_16x16x32_bf16 v[48:51], v[168:171], v[210:213], v[48:51]
	v_mfma_f32_16x16x32_bf16 v[32:35], v[168:171], v[218:221], v[32:35]
	v_mfma_f32_16x16x32_bf16 v[24:27], v[176:179], v[218:221], v[24:27]
	v_mfma_f32_16x16x32_bf16 v[8:11], v[176:179], v[226:229], v[8:11]
	v_mfma_f32_16x16x32_bf16 v[16:19], v[168:171], v[226:229], v[16:19]
	v_mfma_f32_16x16x32_bf16 v[52:55], v[180:183], v[198:201], 0
	v_mfma_f32_16x16x32_bf16 v[44:47], v[188:191], v[198:201], 0
	v_mfma_f32_16x16x32_bf16 v[28:31], v[188:191], v[206:209], 0
	v_mfma_f32_16x16x32_bf16 v[36:39], v[180:183], v[206:209], 0
	v_mfma_f32_16x16x32_bf16 v[20:23], v[180:183], v[214:217], 0
	v_mfma_f32_16x16x32_bf16 v[12:15], v[188:191], v[214:217], 0
	v_mfma_f32_16x16x32_bf16 v[0:3], v[188:191], v[222:225], 0
	v_mfma_f32_16x16x32_bf16 v[4:7], v[180:183], v[222:225], 0
	v_mfma_f32_16x16x32_bf16 v[52:55], v[184:187], v[202:205], v[52:55]
	v_mfma_f32_16x16x32_bf16 v[44:47], v[192:195], v[202:205], v[44:47]
	v_mfma_f32_16x16x32_bf16 v[28:31], v[192:195], v[210:213], v[28:31]
	v_mfma_f32_16x16x32_bf16 v[36:39], v[184:187], v[210:213], v[36:39]
	v_mfma_f32_16x16x32_bf16 v[20:23], v[184:187], v[218:221], v[20:23]
	v_mfma_f32_16x16x32_bf16 v[12:15], v[192:195], v[218:221], v[12:15]
	v_mfma_f32_16x16x32_bf16 v[0:3], v[192:195], v[226:229], v[0:3]
	v_mfma_f32_16x16x32_bf16 v[4:7], v[184:187], v[226:229], v[4:7]
	s_barrier
	s_add_i32 s89, 0, 0x18000
	v_add_u32_e32 v128, s89, v161
	s_add_i32 s90, 0, 0x1c000
	ds_read_b128 v[140:143], v128
	ds_read_b128 v[168:171], v128 offset:1024
	ds_read_b128 v[172:175], v128 offset:2048
	ds_read_b128 v[176:179], v128 offset:3072
	v_add_u32_e32 v128, s90, v161
	ds_read_b128 v[180:183], v128
	ds_read_b128 v[184:187], v128 offset:1024
	ds_read_b128 v[188:191], v128 offset:2048
	ds_read_b128 v[192:195], v128 offset:3072
	s_add_u32 s62, s62, 0x40000
	s_addc_u32 s63, s63, 0
	s_mov_b32 m0, s73
	ds_read_b128 v[198:201], v165 offset:32768
	ds_read_b128 v[202:205], v165 offset:33792
	ds_read_b128 v[206:209], v165 offset:34816
	ds_read_b128 v[210:213], v165 offset:35840
	ds_read_b128 v[214:217], v165 offset:36864
	ds_read_b128 v[218:221], v165 offset:37888
	ds_read_b128 v[222:225], v165 offset:38912
	ds_read_b128 v[226:229], v165 offset:39936
	global_load_lds_dwordx4 v144, s[62:63]
	s_mov_b32 m0, s74
	s_nop 0
	global_load_lds_dwordx4 v148, s[62:63]
	s_waitcnt vmcnt(8)
	s_waitcnt lgkmcnt(0)
	s_barrier
	v_mfma_f32_16x16x32_bf16 v[124:127], v[140:143], v[198:201], v[124:127]
	v_mfma_f32_16x16x32_bf16 v[120:123], v[172:175], v[198:201], v[120:123]
	v_mfma_f32_16x16x32_bf16 v[104:107], v[172:175], v[206:209], v[104:107]
	v_mfma_f32_16x16x32_bf16 v[108:111], v[140:143], v[206:209], v[108:111]
	v_mfma_f32_16x16x32_bf16 v[92:95], v[140:143], v[214:217], v[92:95]
	v_mfma_f32_16x16x32_bf16 v[88:91], v[172:175], v[214:217], v[88:91]
	v_mfma_f32_16x16x32_bf16 v[72:75], v[172:175], v[222:225], v[72:75]
	v_mfma_f32_16x16x32_bf16 v[76:79], v[140:143], v[222:225], v[76:79]
	v_mfma_f32_16x16x32_bf16 v[124:127], v[168:171], v[202:205], v[124:127]
	v_mfma_f32_16x16x32_bf16 v[120:123], v[176:179], v[202:205], v[120:123]
	v_mfma_f32_16x16x32_bf16 v[104:107], v[176:179], v[210:213], v[104:107]
	v_mfma_f32_16x16x32_bf16 v[108:111], v[168:171], v[210:213], v[108:111]
	v_mfma_f32_16x16x32_bf16 v[92:95], v[168:171], v[218:221], v[92:95]
	v_mfma_f32_16x16x32_bf16 v[88:91], v[176:179], v[218:221], v[88:91]
	v_mfma_f32_16x16x32_bf16 v[72:75], v[176:179], v[226:229], v[72:75]
	v_mfma_f32_16x16x32_bf16 v[76:79], v[168:171], v[226:229], v[76:79]
	v_mfma_f32_16x16x32_bf16 v[116:119], v[180:183], v[198:201], v[116:119]
	v_mfma_f32_16x16x32_bf16 v[112:115], v[188:191], v[198:201], v[112:115]
	v_mfma_f32_16x16x32_bf16 v[96:99], v[188:191], v[206:209], v[96:99]
	v_mfma_f32_16x16x32_bf16 v[100:103], v[180:183], v[206:209], v[100:103]
	v_mfma_f32_16x16x32_bf16 v[84:87], v[180:183], v[214:217], v[84:87]
	v_mfma_f32_16x16x32_bf16 v[80:83], v[188:191], v[214:217], v[80:83]
	v_mfma_f32_16x16x32_bf16 v[64:67], v[188:191], v[222:225], v[64:67]
	v_mfma_f32_16x16x32_bf16 v[68:71], v[180:183], v[222:225], v[68:71]
	v_mfma_f32_16x16x32_bf16 v[116:119], v[184:187], v[202:205], v[116:119]
	v_mfma_f32_16x16x32_bf16 v[112:115], v[192:195], v[202:205], v[112:115]
	v_mfma_f32_16x16x32_bf16 v[96:99], v[192:195], v[210:213], v[96:99]
	v_mfma_f32_16x16x32_bf16 v[100:103], v[184:187], v[210:213], v[100:103]
	v_mfma_f32_16x16x32_bf16 v[84:87], v[184:187], v[218:221], v[84:87]
	v_mfma_f32_16x16x32_bf16 v[80:83], v[192:195], v[218:221], v[80:83]
	v_mfma_f32_16x16x32_bf16 v[64:67], v[192:195], v[226:229], v[64:67]
	v_mfma_f32_16x16x32_bf16 v[68:71], v[184:187], v[226:229], v[68:71]
	s_barrier
; #define PG8_STAGE(bufoff, gbase, voff) do { _Pragma("unroll") for (int _i = 0; _i < 2; ++_i) \
;         __builtin_amdgcn_global_load_lds((const unsigned*)((const char*)(gbase) + (voff)[_i]), (PG8_LAS unsigned*)(lds + (bufoff) + ldsw + _i * 8192), 16, 0, 0); } while (0)
; #define PG8_LDA(dst, b, h) do { _Pragma("unroll") for (int m = 0; m < 4; ++m) _Pragma("unroll") for (int k = 0; k < 2; ++k) dst[m][k] = *(const PG8_LAS bf16x8*)(lds + PG8_SA(b, h) + aoff + m * 2048 + k * 1024); } while (0)
; #define PG8_LDB(dst, b, h) do { _Pragma("unroll") for (int n = 0; n < 2; ++n) _Pragma("unroll") for (int k = 0; k < 2; ++k) dst[n][k] = *(const PG8_LAS bf16x8*)(lds + PG8_SB(b, h) + boff + n * 2048 + k * 1024); } while (0)
; #define PG8_MMA(ai, bj, At, Bt) do { __builtin_amdgcn_s_setprio(1); _Pragma("unroll") for (int m = 0; m < 4; ++m) _Pragma("unroll") for (int n = 0; n < 2; ++n) _Pragma("unroll") for (int k = 0; k < 2; ++k) \
;         acc[ai][bj][m][n] = __builtin_amdgcn_mfma_f32_16x16x32_bf16(Bt[n][k], At[m][k], acc[ai][bj][m][n], 0, 0, 0); __builtin_amdgcn_s_setprio(0); } while (0)
; #define PG8_WAIT_V(n) asm volatile("s_waitcnt vmcnt(" #n ")" ::: "memory")
; template <class Epi, class Sched, bool ALIGN_EPI = false, bool SP2 = false>
; __device__ __forceinline__ void gemm_phase(PG8_LAS unsigned char* lds, const Gemm g, const Sched& S, const Epi& E) {
;     ...
;             PG8_LDB(B0, 0, 0); PG8_LDB(B1, 0, 1); PG8_SCHED; PG8_LDA(At, 0, 0); PG8_STAGE(PG8_SA(1, 1), a1 + hstep, voffA);
;             PG8_WAIT_V(8); PG8_WAIT_L(0); PG8_BAR; PG8_MMA(0, 0, At, B0); PG8_MMA(0, 1, At, B1); PG8_BAR; PG8_SCHED;
;             PG8_LDA(At, 0, 1); PG8_STAGE(PG8_SB(0, 0), b2, voffB); PG8_STAGE(PG8_SB(0, 1), b2 + hstep, voffB); PG8_STAGE(PG8_SA(0, 0), a2, voffA);
;             PG8_WAIT_V(8); PG8_WAIT_L(0); PG8_BAR; PG8_MMA(1, 0, At, B0); PG8_MMA(1, 1, At, B1); PG8_BAR; PG8_SCHED;
;             PG8_LDB(B0, 1, 0); PG8_LDB(B1, 1, 1); PG8_SCHED; PG8_LDA(At, 1, 0); PG8_STAGE(PG8_SA(0, 1), a2 + hstep, voffA);
;             PG8_WAIT_V(8); PG8_WAIT_L(0); PG8_BAR; PG8_MMA(0, 0, At, B0); PG8_MMA(0, 1, At, B1); PG8_BAR; PG8_SCHED;
;             PG8_LDA(At, 1, 1); PG8_STAGE(PG8_SB(1, 0), b3, voffB); PG8_STAGE(PG8_SB(1, 1), b3 + hstep, voffB); PG8_STAGE(PG8_SA(1, 0), a3, voffA);
;             PG8_WAIT_V(8); PG8_WAIT_L(0); PG8_BAR; PG8_MMA(1, 0, At, B0); PG8_MMA(1, 1, At, B1); PG8_BAR; PG8_SCHED;
	s_add_i32 s62, s89, s70
	s_mov_b32 m0, s62
	ds_read_b128 v[198:201], v165 offset:49152
	ds_read_b128 v[202:205], v165 offset:50176
	ds_read_b128 v[206:209], v165 offset:51200
	ds_read_b128 v[210:213], v165 offset:52224
	ds_read_b128 v[214:217], v165 offset:53248
	ds_read_b128 v[218:221], v165 offset:54272
	ds_read_b128 v[222:225], v165 offset:55296
	ds_read_b128 v[226:229], v165 offset:56320
	global_load_lds_dwordx4 v146, s[98:99]
	s_add_i32 m0, s62, 0x2000
	s_add_u32 s34, s34, 0x40080
	s_addc_u32 s35, s35, 0
	s_add_i32 s62, s90, s70
	global_load_lds_dwordx4 v150, s[98:99]
	s_mov_b32 m0, s62
	s_nop 0
	global_load_lds_dwordx4 v146, s[34:35]
	s_add_i32 m0, s62, 0x2000
	s_nop 0
	global_load_lds_dwordx4 v150, s[34:35]
	s_mov_b32 m0, s75
	s_nop 0
	global_load_lds_dwordx4 v144, s[100:101]
	s_mov_b32 m0, s76
	s_nop 0
	global_load_lds_dwordx4 v148, s[100:101]
	s_waitcnt vmcnt(8)
	s_waitcnt lgkmcnt(0)
	s_barrier
	v_mfma_f32_16x16x32_bf16 v[60:63], v[140:143], v[198:201], v[60:63]
	v_mfma_f32_16x16x32_bf16 v[56:59], v[172:175], v[198:201], v[56:59]
	v_mfma_f32_16x16x32_bf16 v[40:43], v[172:175], v[206:209], v[40:43]
	v_mfma_f32_16x16x32_bf16 v[48:51], v[140:143], v[206:209], v[48:51]
	v_mfma_f32_16x16x32_bf16 v[32:35], v[140:143], v[214:217], v[32:35]
	v_mfma_f32_16x16x32_bf16 v[24:27], v[172:175], v[214:217], v[24:27]
	v_mfma_f32_16x16x32_bf16 v[8:11], v[172:175], v[222:225], v[8:11]
	v_mfma_f32_16x16x32_bf16 v[16:19], v[140:143], v[222:225], v[16:19]
	v_mfma_f32_16x16x32_bf16 v[60:63], v[168:171], v[202:205], v[60:63]
	v_mfma_f32_16x16x32_bf16 v[56:59], v[176:179], v[202:205], v[56:59]
	v_mfma_f32_16x16x32_bf16 v[40:43], v[176:179], v[210:213], v[40:43]
	v_mfma_f32_16x16x32_bf16 v[48:51], v[168:171], v[210:213], v[48:51]
	v_mfma_f32_16x16x32_bf16 v[32:35], v[168:171], v[218:221], v[32:35]
	v_mfma_f32_16x16x32_bf16 v[24:27], v[176:179], v[218:221], v[24:27]
	v_mfma_f32_16x16x32_bf16 v[8:11], v[176:179], v[226:229], v[8:11]
	v_mfma_f32_16x16x32_bf16 v[16:19], v[168:171], v[226:229], v[16:19]
	v_mfma_f32_16x16x32_bf16 v[52:55], v[180:183], v[198:201], v[52:55]
	v_mfma_f32_16x16x32_bf16 v[44:47], v[188:191], v[198:201], v[44:47]
	v_mfma_f32_16x16x32_bf16 v[28:31], v[188:191], v[206:209], v[28:31]
	v_mfma_f32_16x16x32_bf16 v[36:39], v[180:183], v[206:209], v[36:39]
	v_mfma_f32_16x16x32_bf16 v[20:23], v[180:183], v[214:217], v[20:23]
	v_mfma_f32_16x16x32_bf16 v[12:15], v[188:191], v[214:217], v[12:15]
	v_mfma_f32_16x16x32_bf16 v[0:3], v[188:191], v[222:225], v[0:3]
	v_mfma_f32_16x16x32_bf16 v[4:7], v[180:183], v[222:225], v[4:7]
	v_mfma_f32_16x16x32_bf16 v[52:55], v[184:187], v[202:205], v[52:55]
	v_mfma_f32_16x16x32_bf16 v[44:47], v[192:195], v[202:205], v[44:47]
	v_mfma_f32_16x16x32_bf16 v[28:31], v[192:195], v[210:213], v[28:31]
	v_mfma_f32_16x16x32_bf16 v[36:39], v[184:187], v[210:213], v[36:39]
	v_mfma_f32_16x16x32_bf16 v[20:23], v[184:187], v[218:221], v[20:23]
	v_mfma_f32_16x16x32_bf16 v[12:15], v[192:195], v[218:221], v[12:15]
	v_mfma_f32_16x16x32_bf16 v[0:3], v[192:195], v[226:229], v[0:3]
	v_mfma_f32_16x16x32_bf16 v[4:7], v[184:187], v[226:229], v[4:7]
	s_barrier
	s_add_i32 s88, s88, 2
	s_add_u32 s20, s20, 0x100
	s_addc_u32 s21, s21, 0
	s_add_u32 s86, s86, 0x100
	s_addc_u32 s87, s87, 0
	s_cmp_gt_u32 s88, 13
.LBB0_1200:
	ds_read_b128 v[140:143], v163
	ds_read_b128 v[168:171], v163 offset:1024
	ds_read_b128 v[172:175], v163 offset:2048
	ds_read_b128 v[176:179], v163 offset:3072
	ds_read_b128 v[180:183], v164
	ds_read_b128 v[184:187], v164 offset:1024
	ds_read_b128 v[188:191], v164 offset:2048
	ds_read_b128 v[192:195], v164 offset:3072
	s_add_u32 s34, s20, 0xfffc0080
	s_addc_u32 s35, s21, -1
	s_cmp_eq_u32 s88, 12
	s_cselect_b32 s63, s1, s35
	s_cselect_b32 s62, s57, s34
	s_cselect_b32 s35, s55, s87
	s_cselect_b32 s34, s85, s86
	s_add_i32 m0, s71, 0xc000
	ds_read_b128 v[198:201], v165
	ds_read_b128 v[202:205], v165 offset:1024
	ds_read_b128 v[206:209], v165 offset:2048
	ds_read_b128 v[210:213], v165 offset:3072
	ds_read_b128 v[214:217], v165 offset:4096
	ds_read_b128 v[218:221], v165 offset:5120
	ds_read_b128 v[222:225], v165 offset:6144
	ds_read_b128 v[226:229], v165 offset:7168
	global_load_lds_dwordx4 v132, s[20:21]
	s_add_i32 m0, s71, 0xe000
	s_nop 0
	global_load_lds_dwordx4 v134, s[20:21]
	s_waitcnt vmcnt(8)
	s_waitcnt lgkmcnt(0)
	s_barrier
	v_mfma_f32_16x16x32_bf16 v[124:127], v[140:143], v[198:201], v[124:127]
	v_mfma_f32_16x16x32_bf16 v[120:123], v[172:175], v[198:201], v[120:123]
	v_mfma_f32_16x16x32_bf16 v[104:107], v[172:175], v[206:209], v[104:107]
	v_mfma_f32_16x16x32_bf16 v[108:111], v[140:143], v[206:209], v[108:111]
	v_mfma_f32_16x16x32_bf16 v[92:95], v[140:143], v[214:217], v[92:95]
	v_mfma_f32_16x16x32_bf16 v[88:91], v[172:175], v[214:217], v[88:91]
	v_mfma_f32_16x16x32_bf16 v[72:75], v[172:175], v[222:225], v[72:75]
	v_mfma_f32_16x16x32_bf16 v[76:79], v[140:143], v[222:225], v[76:79]
	v_mfma_f32_16x16x32_bf16 v[124:127], v[168:171], v[202:205], v[124:127]
	v_mfma_f32_16x16x32_bf16 v[120:123], v[176:179], v[202:205], v[120:123]
	v_mfma_f32_16x16x32_bf16 v[104:107], v[176:179], v[210:213], v[104:107]
	v_mfma_f32_16x16x32_bf16 v[108:111], v[168:171], v[210:213], v[108:111]
	v_mfma_f32_16x16x32_bf16 v[92:95], v[168:171], v[218:221], v[92:95]
	v_mfma_f32_16x16x32_bf16 v[88:91], v[176:179], v[218:221], v[88:91]
	v_mfma_f32_16x16x32_bf16 v[72:75], v[176:179], v[226:229], v[72:75]
	v_mfma_f32_16x16x32_bf16 v[76:79], v[168:171], v[226:229], v[76:79]
	v_mfma_f32_16x16x32_bf16 v[116:119], v[180:183], v[198:201], v[116:119]
	v_mfma_f32_16x16x32_bf16 v[112:115], v[188:191], v[198:201], v[112:115]
	v_mfma_f32_16x16x32_bf16 v[96:99], v[188:191], v[206:209], v[96:99]
	v_mfma_f32_16x16x32_bf16 v[100:103], v[180:183], v[206:209], v[100:103]
	v_mfma_f32_16x16x32_bf16 v[84:87], v[180:183], v[214:217], v[84:87]
	v_mfma_f32_16x16x32_bf16 v[80:83], v[188:191], v[214:217], v[80:83]
	v_mfma_f32_16x16x32_bf16 v[64:67], v[188:191], v[222:225], v[64:67]
	v_mfma_f32_16x16x32_bf16 v[68:71], v[180:183], v[222:225], v[68:71]
	v_mfma_f32_16x16x32_bf16 v[116:119], v[184:187], v[202:205], v[116:119]
	v_mfma_f32_16x16x32_bf16 v[112:115], v[192:195], v[202:205], v[112:115]
	v_mfma_f32_16x16x32_bf16 v[96:99], v[192:195], v[210:213], v[96:99]
	v_mfma_f32_16x16x32_bf16 v[100:103], v[184:187], v[210:213], v[100:103]
	v_mfma_f32_16x16x32_bf16 v[84:87], v[184:187], v[218:221], v[84:87]
	v_mfma_f32_16x16x32_bf16 v[80:83], v[192:195], v[218:221], v[80:83]
	v_mfma_f32_16x16x32_bf16 v[64:67], v[192:195], v[226:229], v[64:67]
	v_mfma_f32_16x16x32_bf16 v[68:71], v[184:187], v[226:229], v[68:71]
	s_barrier
; #define PG8_STAGE(bufoff, gbase, voff) do { _Pragma("unroll") for (int _i = 0; _i < 2; ++_i) \
;         __builtin_amdgcn_global_load_lds((const unsigned*)((const char*)(gbase) + (voff)[_i]), (PG8_LAS unsigned*)(lds + (bufoff) + ldsw + _i * 8192), 16, 0, 0); } while (0)
; #define PG8_LDA(dst, b, h) do { _Pragma("unroll") for (int m = 0; m < 4; ++m) _Pragma("unroll") for (int k = 0; k < 2; ++k) dst[m][k] = *(const PG8_LAS bf16x8*)(lds + PG8_SA(b, h) + aoff + m * 2048 + k * 1024); } while (0)
; #define PG8_LDB(dst, b, h) do { _Pragma("unroll") for (int n = 0; n < 2; ++n) _Pragma("unroll") for (int k = 0; k < 2; ++k) dst[n][k] = *(const PG8_LAS bf16x8*)(lds + PG8_SB(b, h) + boff + n * 2048 + k * 1024); } while (0)
; #define PG8_MMA(ai, bj, At, Bt) do { __builtin_amdgcn_s_setprio(1); _Pragma("unroll") for (int m = 0; m < 4; ++m) _Pragma("unroll") for (int n = 0; n < 2; ++n) _Pragma("unroll") for (int k = 0; k < 2; ++k) \
;         acc[ai][bj][m][n] = __builtin_amdgcn_mfma_f32_16x16x32_bf16(Bt[n][k], At[m][k], acc[ai][bj][m][n], 0, 0, 0); __builtin_amdgcn_s_setprio(0); } while (0)
; #define PG8_WAIT_V(n) asm volatile("s_waitcnt vmcnt(" #n ")" ::: "memory")
; #define PG8_WAIT_L(n) asm volatile("s_waitcnt lgkmcnt(" #n ")" ::: "memory")
; #define PG8_BAR __builtin_amdgcn_s_barrier()
; #define PG8_SCHED __builtin_amdgcn_sched_barrier(0)
; template <class Epi, class Sched, bool ALIGN_EPI = false, bool SP2 = false>
; __device__ __forceinline__ void gemm_phase(PG8_LAS unsigned char* lds, const Gemm g, const Sched& S, const Epi& E) {
;     ...
;             PG8_LDA(At, 0, 1); PG8_STAGE(PG8_SB(0, 0), b2, voffB); PG8_STAGE(PG8_SB(0, 1), b2 + hstep, voffB); PG8_STAGE(PG8_SA(0, 0), a2, voffA);
;             PG8_WAIT_V(8); PG8_WAIT_L(0); PG8_BAR; PG8_MMA(1, 0, At, B0); PG8_MMA(1, 1, At, B1); PG8_BAR; PG8_SCHED;
;             PG8_LDB(B0, 1, 0); PG8_LDB(B1, 1, 1); PG8_SCHED; PG8_LDA(At, 1, 0); PG8_STAGE(PG8_SA(0, 1), a2 + hstep, voffA);
;             PG8_WAIT_V(8); PG8_WAIT_L(0); PG8_BAR; PG8_MMA(0, 0, At, B0); PG8_MMA(0, 1, At, B1); PG8_BAR; PG8_SCHED;
	s_add_i32 s89, s77, s70
	s_add_u32 s98, s34, s18
	s_addc_u32 s99, s35, s19
	s_add_u32 s100, s62, s18
	s_addc_u32 s101, s63, s19
	s_mov_b32 m0, s89
	ds_read_b128 v[198:201], v165 offset:16384
	ds_read_b128 v[202:205], v165 offset:17408
	ds_read_b128 v[206:209], v165 offset:18432
	ds_read_b128 v[210:213], v165 offset:19456
	ds_read_b128 v[214:217], v165 offset:20480
	ds_read_b128 v[218:221], v165 offset:21504
	ds_read_b128 v[222:225], v165 offset:22528
	ds_read_b128 v[226:229], v165 offset:23552
	global_load_lds_dwordx4 v146, s[34:35]
	s_add_i32 m0, s89, 0x2000
	s_add_u32 s90, s34, 0x40000
	s_addc_u32 s91, s35, 0
	s_add_i32 s89, s78, s70
	global_load_lds_dwordx4 v150, s[34:35]
	s_mov_b32 m0, s89
	s_nop 0
	global_load_lds_dwordx4 v146, s[90:91]
	s_add_i32 m0, s89, 0x2000
	s_nop 0
	global_load_lds_dwordx4 v150, s[90:91]
	s_mov_b32 m0, s71
	s_nop 0
	global_load_lds_dwordx4 v144, s[62:63]
	s_mov_b32 m0, s72
	s_nop 0
	global_load_lds_dwordx4 v148, s[62:63]
	s_waitcnt vmcnt(8)
	s_waitcnt lgkmcnt(0)
	s_barrier
	v_mfma_f32_16x16x32_bf16 v[60:63], v[140:143], v[198:201], v[60:63]
	v_mfma_f32_16x16x32_bf16 v[56:59], v[172:175], v[198:201], v[56:59]
	v_mfma_f32_16x16x32_bf16 v[40:43], v[172:175], v[206:209], v[40:43]
	v_mfma_f32_16x16x32_bf16 v[48:51], v[140:143], v[206:209], v[48:51]
	v_mfma_f32_16x16x32_bf16 v[32:35], v[140:143], v[214:217], v[32:35]
	v_mfma_f32_16x16x32_bf16 v[24:27], v[172:175], v[214:217], v[24:27]
	v_mfma_f32_16x16x32_bf16 v[8:11], v[172:175], v[222:225], v[8:11]
	v_mfma_f32_16x16x32_bf16 v[16:19], v[140:143], v[222:225], v[16:19]
	v_mfma_f32_16x16x32_bf16 v[60:63], v[168:171], v[202:205], v[60:63]
	v_mfma_f32_16x16x32_bf16 v[56:59], v[176:179], v[202:205], v[56:59]
	v_mfma_f32_16x16x32_bf16 v[40:43], v[176:179], v[210:213], v[40:43]
	v_mfma_f32_16x16x32_bf16 v[48:51], v[168:171], v[210:213], v[48:51]
	v_mfma_f32_16x16x32_bf16 v[32:35], v[168:171], v[218:221], v[32:35]
	v_mfma_f32_16x16x32_bf16 v[24:27], v[176:179], v[218:221], v[24:27]
	v_mfma_f32_16x16x32_bf16 v[8:11], v[176:179], v[226:229], v[8:11]
	v_mfma_f32_16x16x32_bf16 v[16:19], v[168:171], v[226:229], v[16:19]
	v_mfma_f32_16x16x32_bf16 v[52:55], v[180:183], v[198:201], v[52:55]
	v_mfma_f32_16x16x32_bf16 v[44:47], v[188:191], v[198:201], v[44:47]
	v_mfma_f32_16x16x32_bf16 v[28:31], v[188:191], v[206:209], v[28:31]
	v_mfma_f32_16x16x32_bf16 v[36:39], v[180:183], v[206:209], v[36:39]
	v_mfma_f32_16x16x32_bf16 v[20:23], v[180:183], v[214:217], v[20:23]
	v_mfma_f32_16x16x32_bf16 v[12:15], v[188:191], v[214:217], v[12:15]
	v_mfma_f32_16x16x32_bf16 v[0:3], v[188:191], v[222:225], v[0:3]
	v_mfma_f32_16x16x32_bf16 v[4:7], v[180:183], v[222:225], v[4:7]
	v_mfma_f32_16x16x32_bf16 v[52:55], v[184:187], v[202:205], v[52:55]
	v_mfma_f32_16x16x32_bf16 v[44:47], v[192:195], v[202:205], v[44:47]
	v_mfma_f32_16x16x32_bf16 v[28:31], v[192:195], v[210:213], v[28:31]
	v_mfma_f32_16x16x32_bf16 v[36:39], v[184:187], v[210:213], v[36:39]
	v_mfma_f32_16x16x32_bf16 v[20:23], v[184:187], v[218:221], v[20:23]
	v_mfma_f32_16x16x32_bf16 v[12:15], v[192:195], v[218:221], v[12:15]
	v_mfma_f32_16x16x32_bf16 v[0:3], v[192:195], v[226:229], v[0:3]
	v_mfma_f32_16x16x32_bf16 v[4:7], v[184:187], v[226:229], v[4:7]
	s_barrier
	s_add_i32 s89, 0, 0x18000
	v_add_u32_e32 v128, s89, v161
	s_add_i32 s90, 0, 0x1c000
	ds_read_b128 v[140:143], v128
	ds_read_b128 v[168:171], v128 offset:1024
	ds_read_b128 v[172:175], v128 offset:2048
	ds_read_b128 v[176:179], v128 offset:3072
	v_add_u32_e32 v128, s90, v161
	ds_read_b128 v[180:183], v128
	ds_read_b128 v[184:187], v128 offset:1024
	ds_read_b128 v[188:191], v128 offset:2048
	ds_read_b128 v[192:195], v128 offset:3072
	s_add_u32 s62, s62, 0x40000
	s_addc_u32 s63, s63, 0
	s_mov_b32 m0, s73
	ds_read_b128 v[198:201], v165 offset:32768
	ds_read_b128 v[202:205], v165 offset:33792
	ds_read_b128 v[206:209], v165 offset:34816
	ds_read_b128 v[210:213], v165 offset:35840
	ds_read_b128 v[214:217], v165 offset:36864
	ds_read_b128 v[218:221], v165 offset:37888
	ds_read_b128 v[222:225], v165 offset:38912
	ds_read_b128 v[226:229], v165 offset:39936
	global_load_lds_dwordx4 v144, s[62:63]
	s_mov_b32 m0, s74
	s_nop 0
	global_load_lds_dwordx4 v148, s[62:63]
	s_waitcnt vmcnt(8)
	s_waitcnt lgkmcnt(0)
	s_barrier
; #define PG8_STAGE(bufoff, gbase, voff) do { _Pragma("unroll") for (int _i = 0; _i < 2; ++_i) \
;         __builtin_amdgcn_global_load_lds((const unsigned*)((const char*)(gbase) + (voff)[_i]), (PG8_LAS unsigned*)(lds + (bufoff) + ldsw + _i * 8192), 16, 0, 0); } while (0)
; #define PG8_LDA(dst, b, h) do { _Pragma("unroll") for (int m = 0; m < 4; ++m) _Pragma("unroll") for (int k = 0; k < 2; ++k) dst[m][k] = *(const PG8_LAS bf16x8*)(lds + PG8_SA(b, h) + aoff + m * 2048 + k * 1024); } while (0)
; #define PG8_LDB(dst, b, h) do { _Pragma("unroll") for (int n = 0; n < 2; ++n) _Pragma("unroll") for (int k = 0; k < 2; ++k) dst[n][k] = *(const PG8_LAS bf16x8*)(lds + PG8_SB(b, h) + boff + n * 2048 + k * 1024); } while (0)
; #define PG8_MMA(ai, bj, At, Bt) do { __builtin_amdgcn_s_setprio(1); _Pragma("unroll") for (int m = 0; m < 4; ++m) _Pragma("unroll") for (int n = 0; n < 2; ++n) _Pragma("unroll") for (int k = 0; k < 2; ++k) \
;         acc[ai][bj][m][n] = __builtin_amdgcn_mfma_f32_16x16x32_bf16(Bt[n][k], At[m][k], acc[ai][bj][m][n], 0, 0, 0); __builtin_amdgcn_s_setprio(0); } while (0)
; #define PG8_WAIT_V(n) asm volatile("s_waitcnt vmcnt(" #n ")" ::: "memory")
; #define PG8_WAIT_L(n) asm volatile("s_waitcnt lgkmcnt(" #n ")" ::: "memory")
; #define PG8_BAR __builtin_amdgcn_s_barrier()
; #define PG8_SCHED __builtin_amdgcn_sched_barrier(0)
; template <class Epi, class Sched, bool ALIGN_EPI = false, bool SP2 = false>
; __device__ __forceinline__ void gemm_phase(PG8_LAS unsigned char* lds, const Gemm g, const Sched& S, const Epi& E) {
;     ...
;             PG8_LDB(B0, 1, 0); PG8_LDB(B1, 1, 1); PG8_SCHED; PG8_LDA(At, 1, 0); PG8_STAGE(PG8_SA(0, 1), a2 + hstep, voffA);
;             PG8_WAIT_V(8); PG8_WAIT_L(0); PG8_BAR; PG8_MMA(0, 0, At, B0); PG8_MMA(0, 1, At, B1); PG8_BAR; PG8_SCHED;
;             PG8_LDA(At, 1, 1); PG8_STAGE(PG8_SB(1, 0), b3, voffB); PG8_STAGE(PG8_SB(1, 1), b3 + hstep, voffB); PG8_STAGE(PG8_SA(1, 0), a3, voffA);
;             PG8_WAIT_V(8); PG8_WAIT_L(0); PG8_BAR; PG8_MMA(1, 0, At, B0); PG8_MMA(1, 1, At, B1); PG8_BAR; PG8_SCHED;
	v_mfma_f32_16x16x32_bf16 v[124:127], v[140:143], v[198:201], v[124:127]
	v_mfma_f32_16x16x32_bf16 v[120:123], v[172:175], v[198:201], v[120:123]
	v_mfma_f32_16x16x32_bf16 v[104:107], v[172:175], v[206:209], v[104:107]
	v_mfma_f32_16x16x32_bf16 v[108:111], v[140:143], v[206:209], v[108:111]
	v_mfma_f32_16x16x32_bf16 v[92:95], v[140:143], v[214:217], v[92:95]
	v_mfma_f32_16x16x32_bf16 v[88:91], v[172:175], v[214:217], v[88:91]
	v_mfma_f32_16x16x32_bf16 v[72:75], v[172:175], v[222:225], v[72:75]
	v_mfma_f32_16x16x32_bf16 v[76:79], v[140:143], v[222:225], v[76:79]
	v_mfma_f32_16x16x32_bf16 v[124:127], v[168:171], v[202:205], v[124:127]
	v_mfma_f32_16x16x32_bf16 v[120:123], v[176:179], v[202:205], v[120:123]
	v_mfma_f32_16x16x32_bf16 v[104:107], v[176:179], v[210:213], v[104:107]
	v_mfma_f32_16x16x32_bf16 v[108:111], v[168:171], v[210:213], v[108:111]
	v_mfma_f32_16x16x32_bf16 v[92:95], v[168:171], v[218:221], v[92:95]
	v_mfma_f32_16x16x32_bf16 v[88:91], v[176:179], v[218:221], v[88:91]
	v_mfma_f32_16x16x32_bf16 v[72:75], v[176:179], v[226:229], v[72:75]
	v_mfma_f32_16x16x32_bf16 v[76:79], v[168:171], v[226:229], v[76:79]
	v_mfma_f32_16x16x32_bf16 v[116:119], v[180:183], v[198:201], v[116:119]
	v_mfma_f32_16x16x32_bf16 v[112:115], v[188:191], v[198:201], v[112:115]
	v_mfma_f32_16x16x32_bf16 v[96:99], v[188:191], v[206:209], v[96:99]
	v_mfma_f32_16x16x32_bf16 v[100:103], v[180:183], v[206:209], v[100:103]
	v_mfma_f32_16x16x32_bf16 v[84:87], v[180:183], v[214:217], v[84:87]
	v_mfma_f32_16x16x32_bf16 v[80:83], v[188:191], v[214:217], v[80:83]
	v_mfma_f32_16x16x32_bf16 v[64:67], v[188:191], v[222:225], v[64:67]
	v_mfma_f32_16x16x32_bf16 v[68:71], v[180:183], v[222:225], v[68:71]
	v_mfma_f32_16x16x32_bf16 v[116:119], v[184:187], v[202:205], v[116:119]
	v_mfma_f32_16x16x32_bf16 v[112:115], v[192:195], v[202:205], v[112:115]
	v_mfma_f32_16x16x32_bf16 v[96:99], v[192:195], v[210:213], v[96:99]
	v_mfma_f32_16x16x32_bf16 v[100:103], v[184:187], v[210:213], v[100:103]
	v_mfma_f32_16x16x32_bf16 v[84:87], v[184:187], v[218:221], v[84:87]
	v_mfma_f32_16x16x32_bf16 v[80:83], v[192:195], v[218:221], v[80:83]
	v_mfma_f32_16x16x32_bf16 v[64:67], v[192:195], v[226:229], v[64:67]
	v_mfma_f32_16x16x32_bf16 v[68:71], v[184:187], v[226:229], v[68:71]
	s_barrier
	s_add_i32 s62, s89, s70
	s_mov_b32 m0, s62
	ds_read_b128 v[198:201], v165 offset:49152
	ds_read_b128 v[202:205], v165 offset:50176
	ds_read_b128 v[206:209], v165 offset:51200
	ds_read_b128 v[210:213], v165 offset:52224
	ds_read_b128 v[214:217], v165 offset:53248
	ds_read_b128 v[218:221], v165 offset:54272
	ds_read_b128 v[222:225], v165 offset:55296
	ds_read_b128 v[226:229], v165 offset:56320
	global_load_lds_dwordx4 v146, s[98:99]
	s_add_i32 m0, s62, 0x2000
	s_add_u32 s34, s34, 0x40080
	s_addc_u32 s35, s35, 0
	s_add_i32 s62, s90, s70
	global_load_lds_dwordx4 v150, s[98:99]
	s_mov_b32 m0, s62
	s_nop 0
	global_load_lds_dwordx4 v146, s[34:35]
	s_add_i32 m0, s62, 0x2000
	s_nop 0
	global_load_lds_dwordx4 v150, s[34:35]
	s_mov_b32 m0, s75
	s_nop 0
	global_load_lds_dwordx4 v144, s[100:101]
	s_mov_b32 m0, s76
	s_nop 0
	global_load_lds_dwordx4 v148, s[100:101]
	s_waitcnt vmcnt(8)
	s_waitcnt lgkmcnt(0)
	s_barrier
	v_mfma_f32_16x16x32_bf16 v[60:63], v[140:143], v[198:201], v[60:63]
	v_mfma_f32_16x16x32_bf16 v[56:59], v[172:175], v[198:201], v[56:59]
	v_mfma_f32_16x16x32_bf16 v[40:43], v[172:175], v[206:209], v[40:43]
	v_mfma_f32_16x16x32_bf16 v[48:51], v[140:143], v[206:209], v[48:51]
	v_mfma_f32_16x16x32_bf16 v[32:35], v[140:143], v[214:217], v[32:35]
	v_mfma_f32_16x16x32_bf16 v[24:27], v[172:175], v[214:217], v[24:27]
	v_mfma_f32_16x16x32_bf16 v[8:11], v[172:175], v[222:225], v[8:11]
	v_mfma_f32_16x16x32_bf16 v[16:19], v[140:143], v[222:225], v[16:19]
	v_mfma_f32_16x16x32_bf16 v[60:63], v[168:171], v[202:205], v[60:63]
	v_mfma_f32_16x16x32_bf16 v[56:59], v[176:179], v[202:205], v[56:59]
	v_mfma_f32_16x16x32_bf16 v[40:43], v[176:179], v[210:213], v[40:43]
	v_mfma_f32_16x16x32_bf16 v[48:51], v[168:171], v[210:213], v[48:51]
	v_mfma_f32_16x16x32_bf16 v[32:35], v[168:171], v[218:221], v[32:35]
	v_mfma_f32_16x16x32_bf16 v[24:27], v[176:179], v[218:221], v[24:27]
	v_mfma_f32_16x16x32_bf16 v[8:11], v[176:179], v[226:229], v[8:11]
	v_mfma_f32_16x16x32_bf16 v[16:19], v[168:171], v[226:229], v[16:19]
	v_mfma_f32_16x16x32_bf16 v[52:55], v[180:183], v[198:201], v[52:55]
	v_mfma_f32_16x16x32_bf16 v[44:47], v[188:191], v[198:201], v[44:47]
	v_mfma_f32_16x16x32_bf16 v[28:31], v[188:191], v[206:209], v[28:31]
	v_mfma_f32_16x16x32_bf16 v[36:39], v[180:183], v[206:209], v[36:39]
	v_mfma_f32_16x16x32_bf16 v[20:23], v[180:183], v[214:217], v[20:23]
	v_mfma_f32_16x16x32_bf16 v[12:15], v[188:191], v[214:217], v[12:15]
	v_mfma_f32_16x16x32_bf16 v[0:3], v[188:191], v[222:225], v[0:3]
	v_mfma_f32_16x16x32_bf16 v[4:7], v[180:183], v[222:225], v[4:7]
	v_mfma_f32_16x16x32_bf16 v[52:55], v[184:187], v[202:205], v[52:55]
	v_mfma_f32_16x16x32_bf16 v[44:47], v[192:195], v[202:205], v[44:47]
	v_mfma_f32_16x16x32_bf16 v[28:31], v[192:195], v[210:213], v[28:31]
	v_mfma_f32_16x16x32_bf16 v[36:39], v[184:187], v[210:213], v[36:39]
	v_mfma_f32_16x16x32_bf16 v[20:23], v[184:187], v[218:221], v[20:23]
	v_mfma_f32_16x16x32_bf16 v[12:15], v[192:195], v[218:221], v[12:15]
	v_mfma_f32_16x16x32_bf16 v[0:3], v[192:195], v[226:229], v[0:3]
	v_mfma_f32_16x16x32_bf16 v[4:7], v[184:187], v[226:229], v[4:7]
	s_barrier
	s_add_i32 s88, s88, 2
	s_add_u32 s20, s20, 0x100
	s_addc_u32 s21, s21, 0
	s_add_u32 s86, s86, 0x100
	s_addc_u32 s87, s87, 0
	s_cmp_gt_u32 s88, 13
	s_cbranch_scc0 .LBB0_1200
	v_readlane_b32 s101, v249, 49
	s_nop 3
	s_cmp_eq_u32 s101, 0
	s_cbranch_scc1 .Ldw_done_2
	s_add_u32 s98, s28, 0x183500
	s_addc_u32 s99, s29, 0
	v_mov_b32_e32 v251, 0
	s_mov_b32 s100, 0

; #define PG8_STAGE(bufoff, gbase, voff) do { _Pragma("unroll") for (int _i = 0; _i < 2; ++_i) \
;         __builtin_amdgcn_global_load_lds((const unsigned*)((const char*)(gbase) + (voff)[_i]), (PG8_LAS unsigned*)(lds + (bufoff) + ldsw + _i * 8192), 16, 0, 0); } while (0)
; #define PG8_LDA(dst, b, h) do { _Pragma("unroll") for (int m = 0; m < 4; ++m) _Pragma("unroll") for (int k = 0; k < 2; ++k) dst[m][k] = *(const PG8_LAS bf16x8*)(lds + PG8_SA(b, h) + aoff + m * 2048 + k * 1024); } while (0)
; #define PG8_LDB(dst, b, h) do { _Pragma("unroll") for (int n = 0; n < 2; ++n) _Pragma("unroll") for (int k = 0; k < 2; ++k) dst[n][k] = *(const PG8_LAS bf16x8*)(lds + PG8_SB(b, h) + boff + n * 2048 + k * 1024); } while (0)
; #define PG8_WAIT_V(n) asm volatile("s_waitcnt vmcnt(" #n ")" ::: "memory")
; #define PG8_WAIT_L(n) asm volatile("s_waitcnt lgkmcnt(" #n ")" ::: "memory")
; #define PG8_BAR __builtin_amdgcn_s_barrier()
; #define PG8_SCHED __builtin_amdgcn_sched_barrier(0)
; template <class Epi, class Sched, bool ALIGN_EPI = false, bool SP2 = false>
; __device__ __forceinline__ void gemm_phase(PG8_LAS unsigned char* lds, const Gemm g, const Sched& S, const Epi& E) {
;     ...
;         const bool has_next = S.next(ui + 1, nxt);
;         const char* nA = has_next ? (const char*)g.A + (size_t)nxt.pm * tstep : cA; const char* nB = has_next ? (const char*)g.Bt + (size_t)nxt.pn * tstep : cB;
;         for (int t = 0; t < nt; t += 2) {
;             const bool last = (t == nt - 2);
;             const char* a1 = cA + (size_t)(t + 1) * kstep;
;             const char* a2 = last ? nA : cA + (size_t)(t + 2) * kstep; const char* b2 = last ? nB : cB + (size_t)(t + 2) * kstep;
;             const char* a3 = a2 + kstep; const char* b3 = b2 + kstep;
;             if (last && has_next) S.a_ready(nxt);
;             if constexpr (SP2) {
;             PG8_LDB(B0, 0, 0); PG8_LDB(B1, 0, 1); PG8_SCHED; PG8_LDA(At, 0, 0); PG8_STAGE(PG8_SA(1, 1), a1 + hstep, voffA);
;             PG8_WAIT_V(8); PG8_WAIT_L(0); PG8_BAR; PG8_MMA(0, 0, At, B0); PG8_MMA(0, 1, At, B1); PG8_BAR; PG8_SCHED;
;             PG8_LDA(At, 0, 1); PG8_STAGE(PG8_SB(0, 0), b2, voffB); PG8_STAGE(PG8_SB(0, 1), b2 + hstep, voffB); PG8_STAGE(PG8_SA(0, 0), a2, voffA);
;             PG8_WAIT_V(8); PG8_WAIT_L(0); PG8_BAR; PG8_MMA(1, 0, At, B0); PG8_MMA(1, 1, At, B1); PG8_BAR; PG8_SCHED;
.LBB0_1445:
	s_ashr_i32 s15, s14, 31
	s_lshl_b64 s[16:17], s[14:15], 19
	s_add_u32 s16, s49, s16
	s_addc_u32 s17, s50, s17
	s_and_b64 s[18:19], s[4:5], exec
	s_cselect_b32 s15, s17, s21
	s_cselect_b32 s65, s16, s20
	s_ashr_i32 s13, s12, 31
	s_lshl_b64 s[18:19], s[12:13], 19
	s_add_u32 s18, s36, s18
	s_addc_u32 s19, s37, s19
	s_and_b64 s[44:45], s[4:5], exec
	s_cselect_b32 s13, s19, s39
	s_cselect_b32 s66, s18, s38
	s_add_u32 s20, s20, 0x40080
	s_addc_u32 s21, s21, 0
	s_add_u32 s67, s38, 0x100
	s_addc_u32 s68, s39, 0
	s_mov_b32 s69, -2
	ds_read_b128 v[128:131], v153
	ds_read_b128 v[132:135], v153 offset:1024
	ds_read_b128 v[136:139], v153 offset:2048
	ds_read_b128 v[140:143], v153 offset:3072
	ds_read_b128 v[172:175], v155
	ds_read_b128 v[176:179], v155 offset:1024
	ds_read_b128 v[180:183], v155 offset:2048
	ds_read_b128 v[184:187], v155 offset:3072
	s_add_u32 s38, s20, 0xfffc0080
	s_addc_u32 s39, s21, -1
	s_cmp_eq_u32 s69, 12
	s_cselect_b32 s45, s15, s39
	s_cselect_b32 s44, s65, s38
	s_cselect_b32 s39, s13, s68
	s_cselect_b32 s38, s66, s67
	s_add_i32 m0, s35, 0xc000
	ds_read_b128 v[188:191], v157
	ds_read_b128 v[192:195], v157 offset:1024
	ds_read_b128 v[198:201], v157 offset:2048
	ds_read_b128 v[202:205], v157 offset:3072
	ds_read_b128 v[206:209], v157 offset:4096
	ds_read_b128 v[210:213], v157 offset:5120
	ds_read_b128 v[214:217], v157 offset:6144
	ds_read_b128 v[218:221], v157 offset:7168
	global_load_lds_dwordx4 v162, s[20:21]
	s_add_i32 m0, s35, 0xe000
	s_nop 0
	global_load_lds_dwordx4 v164, s[20:21]
	s_waitcnt vmcnt(8)
	s_waitcnt lgkmcnt(0)
	s_barrier
	v_mfma_f32_16x16x32_bf16 v[124:127], v[128:131], v[188:191], 0
	v_mfma_f32_16x16x32_bf16 v[120:123], v[136:139], v[188:191], 0
	v_mfma_f32_16x16x32_bf16 v[104:107], v[136:139], v[198:201], 0
	v_mfma_f32_16x16x32_bf16 v[108:111], v[128:131], v[198:201], 0
	v_mfma_f32_16x16x32_bf16 v[96:99], v[128:131], v[206:209], 0
	v_mfma_f32_16x16x32_bf16 v[88:91], v[136:139], v[206:209], 0
	v_mfma_f32_16x16x32_bf16 v[72:75], v[136:139], v[214:217], 0
	v_mfma_f32_16x16x32_bf16 v[80:83], v[128:131], v[214:217], 0
	v_mfma_f32_16x16x32_bf16 v[124:127], v[132:135], v[192:195], v[124:127]
	v_mfma_f32_16x16x32_bf16 v[120:123], v[140:143], v[192:195], v[120:123]
	v_mfma_f32_16x16x32_bf16 v[104:107], v[140:143], v[202:205], v[104:107]
	v_mfma_f32_16x16x32_bf16 v[108:111], v[132:135], v[202:205], v[108:111]
	v_mfma_f32_16x16x32_bf16 v[96:99], v[132:135], v[210:213], v[96:99]
	v_mfma_f32_16x16x32_bf16 v[88:91], v[140:143], v[210:213], v[88:91]
	v_mfma_f32_16x16x32_bf16 v[72:75], v[140:143], v[218:221], v[72:75]
	v_mfma_f32_16x16x32_bf16 v[80:83], v[132:135], v[218:221], v[80:83]
	v_mfma_f32_16x16x32_bf16 v[116:119], v[172:175], v[188:191], 0
	v_mfma_f32_16x16x32_bf16 v[112:115], v[180:183], v[188:191], 0
	v_mfma_f32_16x16x32_bf16 v[92:95], v[180:183], v[198:201], 0
	v_mfma_f32_16x16x32_bf16 v[100:103], v[172:175], v[198:201], 0
	v_mfma_f32_16x16x32_bf16 v[84:87], v[172:175], v[206:209], 0
	v_mfma_f32_16x16x32_bf16 v[76:79], v[180:183], v[206:209], 0
	v_mfma_f32_16x16x32_bf16 v[64:67], v[180:183], v[214:217], 0
	v_mfma_f32_16x16x32_bf16 v[68:71], v[172:175], v[214:217], 0
	v_mfma_f32_16x16x32_bf16 v[116:119], v[176:179], v[192:195], v[116:119]
	v_mfma_f32_16x16x32_bf16 v[112:115], v[184:187], v[192:195], v[112:115]
	v_mfma_f32_16x16x32_bf16 v[92:95], v[184:187], v[202:205], v[92:95]
	v_mfma_f32_16x16x32_bf16 v[100:103], v[176:179], v[202:205], v[100:103]
	v_mfma_f32_16x16x32_bf16 v[84:87], v[176:179], v[210:213], v[84:87]
	v_mfma_f32_16x16x32_bf16 v[76:79], v[184:187], v[210:213], v[76:79]
	v_mfma_f32_16x16x32_bf16 v[64:67], v[184:187], v[218:221], v[64:67]
	v_mfma_f32_16x16x32_bf16 v[68:71], v[176:179], v[218:221], v[68:71]
	s_barrier
	s_add_i32 s70, s60, s51
	s_add_u32 s98, s38, s6
	s_addc_u32 s99, s39, s7
	s_add_u32 s100, s44, s6
	s_addc_u32 s101, s45, s7
	s_mov_b32 m0, s70
	ds_read_b128 v[188:191], v157 offset:16384
	ds_read_b128 v[192:195], v157 offset:17408
	ds_read_b128 v[198:201], v157 offset:18432
	ds_read_b128 v[202:205], v157 offset:19456
	ds_read_b128 v[206:209], v157 offset:20480
	ds_read_b128 v[210:213], v157 offset:21504
	ds_read_b128 v[214:217], v157 offset:22528
	ds_read_b128 v[218:221], v157 offset:23552
	global_load_lds_dwordx4 v146, s[38:39]
	s_add_i32 m0, s70, 0x2000
	s_add_u32 s70, s38, 0x40000
	s_addc_u32 s71, s39, 0
	s_add_i32 s72, s61, s51
	global_load_lds_dwordx4 v150, s[38:39]
	s_mov_b32 m0, s72
	s_nop 0
	global_load_lds_dwordx4 v146, s[70:71]
	s_add_i32 m0, s72, 0x2000
	s_nop 0
	global_load_lds_dwordx4 v150, s[70:71]
	s_mov_b32 m0, s35
	s_nop 0
	global_load_lds_dwordx4 v144, s[44:45]
	s_mov_b32 m0, s52
	s_nop 0
	global_load_lds_dwordx4 v148, s[44:45]
	s_waitcnt vmcnt(8)
	s_waitcnt lgkmcnt(0)
	s_barrier
; #define PG8_STAGE(bufoff, gbase, voff) do { _Pragma("unroll") for (int _i = 0; _i < 2; ++_i) \
;         __builtin_amdgcn_global_load_lds((const unsigned*)((const char*)(gbase) + (voff)[_i]), (PG8_LAS unsigned*)(lds + (bufoff) + ldsw + _i * 8192), 16, 0, 0); } while (0)
; #define PG8_LDA(dst, b, h) do { _Pragma("unroll") for (int m = 0; m < 4; ++m) _Pragma("unroll") for (int k = 0; k < 2; ++k) dst[m][k] = *(const PG8_LAS bf16x8*)(lds + PG8_SA(b, h) + aoff + m * 2048 + k * 1024); } while (0)
; #define PG8_LDB(dst, b, h) do { _Pragma("unroll") for (int n = 0; n < 2; ++n) _Pragma("unroll") for (int k = 0; k < 2; ++k) dst[n][k] = *(const PG8_LAS bf16x8*)(lds + PG8_SB(b, h) + boff + n * 2048 + k * 1024); } while (0)
; #define PG8_MMA(ai, bj, At, Bt) do { __builtin_amdgcn_s_setprio(1); _Pragma("unroll") for (int m = 0; m < 4; ++m) _Pragma("unroll") for (int n = 0; n < 2; ++n) _Pragma("unroll") for (int k = 0; k < 2; ++k) \
;         acc[ai][bj][m][n] = __builtin_amdgcn_mfma_f32_16x16x32_bf16(Bt[n][k], At[m][k], acc[ai][bj][m][n], 0, 0, 0); __builtin_amdgcn_s_setprio(0); } while (0)
; #define PG8_WAIT_V(n) asm volatile("s_waitcnt vmcnt(" #n ")" ::: "memory")
; #define PG8_WAIT_L(n) asm volatile("s_waitcnt lgkmcnt(" #n ")" ::: "memory")
; #define PG8_BAR __builtin_amdgcn_s_barrier()
; #define PG8_SCHED __builtin_amdgcn_sched_barrier(0)
; template <class Epi, class Sched, bool ALIGN_EPI = false, bool SP2 = false>
; __device__ __forceinline__ void gemm_phase(PG8_LAS unsigned char* lds, const Gemm g, const Sched& S, const Epi& E) {
;     ...
;             PG8_WAIT_V(8); PG8_WAIT_L(0); PG8_BAR; PG8_MMA(1, 0, At, B0); PG8_MMA(1, 1, At, B1); PG8_BAR; PG8_SCHED;
;             PG8_LDB(B0, 1, 0); PG8_LDB(B1, 1, 1); PG8_SCHED; PG8_LDA(At, 1, 0); PG8_STAGE(PG8_SA(0, 1), a2 + hstep, voffA);
;             PG8_WAIT_V(8); PG8_WAIT_L(0); PG8_BAR; PG8_MMA(0, 0, At, B0); PG8_MMA(0, 1, At, B1); PG8_BAR; PG8_SCHED;
	v_mfma_f32_16x16x32_bf16 v[60:63], v[128:131], v[188:191], 0
	v_mfma_f32_16x16x32_bf16 v[56:59], v[136:139], v[188:191], 0
	v_mfma_f32_16x16x32_bf16 v[40:43], v[136:139], v[198:201], 0
	v_mfma_f32_16x16x32_bf16 v[48:51], v[128:131], v[198:201], 0
	v_mfma_f32_16x16x32_bf16 v[32:35], v[128:131], v[206:209], 0
	v_mfma_f32_16x16x32_bf16 v[24:27], v[136:139], v[206:209], 0
	v_mfma_f32_16x16x32_bf16 v[8:11], v[136:139], v[214:217], 0
	v_mfma_f32_16x16x32_bf16 v[16:19], v[128:131], v[214:217], 0
	v_mfma_f32_16x16x32_bf16 v[60:63], v[132:135], v[192:195], v[60:63]
	v_mfma_f32_16x16x32_bf16 v[56:59], v[140:143], v[192:195], v[56:59]
	v_mfma_f32_16x16x32_bf16 v[40:43], v[140:143], v[202:205], v[40:43]
	v_mfma_f32_16x16x32_bf16 v[48:51], v[132:135], v[202:205], v[48:51]
	v_mfma_f32_16x16x32_bf16 v[32:35], v[132:135], v[210:213], v[32:35]
	v_mfma_f32_16x16x32_bf16 v[24:27], v[140:143], v[210:213], v[24:27]
	v_mfma_f32_16x16x32_bf16 v[8:11], v[140:143], v[218:221], v[8:11]
	v_mfma_f32_16x16x32_bf16 v[16:19], v[132:135], v[218:221], v[16:19]
	v_mfma_f32_16x16x32_bf16 v[52:55], v[172:175], v[188:191], 0
	v_mfma_f32_16x16x32_bf16 v[44:47], v[180:183], v[188:191], 0
	v_mfma_f32_16x16x32_bf16 v[28:31], v[180:183], v[198:201], 0
	v_mfma_f32_16x16x32_bf16 v[36:39], v[172:175], v[198:201], 0
	v_mfma_f32_16x16x32_bf16 v[20:23], v[172:175], v[206:209], 0
	v_mfma_f32_16x16x32_bf16 v[12:15], v[180:183], v[206:209], 0
	v_mfma_f32_16x16x32_bf16 v[0:3], v[180:183], v[214:217], 0
	v_mfma_f32_16x16x32_bf16 v[4:7], v[172:175], v[214:217], 0
	v_mfma_f32_16x16x32_bf16 v[52:55], v[176:179], v[192:195], v[52:55]
	v_mfma_f32_16x16x32_bf16 v[44:47], v[184:187], v[192:195], v[44:47]
	v_mfma_f32_16x16x32_bf16 v[28:31], v[184:187], v[202:205], v[28:31]
	v_mfma_f32_16x16x32_bf16 v[36:39], v[176:179], v[202:205], v[36:39]
	v_mfma_f32_16x16x32_bf16 v[20:23], v[176:179], v[210:213], v[20:23]
	v_mfma_f32_16x16x32_bf16 v[12:15], v[184:187], v[210:213], v[12:15]
	v_mfma_f32_16x16x32_bf16 v[0:3], v[184:187], v[218:221], v[0:3]
	v_mfma_f32_16x16x32_bf16 v[4:7], v[176:179], v[218:221], v[4:7]
	s_barrier
	s_add_i32 s70, 0, 0x18000
	s_add_i32 s71, 0, 0x1c000
	v_add_u32_e32 v140, s70, v170
	v_add_u32_e32 v159, s71, v170
	ds_read_b128 v[128:131], v140
	ds_read_b128 v[132:135], v140 offset:1024
	ds_read_b128 v[136:139], v140 offset:2048
	ds_read_b128 v[140:143], v140 offset:3072
	ds_read_b128 v[172:175], v159
	ds_read_b128 v[176:179], v159 offset:1024
	ds_read_b128 v[180:183], v159 offset:2048
	ds_read_b128 v[184:187], v159 offset:3072
	s_add_u32 s44, s44, 0x40000
	s_addc_u32 s45, s45, 0
	s_mov_b32 m0, s53
	ds_read_b128 v[188:191], v157 offset:32768
	ds_read_b128 v[192:195], v157 offset:33792
	ds_read_b128 v[198:201], v157 offset:34816
	ds_read_b128 v[202:205], v157 offset:35840
	ds_read_b128 v[206:209], v157 offset:36864
	ds_read_b128 v[210:213], v157 offset:37888
	ds_read_b128 v[214:217], v157 offset:38912
	ds_read_b128 v[218:221], v157 offset:39936
	global_load_lds_dwordx4 v144, s[44:45]
	s_mov_b32 m0, s54
	s_nop 0
	global_load_lds_dwordx4 v148, s[44:45]
	s_waitcnt vmcnt(8)
	s_waitcnt lgkmcnt(0)
	s_barrier
	v_mfma_f32_16x16x32_bf16 v[124:127], v[128:131], v[188:191], v[124:127]
	v_mfma_f32_16x16x32_bf16 v[120:123], v[136:139], v[188:191], v[120:123]
	v_mfma_f32_16x16x32_bf16 v[104:107], v[136:139], v[198:201], v[104:107]
	v_mfma_f32_16x16x32_bf16 v[108:111], v[128:131], v[198:201], v[108:111]
	v_mfma_f32_16x16x32_bf16 v[96:99], v[128:131], v[206:209], v[96:99]
	v_mfma_f32_16x16x32_bf16 v[88:91], v[136:139], v[206:209], v[88:91]
	v_mfma_f32_16x16x32_bf16 v[72:75], v[136:139], v[214:217], v[72:75]
	v_mfma_f32_16x16x32_bf16 v[80:83], v[128:131], v[214:217], v[80:83]
	v_mfma_f32_16x16x32_bf16 v[124:127], v[132:135], v[192:195], v[124:127]
	v_mfma_f32_16x16x32_bf16 v[120:123], v[140:143], v[192:195], v[120:123]
	v_mfma_f32_16x16x32_bf16 v[104:107], v[140:143], v[202:205], v[104:107]
	v_mfma_f32_16x16x32_bf16 v[108:111], v[132:135], v[202:205], v[108:111]
	v_mfma_f32_16x16x32_bf16 v[96:99], v[132:135], v[210:213], v[96:99]
	v_mfma_f32_16x16x32_bf16 v[88:91], v[140:143], v[210:213], v[88:91]
	v_mfma_f32_16x16x32_bf16 v[72:75], v[140:143], v[218:221], v[72:75]
	v_mfma_f32_16x16x32_bf16 v[80:83], v[132:135], v[218:221], v[80:83]
	v_mfma_f32_16x16x32_bf16 v[116:119], v[172:175], v[188:191], v[116:119]
	v_mfma_f32_16x16x32_bf16 v[112:115], v[180:183], v[188:191], v[112:115]
	v_mfma_f32_16x16x32_bf16 v[92:95], v[180:183], v[198:201], v[92:95]
	v_mfma_f32_16x16x32_bf16 v[100:103], v[172:175], v[198:201], v[100:103]
	v_mfma_f32_16x16x32_bf16 v[84:87], v[172:175], v[206:209], v[84:87]
	v_mfma_f32_16x16x32_bf16 v[76:79], v[180:183], v[206:209], v[76:79]
	v_mfma_f32_16x16x32_bf16 v[64:67], v[180:183], v[214:217], v[64:67]
	v_mfma_f32_16x16x32_bf16 v[68:71], v[172:175], v[214:217], v[68:71]
	v_mfma_f32_16x16x32_bf16 v[116:119], v[176:179], v[192:195], v[116:119]
	v_mfma_f32_16x16x32_bf16 v[112:115], v[184:187], v[192:195], v[112:115]
	v_mfma_f32_16x16x32_bf16 v[92:95], v[184:187], v[202:205], v[92:95]
	v_mfma_f32_16x16x32_bf16 v[100:103], v[176:179], v[202:205], v[100:103]
	v_mfma_f32_16x16x32_bf16 v[84:87], v[176:179], v[210:213], v[84:87]
	v_mfma_f32_16x16x32_bf16 v[76:79], v[184:187], v[210:213], v[76:79]
	v_mfma_f32_16x16x32_bf16 v[64:67], v[184:187], v[218:221], v[64:67]
	v_mfma_f32_16x16x32_bf16 v[68:71], v[176:179], v[218:221], v[68:71]
	s_barrier
; #define PG8_STAGE(bufoff, gbase, voff) do { _Pragma("unroll") for (int _i = 0; _i < 2; ++_i) \
;         __builtin_amdgcn_global_load_lds((const unsigned*)((const char*)(gbase) + (voff)[_i]), (PG8_LAS unsigned*)(lds + (bufoff) + ldsw + _i * 8192), 16, 0, 0); } while (0)
; #define PG8_LDA(dst, b, h) do { _Pragma("unroll") for (int m = 0; m < 4; ++m) _Pragma("unroll") for (int k = 0; k < 2; ++k) dst[m][k] = *(const PG8_LAS bf16x8*)(lds + PG8_SA(b, h) + aoff + m * 2048 + k * 1024); } while (0)
; #define PG8_LDB(dst, b, h) do { _Pragma("unroll") for (int n = 0; n < 2; ++n) _Pragma("unroll") for (int k = 0; k < 2; ++k) dst[n][k] = *(const PG8_LAS bf16x8*)(lds + PG8_SB(b, h) + boff + n * 2048 + k * 1024); } while (0)
; #define PG8_MMA(ai, bj, At, Bt) do { __builtin_amdgcn_s_setprio(1); _Pragma("unroll") for (int m = 0; m < 4; ++m) _Pragma("unroll") for (int n = 0; n < 2; ++n) _Pragma("unroll") for (int k = 0; k < 2; ++k) \
;         acc[ai][bj][m][n] = __builtin_amdgcn_mfma_f32_16x16x32_bf16(Bt[n][k], At[m][k], acc[ai][bj][m][n], 0, 0, 0); __builtin_amdgcn_s_setprio(0); } while (0)
; #define PG8_WAIT_V(n) asm volatile("s_waitcnt vmcnt(" #n ")" ::: "memory")
; #define PG8_WAIT_L(n) asm volatile("s_waitcnt lgkmcnt(" #n ")" ::: "memory")
; #define PG8_BAR __builtin_amdgcn_s_barrier()
; #define PG8_SCHED __builtin_amdgcn_sched_barrier(0)
; template <class Epi, class Sched, bool ALIGN_EPI = false, bool SP2 = false>
; __device__ __forceinline__ void gemm_phase(PG8_LAS unsigned char* lds, const Gemm g, const Sched& S, const Epi& E) {
;     ...
;             PG8_LDB(B0, 0, 0); PG8_LDB(B1, 0, 1); PG8_SCHED; PG8_LDA(At, 0, 0); PG8_STAGE(PG8_SA(1, 1), a1 + hstep, voffA);
;             PG8_WAIT_V(8); PG8_WAIT_L(0); PG8_BAR; PG8_MMA(0, 0, At, B0); PG8_MMA(0, 1, At, B1); PG8_BAR; PG8_SCHED;
;     ...
;             PG8_LDA(At, 1, 1); PG8_STAGE(PG8_SB(1, 0), b3, voffB); PG8_STAGE(PG8_SB(1, 1), b3 + hstep, voffB); PG8_STAGE(PG8_SA(1, 0), a3, voffA);
;             PG8_WAIT_V(8); PG8_WAIT_L(0); PG8_BAR; PG8_MMA(1, 0, At, B0); PG8_MMA(1, 1, At, B1); PG8_BAR; PG8_SCHED;
	s_add_i32 s44, s70, s51
	s_mov_b32 m0, s44
	ds_read_b128 v[188:191], v157 offset:49152
	ds_read_b128 v[192:195], v157 offset:50176
	ds_read_b128 v[198:201], v157 offset:51200
	ds_read_b128 v[202:205], v157 offset:52224
	ds_read_b128 v[206:209], v157 offset:53248
	ds_read_b128 v[210:213], v157 offset:54272
	ds_read_b128 v[214:217], v157 offset:55296
	ds_read_b128 v[218:221], v157 offset:56320
	global_load_lds_dwordx4 v146, s[98:99]
	s_add_i32 m0, s44, 0x2000
	s_add_u32 s38, s38, 0x40080
	s_addc_u32 s39, s39, 0
	s_add_i32 s44, s71, s51
	global_load_lds_dwordx4 v150, s[98:99]
	s_mov_b32 m0, s44
	s_nop 0
	global_load_lds_dwordx4 v146, s[38:39]
	s_add_i32 m0, s44, 0x2000
	s_nop 0
	global_load_lds_dwordx4 v150, s[38:39]
	s_mov_b32 m0, s58
	s_nop 0
	global_load_lds_dwordx4 v144, s[100:101]
	s_mov_b32 m0, s59
	s_nop 0
	global_load_lds_dwordx4 v148, s[100:101]
	s_waitcnt vmcnt(8)
	s_waitcnt lgkmcnt(0)
	s_barrier
	v_mfma_f32_16x16x32_bf16 v[60:63], v[128:131], v[188:191], v[60:63]
	v_mfma_f32_16x16x32_bf16 v[56:59], v[136:139], v[188:191], v[56:59]
	v_mfma_f32_16x16x32_bf16 v[40:43], v[136:139], v[198:201], v[40:43]
	v_mfma_f32_16x16x32_bf16 v[48:51], v[128:131], v[198:201], v[48:51]
	v_mfma_f32_16x16x32_bf16 v[32:35], v[128:131], v[206:209], v[32:35]
	v_mfma_f32_16x16x32_bf16 v[24:27], v[136:139], v[206:209], v[24:27]
	v_mfma_f32_16x16x32_bf16 v[8:11], v[136:139], v[214:217], v[8:11]
	v_mfma_f32_16x16x32_bf16 v[16:19], v[128:131], v[214:217], v[16:19]
	v_mfma_f32_16x16x32_bf16 v[60:63], v[132:135], v[192:195], v[60:63]
	v_mfma_f32_16x16x32_bf16 v[56:59], v[140:143], v[192:195], v[56:59]
	v_mfma_f32_16x16x32_bf16 v[40:43], v[140:143], v[202:205], v[40:43]
	v_mfma_f32_16x16x32_bf16 v[48:51], v[132:135], v[202:205], v[48:51]
	v_mfma_f32_16x16x32_bf16 v[32:35], v[132:135], v[210:213], v[32:35]
	v_mfma_f32_16x16x32_bf16 v[24:27], v[140:143], v[210:213], v[24:27]
	v_mfma_f32_16x16x32_bf16 v[8:11], v[140:143], v[218:221], v[8:11]
	v_mfma_f32_16x16x32_bf16 v[16:19], v[132:135], v[218:221], v[16:19]
	v_mfma_f32_16x16x32_bf16 v[52:55], v[172:175], v[188:191], v[52:55]
	v_mfma_f32_16x16x32_bf16 v[44:47], v[180:183], v[188:191], v[44:47]
	v_mfma_f32_16x16x32_bf16 v[28:31], v[180:183], v[198:201], v[28:31]
	v_mfma_f32_16x16x32_bf16 v[36:39], v[172:175], v[198:201], v[36:39]
	v_mfma_f32_16x16x32_bf16 v[20:23], v[172:175], v[206:209], v[20:23]
	v_mfma_f32_16x16x32_bf16 v[12:15], v[180:183], v[206:209], v[12:15]
	v_mfma_f32_16x16x32_bf16 v[0:3], v[180:183], v[214:217], v[0:3]
	v_mfma_f32_16x16x32_bf16 v[4:7], v[172:175], v[214:217], v[4:7]
	v_mfma_f32_16x16x32_bf16 v[52:55], v[176:179], v[192:195], v[52:55]
	v_mfma_f32_16x16x32_bf16 v[44:47], v[184:187], v[192:195], v[44:47]
	v_mfma_f32_16x16x32_bf16 v[28:31], v[184:187], v[202:205], v[28:31]
	v_mfma_f32_16x16x32_bf16 v[36:39], v[176:179], v[202:205], v[36:39]
	v_mfma_f32_16x16x32_bf16 v[20:23], v[176:179], v[210:213], v[20:23]
	v_mfma_f32_16x16x32_bf16 v[12:15], v[184:187], v[210:213], v[12:15]
	v_mfma_f32_16x16x32_bf16 v[0:3], v[184:187], v[218:221], v[0:3]
	v_mfma_f32_16x16x32_bf16 v[4:7], v[176:179], v[218:221], v[4:7]
	s_barrier
	s_add_i32 s69, s69, 2
	s_add_u32 s20, s20, 0x100
	s_addc_u32 s21, s21, 0
	s_add_u32 s67, s67, 0x100
	s_addc_u32 s68, s68, 0
	s_cmp_gt_u32 s69, 13
.LBB0_1446:
	ds_read_b128 v[128:131], v153
	ds_read_b128 v[132:135], v153 offset:1024
	ds_read_b128 v[136:139], v153 offset:2048
	ds_read_b128 v[140:143], v153 offset:3072
	ds_read_b128 v[172:175], v155
	ds_read_b128 v[176:179], v155 offset:1024
	ds_read_b128 v[180:183], v155 offset:2048
	ds_read_b128 v[184:187], v155 offset:3072
	s_add_u32 s38, s20, 0xfffc0080
	s_addc_u32 s39, s21, -1
	s_cmp_eq_u32 s69, 12
	s_cselect_b32 s45, s15, s39
	s_cselect_b32 s44, s65, s38
	s_cselect_b32 s39, s13, s68
	s_cselect_b32 s38, s66, s67
	s_add_i32 m0, s35, 0xc000
	ds_read_b128 v[188:191], v157
	ds_read_b128 v[192:195], v157 offset:1024
	ds_read_b128 v[198:201], v157 offset:2048
	ds_read_b128 v[202:205], v157 offset:3072
	ds_read_b128 v[206:209], v157 offset:4096
	ds_read_b128 v[210:213], v157 offset:5120
	ds_read_b128 v[214:217], v157 offset:6144
	ds_read_b128 v[218:221], v157 offset:7168
	global_load_lds_dwordx4 v162, s[20:21]
	s_add_i32 m0, s35, 0xe000
	s_nop 0
	global_load_lds_dwordx4 v164, s[20:21]
	s_waitcnt vmcnt(8)
	s_waitcnt lgkmcnt(0)
	s_barrier
	v_mfma_f32_16x16x32_bf16 v[124:127], v[128:131], v[188:191], v[124:127]
	v_mfma_f32_16x16x32_bf16 v[120:123], v[136:139], v[188:191], v[120:123]
	v_mfma_f32_16x16x32_bf16 v[104:107], v[136:139], v[198:201], v[104:107]
	v_mfma_f32_16x16x32_bf16 v[108:111], v[128:131], v[198:201], v[108:111]
	v_mfma_f32_16x16x32_bf16 v[96:99], v[128:131], v[206:209], v[96:99]
	v_mfma_f32_16x16x32_bf16 v[88:91], v[136:139], v[206:209], v[88:91]
	v_mfma_f32_16x16x32_bf16 v[72:75], v[136:139], v[214:217], v[72:75]
	v_mfma_f32_16x16x32_bf16 v[80:83], v[128:131], v[214:217], v[80:83]
	v_mfma_f32_16x16x32_bf16 v[124:127], v[132:135], v[192:195], v[124:127]
	v_mfma_f32_16x16x32_bf16 v[120:123], v[140:143], v[192:195], v[120:123]
	v_mfma_f32_16x16x32_bf16 v[104:107], v[140:143], v[202:205], v[104:107]
	v_mfma_f32_16x16x32_bf16 v[108:111], v[132:135], v[202:205], v[108:111]
	v_mfma_f32_16x16x32_bf16 v[96:99], v[132:135], v[210:213], v[96:99]
	v_mfma_f32_16x16x32_bf16 v[88:91], v[140:143], v[210:213], v[88:91]
	v_mfma_f32_16x16x32_bf16 v[72:75], v[140:143], v[218:221], v[72:75]
	v_mfma_f32_16x16x32_bf16 v[80:83], v[132:135], v[218:221], v[80:83]
	v_mfma_f32_16x16x32_bf16 v[116:119], v[172:175], v[188:191], v[116:119]
	v_mfma_f32_16x16x32_bf16 v[112:115], v[180:183], v[188:191], v[112:115]
	v_mfma_f32_16x16x32_bf16 v[92:95], v[180:183], v[198:201], v[92:95]
	v_mfma_f32_16x16x32_bf16 v[100:103], v[172:175], v[198:201], v[100:103]
	v_mfma_f32_16x16x32_bf16 v[84:87], v[172:175], v[206:209], v[84:87]
	v_mfma_f32_16x16x32_bf16 v[76:79], v[180:183], v[206:209], v[76:79]
	v_mfma_f32_16x16x32_bf16 v[64:67], v[180:183], v[214:217], v[64:67]
	v_mfma_f32_16x16x32_bf16 v[68:71], v[172:175], v[214:217], v[68:71]
	v_mfma_f32_16x16x32_bf16 v[116:119], v[176:179], v[192:195], v[116:119]
	v_mfma_f32_16x16x32_bf16 v[112:115], v[184:187], v[192:195], v[112:115]
	v_mfma_f32_16x16x32_bf16 v[92:95], v[184:187], v[202:205], v[92:95]
	v_mfma_f32_16x16x32_bf16 v[100:103], v[176:179], v[202:205], v[100:103]
	v_mfma_f32_16x16x32_bf16 v[84:87], v[176:179], v[210:213], v[84:87]
	v_mfma_f32_16x16x32_bf16 v[76:79], v[184:187], v[210:213], v[76:79]
	v_mfma_f32_16x16x32_bf16 v[64:67], v[184:187], v[218:221], v[64:67]
	v_mfma_f32_16x16x32_bf16 v[68:71], v[176:179], v[218:221], v[68:71]
	s_barrier
; #define PG8_STAGE(bufoff, gbase, voff) do { _Pragma("unroll") for (int _i = 0; _i < 2; ++_i) \
;         __builtin_amdgcn_global_load_lds((const unsigned*)((const char*)(gbase) + (voff)[_i]), (PG8_LAS unsigned*)(lds + (bufoff) + ldsw + _i * 8192), 16, 0, 0); } while (0)
; #define PG8_LDA(dst, b, h) do { _Pragma("unroll") for (int m = 0; m < 4; ++m) _Pragma("unroll") for (int k = 0; k < 2; ++k) dst[m][k] = *(const PG8_LAS bf16x8*)(lds + PG8_SA(b, h) + aoff + m * 2048 + k * 1024); } while (0)
; #define PG8_LDB(dst, b, h) do { _Pragma("unroll") for (int n = 0; n < 2; ++n) _Pragma("unroll") for (int k = 0; k < 2; ++k) dst[n][k] = *(const PG8_LAS bf16x8*)(lds + PG8_SB(b, h) + boff + n * 2048 + k * 1024); } while (0)
; #define PG8_MMA(ai, bj, At, Bt) do { __builtin_amdgcn_s_setprio(1); _Pragma("unroll") for (int m = 0; m < 4; ++m) _Pragma("unroll") for (int n = 0; n < 2; ++n) _Pragma("unroll") for (int k = 0; k < 2; ++k) \
;         acc[ai][bj][m][n] = __builtin_amdgcn_mfma_f32_16x16x32_bf16(Bt[n][k], At[m][k], acc[ai][bj][m][n], 0, 0, 0); __builtin_amdgcn_s_setprio(0); } while (0)
; #define PG8_WAIT_V(n) asm volatile("s_waitcnt vmcnt(" #n ")" ::: "memory")
; #define PG8_WAIT_L(n) asm volatile("s_waitcnt lgkmcnt(" #n ")" ::: "memory")
; #define PG8_BAR __builtin_amdgcn_s_barrier()
; #define PG8_SCHED __builtin_amdgcn_sched_barrier(0)
; template <class Epi, class Sched, bool ALIGN_EPI = false, bool SP2 = false>
; __device__ __forceinline__ void gemm_phase(PG8_LAS unsigned char* lds, const Gemm g, const Sched& S, const Epi& E) {
;     ...
;             PG8_LDA(At, 0, 1); PG8_STAGE(PG8_SB(0, 0), b2, voffB); PG8_STAGE(PG8_SB(0, 1), b2 + hstep, voffB); PG8_STAGE(PG8_SA(0, 0), a2, voffA);
;             PG8_WAIT_V(8); PG8_WAIT_L(0); PG8_BAR; PG8_MMA(1, 0, At, B0); PG8_MMA(1, 1, At, B1); PG8_BAR; PG8_SCHED;
;             PG8_LDB(B0, 1, 0); PG8_LDB(B1, 1, 1); PG8_SCHED; PG8_LDA(At, 1, 0); PG8_STAGE(PG8_SA(0, 1), a2 + hstep, voffA);
	s_add_i32 s70, s60, s51
	s_add_u32 s98, s38, s6
	s_addc_u32 s99, s39, s7
	s_add_u32 s100, s44, s6
	s_addc_u32 s101, s45, s7
	s_mov_b32 m0, s70
	ds_read_b128 v[188:191], v157 offset:16384
	ds_read_b128 v[192:195], v157 offset:17408
	ds_read_b128 v[198:201], v157 offset:18432
	ds_read_b128 v[202:205], v157 offset:19456
	ds_read_b128 v[206:209], v157 offset:20480
	ds_read_b128 v[210:213], v157 offset:21504
	ds_read_b128 v[214:217], v157 offset:22528
	ds_read_b128 v[218:221], v157 offset:23552
	global_load_lds_dwordx4 v146, s[38:39]
	s_add_i32 m0, s70, 0x2000
	s_add_u32 s70, s38, 0x40000
	s_addc_u32 s71, s39, 0
	s_add_i32 s72, s61, s51
	global_load_lds_dwordx4 v150, s[38:39]
	s_mov_b32 m0, s72
	s_nop 0
	global_load_lds_dwordx4 v146, s[70:71]
	s_add_i32 m0, s72, 0x2000
	s_nop 0
	global_load_lds_dwordx4 v150, s[70:71]
	s_mov_b32 m0, s35
	s_nop 0
	global_load_lds_dwordx4 v144, s[44:45]
	s_mov_b32 m0, s52
	s_nop 0
	global_load_lds_dwordx4 v148, s[44:45]
	s_waitcnt vmcnt(8)
	s_waitcnt lgkmcnt(0)
	s_barrier
	v_mfma_f32_16x16x32_bf16 v[60:63], v[128:131], v[188:191], v[60:63]
	v_mfma_f32_16x16x32_bf16 v[56:59], v[136:139], v[188:191], v[56:59]
	v_mfma_f32_16x16x32_bf16 v[40:43], v[136:139], v[198:201], v[40:43]
	v_mfma_f32_16x16x32_bf16 v[48:51], v[128:131], v[198:201], v[48:51]
	v_mfma_f32_16x16x32_bf16 v[32:35], v[128:131], v[206:209], v[32:35]
	v_mfma_f32_16x16x32_bf16 v[24:27], v[136:139], v[206:209], v[24:27]
	v_mfma_f32_16x16x32_bf16 v[8:11], v[136:139], v[214:217], v[8:11]
	v_mfma_f32_16x16x32_bf16 v[16:19], v[128:131], v[214:217], v[16:19]
	v_mfma_f32_16x16x32_bf16 v[60:63], v[132:135], v[192:195], v[60:63]
	v_mfma_f32_16x16x32_bf16 v[56:59], v[140:143], v[192:195], v[56:59]
	v_mfma_f32_16x16x32_bf16 v[40:43], v[140:143], v[202:205], v[40:43]
	v_mfma_f32_16x16x32_bf16 v[48:51], v[132:135], v[202:205], v[48:51]
	v_mfma_f32_16x16x32_bf16 v[32:35], v[132:135], v[210:213], v[32:35]
	v_mfma_f32_16x16x32_bf16 v[24:27], v[140:143], v[210:213], v[24:27]
	v_mfma_f32_16x16x32_bf16 v[8:11], v[140:143], v[218:221], v[8:11]
	v_mfma_f32_16x16x32_bf16 v[16:19], v[132:135], v[218:221], v[16:19]
	v_mfma_f32_16x16x32_bf16 v[52:55], v[172:175], v[188:191], v[52:55]
	v_mfma_f32_16x16x32_bf16 v[44:47], v[180:183], v[188:191], v[44:47]
	v_mfma_f32_16x16x32_bf16 v[28:31], v[180:183], v[198:201], v[28:31]
	v_mfma_f32_16x16x32_bf16 v[36:39], v[172:175], v[198:201], v[36:39]
	v_mfma_f32_16x16x32_bf16 v[20:23], v[172:175], v[206:209], v[20:23]
	v_mfma_f32_16x16x32_bf16 v[12:15], v[180:183], v[206:209], v[12:15]
	v_mfma_f32_16x16x32_bf16 v[0:3], v[180:183], v[214:217], v[0:3]
	v_mfma_f32_16x16x32_bf16 v[4:7], v[172:175], v[214:217], v[4:7]
	v_mfma_f32_16x16x32_bf16 v[52:55], v[176:179], v[192:195], v[52:55]
	v_mfma_f32_16x16x32_bf16 v[44:47], v[184:187], v[192:195], v[44:47]
	v_mfma_f32_16x16x32_bf16 v[28:31], v[184:187], v[202:205], v[28:31]
	v_mfma_f32_16x16x32_bf16 v[36:39], v[176:179], v[202:205], v[36:39]
	v_mfma_f32_16x16x32_bf16 v[20:23], v[176:179], v[210:213], v[20:23]
	v_mfma_f32_16x16x32_bf16 v[12:15], v[184:187], v[210:213], v[12:15]
	v_mfma_f32_16x16x32_bf16 v[0:3], v[184:187], v[218:221], v[0:3]
	v_mfma_f32_16x16x32_bf16 v[4:7], v[176:179], v[218:221], v[4:7]
	s_barrier
	s_add_i32 s70, 0, 0x18000
	s_add_i32 s71, 0, 0x1c000
	v_add_u32_e32 v140, s70, v170
	v_add_u32_e32 v159, s71, v170
	ds_read_b128 v[128:131], v140
	ds_read_b128 v[132:135], v140 offset:1024
	ds_read_b128 v[136:139], v140 offset:2048
	ds_read_b128 v[140:143], v140 offset:3072
	ds_read_b128 v[172:175], v159
	ds_read_b128 v[176:179], v159 offset:1024
	ds_read_b128 v[180:183], v159 offset:2048
	ds_read_b128 v[184:187], v159 offset:3072
	s_add_u32 s44, s44, 0x40000
	s_addc_u32 s45, s45, 0
	s_mov_b32 m0, s53
	ds_read_b128 v[188:191], v157 offset:32768
	ds_read_b128 v[192:195], v157 offset:33792
	ds_read_b128 v[198:201], v157 offset:34816
	ds_read_b128 v[202:205], v157 offset:35840
	ds_read_b128 v[206:209], v157 offset:36864
	ds_read_b128 v[210:213], v157 offset:37888
	ds_read_b128 v[214:217], v157 offset:38912
	ds_read_b128 v[218:221], v157 offset:39936
	global_load_lds_dwordx4 v144, s[44:45]
	s_mov_b32 m0, s54
	s_nop 0
	global_load_lds_dwordx4 v148, s[44:45]
	s_waitcnt vmcnt(8)
	s_waitcnt lgkmcnt(0)
	s_barrier
; #define PG8_STAGE(bufoff, gbase, voff) do { _Pragma("unroll") for (int _i = 0; _i < 2; ++_i) \
;         __builtin_amdgcn_global_load_lds((const unsigned*)((const char*)(gbase) + (voff)[_i]), (PG8_LAS unsigned*)(lds + (bufoff) + ldsw + _i * 8192), 16, 0, 0); } while (0)
; #define PG8_LDA(dst, b, h) do { _Pragma("unroll") for (int m = 0; m < 4; ++m) _Pragma("unroll") for (int k = 0; k < 2; ++k) dst[m][k] = *(const PG8_LAS bf16x8*)(lds + PG8_SA(b, h) + aoff + m * 2048 + k * 1024); } while (0)
; #define PG8_MMA(ai, bj, At, Bt) do { __builtin_amdgcn_s_setprio(1); _Pragma("unroll") for (int m = 0; m < 4; ++m) _Pragma("unroll") for (int n = 0; n < 2; ++n) _Pragma("unroll") for (int k = 0; k < 2; ++k) \
;         acc[ai][bj][m][n] = __builtin_amdgcn_mfma_f32_16x16x32_bf16(Bt[n][k], At[m][k], acc[ai][bj][m][n], 0, 0, 0); __builtin_amdgcn_s_setprio(0); } while (0)
; #define PG8_WAIT_V(n) asm volatile("s_waitcnt vmcnt(" #n ")" ::: "memory")
; #define PG8_WAIT_L(n) asm volatile("s_waitcnt lgkmcnt(" #n ")" ::: "memory")
; #define PG8_BAR __builtin_amdgcn_s_barrier()
; #define PG8_SCHED __builtin_amdgcn_sched_barrier(0)
; template <class Epi, class Sched, bool ALIGN_EPI = false, bool SP2 = false>
; __device__ __forceinline__ void gemm_phase(PG8_LAS unsigned char* lds, const Gemm g, const Sched& S, const Epi& E) {
;     ...
;             PG8_WAIT_V(8); PG8_WAIT_L(0); PG8_BAR; PG8_MMA(0, 0, At, B0); PG8_MMA(0, 1, At, B1); PG8_BAR; PG8_SCHED;
;             PG8_LDA(At, 1, 1); PG8_STAGE(PG8_SB(1, 0), b3, voffB); PG8_STAGE(PG8_SB(1, 1), b3 + hstep, voffB); PG8_STAGE(PG8_SA(1, 0), a3, voffA);
;             PG8_WAIT_V(8); PG8_WAIT_L(0); PG8_BAR; PG8_MMA(1, 0, At, B0); PG8_MMA(1, 1, At, B1); PG8_BAR; PG8_SCHED;
;     ...
;         if constexpr (ALIGN_EPI) { if (wr == 0) PG8_BAR; }
	v_mfma_f32_16x16x32_bf16 v[124:127], v[128:131], v[188:191], v[124:127]
	v_mfma_f32_16x16x32_bf16 v[120:123], v[136:139], v[188:191], v[120:123]
	v_mfma_f32_16x16x32_bf16 v[104:107], v[136:139], v[198:201], v[104:107]
	v_mfma_f32_16x16x32_bf16 v[108:111], v[128:131], v[198:201], v[108:111]
	v_mfma_f32_16x16x32_bf16 v[96:99], v[128:131], v[206:209], v[96:99]
	v_mfma_f32_16x16x32_bf16 v[88:91], v[136:139], v[206:209], v[88:91]
	v_mfma_f32_16x16x32_bf16 v[72:75], v[136:139], v[214:217], v[72:75]
	v_mfma_f32_16x16x32_bf16 v[80:83], v[128:131], v[214:217], v[80:83]
	v_mfma_f32_16x16x32_bf16 v[124:127], v[132:135], v[192:195], v[124:127]
	v_mfma_f32_16x16x32_bf16 v[120:123], v[140:143], v[192:195], v[120:123]
	v_mfma_f32_16x16x32_bf16 v[104:107], v[140:143], v[202:205], v[104:107]
	v_mfma_f32_16x16x32_bf16 v[108:111], v[132:135], v[202:205], v[108:111]
	v_mfma_f32_16x16x32_bf16 v[96:99], v[132:135], v[210:213], v[96:99]
	v_mfma_f32_16x16x32_bf16 v[88:91], v[140:143], v[210:213], v[88:91]
	v_mfma_f32_16x16x32_bf16 v[72:75], v[140:143], v[218:221], v[72:75]
	v_mfma_f32_16x16x32_bf16 v[80:83], v[132:135], v[218:221], v[80:83]
	v_mfma_f32_16x16x32_bf16 v[116:119], v[172:175], v[188:191], v[116:119]
	v_mfma_f32_16x16x32_bf16 v[112:115], v[180:183], v[188:191], v[112:115]
	v_mfma_f32_16x16x32_bf16 v[92:95], v[180:183], v[198:201], v[92:95]
	v_mfma_f32_16x16x32_bf16 v[100:103], v[172:175], v[198:201], v[100:103]
	v_mfma_f32_16x16x32_bf16 v[84:87], v[172:175], v[206:209], v[84:87]
	v_mfma_f32_16x16x32_bf16 v[76:79], v[180:183], v[206:209], v[76:79]
	v_mfma_f32_16x16x32_bf16 v[64:67], v[180:183], v[214:217], v[64:67]
	v_mfma_f32_16x16x32_bf16 v[68:71], v[172:175], v[214:217], v[68:71]
	v_mfma_f32_16x16x32_bf16 v[116:119], v[176:179], v[192:195], v[116:119]
	v_mfma_f32_16x16x32_bf16 v[112:115], v[184:187], v[192:195], v[112:115]
	v_mfma_f32_16x16x32_bf16 v[92:95], v[184:187], v[202:205], v[92:95]
	v_mfma_f32_16x16x32_bf16 v[100:103], v[176:179], v[202:205], v[100:103]
	v_mfma_f32_16x16x32_bf16 v[84:87], v[176:179], v[210:213], v[84:87]
	v_mfma_f32_16x16x32_bf16 v[76:79], v[184:187], v[210:213], v[76:79]
	v_mfma_f32_16x16x32_bf16 v[64:67], v[184:187], v[218:221], v[64:67]
	v_mfma_f32_16x16x32_bf16 v[68:71], v[176:179], v[218:221], v[68:71]
	s_barrier
	s_add_i32 s44, s70, s51
	s_mov_b32 m0, s44
	ds_read_b128 v[188:191], v157 offset:49152
	ds_read_b128 v[192:195], v157 offset:50176
	ds_read_b128 v[198:201], v157 offset:51200
	ds_read_b128 v[202:205], v157 offset:52224
	ds_read_b128 v[206:209], v157 offset:53248
	ds_read_b128 v[210:213], v157 offset:54272
	ds_read_b128 v[214:217], v157 offset:55296
	ds_read_b128 v[218:221], v157 offset:56320
	global_load_lds_dwordx4 v146, s[98:99]
	s_add_i32 m0, s44, 0x2000
	s_add_u32 s38, s38, 0x40080
	s_addc_u32 s39, s39, 0
	s_add_i32 s44, s71, s51
	global_load_lds_dwordx4 v150, s[98:99]
	s_mov_b32 m0, s44
	s_nop 0
	global_load_lds_dwordx4 v146, s[38:39]
	s_add_i32 m0, s44, 0x2000
	s_nop 0
	global_load_lds_dwordx4 v150, s[38:39]
	s_mov_b32 m0, s58
	s_nop 0
	global_load_lds_dwordx4 v144, s[100:101]
	s_mov_b32 m0, s59
	s_nop 0
	global_load_lds_dwordx4 v148, s[100:101]
	s_waitcnt vmcnt(8)
	s_waitcnt lgkmcnt(0)
	s_barrier
	v_mfma_f32_16x16x32_bf16 v[60:63], v[128:131], v[188:191], v[60:63]
	v_mfma_f32_16x16x32_bf16 v[56:59], v[136:139], v[188:191], v[56:59]
	v_mfma_f32_16x16x32_bf16 v[40:43], v[136:139], v[198:201], v[40:43]
	v_mfma_f32_16x16x32_bf16 v[48:51], v[128:131], v[198:201], v[48:51]
	v_mfma_f32_16x16x32_bf16 v[32:35], v[128:131], v[206:209], v[32:35]
	v_mfma_f32_16x16x32_bf16 v[24:27], v[136:139], v[206:209], v[24:27]
	v_mfma_f32_16x16x32_bf16 v[8:11], v[136:139], v[214:217], v[8:11]
	v_mfma_f32_16x16x32_bf16 v[16:19], v[128:131], v[214:217], v[16:19]
	v_mfma_f32_16x16x32_bf16 v[60:63], v[132:135], v[192:195], v[60:63]
	v_mfma_f32_16x16x32_bf16 v[56:59], v[140:143], v[192:195], v[56:59]
	v_mfma_f32_16x16x32_bf16 v[40:43], v[140:143], v[202:205], v[40:43]
	v_mfma_f32_16x16x32_bf16 v[48:51], v[132:135], v[202:205], v[48:51]
	v_mfma_f32_16x16x32_bf16 v[32:35], v[132:135], v[210:213], v[32:35]
	v_mfma_f32_16x16x32_bf16 v[24:27], v[140:143], v[210:213], v[24:27]
	v_mfma_f32_16x16x32_bf16 v[8:11], v[140:143], v[218:221], v[8:11]
	v_mfma_f32_16x16x32_bf16 v[16:19], v[132:135], v[218:221], v[16:19]
	v_mfma_f32_16x16x32_bf16 v[52:55], v[172:175], v[188:191], v[52:55]
	v_mfma_f32_16x16x32_bf16 v[44:47], v[180:183], v[188:191], v[44:47]
	v_mfma_f32_16x16x32_bf16 v[28:31], v[180:183], v[198:201], v[28:31]
	v_mfma_f32_16x16x32_bf16 v[36:39], v[172:175], v[198:201], v[36:39]
	v_mfma_f32_16x16x32_bf16 v[20:23], v[172:175], v[206:209], v[20:23]
	v_mfma_f32_16x16x32_bf16 v[12:15], v[180:183], v[206:209], v[12:15]
	v_mfma_f32_16x16x32_bf16 v[0:3], v[180:183], v[214:217], v[0:3]
	v_mfma_f32_16x16x32_bf16 v[4:7], v[172:175], v[214:217], v[4:7]
	v_mfma_f32_16x16x32_bf16 v[52:55], v[176:179], v[192:195], v[52:55]
	v_mfma_f32_16x16x32_bf16 v[44:47], v[184:187], v[192:195], v[44:47]
	v_mfma_f32_16x16x32_bf16 v[28:31], v[184:187], v[202:205], v[28:31]
	v_mfma_f32_16x16x32_bf16 v[36:39], v[176:179], v[202:205], v[36:39]
	v_mfma_f32_16x16x32_bf16 v[20:23], v[176:179], v[210:213], v[20:23]
	v_mfma_f32_16x16x32_bf16 v[12:15], v[184:187], v[210:213], v[12:15]
	v_mfma_f32_16x16x32_bf16 v[0:3], v[184:187], v[218:221], v[0:3]
	v_mfma_f32_16x16x32_bf16 v[4:7], v[176:179], v[218:221], v[4:7]
	s_barrier
	s_add_i32 s69, s69, 2
	s_add_u32 s20, s20, 0x100
	s_addc_u32 s21, s21, 0
	s_add_u32 s67, s67, 0x100
	s_addc_u32 s68, s68, 0
	s_cmp_gt_u32 s69, 13
	s_cbranch_scc0 .LBB0_1446
	s_and_b64 vcc, exec, s[8:9]
	s_cbranch_vccz .LBB0_1449
	s_barrier

; #define PG8_STAGE(bufoff, gbase, voff) do { _Pragma("unroll") for (int _i = 0; _i < 2; ++_i) \
;         __builtin_amdgcn_global_load_lds((const unsigned*)((const char*)(gbase) + (voff)[_i]), (PG8_LAS unsigned*)(lds + (bufoff) + ldsw + _i * 8192), 16, 0, 0); } while (0)
; #define PG8_LDA(dst, b, h) do { _Pragma("unroll") for (int m = 0; m < 4; ++m) _Pragma("unroll") for (int k = 0; k < 2; ++k) dst[m][k] = *(const PG8_LAS bf16x8*)(lds + PG8_SA(b, h) + aoff + m * 2048 + k * 1024); } while (0)
; #define PG8_LDB(dst, b, h) do { _Pragma("unroll") for (int n = 0; n < 2; ++n) _Pragma("unroll") for (int k = 0; k < 2; ++k) dst[n][k] = *(const PG8_LAS bf16x8*)(lds + PG8_SB(b, h) + boff + n * 2048 + k * 1024); } while (0)
; #define PG8_WAIT_V(n) asm volatile("s_waitcnt vmcnt(" #n ")" ::: "memory")
; #define PG8_WAIT_L(n) asm volatile("s_waitcnt lgkmcnt(" #n ")" ::: "memory")
; #define PG8_BAR __builtin_amdgcn_s_barrier()
; #define PG8_SCHED __builtin_amdgcn_sched_barrier(0)
; template <class Epi, class Sched, bool ALIGN_EPI = false, bool SP2 = false>
; __device__ __forceinline__ void gemm_phase(PG8_LAS unsigned char* lds, const Gemm g, const Sched& S, const Epi& E) {
;     ...
;         const bool has_next = S.next(ui + 1, nxt);
;         const char* nA = has_next ? (const char*)g.A + (size_t)nxt.pm * tstep : cA; const char* nB = has_next ? (const char*)g.Bt + (size_t)nxt.pn * tstep : cB;
;         for (int t = 0; t < nt; t += 2) {
;             const bool last = (t == nt - 2);
;             const char* a1 = cA + (size_t)(t + 1) * kstep;
;             const char* a2 = last ? nA : cA + (size_t)(t + 2) * kstep; const char* b2 = last ? nB : cB + (size_t)(t + 2) * kstep;
;             const char* a3 = a2 + kstep; const char* b3 = b2 + kstep;
;             if (last && has_next) S.a_ready(nxt);
;             if constexpr (SP2) {
;             PG8_LDB(B0, 0, 0); PG8_LDB(B1, 0, 1); PG8_SCHED; PG8_LDA(At, 0, 0); PG8_STAGE(PG8_SA(1, 1), a1 + hstep, voffA);
;             PG8_WAIT_V(8); PG8_WAIT_L(0); PG8_BAR; PG8_MMA(0, 0, At, B0); PG8_MMA(0, 1, At, B1); PG8_BAR; PG8_SCHED;
;             PG8_LDA(At, 0, 1); PG8_STAGE(PG8_SB(0, 0), b2, voffB); PG8_STAGE(PG8_SB(0, 1), b2 + hstep, voffB); PG8_STAGE(PG8_SA(0, 0), a2, voffA);
;             PG8_WAIT_V(8); PG8_WAIT_L(0); PG8_BAR; PG8_MMA(1, 0, At, B0); PG8_MMA(1, 1, At, B1); PG8_BAR; PG8_SCHED;
.LBB0_1634:
	s_ashr_i32 s47, s46, 31
	s_lshl_b64 s[48:49], s[46:47], 19
	s_add_u32 s48, s18, s48
	s_addc_u32 s49, s19, s49
	s_and_b64 s[50:51], s[6:7], exec
	s_cselect_b32 s35, s49, s21
	s_cselect_b32 s47, s48, s20
	s_ashr_i32 s45, s44, 31
	s_lshl_b64 s[50:51], s[44:45], 19
	s_add_u32 s50, s3, s50
	s_addc_u32 s51, s33, s51
	s_and_b64 s[56:57], s[6:7], exec
	s_cselect_b32 s45, s51, s55
	s_cselect_b32 s73, s50, s54
	s_add_u32 s20, s20, 0x40080
	s_addc_u32 s21, s21, 0
	s_add_u32 s74, s54, 0x100
	s_addc_u32 s75, s55, 0
	s_mov_b32 s76, -2
	s_waitcnt lgkmcnt(0)
	ds_read_b128 v[96:99], v223
	ds_read_b128 v[108:111], v223 offset:1024
	ds_read_b128 v[120:123], v223 offset:2048
	ds_read_b128 v[128:131], v223 offset:3072
	ds_read_b128 v[144:147], v224
	ds_read_b128 v[148:151], v224 offset:1024
	ds_read_b128 v[152:155], v224 offset:2048
	ds_read_b128 v[156:159], v224 offset:3072
	s_add_u32 s54, s20, 0xfffc0080
	s_addc_u32 s55, s21, -1
	s_cmp_eq_u32 s76, 12
	s_cselect_b32 s57, s35, s55
	s_cselect_b32 s56, s47, s54
	s_cselect_b32 s55, s45, s75
	s_cselect_b32 s54, s73, s74
	s_add_i32 m0, s53, 0xc000
	ds_read_b128 v[160:163], v225
	ds_read_b128 v[164:167], v225 offset:1024
	ds_read_b128 v[168:171], v225 offset:2048
	ds_read_b128 v[172:175], v225 offset:3072
	ds_read_b128 v[176:179], v225 offset:4096
	ds_read_b128 v[180:183], v225 offset:5120
	ds_read_b128 v[202:205], v225 offset:6144
	ds_read_b128 v[206:209], v225 offset:7168
	global_load_lds_dwordx4 v192, s[20:21]
	s_add_i32 m0, s53, 0xe000
	s_nop 0
	global_load_lds_dwordx4 v194, s[20:21]
	s_waitcnt vmcnt(8)
	s_waitcnt lgkmcnt(0)
	s_barrier
	v_mfma_f32_16x16x32_bf16 v[140:143], v[96:99], v[160:163], 0
	v_mfma_f32_16x16x32_bf16 v[136:139], v[120:123], v[160:163], 0
	v_mfma_f32_16x16x32_bf16 v[112:115], v[120:123], v[168:171], 0
	v_mfma_f32_16x16x32_bf16 v[116:119], v[96:99], v[168:171], 0
	v_mfma_f32_16x16x32_bf16 v[92:95], v[96:99], v[176:179], 0
	v_mfma_f32_16x16x32_bf16 v[88:91], v[120:123], v[176:179], 0
	v_mfma_f32_16x16x32_bf16 v[72:75], v[120:123], v[202:205], 0
	v_mfma_f32_16x16x32_bf16 v[76:79], v[96:99], v[202:205], 0
	v_mfma_f32_16x16x32_bf16 v[140:143], v[108:111], v[164:167], v[140:143]
	v_mfma_f32_16x16x32_bf16 v[136:139], v[128:131], v[164:167], v[136:139]
	v_mfma_f32_16x16x32_bf16 v[112:115], v[128:131], v[172:175], v[112:115]
	v_mfma_f32_16x16x32_bf16 v[116:119], v[108:111], v[172:175], v[116:119]
	v_mfma_f32_16x16x32_bf16 v[92:95], v[108:111], v[180:183], v[92:95]
	v_mfma_f32_16x16x32_bf16 v[88:91], v[128:131], v[180:183], v[88:91]
	v_mfma_f32_16x16x32_bf16 v[72:75], v[128:131], v[206:209], v[72:75]
	v_mfma_f32_16x16x32_bf16 v[76:79], v[108:111], v[206:209], v[76:79]
	v_mfma_f32_16x16x32_bf16 v[132:135], v[144:147], v[160:163], 0
	v_mfma_f32_16x16x32_bf16 v[124:127], v[152:155], v[160:163], 0
	v_mfma_f32_16x16x32_bf16 v[100:103], v[152:155], v[168:171], 0
	v_mfma_f32_16x16x32_bf16 v[104:107], v[144:147], v[168:171], 0
	v_mfma_f32_16x16x32_bf16 v[84:87], v[144:147], v[176:179], 0
	v_mfma_f32_16x16x32_bf16 v[80:83], v[152:155], v[176:179], 0
	v_mfma_f32_16x16x32_bf16 v[64:67], v[152:155], v[202:205], 0
	v_mfma_f32_16x16x32_bf16 v[68:71], v[144:147], v[202:205], 0
	v_mfma_f32_16x16x32_bf16 v[132:135], v[148:151], v[164:167], v[132:135]
	v_mfma_f32_16x16x32_bf16 v[124:127], v[156:159], v[164:167], v[124:127]
	v_mfma_f32_16x16x32_bf16 v[100:103], v[156:159], v[172:175], v[100:103]
	v_mfma_f32_16x16x32_bf16 v[104:107], v[148:151], v[172:175], v[104:107]
	v_mfma_f32_16x16x32_bf16 v[84:87], v[148:151], v[180:183], v[84:87]
	v_mfma_f32_16x16x32_bf16 v[80:83], v[156:159], v[180:183], v[80:83]
	v_mfma_f32_16x16x32_bf16 v[64:67], v[156:159], v[206:209], v[64:67]
	v_mfma_f32_16x16x32_bf16 v[68:71], v[148:151], v[206:209], v[68:71]
	s_barrier
	s_add_i32 s77, s71, s58
	s_add_u32 s98, s54, s12
	s_addc_u32 s99, s55, s13
	s_add_u32 s100, s56, s12
	s_addc_u32 s101, s57, s13
	s_mov_b32 m0, s77
	ds_read_b128 v[160:163], v225 offset:16384
	ds_read_b128 v[164:167], v225 offset:17408
	ds_read_b128 v[168:171], v225 offset:18432
	ds_read_b128 v[172:175], v225 offset:19456
	ds_read_b128 v[176:179], v225 offset:20480
	ds_read_b128 v[180:183], v225 offset:21504
	ds_read_b128 v[202:205], v225 offset:22528
	ds_read_b128 v[206:209], v225 offset:23552
	global_load_lds_dwordx4 v186, s[54:55]
	s_add_i32 m0, s77, 0x2000
	s_add_u32 s78, s54, 0x40000
	s_addc_u32 s79, s55, 0
	s_add_i32 s77, s72, s58
	global_load_lds_dwordx4 v190, s[54:55]
	s_mov_b32 m0, s77
	s_nop 0
	global_load_lds_dwordx4 v186, s[78:79]
	s_add_i32 m0, s77, 0x2000
	s_nop 0
	global_load_lds_dwordx4 v190, s[78:79]
	s_mov_b32 m0, s53
	s_nop 0
	global_load_lds_dwordx4 v184, s[56:57]
	s_mov_b32 m0, s59
	s_nop 0
	global_load_lds_dwordx4 v188, s[56:57]
	s_waitcnt vmcnt(8)
	s_waitcnt lgkmcnt(0)
	s_barrier
; #define PG8_STAGE(bufoff, gbase, voff) do { _Pragma("unroll") for (int _i = 0; _i < 2; ++_i) \
;         __builtin_amdgcn_global_load_lds((const unsigned*)((const char*)(gbase) + (voff)[_i]), (PG8_LAS unsigned*)(lds + (bufoff) + ldsw + _i * 8192), 16, 0, 0); } while (0)
; #define PG8_LDA(dst, b, h) do { _Pragma("unroll") for (int m = 0; m < 4; ++m) _Pragma("unroll") for (int k = 0; k < 2; ++k) dst[m][k] = *(const PG8_LAS bf16x8*)(lds + PG8_SA(b, h) + aoff + m * 2048 + k * 1024); } while (0)
; #define PG8_LDB(dst, b, h) do { _Pragma("unroll") for (int n = 0; n < 2; ++n) _Pragma("unroll") for (int k = 0; k < 2; ++k) dst[n][k] = *(const PG8_LAS bf16x8*)(lds + PG8_SB(b, h) + boff + n * 2048 + k * 1024); } while (0)
; #define PG8_MMA(ai, bj, At, Bt) do { __builtin_amdgcn_s_setprio(1); _Pragma("unroll") for (int m = 0; m < 4; ++m) _Pragma("unroll") for (int n = 0; n < 2; ++n) _Pragma("unroll") for (int k = 0; k < 2; ++k) \
;         acc[ai][bj][m][n] = __builtin_amdgcn_mfma_f32_16x16x32_bf16(Bt[n][k], At[m][k], acc[ai][bj][m][n], 0, 0, 0); __builtin_amdgcn_s_setprio(0); } while (0)
; #define PG8_WAIT_V(n) asm volatile("s_waitcnt vmcnt(" #n ")" ::: "memory")
; #define PG8_WAIT_L(n) asm volatile("s_waitcnt lgkmcnt(" #n ")" ::: "memory")
; #define PG8_BAR __builtin_amdgcn_s_barrier()
; #define PG8_SCHED __builtin_amdgcn_sched_barrier(0)
; template <class Epi, class Sched, bool ALIGN_EPI = false, bool SP2 = false>
; __device__ __forceinline__ void gemm_phase(PG8_LAS unsigned char* lds, const Gemm g, const Sched& S, const Epi& E) {
;     ...
;             PG8_WAIT_V(8); PG8_WAIT_L(0); PG8_BAR; PG8_MMA(1, 0, At, B0); PG8_MMA(1, 1, At, B1); PG8_BAR; PG8_SCHED;
;             PG8_LDB(B0, 1, 0); PG8_LDB(B1, 1, 1); PG8_SCHED; PG8_LDA(At, 1, 0); PG8_STAGE(PG8_SA(0, 1), a2 + hstep, voffA);
;             PG8_WAIT_V(8); PG8_WAIT_L(0); PG8_BAR; PG8_MMA(0, 0, At, B0); PG8_MMA(0, 1, At, B1); PG8_BAR; PG8_SCHED;
	v_mfma_f32_16x16x32_bf16 v[60:63], v[96:99], v[160:163], 0
	v_mfma_f32_16x16x32_bf16 v[56:59], v[120:123], v[160:163], 0
	v_mfma_f32_16x16x32_bf16 v[40:43], v[120:123], v[168:171], 0
	v_mfma_f32_16x16x32_bf16 v[44:47], v[96:99], v[168:171], 0
	v_mfma_f32_16x16x32_bf16 v[28:31], v[96:99], v[176:179], 0
	v_mfma_f32_16x16x32_bf16 v[24:27], v[120:123], v[176:179], 0
	v_mfma_f32_16x16x32_bf16 v[8:11], v[120:123], v[202:205], 0
	v_mfma_f32_16x16x32_bf16 v[12:15], v[96:99], v[202:205], 0
	v_mfma_f32_16x16x32_bf16 v[60:63], v[108:111], v[164:167], v[60:63]
	v_mfma_f32_16x16x32_bf16 v[56:59], v[128:131], v[164:167], v[56:59]
	v_mfma_f32_16x16x32_bf16 v[40:43], v[128:131], v[172:175], v[40:43]
	v_mfma_f32_16x16x32_bf16 v[44:47], v[108:111], v[172:175], v[44:47]
	v_mfma_f32_16x16x32_bf16 v[28:31], v[108:111], v[180:183], v[28:31]
	v_mfma_f32_16x16x32_bf16 v[24:27], v[128:131], v[180:183], v[24:27]
	v_mfma_f32_16x16x32_bf16 v[8:11], v[128:131], v[206:209], v[8:11]
	v_mfma_f32_16x16x32_bf16 v[12:15], v[108:111], v[206:209], v[12:15]
	v_mfma_f32_16x16x32_bf16 v[52:55], v[144:147], v[160:163], 0
	v_mfma_f32_16x16x32_bf16 v[48:51], v[152:155], v[160:163], 0
	v_mfma_f32_16x16x32_bf16 v[32:35], v[152:155], v[168:171], 0
	v_mfma_f32_16x16x32_bf16 v[36:39], v[144:147], v[168:171], 0
	v_mfma_f32_16x16x32_bf16 v[20:23], v[144:147], v[176:179], 0
	v_mfma_f32_16x16x32_bf16 v[16:19], v[152:155], v[176:179], 0
	v_mfma_f32_16x16x32_bf16 v[0:3], v[152:155], v[202:205], 0
	v_mfma_f32_16x16x32_bf16 v[4:7], v[144:147], v[202:205], 0
	v_mfma_f32_16x16x32_bf16 v[52:55], v[148:151], v[164:167], v[52:55]
	v_mfma_f32_16x16x32_bf16 v[48:51], v[156:159], v[164:167], v[48:51]
	v_mfma_f32_16x16x32_bf16 v[32:35], v[156:159], v[172:175], v[32:35]
	v_mfma_f32_16x16x32_bf16 v[36:39], v[148:151], v[172:175], v[36:39]
	v_mfma_f32_16x16x32_bf16 v[20:23], v[148:151], v[180:183], v[20:23]
	v_mfma_f32_16x16x32_bf16 v[16:19], v[156:159], v[180:183], v[16:19]
	v_mfma_f32_16x16x32_bf16 v[0:3], v[156:159], v[206:209], v[0:3]
	v_mfma_f32_16x16x32_bf16 v[4:7], v[148:151], v[206:209], v[4:7]
	s_barrier
	s_add_i32 s77, 0, 0x18000
	s_add_i32 s78, 0, 0x1c000
	v_add_u32_e32 v128, s77, v221
	v_add_u32_e32 v156, s78, v221
	ds_read_b128 v[96:99], v128
	ds_read_b128 v[108:111], v128 offset:1024
	ds_read_b128 v[120:123], v128 offset:2048
	ds_read_b128 v[128:131], v128 offset:3072
	ds_read_b128 v[144:147], v156
	ds_read_b128 v[148:151], v156 offset:1024
	ds_read_b128 v[152:155], v156 offset:2048
	ds_read_b128 v[156:159], v156 offset:3072
	s_add_u32 s56, s56, 0x40000
	s_addc_u32 s57, s57, 0
	s_mov_b32 m0, s60
	ds_read_b128 v[160:163], v225 offset:32768
	ds_read_b128 v[164:167], v225 offset:33792
	ds_read_b128 v[168:171], v225 offset:34816
	ds_read_b128 v[172:175], v225 offset:35840
	ds_read_b128 v[176:179], v225 offset:36864
	ds_read_b128 v[180:183], v225 offset:37888
	ds_read_b128 v[202:205], v225 offset:38912
	ds_read_b128 v[206:209], v225 offset:39936
	global_load_lds_dwordx4 v184, s[56:57]
	s_mov_b32 m0, s61
	s_nop 0
	global_load_lds_dwordx4 v188, s[56:57]
	s_waitcnt vmcnt(8)
	s_waitcnt lgkmcnt(0)
	s_barrier
	v_mfma_f32_16x16x32_bf16 v[140:143], v[96:99], v[160:163], v[140:143]
	v_mfma_f32_16x16x32_bf16 v[136:139], v[120:123], v[160:163], v[136:139]
	v_mfma_f32_16x16x32_bf16 v[112:115], v[120:123], v[168:171], v[112:115]
	v_mfma_f32_16x16x32_bf16 v[116:119], v[96:99], v[168:171], v[116:119]
	v_mfma_f32_16x16x32_bf16 v[92:95], v[96:99], v[176:179], v[92:95]
	v_mfma_f32_16x16x32_bf16 v[88:91], v[120:123], v[176:179], v[88:91]
	v_mfma_f32_16x16x32_bf16 v[72:75], v[120:123], v[202:205], v[72:75]
	v_mfma_f32_16x16x32_bf16 v[76:79], v[96:99], v[202:205], v[76:79]
	v_mfma_f32_16x16x32_bf16 v[140:143], v[108:111], v[164:167], v[140:143]
	v_mfma_f32_16x16x32_bf16 v[136:139], v[128:131], v[164:167], v[136:139]
	v_mfma_f32_16x16x32_bf16 v[112:115], v[128:131], v[172:175], v[112:115]
	v_mfma_f32_16x16x32_bf16 v[116:119], v[108:111], v[172:175], v[116:119]
	v_mfma_f32_16x16x32_bf16 v[92:95], v[108:111], v[180:183], v[92:95]
	v_mfma_f32_16x16x32_bf16 v[88:91], v[128:131], v[180:183], v[88:91]
	v_mfma_f32_16x16x32_bf16 v[72:75], v[128:131], v[206:209], v[72:75]
	v_mfma_f32_16x16x32_bf16 v[76:79], v[108:111], v[206:209], v[76:79]
	v_mfma_f32_16x16x32_bf16 v[132:135], v[144:147], v[160:163], v[132:135]
	v_mfma_f32_16x16x32_bf16 v[124:127], v[152:155], v[160:163], v[124:127]
	v_mfma_f32_16x16x32_bf16 v[100:103], v[152:155], v[168:171], v[100:103]
	v_mfma_f32_16x16x32_bf16 v[104:107], v[144:147], v[168:171], v[104:107]
	v_mfma_f32_16x16x32_bf16 v[84:87], v[144:147], v[176:179], v[84:87]
	v_mfma_f32_16x16x32_bf16 v[80:83], v[152:155], v[176:179], v[80:83]
	v_mfma_f32_16x16x32_bf16 v[64:67], v[152:155], v[202:205], v[64:67]
	v_mfma_f32_16x16x32_bf16 v[68:71], v[144:147], v[202:205], v[68:71]
	v_mfma_f32_16x16x32_bf16 v[132:135], v[148:151], v[164:167], v[132:135]
	v_mfma_f32_16x16x32_bf16 v[124:127], v[156:159], v[164:167], v[124:127]
	v_mfma_f32_16x16x32_bf16 v[100:103], v[156:159], v[172:175], v[100:103]
	v_mfma_f32_16x16x32_bf16 v[104:107], v[148:151], v[172:175], v[104:107]
	v_mfma_f32_16x16x32_bf16 v[84:87], v[148:151], v[180:183], v[84:87]
	v_mfma_f32_16x16x32_bf16 v[80:83], v[156:159], v[180:183], v[80:83]
	v_mfma_f32_16x16x32_bf16 v[64:67], v[156:159], v[206:209], v[64:67]
	v_mfma_f32_16x16x32_bf16 v[68:71], v[148:151], v[206:209], v[68:71]
	s_barrier
; #define PG8_STAGE(bufoff, gbase, voff) do { _Pragma("unroll") for (int _i = 0; _i < 2; ++_i) \
;         __builtin_amdgcn_global_load_lds((const unsigned*)((const char*)(gbase) + (voff)[_i]), (PG8_LAS unsigned*)(lds + (bufoff) + ldsw + _i * 8192), 16, 0, 0); } while (0)
; #define PG8_LDA(dst, b, h) do { _Pragma("unroll") for (int m = 0; m < 4; ++m) _Pragma("unroll") for (int k = 0; k < 2; ++k) dst[m][k] = *(const PG8_LAS bf16x8*)(lds + PG8_SA(b, h) + aoff + m * 2048 + k * 1024); } while (0)
; #define PG8_MMA(ai, bj, At, Bt) do { __builtin_amdgcn_s_setprio(1); _Pragma("unroll") for (int m = 0; m < 4; ++m) _Pragma("unroll") for (int n = 0; n < 2; ++n) _Pragma("unroll") for (int k = 0; k < 2; ++k) \
;         acc[ai][bj][m][n] = __builtin_amdgcn_mfma_f32_16x16x32_bf16(Bt[n][k], At[m][k], acc[ai][bj][m][n], 0, 0, 0); __builtin_amdgcn_s_setprio(0); } while (0)
; #define PG8_WAIT_V(n) asm volatile("s_waitcnt vmcnt(" #n ")" ::: "memory")
; #define PG8_WAIT_L(n) asm volatile("s_waitcnt lgkmcnt(" #n ")" ::: "memory")
; #define PG8_BAR __builtin_amdgcn_s_barrier()
; #define PG8_SCHED __builtin_amdgcn_sched_barrier(0)
; template <class Epi, class Sched, bool ALIGN_EPI = false, bool SP2 = false>
; __device__ __forceinline__ void gemm_phase(PG8_LAS unsigned char* lds, const Gemm g, const Sched& S, const Epi& E) {
;     ...
;             PG8_LDA(At, 1, 1); PG8_STAGE(PG8_SB(1, 0), b3, voffB); PG8_STAGE(PG8_SB(1, 1), b3 + hstep, voffB); PG8_STAGE(PG8_SA(1, 0), a3, voffA);
;             PG8_WAIT_V(8); PG8_WAIT_L(0); PG8_BAR; PG8_MMA(1, 0, At, B0); PG8_MMA(1, 1, At, B1); PG8_BAR; PG8_SCHED;
	s_add_i32 s56, s77, s58
	s_mov_b32 m0, s56
	ds_read_b128 v[160:163], v225 offset:49152
	ds_read_b128 v[164:167], v225 offset:50176
	ds_read_b128 v[168:171], v225 offset:51200
	ds_read_b128 v[172:175], v225 offset:52224
	ds_read_b128 v[176:179], v225 offset:53248
	ds_read_b128 v[180:183], v225 offset:54272
	ds_read_b128 v[202:205], v225 offset:55296
	ds_read_b128 v[206:209], v225 offset:56320
	global_load_lds_dwordx4 v186, s[98:99]
	s_add_i32 m0, s56, 0x2000
	s_add_u32 s54, s54, 0x40080
	s_addc_u32 s55, s55, 0
	s_add_i32 s56, s78, s58
	global_load_lds_dwordx4 v190, s[98:99]
	s_mov_b32 m0, s56
	s_nop 0
	global_load_lds_dwordx4 v186, s[54:55]
	s_add_i32 m0, s56, 0x2000
	s_nop 0
	global_load_lds_dwordx4 v190, s[54:55]
	s_mov_b32 m0, s66
	s_nop 0
	global_load_lds_dwordx4 v184, s[100:101]
	s_mov_b32 m0, s67
	s_nop 0
	global_load_lds_dwordx4 v188, s[100:101]
	s_waitcnt vmcnt(8)
	s_waitcnt lgkmcnt(0)
	s_barrier
	v_mfma_f32_16x16x32_bf16 v[60:63], v[96:99], v[160:163], v[60:63]
	v_mfma_f32_16x16x32_bf16 v[56:59], v[120:123], v[160:163], v[56:59]
	v_mfma_f32_16x16x32_bf16 v[40:43], v[120:123], v[168:171], v[40:43]
	v_mfma_f32_16x16x32_bf16 v[44:47], v[96:99], v[168:171], v[44:47]
	v_mfma_f32_16x16x32_bf16 v[28:31], v[96:99], v[176:179], v[28:31]
	v_mfma_f32_16x16x32_bf16 v[24:27], v[120:123], v[176:179], v[24:27]
	v_mfma_f32_16x16x32_bf16 v[8:11], v[120:123], v[202:205], v[8:11]
	v_mfma_f32_16x16x32_bf16 v[12:15], v[96:99], v[202:205], v[12:15]
	v_mfma_f32_16x16x32_bf16 v[60:63], v[108:111], v[164:167], v[60:63]
	v_mfma_f32_16x16x32_bf16 v[56:59], v[128:131], v[164:167], v[56:59]
	v_mfma_f32_16x16x32_bf16 v[40:43], v[128:131], v[172:175], v[40:43]
	v_mfma_f32_16x16x32_bf16 v[44:47], v[108:111], v[172:175], v[44:47]
	v_mfma_f32_16x16x32_bf16 v[28:31], v[108:111], v[180:183], v[28:31]
	v_mfma_f32_16x16x32_bf16 v[24:27], v[128:131], v[180:183], v[24:27]
	v_mfma_f32_16x16x32_bf16 v[8:11], v[128:131], v[206:209], v[8:11]
	v_mfma_f32_16x16x32_bf16 v[12:15], v[108:111], v[206:209], v[12:15]
	v_mfma_f32_16x16x32_bf16 v[52:55], v[144:147], v[160:163], v[52:55]
	v_mfma_f32_16x16x32_bf16 v[48:51], v[152:155], v[160:163], v[48:51]
	v_mfma_f32_16x16x32_bf16 v[32:35], v[152:155], v[168:171], v[32:35]
	v_mfma_f32_16x16x32_bf16 v[36:39], v[144:147], v[168:171], v[36:39]
	v_mfma_f32_16x16x32_bf16 v[20:23], v[144:147], v[176:179], v[20:23]
	v_mfma_f32_16x16x32_bf16 v[16:19], v[152:155], v[176:179], v[16:19]
	v_mfma_f32_16x16x32_bf16 v[0:3], v[152:155], v[202:205], v[0:3]
	v_mfma_f32_16x16x32_bf16 v[4:7], v[144:147], v[202:205], v[4:7]
	v_mfma_f32_16x16x32_bf16 v[52:55], v[148:151], v[164:167], v[52:55]
	v_mfma_f32_16x16x32_bf16 v[48:51], v[156:159], v[164:167], v[48:51]
	v_mfma_f32_16x16x32_bf16 v[32:35], v[156:159], v[172:175], v[32:35]
	v_mfma_f32_16x16x32_bf16 v[36:39], v[148:151], v[172:175], v[36:39]
	v_mfma_f32_16x16x32_bf16 v[20:23], v[148:151], v[180:183], v[20:23]
	v_mfma_f32_16x16x32_bf16 v[16:19], v[156:159], v[180:183], v[16:19]
	v_mfma_f32_16x16x32_bf16 v[0:3], v[156:159], v[206:209], v[0:3]
	v_mfma_f32_16x16x32_bf16 v[4:7], v[148:151], v[206:209], v[4:7]
	s_barrier
	s_add_i32 s76, s76, 2
	s_add_u32 s20, s20, 0x100
	s_addc_u32 s21, s21, 0
	s_add_u32 s74, s74, 0x100
	s_addc_u32 s75, s75, 0
	s_cmp_gt_u32 s76, 13

; #define PG8_STAGE(bufoff, gbase, voff) do { _Pragma("unroll") for (int _i = 0; _i < 2; ++_i) \
;         __builtin_amdgcn_global_load_lds((const unsigned*)((const char*)(gbase) + (voff)[_i]), (PG8_LAS unsigned*)(lds + (bufoff) + ldsw + _i * 8192), 16, 0, 0); } while (0)
; #define PG8_LDA(dst, b, h) do { _Pragma("unroll") for (int m = 0; m < 4; ++m) _Pragma("unroll") for (int k = 0; k < 2; ++k) dst[m][k] = *(const PG8_LAS bf16x8*)(lds + PG8_SA(b, h) + aoff + m * 2048 + k * 1024); } while (0)
; #define PG8_LDB(dst, b, h) do { _Pragma("unroll") for (int n = 0; n < 2; ++n) _Pragma("unroll") for (int k = 0; k < 2; ++k) dst[n][k] = *(const PG8_LAS bf16x8*)(lds + PG8_SB(b, h) + boff + n * 2048 + k * 1024); } while (0)
; #define PG8_MMA(ai, bj, At, Bt) do { __builtin_amdgcn_s_setprio(1); _Pragma("unroll") for (int m = 0; m < 4; ++m) _Pragma("unroll") for (int n = 0; n < 2; ++n) _Pragma("unroll") for (int k = 0; k < 2; ++k) \
;         acc[ai][bj][m][n] = __builtin_amdgcn_mfma_f32_16x16x32_bf16(Bt[n][k], At[m][k], acc[ai][bj][m][n], 0, 0, 0); __builtin_amdgcn_s_setprio(0); } while (0)
; #define PG8_BAR __builtin_amdgcn_s_barrier()
; template <class Epi, class Sched, bool ALIGN_EPI = false, bool SP2 = false>
; __device__ __forceinline__ void gemm_phase(PG8_LAS unsigned char* lds, const Gemm g, const Sched& S, const Epi& E) {
;     ...
;         const bool has_next = S.next(ui + 1, nxt);
;         const char* nA = has_next ? (const char*)g.A + (size_t)nxt.pm * tstep : cA; const char* nB = has_next ? (const char*)g.Bt + (size_t)nxt.pn * tstep : cB;
;         for (int t = 0; t < nt; t += 2) {
;             const bool last = (t == nt - 2);
;             const char* a1 = cA + (size_t)(t + 1) * kstep;
;             const char* a2 = last ? nA : cA + (size_t)(t + 2) * kstep; const char* b2 = last ? nB : cB + (size_t)(t + 2) * kstep;
;             const char* a3 = a2 + kstep; const char* b3 = b2 + kstep;
;             if (last && has_next) S.a_ready(nxt);
;             if constexpr (SP2) {
;             PG8_LDB(B0, 0, 0); PG8_LDB(B1, 0, 1); PG8_SCHED; PG8_LDA(At, 0, 0); PG8_STAGE(PG8_SA(1, 1), a1 + hstep, voffA);
;             PG8_WAIT_V(8); PG8_WAIT_L(0); PG8_BAR; PG8_MMA(0, 0, At, B0); PG8_MMA(0, 1, At, B1); PG8_BAR; PG8_SCHED;
;             PG8_LDA(At, 0, 1); PG8_STAGE(PG8_SB(0, 0), b2, voffB); PG8_STAGE(PG8_SB(0, 1), b2 + hstep, voffB); PG8_STAGE(PG8_SA(0, 0), a2, voffA);
.LBB0_1739:
	s_ashr_i32 s15, s14, 31
	s_lshl_b64 s[16:17], s[14:15], 19
	s_add_u32 s16, s36, s16
	s_addc_u32 s17, s37, s17
	s_and_b64 s[18:19], s[4:5], exec
	s_cselect_b32 s15, s17, s21
	s_cselect_b32 s63, s16, s20
	s_ashr_i32 s13, s12, 31
	s_lshl_b64 s[18:19], s[12:13], 19
	s_add_u32 s18, s48, s18
	s_addc_u32 s19, s49, s19
	s_and_b64 s[42:43], s[4:5], exec
	s_cselect_b32 s13, s19, s39
	s_cselect_b32 s64, s18, s38
	s_add_u32 s20, s20, 0x40080
	s_addc_u32 s21, s21, 0
	s_add_u32 s65, s38, 0x100
	s_addc_u32 s66, s39, 0
	s_mov_b32 s67, -2
	ds_read_b128 v[154:157], v150
	ds_read_b128 v[158:161], v150 offset:1024
	ds_read_b128 v[162:165], v150 offset:2048
	ds_read_b128 v[166:169], v150 offset:3072
	ds_read_b128 v[170:173], v151
	ds_read_b128 v[174:177], v151 offset:1024
	ds_read_b128 v[178:181], v151 offset:2048
	ds_read_b128 v[182:185], v151 offset:3072
	s_add_u32 s38, s20, 0xfffc0080
	s_addc_u32 s39, s21, -1
	s_cmp_eq_u32 s67, 12
	s_cselect_b32 s43, s15, s39
	s_cselect_b32 s42, s63, s38
	s_cselect_b32 s39, s13, s66
	s_cselect_b32 s38, s64, s65
	s_add_i32 m0, s35, 0xc000
	ds_read_b128 v[186:189], v152
	ds_read_b128 v[190:193], v152 offset:1024
	ds_read_b128 v[198:201], v152 offset:2048
	ds_read_b128 v[202:205], v152 offset:3072
	ds_read_b128 v[206:209], v152 offset:4096
	ds_read_b128 v[210:213], v152 offset:5120
	ds_read_b128 v[214:217], v152 offset:6144
	ds_read_b128 v[218:221], v152 offset:7168
	global_load_lds_dwordx4 v136, s[20:21]
	s_add_i32 m0, s35, 0xe000
	s_nop 0
	global_load_lds_dwordx4 v138, s[20:21]
	s_waitcnt vmcnt(8)
	s_waitcnt lgkmcnt(0)
	s_barrier
	v_mfma_f32_16x16x32_bf16 v[124:127], v[154:157], v[186:189], 0
	v_mfma_f32_16x16x32_bf16 v[116:119], v[162:165], v[186:189], 0
	v_mfma_f32_16x16x32_bf16 v[100:103], v[162:165], v[198:201], 0
	v_mfma_f32_16x16x32_bf16 v[108:111], v[154:157], v[198:201], 0
	v_mfma_f32_16x16x32_bf16 v[92:95], v[154:157], v[206:209], 0
	v_mfma_f32_16x16x32_bf16 v[84:87], v[162:165], v[206:209], 0
	v_mfma_f32_16x16x32_bf16 v[68:71], v[162:165], v[214:217], 0
	v_mfma_f32_16x16x32_bf16 v[76:79], v[154:157], v[214:217], 0
	v_mfma_f32_16x16x32_bf16 v[124:127], v[158:161], v[190:193], v[124:127]
	v_mfma_f32_16x16x32_bf16 v[116:119], v[166:169], v[190:193], v[116:119]
	v_mfma_f32_16x16x32_bf16 v[100:103], v[166:169], v[202:205], v[100:103]
	v_mfma_f32_16x16x32_bf16 v[108:111], v[158:161], v[202:205], v[108:111]
	v_mfma_f32_16x16x32_bf16 v[92:95], v[158:161], v[210:213], v[92:95]
	v_mfma_f32_16x16x32_bf16 v[84:87], v[166:169], v[210:213], v[84:87]
	v_mfma_f32_16x16x32_bf16 v[68:71], v[166:169], v[218:221], v[68:71]
	v_mfma_f32_16x16x32_bf16 v[76:79], v[158:161], v[218:221], v[76:79]
	v_mfma_f32_16x16x32_bf16 v[120:123], v[170:173], v[186:189], 0
	v_mfma_f32_16x16x32_bf16 v[112:115], v[178:181], v[186:189], 0
	v_mfma_f32_16x16x32_bf16 v[96:99], v[178:181], v[198:201], 0
	v_mfma_f32_16x16x32_bf16 v[104:107], v[170:173], v[198:201], 0
	v_mfma_f32_16x16x32_bf16 v[88:91], v[170:173], v[206:209], 0
	v_mfma_f32_16x16x32_bf16 v[80:83], v[178:181], v[206:209], 0
	v_mfma_f32_16x16x32_bf16 v[64:67], v[178:181], v[214:217], 0
	v_mfma_f32_16x16x32_bf16 v[72:75], v[170:173], v[214:217], 0
	v_mfma_f32_16x16x32_bf16 v[120:123], v[174:177], v[190:193], v[120:123]
	v_mfma_f32_16x16x32_bf16 v[112:115], v[182:185], v[190:193], v[112:115]
	v_mfma_f32_16x16x32_bf16 v[96:99], v[182:185], v[202:205], v[96:99]
	v_mfma_f32_16x16x32_bf16 v[104:107], v[174:177], v[202:205], v[104:107]
	v_mfma_f32_16x16x32_bf16 v[88:91], v[174:177], v[210:213], v[88:91]
	v_mfma_f32_16x16x32_bf16 v[80:83], v[182:185], v[210:213], v[80:83]
	v_mfma_f32_16x16x32_bf16 v[64:67], v[182:185], v[218:221], v[64:67]
	v_mfma_f32_16x16x32_bf16 v[72:75], v[174:177], v[218:221], v[72:75]
	s_barrier
	s_add_i32 s68, s58, s50
	s_add_u32 s98, s38, s8
	s_addc_u32 s99, s39, s9
	s_add_u32 s100, s42, s8
	s_addc_u32 s101, s43, s9
	s_mov_b32 m0, s68
	ds_read_b128 v[186:189], v152 offset:16384
	ds_read_b128 v[190:193], v152 offset:17408
	ds_read_b128 v[198:201], v152 offset:18432
	ds_read_b128 v[202:205], v152 offset:19456
	ds_read_b128 v[206:209], v152 offset:20480
	ds_read_b128 v[210:213], v152 offset:21504
	ds_read_b128 v[214:217], v152 offset:22528
	ds_read_b128 v[218:221], v152 offset:23552
	global_load_lds_dwordx4 v132, s[38:39]
	s_add_i32 m0, s68, 0x2000
	s_add_u32 s68, s38, 0x40000
	s_addc_u32 s69, s39, 0
	s_add_i32 s70, s59, s50
	global_load_lds_dwordx4 v128, s[38:39]
	s_mov_b32 m0, s70
	s_nop 0
	global_load_lds_dwordx4 v132, s[68:69]
	s_add_i32 m0, s70, 0x2000
	s_nop 0
	global_load_lds_dwordx4 v128, s[68:69]
	s_mov_b32 m0, s35
	s_nop 0
	global_load_lds_dwordx4 v134, s[42:43]
	s_mov_b32 m0, s52
	s_nop 0
	global_load_lds_dwordx4 v130, s[42:43]
	s_waitcnt vmcnt(8)
	s_waitcnt lgkmcnt(0)
	s_barrier
; #define PG8_STAGE(bufoff, gbase, voff) do { _Pragma("unroll") for (int _i = 0; _i < 2; ++_i) \
;         __builtin_amdgcn_global_load_lds((const unsigned*)((const char*)(gbase) + (voff)[_i]), (PG8_LAS unsigned*)(lds + (bufoff) + ldsw + _i * 8192), 16, 0, 0); } while (0)
; #define PG8_LDA(dst, b, h) do { _Pragma("unroll") for (int m = 0; m < 4; ++m) _Pragma("unroll") for (int k = 0; k < 2; ++k) dst[m][k] = *(const PG8_LAS bf16x8*)(lds + PG8_SA(b, h) + aoff + m * 2048 + k * 1024); } while (0)
; #define PG8_LDB(dst, b, h) do { _Pragma("unroll") for (int n = 0; n < 2; ++n) _Pragma("unroll") for (int k = 0; k < 2; ++k) dst[n][k] = *(const PG8_LAS bf16x8*)(lds + PG8_SB(b, h) + boff + n * 2048 + k * 1024); } while (0)
; #define PG8_MMA(ai, bj, At, Bt) do { __builtin_amdgcn_s_setprio(1); _Pragma("unroll") for (int m = 0; m < 4; ++m) _Pragma("unroll") for (int n = 0; n < 2; ++n) _Pragma("unroll") for (int k = 0; k < 2; ++k) \
;         acc[ai][bj][m][n] = __builtin_amdgcn_mfma_f32_16x16x32_bf16(Bt[n][k], At[m][k], acc[ai][bj][m][n], 0, 0, 0); __builtin_amdgcn_s_setprio(0); } while (0)
; #define PG8_WAIT_V(n) asm volatile("s_waitcnt vmcnt(" #n ")" ::: "memory")
; #define PG8_WAIT_L(n) asm volatile("s_waitcnt lgkmcnt(" #n ")" ::: "memory")
; #define PG8_BAR __builtin_amdgcn_s_barrier()
; #define PG8_SCHED __builtin_amdgcn_sched_barrier(0)
; template <class Epi, class Sched, bool ALIGN_EPI = false, bool SP2 = false>
; __device__ __forceinline__ void gemm_phase(PG8_LAS unsigned char* lds, const Gemm g, const Sched& S, const Epi& E) {
;     ...
;             PG8_WAIT_V(8); PG8_WAIT_L(0); PG8_BAR; PG8_MMA(1, 0, At, B0); PG8_MMA(1, 1, At, B1); PG8_BAR; PG8_SCHED;
;             PG8_LDB(B0, 1, 0); PG8_LDB(B1, 1, 1); PG8_SCHED; PG8_LDA(At, 1, 0); PG8_STAGE(PG8_SA(0, 1), a2 + hstep, voffA);
;             PG8_WAIT_V(8); PG8_WAIT_L(0); PG8_BAR; PG8_MMA(0, 0, At, B0); PG8_MMA(0, 1, At, B1); PG8_BAR; PG8_SCHED;
	v_mfma_f32_16x16x32_bf16 v[60:63], v[154:157], v[186:189], 0
	v_mfma_f32_16x16x32_bf16 v[52:55], v[162:165], v[186:189], 0
	v_mfma_f32_16x16x32_bf16 v[36:39], v[162:165], v[198:201], 0
	v_mfma_f32_16x16x32_bf16 v[44:47], v[154:157], v[198:201], 0
	v_mfma_f32_16x16x32_bf16 v[28:31], v[154:157], v[206:209], 0
	v_mfma_f32_16x16x32_bf16 v[20:23], v[162:165], v[206:209], 0
	v_mfma_f32_16x16x32_bf16 v[4:7], v[162:165], v[214:217], 0
	v_mfma_f32_16x16x32_bf16 v[12:15], v[154:157], v[214:217], 0
	v_mfma_f32_16x16x32_bf16 v[60:63], v[158:161], v[190:193], v[60:63]
	v_mfma_f32_16x16x32_bf16 v[52:55], v[166:169], v[190:193], v[52:55]
	v_mfma_f32_16x16x32_bf16 v[36:39], v[166:169], v[202:205], v[36:39]
	v_mfma_f32_16x16x32_bf16 v[44:47], v[158:161], v[202:205], v[44:47]
	v_mfma_f32_16x16x32_bf16 v[28:31], v[158:161], v[210:213], v[28:31]
	v_mfma_f32_16x16x32_bf16 v[20:23], v[166:169], v[210:213], v[20:23]
	v_mfma_f32_16x16x32_bf16 v[4:7], v[166:169], v[218:221], v[4:7]
	v_mfma_f32_16x16x32_bf16 v[12:15], v[158:161], v[218:221], v[12:15]
	v_mfma_f32_16x16x32_bf16 v[56:59], v[170:173], v[186:189], 0
	v_mfma_f32_16x16x32_bf16 v[48:51], v[178:181], v[186:189], 0
	v_mfma_f32_16x16x32_bf16 v[32:35], v[178:181], v[198:201], 0
	v_mfma_f32_16x16x32_bf16 v[40:43], v[170:173], v[198:201], 0
	v_mfma_f32_16x16x32_bf16 v[24:27], v[170:173], v[206:209], 0
	v_mfma_f32_16x16x32_bf16 v[16:19], v[178:181], v[206:209], 0
	v_mfma_f32_16x16x32_bf16 v[0:3], v[178:181], v[214:217], 0
	v_mfma_f32_16x16x32_bf16 v[8:11], v[170:173], v[214:217], 0
	v_mfma_f32_16x16x32_bf16 v[56:59], v[174:177], v[190:193], v[56:59]
	v_mfma_f32_16x16x32_bf16 v[48:51], v[182:185], v[190:193], v[48:51]
	v_mfma_f32_16x16x32_bf16 v[32:35], v[182:185], v[202:205], v[32:35]
	v_mfma_f32_16x16x32_bf16 v[40:43], v[174:177], v[202:205], v[40:43]
	v_mfma_f32_16x16x32_bf16 v[24:27], v[174:177], v[210:213], v[24:27]
	v_mfma_f32_16x16x32_bf16 v[16:19], v[182:185], v[210:213], v[16:19]
	v_mfma_f32_16x16x32_bf16 v[0:3], v[182:185], v[218:221], v[0:3]
	v_mfma_f32_16x16x32_bf16 v[8:11], v[174:177], v[218:221], v[8:11]
	s_barrier
	s_add_i32 s68, 0, 0x18000
	v_add_u32_e32 v153, s68, v147
	s_add_i32 s69, 0, 0x1c000
	ds_read_b128 v[154:157], v153
	ds_read_b128 v[158:161], v153 offset:1024
	ds_read_b128 v[162:165], v153 offset:2048
	ds_read_b128 v[166:169], v153 offset:3072
	v_add_u32_e32 v153, s69, v147
	ds_read_b128 v[170:173], v153
	ds_read_b128 v[174:177], v153 offset:1024
	ds_read_b128 v[178:181], v153 offset:2048
	ds_read_b128 v[182:185], v153 offset:3072
	s_add_u32 s42, s42, 0x40000
	s_addc_u32 s43, s43, 0
	s_mov_b32 m0, s53
	ds_read_b128 v[186:189], v152 offset:32768
	ds_read_b128 v[190:193], v152 offset:33792
	ds_read_b128 v[198:201], v152 offset:34816
	ds_read_b128 v[202:205], v152 offset:35840
	ds_read_b128 v[206:209], v152 offset:36864
	ds_read_b128 v[210:213], v152 offset:37888
	ds_read_b128 v[214:217], v152 offset:38912
	ds_read_b128 v[218:221], v152 offset:39936
	global_load_lds_dwordx4 v134, s[42:43]
	s_mov_b32 m0, s54
	s_nop 0
	global_load_lds_dwordx4 v130, s[42:43]
	s_waitcnt vmcnt(8)
	s_waitcnt lgkmcnt(0)
	s_barrier
	v_mfma_f32_16x16x32_bf16 v[124:127], v[154:157], v[186:189], v[124:127]
	v_mfma_f32_16x16x32_bf16 v[116:119], v[162:165], v[186:189], v[116:119]
	v_mfma_f32_16x16x32_bf16 v[100:103], v[162:165], v[198:201], v[100:103]
	v_mfma_f32_16x16x32_bf16 v[108:111], v[154:157], v[198:201], v[108:111]
	v_mfma_f32_16x16x32_bf16 v[92:95], v[154:157], v[206:209], v[92:95]
	v_mfma_f32_16x16x32_bf16 v[84:87], v[162:165], v[206:209], v[84:87]
	v_mfma_f32_16x16x32_bf16 v[68:71], v[162:165], v[214:217], v[68:71]
	v_mfma_f32_16x16x32_bf16 v[76:79], v[154:157], v[214:217], v[76:79]
	v_mfma_f32_16x16x32_bf16 v[124:127], v[158:161], v[190:193], v[124:127]
	v_mfma_f32_16x16x32_bf16 v[116:119], v[166:169], v[190:193], v[116:119]
	v_mfma_f32_16x16x32_bf16 v[100:103], v[166:169], v[202:205], v[100:103]
	v_mfma_f32_16x16x32_bf16 v[108:111], v[158:161], v[202:205], v[108:111]
	v_mfma_f32_16x16x32_bf16 v[92:95], v[158:161], v[210:213], v[92:95]
	v_mfma_f32_16x16x32_bf16 v[84:87], v[166:169], v[210:213], v[84:87]
	v_mfma_f32_16x16x32_bf16 v[68:71], v[166:169], v[218:221], v[68:71]
	v_mfma_f32_16x16x32_bf16 v[76:79], v[158:161], v[218:221], v[76:79]
	v_mfma_f32_16x16x32_bf16 v[120:123], v[170:173], v[186:189], v[120:123]
	v_mfma_f32_16x16x32_bf16 v[112:115], v[178:181], v[186:189], v[112:115]
	v_mfma_f32_16x16x32_bf16 v[96:99], v[178:181], v[198:201], v[96:99]
	v_mfma_f32_16x16x32_bf16 v[104:107], v[170:173], v[198:201], v[104:107]
	v_mfma_f32_16x16x32_bf16 v[88:91], v[170:173], v[206:209], v[88:91]
	v_mfma_f32_16x16x32_bf16 v[80:83], v[178:181], v[206:209], v[80:83]
	v_mfma_f32_16x16x32_bf16 v[64:67], v[178:181], v[214:217], v[64:67]
	v_mfma_f32_16x16x32_bf16 v[72:75], v[170:173], v[214:217], v[72:75]
	v_mfma_f32_16x16x32_bf16 v[120:123], v[174:177], v[190:193], v[120:123]
	v_mfma_f32_16x16x32_bf16 v[112:115], v[182:185], v[190:193], v[112:115]
	v_mfma_f32_16x16x32_bf16 v[96:99], v[182:185], v[202:205], v[96:99]
	v_mfma_f32_16x16x32_bf16 v[104:107], v[174:177], v[202:205], v[104:107]
	v_mfma_f32_16x16x32_bf16 v[88:91], v[174:177], v[210:213], v[88:91]
	v_mfma_f32_16x16x32_bf16 v[80:83], v[182:185], v[210:213], v[80:83]
	v_mfma_f32_16x16x32_bf16 v[64:67], v[182:185], v[218:221], v[64:67]
	v_mfma_f32_16x16x32_bf16 v[72:75], v[174:177], v[218:221], v[72:75]
	s_barrier
; #define PG8_STAGE(bufoff, gbase, voff) do { _Pragma("unroll") for (int _i = 0; _i < 2; ++_i) \
;         __builtin_amdgcn_global_load_lds((const unsigned*)((const char*)(gbase) + (voff)[_i]), (PG8_LAS unsigned*)(lds + (bufoff) + ldsw + _i * 8192), 16, 0, 0); } while (0)
; #define PG8_LDA(dst, b, h) do { _Pragma("unroll") for (int m = 0; m < 4; ++m) _Pragma("unroll") for (int k = 0; k < 2; ++k) dst[m][k] = *(const PG8_LAS bf16x8*)(lds + PG8_SA(b, h) + aoff + m * 2048 + k * 1024); } while (0)
; #define PG8_LDB(dst, b, h) do { _Pragma("unroll") for (int n = 0; n < 2; ++n) _Pragma("unroll") for (int k = 0; k < 2; ++k) dst[n][k] = *(const PG8_LAS bf16x8*)(lds + PG8_SB(b, h) + boff + n * 2048 + k * 1024); } while (0)
; #define PG8_MMA(ai, bj, At, Bt) do { __builtin_amdgcn_s_setprio(1); _Pragma("unroll") for (int m = 0; m < 4; ++m) _Pragma("unroll") for (int n = 0; n < 2; ++n) _Pragma("unroll") for (int k = 0; k < 2; ++k) \
;         acc[ai][bj][m][n] = __builtin_amdgcn_mfma_f32_16x16x32_bf16(Bt[n][k], At[m][k], acc[ai][bj][m][n], 0, 0, 0); __builtin_amdgcn_s_setprio(0); } while (0)
; #define PG8_WAIT_V(n) asm volatile("s_waitcnt vmcnt(" #n ")" ::: "memory")
; #define PG8_WAIT_L(n) asm volatile("s_waitcnt lgkmcnt(" #n ")" ::: "memory")
; #define PG8_BAR __builtin_amdgcn_s_barrier()
; #define PG8_SCHED __builtin_amdgcn_sched_barrier(0)
; template <class Epi, class Sched, bool ALIGN_EPI = false, bool SP2 = false>
; __device__ __forceinline__ void gemm_phase(PG8_LAS unsigned char* lds, const Gemm g, const Sched& S, const Epi& E) {
;     ...
;             PG8_LDB(B0, 0, 0); PG8_LDB(B1, 0, 1); PG8_SCHED; PG8_LDA(At, 0, 0); PG8_STAGE(PG8_SA(1, 1), a1 + hstep, voffA);
;             PG8_WAIT_V(8); PG8_WAIT_L(0); PG8_BAR; PG8_MMA(0, 0, At, B0); PG8_MMA(0, 1, At, B1); PG8_BAR; PG8_SCHED;
;     ...
;             PG8_LDA(At, 1, 1); PG8_STAGE(PG8_SB(1, 0), b3, voffB); PG8_STAGE(PG8_SB(1, 1), b3 + hstep, voffB); PG8_STAGE(PG8_SA(1, 0), a3, voffA);
;             PG8_WAIT_V(8); PG8_WAIT_L(0); PG8_BAR; PG8_MMA(1, 0, At, B0); PG8_MMA(1, 1, At, B1); PG8_BAR; PG8_SCHED;
	s_add_i32 s42, s68, s50
	s_mov_b32 m0, s42
	ds_read_b128 v[186:189], v152 offset:49152
	ds_read_b128 v[190:193], v152 offset:50176
	ds_read_b128 v[198:201], v152 offset:51200
	ds_read_b128 v[202:205], v152 offset:52224
	ds_read_b128 v[206:209], v152 offset:53248
	ds_read_b128 v[210:213], v152 offset:54272
	ds_read_b128 v[214:217], v152 offset:55296
	ds_read_b128 v[218:221], v152 offset:56320
	global_load_lds_dwordx4 v132, s[98:99]
	s_add_i32 m0, s42, 0x2000
	s_add_u32 s38, s38, 0x40080
	s_addc_u32 s39, s39, 0
	s_add_i32 s42, s69, s50
	global_load_lds_dwordx4 v128, s[98:99]
	s_mov_b32 m0, s42
	s_nop 0
	global_load_lds_dwordx4 v132, s[38:39]
	s_add_i32 m0, s42, 0x2000
	s_nop 0
	global_load_lds_dwordx4 v128, s[38:39]
	s_mov_b32 m0, s56
	s_nop 0
	global_load_lds_dwordx4 v134, s[100:101]
	s_mov_b32 m0, s57
	s_nop 0
	global_load_lds_dwordx4 v130, s[100:101]
	s_waitcnt vmcnt(8)
	s_waitcnt lgkmcnt(0)
	s_barrier
	v_mfma_f32_16x16x32_bf16 v[60:63], v[154:157], v[186:189], v[60:63]
	v_mfma_f32_16x16x32_bf16 v[52:55], v[162:165], v[186:189], v[52:55]
	v_mfma_f32_16x16x32_bf16 v[36:39], v[162:165], v[198:201], v[36:39]
	v_mfma_f32_16x16x32_bf16 v[44:47], v[154:157], v[198:201], v[44:47]
	v_mfma_f32_16x16x32_bf16 v[28:31], v[154:157], v[206:209], v[28:31]
	v_mfma_f32_16x16x32_bf16 v[20:23], v[162:165], v[206:209], v[20:23]
	v_mfma_f32_16x16x32_bf16 v[4:7], v[162:165], v[214:217], v[4:7]
	v_mfma_f32_16x16x32_bf16 v[12:15], v[154:157], v[214:217], v[12:15]
	v_mfma_f32_16x16x32_bf16 v[60:63], v[158:161], v[190:193], v[60:63]
	v_mfma_f32_16x16x32_bf16 v[52:55], v[166:169], v[190:193], v[52:55]
	v_mfma_f32_16x16x32_bf16 v[36:39], v[166:169], v[202:205], v[36:39]
	v_mfma_f32_16x16x32_bf16 v[44:47], v[158:161], v[202:205], v[44:47]
	v_mfma_f32_16x16x32_bf16 v[28:31], v[158:161], v[210:213], v[28:31]
	v_mfma_f32_16x16x32_bf16 v[20:23], v[166:169], v[210:213], v[20:23]
	v_mfma_f32_16x16x32_bf16 v[4:7], v[166:169], v[218:221], v[4:7]
	v_mfma_f32_16x16x32_bf16 v[12:15], v[158:161], v[218:221], v[12:15]
	v_mfma_f32_16x16x32_bf16 v[56:59], v[170:173], v[186:189], v[56:59]
	v_mfma_f32_16x16x32_bf16 v[48:51], v[178:181], v[186:189], v[48:51]
	v_mfma_f32_16x16x32_bf16 v[32:35], v[178:181], v[198:201], v[32:35]
	v_mfma_f32_16x16x32_bf16 v[40:43], v[170:173], v[198:201], v[40:43]
	v_mfma_f32_16x16x32_bf16 v[24:27], v[170:173], v[206:209], v[24:27]
	v_mfma_f32_16x16x32_bf16 v[16:19], v[178:181], v[206:209], v[16:19]
	v_mfma_f32_16x16x32_bf16 v[0:3], v[178:181], v[214:217], v[0:3]
	v_mfma_f32_16x16x32_bf16 v[8:11], v[170:173], v[214:217], v[8:11]
	v_mfma_f32_16x16x32_bf16 v[56:59], v[174:177], v[190:193], v[56:59]
	v_mfma_f32_16x16x32_bf16 v[48:51], v[182:185], v[190:193], v[48:51]
	v_mfma_f32_16x16x32_bf16 v[32:35], v[182:185], v[202:205], v[32:35]
	v_mfma_f32_16x16x32_bf16 v[40:43], v[174:177], v[202:205], v[40:43]
	v_mfma_f32_16x16x32_bf16 v[24:27], v[174:177], v[210:213], v[24:27]
	v_mfma_f32_16x16x32_bf16 v[16:19], v[182:185], v[210:213], v[16:19]
	v_mfma_f32_16x16x32_bf16 v[0:3], v[182:185], v[218:221], v[0:3]
	v_mfma_f32_16x16x32_bf16 v[8:11], v[174:177], v[218:221], v[8:11]
	s_barrier
	s_add_i32 s67, s67, 2
	s_add_u32 s20, s20, 0x100
	s_addc_u32 s21, s21, 0
	s_add_u32 s65, s65, 0x100
	s_addc_u32 s66, s66, 0
	s_cmp_gt_u32 s67, 13
.LBB0_1740:
	ds_read_b128 v[154:157], v150
	ds_read_b128 v[158:161], v150 offset:1024
	ds_read_b128 v[162:165], v150 offset:2048
	ds_read_b128 v[166:169], v150 offset:3072
	ds_read_b128 v[170:173], v151
	ds_read_b128 v[174:177], v151 offset:1024
	ds_read_b128 v[178:181], v151 offset:2048
	ds_read_b128 v[182:185], v151 offset:3072
	s_add_u32 s38, s20, 0xfffc0080
	s_addc_u32 s39, s21, -1
	s_cmp_eq_u32 s67, 12
	s_cselect_b32 s43, s15, s39
	s_cselect_b32 s42, s63, s38
	s_cselect_b32 s39, s13, s66
	s_cselect_b32 s38, s64, s65
	s_add_i32 m0, s35, 0xc000
	ds_read_b128 v[186:189], v152
	ds_read_b128 v[190:193], v152 offset:1024
	ds_read_b128 v[198:201], v152 offset:2048
	ds_read_b128 v[202:205], v152 offset:3072
	ds_read_b128 v[206:209], v152 offset:4096
	ds_read_b128 v[210:213], v152 offset:5120
	ds_read_b128 v[214:217], v152 offset:6144
	ds_read_b128 v[218:221], v152 offset:7168
	global_load_lds_dwordx4 v136, s[20:21]
	s_add_i32 m0, s35, 0xe000
	s_nop 0
	global_load_lds_dwordx4 v138, s[20:21]
	s_waitcnt vmcnt(8)
	s_waitcnt lgkmcnt(0)
	s_barrier
	v_mfma_f32_16x16x32_bf16 v[124:127], v[154:157], v[186:189], v[124:127]
	v_mfma_f32_16x16x32_bf16 v[116:119], v[162:165], v[186:189], v[116:119]
	v_mfma_f32_16x16x32_bf16 v[100:103], v[162:165], v[198:201], v[100:103]
	v_mfma_f32_16x16x32_bf16 v[108:111], v[154:157], v[198:201], v[108:111]
	v_mfma_f32_16x16x32_bf16 v[92:95], v[154:157], v[206:209], v[92:95]
	v_mfma_f32_16x16x32_bf16 v[84:87], v[162:165], v[206:209], v[84:87]
	v_mfma_f32_16x16x32_bf16 v[68:71], v[162:165], v[214:217], v[68:71]
	v_mfma_f32_16x16x32_bf16 v[76:79], v[154:157], v[214:217], v[76:79]
	v_mfma_f32_16x16x32_bf16 v[124:127], v[158:161], v[190:193], v[124:127]
	v_mfma_f32_16x16x32_bf16 v[116:119], v[166:169], v[190:193], v[116:119]
	v_mfma_f32_16x16x32_bf16 v[100:103], v[166:169], v[202:205], v[100:103]
	v_mfma_f32_16x16x32_bf16 v[108:111], v[158:161], v[202:205], v[108:111]
	v_mfma_f32_16x16x32_bf16 v[92:95], v[158:161], v[210:213], v[92:95]
	v_mfma_f32_16x16x32_bf16 v[84:87], v[166:169], v[210:213], v[84:87]
	v_mfma_f32_16x16x32_bf16 v[68:71], v[166:169], v[218:221], v[68:71]
	v_mfma_f32_16x16x32_bf16 v[76:79], v[158:161], v[218:221], v[76:79]
	v_mfma_f32_16x16x32_bf16 v[120:123], v[170:173], v[186:189], v[120:123]
	v_mfma_f32_16x16x32_bf16 v[112:115], v[178:181], v[186:189], v[112:115]
	v_mfma_f32_16x16x32_bf16 v[96:99], v[178:181], v[198:201], v[96:99]
	v_mfma_f32_16x16x32_bf16 v[104:107], v[170:173], v[198:201], v[104:107]
	v_mfma_f32_16x16x32_bf16 v[88:91], v[170:173], v[206:209], v[88:91]
	v_mfma_f32_16x16x32_bf16 v[80:83], v[178:181], v[206:209], v[80:83]
	v_mfma_f32_16x16x32_bf16 v[64:67], v[178:181], v[214:217], v[64:67]
	v_mfma_f32_16x16x32_bf16 v[72:75], v[170:173], v[214:217], v[72:75]
	v_mfma_f32_16x16x32_bf16 v[120:123], v[174:177], v[190:193], v[120:123]
	v_mfma_f32_16x16x32_bf16 v[112:115], v[182:185], v[190:193], v[112:115]
	v_mfma_f32_16x16x32_bf16 v[96:99], v[182:185], v[202:205], v[96:99]
	v_mfma_f32_16x16x32_bf16 v[104:107], v[174:177], v[202:205], v[104:107]
	v_mfma_f32_16x16x32_bf16 v[88:91], v[174:177], v[210:213], v[88:91]
	v_mfma_f32_16x16x32_bf16 v[80:83], v[182:185], v[210:213], v[80:83]
	v_mfma_f32_16x16x32_bf16 v[64:67], v[182:185], v[218:221], v[64:67]
	v_mfma_f32_16x16x32_bf16 v[72:75], v[174:177], v[218:221], v[72:75]
	s_barrier
; #define PG8_STAGE(bufoff, gbase, voff) do { _Pragma("unroll") for (int _i = 0; _i < 2; ++_i) \
;         __builtin_amdgcn_global_load_lds((const unsigned*)((const char*)(gbase) + (voff)[_i]), (PG8_LAS unsigned*)(lds + (bufoff) + ldsw + _i * 8192), 16, 0, 0); } while (0)
; #define PG8_LDA(dst, b, h) do { _Pragma("unroll") for (int m = 0; m < 4; ++m) _Pragma("unroll") for (int k = 0; k < 2; ++k) dst[m][k] = *(const PG8_LAS bf16x8*)(lds + PG8_SA(b, h) + aoff + m * 2048 + k * 1024); } while (0)
; #define PG8_LDB(dst, b, h) do { _Pragma("unroll") for (int n = 0; n < 2; ++n) _Pragma("unroll") for (int k = 0; k < 2; ++k) dst[n][k] = *(const PG8_LAS bf16x8*)(lds + PG8_SB(b, h) + boff + n * 2048 + k * 1024); } while (0)
; #define PG8_MMA(ai, bj, At, Bt) do { __builtin_amdgcn_s_setprio(1); _Pragma("unroll") for (int m = 0; m < 4; ++m) _Pragma("unroll") for (int n = 0; n < 2; ++n) _Pragma("unroll") for (int k = 0; k < 2; ++k) \
;         acc[ai][bj][m][n] = __builtin_amdgcn_mfma_f32_16x16x32_bf16(Bt[n][k], At[m][k], acc[ai][bj][m][n], 0, 0, 0); __builtin_amdgcn_s_setprio(0); } while (0)
; #define PG8_WAIT_V(n) asm volatile("s_waitcnt vmcnt(" #n ")" ::: "memory")
; #define PG8_WAIT_L(n) asm volatile("s_waitcnt lgkmcnt(" #n ")" ::: "memory")
; #define PG8_BAR __builtin_amdgcn_s_barrier()
; #define PG8_SCHED __builtin_amdgcn_sched_barrier(0)
; template <class Epi, class Sched, bool ALIGN_EPI = false, bool SP2 = false>
; __device__ __forceinline__ void gemm_phase(PG8_LAS unsigned char* lds, const Gemm g, const Sched& S, const Epi& E) {
;     ...
;             PG8_LDA(At, 0, 1); PG8_STAGE(PG8_SB(0, 0), b2, voffB); PG8_STAGE(PG8_SB(0, 1), b2 + hstep, voffB); PG8_STAGE(PG8_SA(0, 0), a2, voffA);
;             PG8_WAIT_V(8); PG8_WAIT_L(0); PG8_BAR; PG8_MMA(1, 0, At, B0); PG8_MMA(1, 1, At, B1); PG8_BAR; PG8_SCHED;
;             PG8_LDB(B0, 1, 0); PG8_LDB(B1, 1, 1); PG8_SCHED; PG8_LDA(At, 1, 0); PG8_STAGE(PG8_SA(0, 1), a2 + hstep, voffA);
	s_add_i32 s68, s58, s50
	s_add_u32 s98, s38, s8
	s_addc_u32 s99, s39, s9
	s_add_u32 s100, s42, s8
	s_addc_u32 s101, s43, s9
	s_mov_b32 m0, s68
	ds_read_b128 v[186:189], v152 offset:16384
	ds_read_b128 v[190:193], v152 offset:17408
	ds_read_b128 v[198:201], v152 offset:18432
	ds_read_b128 v[202:205], v152 offset:19456
	ds_read_b128 v[206:209], v152 offset:20480
	ds_read_b128 v[210:213], v152 offset:21504
	ds_read_b128 v[214:217], v152 offset:22528
	ds_read_b128 v[218:221], v152 offset:23552
	global_load_lds_dwordx4 v132, s[38:39]
	s_add_i32 m0, s68, 0x2000
	s_add_u32 s68, s38, 0x40000
	s_addc_u32 s69, s39, 0
	s_add_i32 s70, s59, s50
	global_load_lds_dwordx4 v128, s[38:39]
	s_mov_b32 m0, s70
	s_nop 0
	global_load_lds_dwordx4 v132, s[68:69]
	s_add_i32 m0, s70, 0x2000
	s_nop 0
	global_load_lds_dwordx4 v128, s[68:69]
	s_mov_b32 m0, s35
	s_nop 0
	global_load_lds_dwordx4 v134, s[42:43]
	s_mov_b32 m0, s52
	s_nop 0
	global_load_lds_dwordx4 v130, s[42:43]
	s_waitcnt vmcnt(8)
	s_waitcnt lgkmcnt(0)
	s_barrier
	v_mfma_f32_16x16x32_bf16 v[60:63], v[154:157], v[186:189], v[60:63]
	v_mfma_f32_16x16x32_bf16 v[52:55], v[162:165], v[186:189], v[52:55]
	v_mfma_f32_16x16x32_bf16 v[36:39], v[162:165], v[198:201], v[36:39]
	v_mfma_f32_16x16x32_bf16 v[44:47], v[154:157], v[198:201], v[44:47]
	v_mfma_f32_16x16x32_bf16 v[28:31], v[154:157], v[206:209], v[28:31]
	v_mfma_f32_16x16x32_bf16 v[20:23], v[162:165], v[206:209], v[20:23]
	v_mfma_f32_16x16x32_bf16 v[4:7], v[162:165], v[214:217], v[4:7]
	v_mfma_f32_16x16x32_bf16 v[12:15], v[154:157], v[214:217], v[12:15]
	v_mfma_f32_16x16x32_bf16 v[60:63], v[158:161], v[190:193], v[60:63]
	v_mfma_f32_16x16x32_bf16 v[52:55], v[166:169], v[190:193], v[52:55]
	v_mfma_f32_16x16x32_bf16 v[36:39], v[166:169], v[202:205], v[36:39]
	v_mfma_f32_16x16x32_bf16 v[44:47], v[158:161], v[202:205], v[44:47]
	v_mfma_f32_16x16x32_bf16 v[28:31], v[158:161], v[210:213], v[28:31]
	v_mfma_f32_16x16x32_bf16 v[20:23], v[166:169], v[210:213], v[20:23]
	v_mfma_f32_16x16x32_bf16 v[4:7], v[166:169], v[218:221], v[4:7]
	v_mfma_f32_16x16x32_bf16 v[12:15], v[158:161], v[218:221], v[12:15]
	v_mfma_f32_16x16x32_bf16 v[56:59], v[170:173], v[186:189], v[56:59]
	v_mfma_f32_16x16x32_bf16 v[48:51], v[178:181], v[186:189], v[48:51]
	v_mfma_f32_16x16x32_bf16 v[32:35], v[178:181], v[198:201], v[32:35]
	v_mfma_f32_16x16x32_bf16 v[40:43], v[170:173], v[198:201], v[40:43]
	v_mfma_f32_16x16x32_bf16 v[24:27], v[170:173], v[206:209], v[24:27]
	v_mfma_f32_16x16x32_bf16 v[16:19], v[178:181], v[206:209], v[16:19]
	v_mfma_f32_16x16x32_bf16 v[0:3], v[178:181], v[214:217], v[0:3]
	v_mfma_f32_16x16x32_bf16 v[8:11], v[170:173], v[214:217], v[8:11]
	v_mfma_f32_16x16x32_bf16 v[56:59], v[174:177], v[190:193], v[56:59]
	v_mfma_f32_16x16x32_bf16 v[48:51], v[182:185], v[190:193], v[48:51]
	v_mfma_f32_16x16x32_bf16 v[32:35], v[182:185], v[202:205], v[32:35]
	v_mfma_f32_16x16x32_bf16 v[40:43], v[174:177], v[202:205], v[40:43]
	v_mfma_f32_16x16x32_bf16 v[24:27], v[174:177], v[210:213], v[24:27]
	v_mfma_f32_16x16x32_bf16 v[16:19], v[182:185], v[210:213], v[16:19]
	v_mfma_f32_16x16x32_bf16 v[0:3], v[182:185], v[218:221], v[0:3]
	v_mfma_f32_16x16x32_bf16 v[8:11], v[174:177], v[218:221], v[8:11]
	s_barrier
	s_add_i32 s68, 0, 0x18000
	v_add_u32_e32 v153, s68, v147
	s_add_i32 s69, 0, 0x1c000
	ds_read_b128 v[154:157], v153
	ds_read_b128 v[158:161], v153 offset:1024
	ds_read_b128 v[162:165], v153 offset:2048
	ds_read_b128 v[166:169], v153 offset:3072
	v_add_u32_e32 v153, s69, v147
	ds_read_b128 v[170:173], v153
	ds_read_b128 v[174:177], v153 offset:1024
	ds_read_b128 v[178:181], v153 offset:2048
	ds_read_b128 v[182:185], v153 offset:3072
	s_add_u32 s42, s42, 0x40000
	s_addc_u32 s43, s43, 0
	s_mov_b32 m0, s53
	ds_read_b128 v[186:189], v152 offset:32768
	ds_read_b128 v[190:193], v152 offset:33792
	ds_read_b128 v[198:201], v152 offset:34816
	ds_read_b128 v[202:205], v152 offset:35840
	ds_read_b128 v[206:209], v152 offset:36864
	ds_read_b128 v[210:213], v152 offset:37888
	ds_read_b128 v[214:217], v152 offset:38912
	ds_read_b128 v[218:221], v152 offset:39936
	global_load_lds_dwordx4 v134, s[42:43]
	s_mov_b32 m0, s54
	s_nop 0
	global_load_lds_dwordx4 v130, s[42:43]
	s_waitcnt vmcnt(8)
	s_waitcnt lgkmcnt(0)
	s_barrier
; #define PG8_STAGE(bufoff, gbase, voff) do { _Pragma("unroll") for (int _i = 0; _i < 2; ++_i) \
;         __builtin_amdgcn_global_load_lds((const unsigned*)((const char*)(gbase) + (voff)[_i]), (PG8_LAS unsigned*)(lds + (bufoff) + ldsw + _i * 8192), 16, 0, 0); } while (0)
; #define PG8_LDA(dst, b, h) do { _Pragma("unroll") for (int m = 0; m < 4; ++m) _Pragma("unroll") for (int k = 0; k < 2; ++k) dst[m][k] = *(const PG8_LAS bf16x8*)(lds + PG8_SA(b, h) + aoff + m * 2048 + k * 1024); } while (0)
; #define PG8_MMA(ai, bj, At, Bt) do { __builtin_amdgcn_s_setprio(1); _Pragma("unroll") for (int m = 0; m < 4; ++m) _Pragma("unroll") for (int n = 0; n < 2; ++n) _Pragma("unroll") for (int k = 0; k < 2; ++k) \
;         acc[ai][bj][m][n] = __builtin_amdgcn_mfma_f32_16x16x32_bf16(Bt[n][k], At[m][k], acc[ai][bj][m][n], 0, 0, 0); __builtin_amdgcn_s_setprio(0); } while (0)
; #define PG8_WAIT_V(n) asm volatile("s_waitcnt vmcnt(" #n ")" ::: "memory")
; #define PG8_WAIT_L(n) asm volatile("s_waitcnt lgkmcnt(" #n ")" ::: "memory")
; #define PG8_BAR __builtin_amdgcn_s_barrier()
; #define PG8_SCHED __builtin_amdgcn_sched_barrier(0)
; template <class Epi, class Sched, bool ALIGN_EPI = false, bool SP2 = false>
; __device__ __forceinline__ void gemm_phase(PG8_LAS unsigned char* lds, const Gemm g, const Sched& S, const Epi& E) {
;     ...
;             PG8_WAIT_V(8); PG8_WAIT_L(0); PG8_BAR; PG8_MMA(0, 0, At, B0); PG8_MMA(0, 1, At, B1); PG8_BAR; PG8_SCHED;
;             PG8_LDA(At, 1, 1); PG8_STAGE(PG8_SB(1, 0), b3, voffB); PG8_STAGE(PG8_SB(1, 1), b3 + hstep, voffB); PG8_STAGE(PG8_SA(1, 0), a3, voffA);
;             PG8_WAIT_V(8); PG8_WAIT_L(0); PG8_BAR; PG8_MMA(1, 0, At, B0); PG8_MMA(1, 1, At, B1); PG8_BAR; PG8_SCHED;
;     ...
;         if constexpr (ALIGN_EPI) { if (wr == 0) PG8_BAR; }
	v_mfma_f32_16x16x32_bf16 v[124:127], v[154:157], v[186:189], v[124:127]
	v_mfma_f32_16x16x32_bf16 v[116:119], v[162:165], v[186:189], v[116:119]
	v_mfma_f32_16x16x32_bf16 v[100:103], v[162:165], v[198:201], v[100:103]
	v_mfma_f32_16x16x32_bf16 v[108:111], v[154:157], v[198:201], v[108:111]
	v_mfma_f32_16x16x32_bf16 v[92:95], v[154:157], v[206:209], v[92:95]
	v_mfma_f32_16x16x32_bf16 v[84:87], v[162:165], v[206:209], v[84:87]
	v_mfma_f32_16x16x32_bf16 v[68:71], v[162:165], v[214:217], v[68:71]
	v_mfma_f32_16x16x32_bf16 v[76:79], v[154:157], v[214:217], v[76:79]
	v_mfma_f32_16x16x32_bf16 v[124:127], v[158:161], v[190:193], v[124:127]
	v_mfma_f32_16x16x32_bf16 v[116:119], v[166:169], v[190:193], v[116:119]
	v_mfma_f32_16x16x32_bf16 v[100:103], v[166:169], v[202:205], v[100:103]
	v_mfma_f32_16x16x32_bf16 v[108:111], v[158:161], v[202:205], v[108:111]
	v_mfma_f32_16x16x32_bf16 v[92:95], v[158:161], v[210:213], v[92:95]
	v_mfma_f32_16x16x32_bf16 v[84:87], v[166:169], v[210:213], v[84:87]
	v_mfma_f32_16x16x32_bf16 v[68:71], v[166:169], v[218:221], v[68:71]
	v_mfma_f32_16x16x32_bf16 v[76:79], v[158:161], v[218:221], v[76:79]
	v_mfma_f32_16x16x32_bf16 v[120:123], v[170:173], v[186:189], v[120:123]
	v_mfma_f32_16x16x32_bf16 v[112:115], v[178:181], v[186:189], v[112:115]
	v_mfma_f32_16x16x32_bf16 v[96:99], v[178:181], v[198:201], v[96:99]
	v_mfma_f32_16x16x32_bf16 v[104:107], v[170:173], v[198:201], v[104:107]
	v_mfma_f32_16x16x32_bf16 v[88:91], v[170:173], v[206:209], v[88:91]
	v_mfma_f32_16x16x32_bf16 v[80:83], v[178:181], v[206:209], v[80:83]
	v_mfma_f32_16x16x32_bf16 v[64:67], v[178:181], v[214:217], v[64:67]
	v_mfma_f32_16x16x32_bf16 v[72:75], v[170:173], v[214:217], v[72:75]
	v_mfma_f32_16x16x32_bf16 v[120:123], v[174:177], v[190:193], v[120:123]
	v_mfma_f32_16x16x32_bf16 v[112:115], v[182:185], v[190:193], v[112:115]
	v_mfma_f32_16x16x32_bf16 v[96:99], v[182:185], v[202:205], v[96:99]
	v_mfma_f32_16x16x32_bf16 v[104:107], v[174:177], v[202:205], v[104:107]
	v_mfma_f32_16x16x32_bf16 v[88:91], v[174:177], v[210:213], v[88:91]
	v_mfma_f32_16x16x32_bf16 v[80:83], v[182:185], v[210:213], v[80:83]
	v_mfma_f32_16x16x32_bf16 v[64:67], v[182:185], v[218:221], v[64:67]
	v_mfma_f32_16x16x32_bf16 v[72:75], v[174:177], v[218:221], v[72:75]
	s_barrier
	s_add_i32 s42, s68, s50
	s_mov_b32 m0, s42
	ds_read_b128 v[186:189], v152 offset:49152
	ds_read_b128 v[190:193], v152 offset:50176
	ds_read_b128 v[198:201], v152 offset:51200
	ds_read_b128 v[202:205], v152 offset:52224
	ds_read_b128 v[206:209], v152 offset:53248
	ds_read_b128 v[210:213], v152 offset:54272
	ds_read_b128 v[214:217], v152 offset:55296
	ds_read_b128 v[218:221], v152 offset:56320
	global_load_lds_dwordx4 v132, s[98:99]
	s_add_i32 m0, s42, 0x2000
	s_add_u32 s38, s38, 0x40080
	s_addc_u32 s39, s39, 0
	s_add_i32 s42, s69, s50
	global_load_lds_dwordx4 v128, s[98:99]
	s_mov_b32 m0, s42
	s_nop 0
	global_load_lds_dwordx4 v132, s[38:39]
	s_add_i32 m0, s42, 0x2000
	s_nop 0
	global_load_lds_dwordx4 v128, s[38:39]
	s_mov_b32 m0, s56
	s_nop 0
	global_load_lds_dwordx4 v134, s[100:101]
	s_mov_b32 m0, s57
	s_nop 0
	global_load_lds_dwordx4 v130, s[100:101]
	s_waitcnt vmcnt(8)
	s_waitcnt lgkmcnt(0)
	s_barrier
	v_mfma_f32_16x16x32_bf16 v[60:63], v[154:157], v[186:189], v[60:63]
	v_mfma_f32_16x16x32_bf16 v[52:55], v[162:165], v[186:189], v[52:55]
	v_mfma_f32_16x16x32_bf16 v[36:39], v[162:165], v[198:201], v[36:39]
	v_mfma_f32_16x16x32_bf16 v[44:47], v[154:157], v[198:201], v[44:47]
	v_mfma_f32_16x16x32_bf16 v[28:31], v[154:157], v[206:209], v[28:31]
	v_mfma_f32_16x16x32_bf16 v[20:23], v[162:165], v[206:209], v[20:23]
	v_mfma_f32_16x16x32_bf16 v[4:7], v[162:165], v[214:217], v[4:7]
	v_mfma_f32_16x16x32_bf16 v[12:15], v[154:157], v[214:217], v[12:15]
	v_mfma_f32_16x16x32_bf16 v[60:63], v[158:161], v[190:193], v[60:63]
	v_mfma_f32_16x16x32_bf16 v[52:55], v[166:169], v[190:193], v[52:55]
	v_mfma_f32_16x16x32_bf16 v[36:39], v[166:169], v[202:205], v[36:39]
	v_mfma_f32_16x16x32_bf16 v[44:47], v[158:161], v[202:205], v[44:47]
	v_mfma_f32_16x16x32_bf16 v[28:31], v[158:161], v[210:213], v[28:31]
	v_mfma_f32_16x16x32_bf16 v[20:23], v[166:169], v[210:213], v[20:23]
	v_mfma_f32_16x16x32_bf16 v[4:7], v[166:169], v[218:221], v[4:7]
	v_mfma_f32_16x16x32_bf16 v[12:15], v[158:161], v[218:221], v[12:15]
	v_mfma_f32_16x16x32_bf16 v[56:59], v[170:173], v[186:189], v[56:59]
	v_mfma_f32_16x16x32_bf16 v[48:51], v[178:181], v[186:189], v[48:51]
	v_mfma_f32_16x16x32_bf16 v[32:35], v[178:181], v[198:201], v[32:35]
	v_mfma_f32_16x16x32_bf16 v[40:43], v[170:173], v[198:201], v[40:43]
	v_mfma_f32_16x16x32_bf16 v[24:27], v[170:173], v[206:209], v[24:27]
	v_mfma_f32_16x16x32_bf16 v[16:19], v[178:181], v[206:209], v[16:19]
	v_mfma_f32_16x16x32_bf16 v[0:3], v[178:181], v[214:217], v[0:3]
	v_mfma_f32_16x16x32_bf16 v[8:11], v[170:173], v[214:217], v[8:11]
	v_mfma_f32_16x16x32_bf16 v[56:59], v[174:177], v[190:193], v[56:59]
	v_mfma_f32_16x16x32_bf16 v[48:51], v[182:185], v[190:193], v[48:51]
	v_mfma_f32_16x16x32_bf16 v[32:35], v[182:185], v[202:205], v[32:35]
	v_mfma_f32_16x16x32_bf16 v[40:43], v[174:177], v[202:205], v[40:43]
	v_mfma_f32_16x16x32_bf16 v[24:27], v[174:177], v[210:213], v[24:27]
	v_mfma_f32_16x16x32_bf16 v[16:19], v[182:185], v[210:213], v[16:19]
	v_mfma_f32_16x16x32_bf16 v[0:3], v[182:185], v[218:221], v[0:3]
	v_mfma_f32_16x16x32_bf16 v[8:11], v[174:177], v[218:221], v[8:11]
	s_barrier
	s_add_i32 s67, s67, 2
	s_add_u32 s20, s20, 0x100
	s_addc_u32 s21, s21, 0
	s_add_u32 s65, s65, 0x100
	s_addc_u32 s66, s66, 0
	s_cmp_gt_u32 s67, 13
	s_cbranch_scc0 .LBB0_1740
	v_readlane_b32 s101, v249, 49
	s_nop 3
	s_cmp_eq_u32 s101, 0
	s_cbranch_scc1 .Ldw_done_3
	s_add_u32 s98, s28, 0x183500
	s_addc_u32 s99, s29, 0
	v_mov_b32_e32 v251, 0
	s_mov_b32 s100, 0

; #define PG8_STAGE(bufoff, gbase, voff) do { _Pragma("unroll") for (int _i = 0; _i < 2; ++_i) \
;         __builtin_amdgcn_global_load_lds((const unsigned*)((const char*)(gbase) + (voff)[_i]), (PG8_LAS unsigned*)(lds + (bufoff) + ldsw + _i * 8192), 16, 0, 0); } while (0)
; #define PG8_LDA(dst, b, h) do { _Pragma("unroll") for (int m = 0; m < 4; ++m) _Pragma("unroll") for (int k = 0; k < 2; ++k) dst[m][k] = *(const PG8_LAS bf16x8*)(lds + PG8_SA(b, h) + aoff + m * 2048 + k * 1024); } while (0)
; #define PG8_LDB(dst, b, h) do { _Pragma("unroll") for (int n = 0; n < 2; ++n) _Pragma("unroll") for (int k = 0; k < 2; ++k) dst[n][k] = *(const PG8_LAS bf16x8*)(lds + PG8_SB(b, h) + boff + n * 2048 + k * 1024); } while (0)
; #define PG8_MMA(ai, bj, At, Bt) do { __builtin_amdgcn_s_setprio(1); _Pragma("unroll") for (int m = 0; m < 4; ++m) _Pragma("unroll") for (int n = 0; n < 2; ++n) _Pragma("unroll") for (int k = 0; k < 2; ++k) \
;         acc[ai][bj][m][n] = __builtin_amdgcn_mfma_f32_16x16x32_bf16(Bt[n][k], At[m][k], acc[ai][bj][m][n], 0, 0, 0); __builtin_amdgcn_s_setprio(0); } while (0)
; #define PG8_WAIT_V(n) asm volatile("s_waitcnt vmcnt(" #n ")" ::: "memory")
; #define PG8_WAIT_L(n) asm volatile("s_waitcnt lgkmcnt(" #n ")" ::: "memory")
; #define PG8_BAR __builtin_amdgcn_s_barrier()
; #define PG8_SCHED __builtin_amdgcn_sched_barrier(0)
; template <class Epi, class Sched, bool ALIGN_EPI = false, bool SP2 = false>
; __device__ __forceinline__ void gemm_phase(PG8_LAS unsigned char* lds, const Gemm g, const Sched& S, const Epi& E) {
;     ...
;             PG8_LDB(B0, 0, 0); PG8_LDB(B1, 0, 1); PG8_SCHED; PG8_LDA(At, 0, 0); PG8_STAGE(PG8_SA(1, 1), a1 + hstep, voffA);
;             PG8_WAIT_V(8); PG8_WAIT_L(0); PG8_BAR; PG8_MMA(0, 0, At, B0); PG8_MMA(0, 1, At, B1); PG8_BAR; PG8_SCHED;
;             PG8_LDA(At, 0, 1); PG8_STAGE(PG8_SB(0, 0), b2, voffB); PG8_STAGE(PG8_SB(0, 1), b2 + hstep, voffB); PG8_STAGE(PG8_SA(0, 0), a2, voffA);
;             PG8_WAIT_V(8); PG8_WAIT_L(0); PG8_BAR; PG8_MMA(1, 0, At, B0); PG8_MMA(1, 1, At, B1); PG8_BAR; PG8_SCHED;
.LBB0_1824:
	s_add_u32 s20, s20, 0xb0080
	s_addc_u32 s21, s21, 0
	s_add_u32 s68, s34, 0x100
	s_addc_u32 s69, s35, 0
	s_mov_b32 s70, -2
	s_waitcnt lgkmcnt(0)
	ds_read_b128 v[96:99], v222
	ds_read_b128 v[108:111], v222 offset:1024
	ds_read_b128 v[120:123], v222 offset:2048
	ds_read_b128 v[128:131], v222 offset:3072
	ds_read_b128 v[144:147], v223
	ds_read_b128 v[148:151], v223 offset:1024
	ds_read_b128 v[152:155], v223 offset:2048
	ds_read_b128 v[156:159], v223 offset:3072
	s_add_u32 s34, s20, 0xfff50080
	s_addc_u32 s35, s21, -1
	s_cmp_eq_u32 s70, 40
	s_cselect_b32 s47, s1, s35
	s_cselect_b32 s46, s0, s34
	s_cselect_b32 s35, s45, s69
	s_cselect_b32 s34, s44, s68
	s_add_i32 m0, s49, 0xc000
	ds_read_b128 v[160:163], v224
	ds_read_b128 v[164:167], v224 offset:1024
	ds_read_b128 v[168:171], v224 offset:2048
	ds_read_b128 v[172:175], v224 offset:3072
	ds_read_b128 v[176:179], v224 offset:4096
	ds_read_b128 v[180:183], v224 offset:5120
	ds_read_b128 v[202:205], v224 offset:6144
	ds_read_b128 v[206:209], v224 offset:7168
	global_load_lds_dwordx4 v192, s[20:21]
	s_add_i32 m0, s49, 0xe000
	s_nop 0
	global_load_lds_dwordx4 v194, s[20:21]
	s_waitcnt vmcnt(8)
	s_waitcnt lgkmcnt(0)
	s_barrier
	v_mfma_f32_16x16x32_bf16 v[140:143], v[96:99], v[160:163], 0
	v_mfma_f32_16x16x32_bf16 v[136:139], v[120:123], v[160:163], 0
	v_mfma_f32_16x16x32_bf16 v[112:115], v[120:123], v[168:171], 0
	v_mfma_f32_16x16x32_bf16 v[116:119], v[96:99], v[168:171], 0
	v_mfma_f32_16x16x32_bf16 v[92:95], v[96:99], v[176:179], 0
	v_mfma_f32_16x16x32_bf16 v[88:91], v[120:123], v[176:179], 0
	v_mfma_f32_16x16x32_bf16 v[72:75], v[120:123], v[202:205], 0
	v_mfma_f32_16x16x32_bf16 v[76:79], v[96:99], v[202:205], 0
	v_mfma_f32_16x16x32_bf16 v[140:143], v[108:111], v[164:167], v[140:143]
	v_mfma_f32_16x16x32_bf16 v[136:139], v[128:131], v[164:167], v[136:139]
	v_mfma_f32_16x16x32_bf16 v[112:115], v[128:131], v[172:175], v[112:115]
	v_mfma_f32_16x16x32_bf16 v[116:119], v[108:111], v[172:175], v[116:119]
	v_mfma_f32_16x16x32_bf16 v[92:95], v[108:111], v[180:183], v[92:95]
	v_mfma_f32_16x16x32_bf16 v[88:91], v[128:131], v[180:183], v[88:91]
	v_mfma_f32_16x16x32_bf16 v[72:75], v[128:131], v[206:209], v[72:75]
	v_mfma_f32_16x16x32_bf16 v[76:79], v[108:111], v[206:209], v[76:79]
	v_mfma_f32_16x16x32_bf16 v[132:135], v[144:147], v[160:163], 0
	v_mfma_f32_16x16x32_bf16 v[124:127], v[152:155], v[160:163], 0
	v_mfma_f32_16x16x32_bf16 v[100:103], v[152:155], v[168:171], 0
	v_mfma_f32_16x16x32_bf16 v[104:107], v[144:147], v[168:171], 0
	v_mfma_f32_16x16x32_bf16 v[84:87], v[144:147], v[176:179], 0
	v_mfma_f32_16x16x32_bf16 v[80:83], v[152:155], v[176:179], 0
	v_mfma_f32_16x16x32_bf16 v[64:67], v[152:155], v[202:205], 0
	v_mfma_f32_16x16x32_bf16 v[68:71], v[144:147], v[202:205], 0
	v_mfma_f32_16x16x32_bf16 v[132:135], v[148:151], v[164:167], v[132:135]
	v_mfma_f32_16x16x32_bf16 v[124:127], v[156:159], v[164:167], v[124:127]
	v_mfma_f32_16x16x32_bf16 v[100:103], v[156:159], v[172:175], v[100:103]
	v_mfma_f32_16x16x32_bf16 v[104:107], v[148:151], v[172:175], v[104:107]
	v_mfma_f32_16x16x32_bf16 v[84:87], v[148:151], v[180:183], v[84:87]
	v_mfma_f32_16x16x32_bf16 v[80:83], v[156:159], v[180:183], v[80:83]
	v_mfma_f32_16x16x32_bf16 v[64:67], v[156:159], v[206:209], v[64:67]
	v_mfma_f32_16x16x32_bf16 v[68:71], v[148:151], v[206:209], v[68:71]
	s_barrier
	s_add_i32 s71, s62, s48
	s_add_u32 s98, s34, s12
	s_addc_u32 s99, s35, s13
	s_add_u32 s100, s46, s12
	s_addc_u32 s101, s47, s13
	s_mov_b32 m0, s71
	ds_read_b128 v[160:163], v224 offset:16384
	ds_read_b128 v[164:167], v224 offset:17408
	ds_read_b128 v[168:171], v224 offset:18432
	ds_read_b128 v[172:175], v224 offset:19456
	ds_read_b128 v[176:179], v224 offset:20480
	ds_read_b128 v[180:183], v224 offset:21504
	ds_read_b128 v[202:205], v224 offset:22528
	ds_read_b128 v[206:209], v224 offset:23552
	global_load_lds_dwordx4 v186, s[34:35]
	s_add_i32 m0, s71, 0x2000
	s_add_u32 s72, s34, 0xb0000
	s_addc_u32 s73, s35, 0
	s_add_i32 s71, s63, s48
	global_load_lds_dwordx4 v190, s[34:35]
	s_mov_b32 m0, s71
	s_nop 0
	global_load_lds_dwordx4 v186, s[72:73]
	s_add_i32 m0, s71, 0x2000
	s_nop 0
	global_load_lds_dwordx4 v190, s[72:73]
	s_mov_b32 m0, s49
	s_nop 0
	global_load_lds_dwordx4 v184, s[46:47]
	s_mov_b32 m0, s50
	s_nop 0
	global_load_lds_dwordx4 v188, s[46:47]
	s_waitcnt vmcnt(8)
	s_waitcnt lgkmcnt(0)
	s_barrier
	v_mfma_f32_16x16x32_bf16 v[60:63], v[96:99], v[160:163], 0
	v_mfma_f32_16x16x32_bf16 v[56:59], v[120:123], v[160:163], 0
	v_mfma_f32_16x16x32_bf16 v[40:43], v[120:123], v[168:171], 0
	v_mfma_f32_16x16x32_bf16 v[44:47], v[96:99], v[168:171], 0
	v_mfma_f32_16x16x32_bf16 v[28:31], v[96:99], v[176:179], 0
	v_mfma_f32_16x16x32_bf16 v[24:27], v[120:123], v[176:179], 0
	v_mfma_f32_16x16x32_bf16 v[8:11], v[120:123], v[202:205], 0
	v_mfma_f32_16x16x32_bf16 v[12:15], v[96:99], v[202:205], 0
	v_mfma_f32_16x16x32_bf16 v[60:63], v[108:111], v[164:167], v[60:63]
	v_mfma_f32_16x16x32_bf16 v[56:59], v[128:131], v[164:167], v[56:59]
	v_mfma_f32_16x16x32_bf16 v[40:43], v[128:131], v[172:175], v[40:43]
	v_mfma_f32_16x16x32_bf16 v[44:47], v[108:111], v[172:175], v[44:47]
	v_mfma_f32_16x16x32_bf16 v[28:31], v[108:111], v[180:183], v[28:31]
	v_mfma_f32_16x16x32_bf16 v[24:27], v[128:131], v[180:183], v[24:27]
	v_mfma_f32_16x16x32_bf16 v[8:11], v[128:131], v[206:209], v[8:11]
	v_mfma_f32_16x16x32_bf16 v[12:15], v[108:111], v[206:209], v[12:15]
	v_mfma_f32_16x16x32_bf16 v[52:55], v[144:147], v[160:163], 0
	v_mfma_f32_16x16x32_bf16 v[48:51], v[152:155], v[160:163], 0
	v_mfma_f32_16x16x32_bf16 v[32:35], v[152:155], v[168:171], 0
	v_mfma_f32_16x16x32_bf16 v[36:39], v[144:147], v[168:171], 0
	v_mfma_f32_16x16x32_bf16 v[20:23], v[144:147], v[176:179], 0
	v_mfma_f32_16x16x32_bf16 v[16:19], v[152:155], v[176:179], 0
	v_mfma_f32_16x16x32_bf16 v[0:3], v[152:155], v[202:205], 0
	v_mfma_f32_16x16x32_bf16 v[4:7], v[144:147], v[202:205], 0
	v_mfma_f32_16x16x32_bf16 v[52:55], v[148:151], v[164:167], v[52:55]
	v_mfma_f32_16x16x32_bf16 v[48:51], v[156:159], v[164:167], v[48:51]
	v_mfma_f32_16x16x32_bf16 v[32:35], v[156:159], v[172:175], v[32:35]
	v_mfma_f32_16x16x32_bf16 v[36:39], v[148:151], v[172:175], v[36:39]
	v_mfma_f32_16x16x32_bf16 v[20:23], v[148:151], v[180:183], v[20:23]
	v_mfma_f32_16x16x32_bf16 v[16:19], v[156:159], v[180:183], v[16:19]
	v_mfma_f32_16x16x32_bf16 v[0:3], v[156:159], v[206:209], v[0:3]
	v_mfma_f32_16x16x32_bf16 v[4:7], v[148:151], v[206:209], v[4:7]
	s_barrier
; #define PG8_STAGE(bufoff, gbase, voff) do { _Pragma("unroll") for (int _i = 0; _i < 2; ++_i) \
;         __builtin_amdgcn_global_load_lds((const unsigned*)((const char*)(gbase) + (voff)[_i]), (PG8_LAS unsigned*)(lds + (bufoff) + ldsw + _i * 8192), 16, 0, 0); } while (0)
; #define PG8_LDA(dst, b, h) do { _Pragma("unroll") for (int m = 0; m < 4; ++m) _Pragma("unroll") for (int k = 0; k < 2; ++k) dst[m][k] = *(const PG8_LAS bf16x8*)(lds + PG8_SA(b, h) + aoff + m * 2048 + k * 1024); } while (0)
; #define PG8_LDB(dst, b, h) do { _Pragma("unroll") for (int n = 0; n < 2; ++n) _Pragma("unroll") for (int k = 0; k < 2; ++k) dst[n][k] = *(const PG8_LAS bf16x8*)(lds + PG8_SB(b, h) + boff + n * 2048 + k * 1024); } while (0)
; #define PG8_MMA(ai, bj, At, Bt) do { __builtin_amdgcn_s_setprio(1); _Pragma("unroll") for (int m = 0; m < 4; ++m) _Pragma("unroll") for (int n = 0; n < 2; ++n) _Pragma("unroll") for (int k = 0; k < 2; ++k) \
;         acc[ai][bj][m][n] = __builtin_amdgcn_mfma_f32_16x16x32_bf16(Bt[n][k], At[m][k], acc[ai][bj][m][n], 0, 0, 0); __builtin_amdgcn_s_setprio(0); } while (0)
; #define PG8_WAIT_V(n) asm volatile("s_waitcnt vmcnt(" #n ")" ::: "memory")
; #define PG8_WAIT_L(n) asm volatile("s_waitcnt lgkmcnt(" #n ")" ::: "memory")
; #define PG8_BAR __builtin_amdgcn_s_barrier()
; #define PG8_SCHED __builtin_amdgcn_sched_barrier(0)
; template <class Epi, class Sched, bool ALIGN_EPI = false, bool SP2 = false>
; __device__ __forceinline__ void gemm_phase(PG8_LAS unsigned char* lds, const Gemm g, const Sched& S, const Epi& E) {
;     ...
;             PG8_LDB(B0, 1, 0); PG8_LDB(B1, 1, 1); PG8_SCHED; PG8_LDA(At, 1, 0); PG8_STAGE(PG8_SA(0, 1), a2 + hstep, voffA);
;             PG8_WAIT_V(8); PG8_WAIT_L(0); PG8_BAR; PG8_MMA(0, 0, At, B0); PG8_MMA(0, 1, At, B1); PG8_BAR; PG8_SCHED;
;             PG8_LDA(At, 1, 1); PG8_STAGE(PG8_SB(1, 0), b3, voffB); PG8_STAGE(PG8_SB(1, 1), b3 + hstep, voffB); PG8_STAGE(PG8_SA(1, 0), a3, voffA);
;             PG8_WAIT_V(8); PG8_WAIT_L(0); PG8_BAR; PG8_MMA(1, 0, At, B0); PG8_MMA(1, 1, At, B1); PG8_BAR; PG8_SCHED;
	s_add_i32 s71, 0, 0x18000
	s_add_i32 s72, 0, 0x1c000
	v_add_u32_e32 v128, s71, v197
	v_add_u32_e32 v156, s72, v197
	ds_read_b128 v[96:99], v128
	ds_read_b128 v[108:111], v128 offset:1024
	ds_read_b128 v[120:123], v128 offset:2048
	ds_read_b128 v[128:131], v128 offset:3072
	ds_read_b128 v[144:147], v156
	ds_read_b128 v[148:151], v156 offset:1024
	ds_read_b128 v[152:155], v156 offset:2048
	ds_read_b128 v[156:159], v156 offset:3072
	s_add_u32 s46, s46, 0xb0000
	s_addc_u32 s47, s47, 0
	s_mov_b32 m0, s51
	ds_read_b128 v[160:163], v224 offset:32768
	ds_read_b128 v[164:167], v224 offset:33792
	ds_read_b128 v[168:171], v224 offset:34816
	ds_read_b128 v[172:175], v224 offset:35840
	ds_read_b128 v[176:179], v224 offset:36864
	ds_read_b128 v[180:183], v224 offset:37888
	ds_read_b128 v[202:205], v224 offset:38912
	ds_read_b128 v[206:209], v224 offset:39936
	global_load_lds_dwordx4 v184, s[46:47]
	s_mov_b32 m0, s52
	s_nop 0
	global_load_lds_dwordx4 v188, s[46:47]
	s_waitcnt vmcnt(8)
	s_waitcnt lgkmcnt(0)
	s_barrier
	v_mfma_f32_16x16x32_bf16 v[140:143], v[96:99], v[160:163], v[140:143]
	v_mfma_f32_16x16x32_bf16 v[136:139], v[120:123], v[160:163], v[136:139]
	v_mfma_f32_16x16x32_bf16 v[112:115], v[120:123], v[168:171], v[112:115]
	v_mfma_f32_16x16x32_bf16 v[116:119], v[96:99], v[168:171], v[116:119]
	v_mfma_f32_16x16x32_bf16 v[92:95], v[96:99], v[176:179], v[92:95]
	v_mfma_f32_16x16x32_bf16 v[88:91], v[120:123], v[176:179], v[88:91]
	v_mfma_f32_16x16x32_bf16 v[72:75], v[120:123], v[202:205], v[72:75]
	v_mfma_f32_16x16x32_bf16 v[76:79], v[96:99], v[202:205], v[76:79]
	v_mfma_f32_16x16x32_bf16 v[140:143], v[108:111], v[164:167], v[140:143]
	v_mfma_f32_16x16x32_bf16 v[136:139], v[128:131], v[164:167], v[136:139]
	v_mfma_f32_16x16x32_bf16 v[112:115], v[128:131], v[172:175], v[112:115]
	v_mfma_f32_16x16x32_bf16 v[116:119], v[108:111], v[172:175], v[116:119]
	v_mfma_f32_16x16x32_bf16 v[92:95], v[108:111], v[180:183], v[92:95]
	v_mfma_f32_16x16x32_bf16 v[88:91], v[128:131], v[180:183], v[88:91]
	v_mfma_f32_16x16x32_bf16 v[72:75], v[128:131], v[206:209], v[72:75]
	v_mfma_f32_16x16x32_bf16 v[76:79], v[108:111], v[206:209], v[76:79]
	v_mfma_f32_16x16x32_bf16 v[132:135], v[144:147], v[160:163], v[132:135]
	v_mfma_f32_16x16x32_bf16 v[124:127], v[152:155], v[160:163], v[124:127]
	v_mfma_f32_16x16x32_bf16 v[100:103], v[152:155], v[168:171], v[100:103]
	v_mfma_f32_16x16x32_bf16 v[104:107], v[144:147], v[168:171], v[104:107]
	v_mfma_f32_16x16x32_bf16 v[84:87], v[144:147], v[176:179], v[84:87]
	v_mfma_f32_16x16x32_bf16 v[80:83], v[152:155], v[176:179], v[80:83]
	v_mfma_f32_16x16x32_bf16 v[64:67], v[152:155], v[202:205], v[64:67]
	v_mfma_f32_16x16x32_bf16 v[68:71], v[144:147], v[202:205], v[68:71]
	v_mfma_f32_16x16x32_bf16 v[132:135], v[148:151], v[164:167], v[132:135]
	v_mfma_f32_16x16x32_bf16 v[124:127], v[156:159], v[164:167], v[124:127]
	v_mfma_f32_16x16x32_bf16 v[100:103], v[156:159], v[172:175], v[100:103]
	v_mfma_f32_16x16x32_bf16 v[104:107], v[148:151], v[172:175], v[104:107]
	v_mfma_f32_16x16x32_bf16 v[84:87], v[148:151], v[180:183], v[84:87]
	v_mfma_f32_16x16x32_bf16 v[80:83], v[156:159], v[180:183], v[80:83]
	v_mfma_f32_16x16x32_bf16 v[64:67], v[156:159], v[206:209], v[64:67]
	v_mfma_f32_16x16x32_bf16 v[68:71], v[148:151], v[206:209], v[68:71]
	s_barrier
	s_add_i32 s46, s71, s48
	s_mov_b32 m0, s46
	ds_read_b128 v[160:163], v224 offset:49152
	ds_read_b128 v[164:167], v224 offset:50176
	ds_read_b128 v[168:171], v224 offset:51200
	ds_read_b128 v[172:175], v224 offset:52224
	ds_read_b128 v[176:179], v224 offset:53248
	ds_read_b128 v[180:183], v224 offset:54272
	ds_read_b128 v[202:205], v224 offset:55296
	ds_read_b128 v[206:209], v224 offset:56320
	global_load_lds_dwordx4 v186, s[98:99]
	s_add_i32 m0, s46, 0x2000
	s_add_u32 s34, s34, 0xb0080
	s_addc_u32 s35, s35, 0
	s_add_i32 s46, s72, s48
	global_load_lds_dwordx4 v190, s[98:99]
	s_mov_b32 m0, s46
	s_nop 0
	global_load_lds_dwordx4 v186, s[34:35]
	s_add_i32 m0, s46, 0x2000
	s_nop 0
	global_load_lds_dwordx4 v190, s[34:35]
	s_mov_b32 m0, s57
	s_nop 0
	global_load_lds_dwordx4 v184, s[100:101]
	s_mov_b32 m0, s58
	s_nop 0
	global_load_lds_dwordx4 v188, s[100:101]
	s_waitcnt vmcnt(8)
	s_waitcnt lgkmcnt(0)
	s_barrier
	v_mfma_f32_16x16x32_bf16 v[60:63], v[96:99], v[160:163], v[60:63]
	v_mfma_f32_16x16x32_bf16 v[56:59], v[120:123], v[160:163], v[56:59]
	v_mfma_f32_16x16x32_bf16 v[40:43], v[120:123], v[168:171], v[40:43]
	v_mfma_f32_16x16x32_bf16 v[44:47], v[96:99], v[168:171], v[44:47]
	v_mfma_f32_16x16x32_bf16 v[28:31], v[96:99], v[176:179], v[28:31]
	v_mfma_f32_16x16x32_bf16 v[24:27], v[120:123], v[176:179], v[24:27]
	v_mfma_f32_16x16x32_bf16 v[8:11], v[120:123], v[202:205], v[8:11]
	v_mfma_f32_16x16x32_bf16 v[12:15], v[96:99], v[202:205], v[12:15]
	v_mfma_f32_16x16x32_bf16 v[60:63], v[108:111], v[164:167], v[60:63]
	v_mfma_f32_16x16x32_bf16 v[56:59], v[128:131], v[164:167], v[56:59]
	v_mfma_f32_16x16x32_bf16 v[40:43], v[128:131], v[172:175], v[40:43]
	v_mfma_f32_16x16x32_bf16 v[44:47], v[108:111], v[172:175], v[44:47]
	v_mfma_f32_16x16x32_bf16 v[28:31], v[108:111], v[180:183], v[28:31]
	v_mfma_f32_16x16x32_bf16 v[24:27], v[128:131], v[180:183], v[24:27]
	v_mfma_f32_16x16x32_bf16 v[8:11], v[128:131], v[206:209], v[8:11]
	v_mfma_f32_16x16x32_bf16 v[12:15], v[108:111], v[206:209], v[12:15]
	v_mfma_f32_16x16x32_bf16 v[52:55], v[144:147], v[160:163], v[52:55]
	v_mfma_f32_16x16x32_bf16 v[48:51], v[152:155], v[160:163], v[48:51]
	v_mfma_f32_16x16x32_bf16 v[32:35], v[152:155], v[168:171], v[32:35]
	v_mfma_f32_16x16x32_bf16 v[36:39], v[144:147], v[168:171], v[36:39]
	v_mfma_f32_16x16x32_bf16 v[20:23], v[144:147], v[176:179], v[20:23]
	v_mfma_f32_16x16x32_bf16 v[16:19], v[152:155], v[176:179], v[16:19]
	v_mfma_f32_16x16x32_bf16 v[0:3], v[152:155], v[202:205], v[0:3]
	v_mfma_f32_16x16x32_bf16 v[4:7], v[144:147], v[202:205], v[4:7]
	v_mfma_f32_16x16x32_bf16 v[52:55], v[148:151], v[164:167], v[52:55]
	v_mfma_f32_16x16x32_bf16 v[48:51], v[156:159], v[164:167], v[48:51]
	v_mfma_f32_16x16x32_bf16 v[32:35], v[156:159], v[172:175], v[32:35]
	v_mfma_f32_16x16x32_bf16 v[36:39], v[148:151], v[172:175], v[36:39]
	v_mfma_f32_16x16x32_bf16 v[20:23], v[148:151], v[180:183], v[20:23]
	v_mfma_f32_16x16x32_bf16 v[16:19], v[156:159], v[180:183], v[16:19]
	v_mfma_f32_16x16x32_bf16 v[0:3], v[156:159], v[206:209], v[0:3]
	v_mfma_f32_16x16x32_bf16 v[4:7], v[148:151], v[206:209], v[4:7]
	s_barrier
	s_add_i32 s70, s70, 2
	s_add_u32 s20, s20, 0x100
	s_addc_u32 s21, s21, 0
	s_add_u32 s68, s68, 0x100
	s_addc_u32 s69, s69, 0
	s_cmp_gt_u32 s70, 41
; #define PG8_STAGE(bufoff, gbase, voff) do { _Pragma("unroll") for (int _i = 0; _i < 2; ++_i) \
;         __builtin_amdgcn_global_load_lds((const unsigned*)((const char*)(gbase) + (voff)[_i]), (PG8_LAS unsigned*)(lds + (bufoff) + ldsw + _i * 8192), 16, 0, 0); } while (0)
; #define PG8_LDA(dst, b, h) do { _Pragma("unroll") for (int m = 0; m < 4; ++m) _Pragma("unroll") for (int k = 0; k < 2; ++k) dst[m][k] = *(const PG8_LAS bf16x8*)(lds + PG8_SA(b, h) + aoff + m * 2048 + k * 1024); } while (0)
; #define PG8_LDB(dst, b, h) do { _Pragma("unroll") for (int n = 0; n < 2; ++n) _Pragma("unroll") for (int k = 0; k < 2; ++k) dst[n][k] = *(const PG8_LAS bf16x8*)(lds + PG8_SB(b, h) + boff + n * 2048 + k * 1024); } while (0)
; #define PG8_MMA(ai, bj, At, Bt) do { __builtin_amdgcn_s_setprio(1); _Pragma("unroll") for (int m = 0; m < 4; ++m) _Pragma("unroll") for (int n = 0; n < 2; ++n) _Pragma("unroll") for (int k = 0; k < 2; ++k) \
;         acc[ai][bj][m][n] = __builtin_amdgcn_mfma_f32_16x16x32_bf16(Bt[n][k], At[m][k], acc[ai][bj][m][n], 0, 0, 0); __builtin_amdgcn_s_setprio(0); } while (0)
; #define PG8_WAIT_V(n) asm volatile("s_waitcnt vmcnt(" #n ")" ::: "memory")
; #define PG8_WAIT_L(n) asm volatile("s_waitcnt lgkmcnt(" #n ")" ::: "memory")
; #define PG8_BAR __builtin_amdgcn_s_barrier()
; #define PG8_SCHED __builtin_amdgcn_sched_barrier(0)
; template <class Epi, class Sched, bool ALIGN_EPI = false, bool SP2 = false>
; __device__ __forceinline__ void gemm_phase(PG8_LAS unsigned char* lds, const Gemm g, const Sched& S, const Epi& E) {
;     ...
;             PG8_LDB(B0, 0, 0); PG8_LDB(B1, 0, 1); PG8_SCHED; PG8_LDA(At, 0, 0); PG8_STAGE(PG8_SA(1, 1), a1 + hstep, voffA);
;             PG8_WAIT_V(8); PG8_WAIT_L(0); PG8_BAR; PG8_MMA(0, 0, At, B0); PG8_MMA(0, 1, At, B1); PG8_BAR; PG8_SCHED;
;             PG8_LDA(At, 0, 1); PG8_STAGE(PG8_SB(0, 0), b2, voffB); PG8_STAGE(PG8_SB(0, 1), b2 + hstep, voffB); PG8_STAGE(PG8_SA(0, 0), a2, voffA);
;             PG8_WAIT_V(8); PG8_WAIT_L(0); PG8_BAR; PG8_MMA(1, 0, At, B0); PG8_MMA(1, 1, At, B1); PG8_BAR; PG8_SCHED;
.LBB0_1825:
	ds_read_b128 v[96:99], v222
	ds_read_b128 v[108:111], v222 offset:1024
	ds_read_b128 v[120:123], v222 offset:2048
	ds_read_b128 v[128:131], v222 offset:3072
	ds_read_b128 v[144:147], v223
	ds_read_b128 v[148:151], v223 offset:1024
	ds_read_b128 v[152:155], v223 offset:2048
	ds_read_b128 v[156:159], v223 offset:3072
	s_add_u32 s34, s20, 0xfff50080
	s_addc_u32 s35, s21, -1
	s_cmp_eq_u32 s70, 40
	s_cselect_b32 s47, s1, s35
	s_cselect_b32 s46, s0, s34
	s_cselect_b32 s35, s45, s69
	s_cselect_b32 s34, s44, s68
	s_add_i32 m0, s49, 0xc000
	ds_read_b128 v[160:163], v224
	ds_read_b128 v[164:167], v224 offset:1024
	ds_read_b128 v[168:171], v224 offset:2048
	ds_read_b128 v[172:175], v224 offset:3072
	ds_read_b128 v[176:179], v224 offset:4096
	ds_read_b128 v[180:183], v224 offset:5120
	ds_read_b128 v[202:205], v224 offset:6144
	ds_read_b128 v[206:209], v224 offset:7168
	global_load_lds_dwordx4 v192, s[20:21]
	s_add_i32 m0, s49, 0xe000
	s_nop 0
	global_load_lds_dwordx4 v194, s[20:21]
	s_waitcnt vmcnt(8)
	s_waitcnt lgkmcnt(0)
	s_barrier
	v_mfma_f32_16x16x32_bf16 v[140:143], v[96:99], v[160:163], v[140:143]
	v_mfma_f32_16x16x32_bf16 v[136:139], v[120:123], v[160:163], v[136:139]
	v_mfma_f32_16x16x32_bf16 v[112:115], v[120:123], v[168:171], v[112:115]
	v_mfma_f32_16x16x32_bf16 v[116:119], v[96:99], v[168:171], v[116:119]
	v_mfma_f32_16x16x32_bf16 v[92:95], v[96:99], v[176:179], v[92:95]
	v_mfma_f32_16x16x32_bf16 v[88:91], v[120:123], v[176:179], v[88:91]
	v_mfma_f32_16x16x32_bf16 v[72:75], v[120:123], v[202:205], v[72:75]
	v_mfma_f32_16x16x32_bf16 v[76:79], v[96:99], v[202:205], v[76:79]
	v_mfma_f32_16x16x32_bf16 v[140:143], v[108:111], v[164:167], v[140:143]
	v_mfma_f32_16x16x32_bf16 v[136:139], v[128:131], v[164:167], v[136:139]
	v_mfma_f32_16x16x32_bf16 v[112:115], v[128:131], v[172:175], v[112:115]
	v_mfma_f32_16x16x32_bf16 v[116:119], v[108:111], v[172:175], v[116:119]
	v_mfma_f32_16x16x32_bf16 v[92:95], v[108:111], v[180:183], v[92:95]
	v_mfma_f32_16x16x32_bf16 v[88:91], v[128:131], v[180:183], v[88:91]
	v_mfma_f32_16x16x32_bf16 v[72:75], v[128:131], v[206:209], v[72:75]
	v_mfma_f32_16x16x32_bf16 v[76:79], v[108:111], v[206:209], v[76:79]
	v_mfma_f32_16x16x32_bf16 v[132:135], v[144:147], v[160:163], v[132:135]
	v_mfma_f32_16x16x32_bf16 v[124:127], v[152:155], v[160:163], v[124:127]
	v_mfma_f32_16x16x32_bf16 v[100:103], v[152:155], v[168:171], v[100:103]
	v_mfma_f32_16x16x32_bf16 v[104:107], v[144:147], v[168:171], v[104:107]
	v_mfma_f32_16x16x32_bf16 v[84:87], v[144:147], v[176:179], v[84:87]
	v_mfma_f32_16x16x32_bf16 v[80:83], v[152:155], v[176:179], v[80:83]
	v_mfma_f32_16x16x32_bf16 v[64:67], v[152:155], v[202:205], v[64:67]
	v_mfma_f32_16x16x32_bf16 v[68:71], v[144:147], v[202:205], v[68:71]
	v_mfma_f32_16x16x32_bf16 v[132:135], v[148:151], v[164:167], v[132:135]
	v_mfma_f32_16x16x32_bf16 v[124:127], v[156:159], v[164:167], v[124:127]
	v_mfma_f32_16x16x32_bf16 v[100:103], v[156:159], v[172:175], v[100:103]
	v_mfma_f32_16x16x32_bf16 v[104:107], v[148:151], v[172:175], v[104:107]
	v_mfma_f32_16x16x32_bf16 v[84:87], v[148:151], v[180:183], v[84:87]
	v_mfma_f32_16x16x32_bf16 v[80:83], v[156:159], v[180:183], v[80:83]
	v_mfma_f32_16x16x32_bf16 v[64:67], v[156:159], v[206:209], v[64:67]
	v_mfma_f32_16x16x32_bf16 v[68:71], v[148:151], v[206:209], v[68:71]
	s_barrier
	s_add_i32 s71, s62, s48
	s_add_u32 s98, s34, s12
	s_addc_u32 s99, s35, s13
	s_add_u32 s100, s46, s12
	s_addc_u32 s101, s47, s13
	s_mov_b32 m0, s71
	ds_read_b128 v[160:163], v224 offset:16384
	ds_read_b128 v[164:167], v224 offset:17408
	ds_read_b128 v[168:171], v224 offset:18432
	ds_read_b128 v[172:175], v224 offset:19456
	ds_read_b128 v[176:179], v224 offset:20480
	ds_read_b128 v[180:183], v224 offset:21504
	ds_read_b128 v[202:205], v224 offset:22528
	ds_read_b128 v[206:209], v224 offset:23552
	global_load_lds_dwordx4 v186, s[34:35]
	s_add_i32 m0, s71, 0x2000
	s_add_u32 s72, s34, 0xb0000
	s_addc_u32 s73, s35, 0
	s_add_i32 s71, s63, s48
	global_load_lds_dwordx4 v190, s[34:35]
	s_mov_b32 m0, s71
	s_nop 0
	global_load_lds_dwordx4 v186, s[72:73]
	s_add_i32 m0, s71, 0x2000
	s_nop 0
	global_load_lds_dwordx4 v190, s[72:73]
	s_mov_b32 m0, s49
	s_nop 0
	global_load_lds_dwordx4 v184, s[46:47]
	s_mov_b32 m0, s50
	s_nop 0
	global_load_lds_dwordx4 v188, s[46:47]
	s_waitcnt vmcnt(8)
	s_waitcnt lgkmcnt(0)
	s_barrier
	v_mfma_f32_16x16x32_bf16 v[60:63], v[96:99], v[160:163], v[60:63]
	v_mfma_f32_16x16x32_bf16 v[56:59], v[120:123], v[160:163], v[56:59]
	v_mfma_f32_16x16x32_bf16 v[40:43], v[120:123], v[168:171], v[40:43]
	v_mfma_f32_16x16x32_bf16 v[44:47], v[96:99], v[168:171], v[44:47]
	v_mfma_f32_16x16x32_bf16 v[28:31], v[96:99], v[176:179], v[28:31]
	v_mfma_f32_16x16x32_bf16 v[24:27], v[120:123], v[176:179], v[24:27]
	v_mfma_f32_16x16x32_bf16 v[8:11], v[120:123], v[202:205], v[8:11]
	v_mfma_f32_16x16x32_bf16 v[12:15], v[96:99], v[202:205], v[12:15]
	v_mfma_f32_16x16x32_bf16 v[60:63], v[108:111], v[164:167], v[60:63]
	v_mfma_f32_16x16x32_bf16 v[56:59], v[128:131], v[164:167], v[56:59]
	v_mfma_f32_16x16x32_bf16 v[40:43], v[128:131], v[172:175], v[40:43]
	v_mfma_f32_16x16x32_bf16 v[44:47], v[108:111], v[172:175], v[44:47]
	v_mfma_f32_16x16x32_bf16 v[28:31], v[108:111], v[180:183], v[28:31]
	v_mfma_f32_16x16x32_bf16 v[24:27], v[128:131], v[180:183], v[24:27]
	v_mfma_f32_16x16x32_bf16 v[8:11], v[128:131], v[206:209], v[8:11]
	v_mfma_f32_16x16x32_bf16 v[12:15], v[108:111], v[206:209], v[12:15]
	v_mfma_f32_16x16x32_bf16 v[52:55], v[144:147], v[160:163], v[52:55]
	v_mfma_f32_16x16x32_bf16 v[48:51], v[152:155], v[160:163], v[48:51]
	v_mfma_f32_16x16x32_bf16 v[32:35], v[152:155], v[168:171], v[32:35]
	v_mfma_f32_16x16x32_bf16 v[36:39], v[144:147], v[168:171], v[36:39]
	v_mfma_f32_16x16x32_bf16 v[20:23], v[144:147], v[176:179], v[20:23]
	v_mfma_f32_16x16x32_bf16 v[16:19], v[152:155], v[176:179], v[16:19]
	v_mfma_f32_16x16x32_bf16 v[0:3], v[152:155], v[202:205], v[0:3]
	v_mfma_f32_16x16x32_bf16 v[4:7], v[144:147], v[202:205], v[4:7]
	v_mfma_f32_16x16x32_bf16 v[52:55], v[148:151], v[164:167], v[52:55]
	v_mfma_f32_16x16x32_bf16 v[48:51], v[156:159], v[164:167], v[48:51]
	v_mfma_f32_16x16x32_bf16 v[32:35], v[156:159], v[172:175], v[32:35]
	v_mfma_f32_16x16x32_bf16 v[36:39], v[148:151], v[172:175], v[36:39]
	v_mfma_f32_16x16x32_bf16 v[20:23], v[148:151], v[180:183], v[20:23]
	v_mfma_f32_16x16x32_bf16 v[16:19], v[156:159], v[180:183], v[16:19]
	v_mfma_f32_16x16x32_bf16 v[0:3], v[156:159], v[206:209], v[0:3]
	v_mfma_f32_16x16x32_bf16 v[4:7], v[148:151], v[206:209], v[4:7]
	s_barrier
; #define PG8_STAGE(bufoff, gbase, voff) do { _Pragma("unroll") for (int _i = 0; _i < 2; ++_i) \
;         __builtin_amdgcn_global_load_lds((const unsigned*)((const char*)(gbase) + (voff)[_i]), (PG8_LAS unsigned*)(lds + (bufoff) + ldsw + _i * 8192), 16, 0, 0); } while (0)
; #define PG8_LDA(dst, b, h) do { _Pragma("unroll") for (int m = 0; m < 4; ++m) _Pragma("unroll") for (int k = 0; k < 2; ++k) dst[m][k] = *(const PG8_LAS bf16x8*)(lds + PG8_SA(b, h) + aoff + m * 2048 + k * 1024); } while (0)
; #define PG8_LDB(dst, b, h) do { _Pragma("unroll") for (int n = 0; n < 2; ++n) _Pragma("unroll") for (int k = 0; k < 2; ++k) dst[n][k] = *(const PG8_LAS bf16x8*)(lds + PG8_SB(b, h) + boff + n * 2048 + k * 1024); } while (0)
; #define PG8_MMA(ai, bj, At, Bt) do { __builtin_amdgcn_s_setprio(1); _Pragma("unroll") for (int m = 0; m < 4; ++m) _Pragma("unroll") for (int n = 0; n < 2; ++n) _Pragma("unroll") for (int k = 0; k < 2; ++k) \
;         acc[ai][bj][m][n] = __builtin_amdgcn_mfma_f32_16x16x32_bf16(Bt[n][k], At[m][k], acc[ai][bj][m][n], 0, 0, 0); __builtin_amdgcn_s_setprio(0); } while (0)
; #define PG8_WAIT_V(n) asm volatile("s_waitcnt vmcnt(" #n ")" ::: "memory")
; #define PG8_WAIT_L(n) asm volatile("s_waitcnt lgkmcnt(" #n ")" ::: "memory")
; #define PG8_BAR __builtin_amdgcn_s_barrier()
; #define PG8_SCHED __builtin_amdgcn_sched_barrier(0)
; template <class Epi, class Sched, bool ALIGN_EPI = false, bool SP2 = false>
; __device__ __forceinline__ void gemm_phase(PG8_LAS unsigned char* lds, const Gemm g, const Sched& S, const Epi& E) {
;     ...
;             PG8_LDB(B0, 1, 0); PG8_LDB(B1, 1, 1); PG8_SCHED; PG8_LDA(At, 1, 0); PG8_STAGE(PG8_SA(0, 1), a2 + hstep, voffA);
;             PG8_WAIT_V(8); PG8_WAIT_L(0); PG8_BAR; PG8_MMA(0, 0, At, B0); PG8_MMA(0, 1, At, B1); PG8_BAR; PG8_SCHED;
;             PG8_LDA(At, 1, 1); PG8_STAGE(PG8_SB(1, 0), b3, voffB); PG8_STAGE(PG8_SB(1, 1), b3 + hstep, voffB); PG8_STAGE(PG8_SA(1, 0), a3, voffA);
;             PG8_WAIT_V(8); PG8_WAIT_L(0); PG8_BAR; PG8_MMA(1, 0, At, B0); PG8_MMA(1, 1, At, B1); PG8_BAR; PG8_SCHED;
;     ...
;         if constexpr (ALIGN_EPI) { if (wr == 0) PG8_BAR; }
	s_add_i32 s71, 0, 0x18000
	s_add_i32 s72, 0, 0x1c000
	v_add_u32_e32 v128, s71, v197
	v_add_u32_e32 v156, s72, v197
	ds_read_b128 v[96:99], v128
	ds_read_b128 v[108:111], v128 offset:1024
	ds_read_b128 v[120:123], v128 offset:2048
	ds_read_b128 v[128:131], v128 offset:3072
	ds_read_b128 v[144:147], v156
	ds_read_b128 v[148:151], v156 offset:1024
	ds_read_b128 v[152:155], v156 offset:2048
	ds_read_b128 v[156:159], v156 offset:3072
	s_add_u32 s46, s46, 0xb0000
	s_addc_u32 s47, s47, 0
	s_mov_b32 m0, s51
	ds_read_b128 v[160:163], v224 offset:32768
	ds_read_b128 v[164:167], v224 offset:33792
	ds_read_b128 v[168:171], v224 offset:34816
	ds_read_b128 v[172:175], v224 offset:35840
	ds_read_b128 v[176:179], v224 offset:36864
	ds_read_b128 v[180:183], v224 offset:37888
	ds_read_b128 v[202:205], v224 offset:38912
	ds_read_b128 v[206:209], v224 offset:39936
	global_load_lds_dwordx4 v184, s[46:47]
	s_mov_b32 m0, s52
	s_nop 0
	global_load_lds_dwordx4 v188, s[46:47]
	s_waitcnt vmcnt(8)
	s_waitcnt lgkmcnt(0)
	s_barrier
	v_mfma_f32_16x16x32_bf16 v[140:143], v[96:99], v[160:163], v[140:143]
	v_mfma_f32_16x16x32_bf16 v[136:139], v[120:123], v[160:163], v[136:139]
	v_mfma_f32_16x16x32_bf16 v[112:115], v[120:123], v[168:171], v[112:115]
	v_mfma_f32_16x16x32_bf16 v[116:119], v[96:99], v[168:171], v[116:119]
	v_mfma_f32_16x16x32_bf16 v[92:95], v[96:99], v[176:179], v[92:95]
	v_mfma_f32_16x16x32_bf16 v[88:91], v[120:123], v[176:179], v[88:91]
	v_mfma_f32_16x16x32_bf16 v[72:75], v[120:123], v[202:205], v[72:75]
	v_mfma_f32_16x16x32_bf16 v[76:79], v[96:99], v[202:205], v[76:79]
	v_mfma_f32_16x16x32_bf16 v[140:143], v[108:111], v[164:167], v[140:143]
	v_mfma_f32_16x16x32_bf16 v[136:139], v[128:131], v[164:167], v[136:139]
	v_mfma_f32_16x16x32_bf16 v[112:115], v[128:131], v[172:175], v[112:115]
	v_mfma_f32_16x16x32_bf16 v[116:119], v[108:111], v[172:175], v[116:119]
	v_mfma_f32_16x16x32_bf16 v[92:95], v[108:111], v[180:183], v[92:95]
	v_mfma_f32_16x16x32_bf16 v[88:91], v[128:131], v[180:183], v[88:91]
	v_mfma_f32_16x16x32_bf16 v[72:75], v[128:131], v[206:209], v[72:75]
	v_mfma_f32_16x16x32_bf16 v[76:79], v[108:111], v[206:209], v[76:79]
	v_mfma_f32_16x16x32_bf16 v[132:135], v[144:147], v[160:163], v[132:135]
	v_mfma_f32_16x16x32_bf16 v[124:127], v[152:155], v[160:163], v[124:127]
	v_mfma_f32_16x16x32_bf16 v[100:103], v[152:155], v[168:171], v[100:103]
	v_mfma_f32_16x16x32_bf16 v[104:107], v[144:147], v[168:171], v[104:107]
	v_mfma_f32_16x16x32_bf16 v[84:87], v[144:147], v[176:179], v[84:87]
	v_mfma_f32_16x16x32_bf16 v[80:83], v[152:155], v[176:179], v[80:83]
	v_mfma_f32_16x16x32_bf16 v[64:67], v[152:155], v[202:205], v[64:67]
	v_mfma_f32_16x16x32_bf16 v[68:71], v[144:147], v[202:205], v[68:71]
	v_mfma_f32_16x16x32_bf16 v[132:135], v[148:151], v[164:167], v[132:135]
	v_mfma_f32_16x16x32_bf16 v[124:127], v[156:159], v[164:167], v[124:127]
	v_mfma_f32_16x16x32_bf16 v[100:103], v[156:159], v[172:175], v[100:103]
	v_mfma_f32_16x16x32_bf16 v[104:107], v[148:151], v[172:175], v[104:107]
	v_mfma_f32_16x16x32_bf16 v[84:87], v[148:151], v[180:183], v[84:87]
	v_mfma_f32_16x16x32_bf16 v[80:83], v[156:159], v[180:183], v[80:83]
	v_mfma_f32_16x16x32_bf16 v[64:67], v[156:159], v[206:209], v[64:67]
	v_mfma_f32_16x16x32_bf16 v[68:71], v[148:151], v[206:209], v[68:71]
	s_barrier
	s_add_i32 s46, s71, s48
	s_mov_b32 m0, s46
	ds_read_b128 v[160:163], v224 offset:49152
	ds_read_b128 v[164:167], v224 offset:50176
	ds_read_b128 v[168:171], v224 offset:51200
	ds_read_b128 v[172:175], v224 offset:52224
	ds_read_b128 v[176:179], v224 offset:53248
	ds_read_b128 v[180:183], v224 offset:54272
	ds_read_b128 v[202:205], v224 offset:55296
	ds_read_b128 v[206:209], v224 offset:56320
	global_load_lds_dwordx4 v186, s[98:99]
	s_add_i32 m0, s46, 0x2000
	s_add_u32 s34, s34, 0xb0080
	s_addc_u32 s35, s35, 0
	s_add_i32 s46, s72, s48
	global_load_lds_dwordx4 v190, s[98:99]
	s_mov_b32 m0, s46
	s_nop 0
	global_load_lds_dwordx4 v186, s[34:35]
	s_add_i32 m0, s46, 0x2000
	s_nop 0
	global_load_lds_dwordx4 v190, s[34:35]
	s_mov_b32 m0, s57
	s_nop 0
	global_load_lds_dwordx4 v184, s[100:101]
	s_mov_b32 m0, s58
	s_nop 0
	global_load_lds_dwordx4 v188, s[100:101]
	s_waitcnt vmcnt(8)
	s_waitcnt lgkmcnt(0)
	s_barrier
	v_mfma_f32_16x16x32_bf16 v[60:63], v[96:99], v[160:163], v[60:63]
	v_mfma_f32_16x16x32_bf16 v[56:59], v[120:123], v[160:163], v[56:59]
	v_mfma_f32_16x16x32_bf16 v[40:43], v[120:123], v[168:171], v[40:43]
	v_mfma_f32_16x16x32_bf16 v[44:47], v[96:99], v[168:171], v[44:47]
	v_mfma_f32_16x16x32_bf16 v[28:31], v[96:99], v[176:179], v[28:31]
	v_mfma_f32_16x16x32_bf16 v[24:27], v[120:123], v[176:179], v[24:27]
	v_mfma_f32_16x16x32_bf16 v[8:11], v[120:123], v[202:205], v[8:11]
	v_mfma_f32_16x16x32_bf16 v[12:15], v[96:99], v[202:205], v[12:15]
	v_mfma_f32_16x16x32_bf16 v[60:63], v[108:111], v[164:167], v[60:63]
	v_mfma_f32_16x16x32_bf16 v[56:59], v[128:131], v[164:167], v[56:59]
	v_mfma_f32_16x16x32_bf16 v[40:43], v[128:131], v[172:175], v[40:43]
	v_mfma_f32_16x16x32_bf16 v[44:47], v[108:111], v[172:175], v[44:47]
	v_mfma_f32_16x16x32_bf16 v[28:31], v[108:111], v[180:183], v[28:31]
	v_mfma_f32_16x16x32_bf16 v[24:27], v[128:131], v[180:183], v[24:27]
	v_mfma_f32_16x16x32_bf16 v[8:11], v[128:131], v[206:209], v[8:11]
	v_mfma_f32_16x16x32_bf16 v[12:15], v[108:111], v[206:209], v[12:15]
	v_mfma_f32_16x16x32_bf16 v[52:55], v[144:147], v[160:163], v[52:55]
	v_mfma_f32_16x16x32_bf16 v[48:51], v[152:155], v[160:163], v[48:51]
	v_mfma_f32_16x16x32_bf16 v[32:35], v[152:155], v[168:171], v[32:35]
	v_mfma_f32_16x16x32_bf16 v[36:39], v[144:147], v[168:171], v[36:39]
	v_mfma_f32_16x16x32_bf16 v[20:23], v[144:147], v[176:179], v[20:23]
	v_mfma_f32_16x16x32_bf16 v[16:19], v[152:155], v[176:179], v[16:19]
	v_mfma_f32_16x16x32_bf16 v[0:3], v[152:155], v[202:205], v[0:3]
	v_mfma_f32_16x16x32_bf16 v[4:7], v[144:147], v[202:205], v[4:7]
	v_mfma_f32_16x16x32_bf16 v[52:55], v[148:151], v[164:167], v[52:55]
	v_mfma_f32_16x16x32_bf16 v[48:51], v[156:159], v[164:167], v[48:51]
	v_mfma_f32_16x16x32_bf16 v[32:35], v[156:159], v[172:175], v[32:35]
	v_mfma_f32_16x16x32_bf16 v[36:39], v[148:151], v[172:175], v[36:39]
	v_mfma_f32_16x16x32_bf16 v[20:23], v[148:151], v[180:183], v[20:23]
	v_mfma_f32_16x16x32_bf16 v[16:19], v[156:159], v[180:183], v[16:19]
	v_mfma_f32_16x16x32_bf16 v[0:3], v[156:159], v[206:209], v[0:3]
	v_mfma_f32_16x16x32_bf16 v[4:7], v[148:151], v[206:209], v[4:7]
	s_barrier
	s_add_i32 s70, s70, 2
	s_add_u32 s20, s20, 0x100
	s_addc_u32 s21, s21, 0
	s_add_u32 s68, s68, 0x100
	s_addc_u32 s69, s69, 0
	s_cmp_gt_u32 s70, 41
	s_cbranch_scc0 .LBB0_1825
	s_and_b64 vcc, exec, s[14:15]
	s_cbranch_vccz .LBB0_1828
	s_barrier
